# one static priority raise for the second workgroup of each CU pair (id >= 256) in the GEMM phases; hipcc per-cluster s_setprio flips removed; attention at priority 0
# baseline (speedup 1.0000x reference)
; __global__ void __launch_bounds__(256, 2) fwd_megakernel(Params pk) {
;     ...
;   for (int ph = 0; ph < 22; ++ph) {
;     const int l = ph >= 11 ? 1 : 0, q = ph - l * 11;
;     Params p = pk;
;     {
;       asm volatile("" ::: "memory");
;       unsigned long long w_ = g_base_sh[0], o_ = g_base_sh[1];
;       unsigned wl_ = (unsigned)w_, wh_ = (unsigned)(w_ >> 32), ol_ = (unsigned)o_, oh_ = (unsigned)(o_ >> 32);
;       wl_ = __builtin_amdgcn_readfirstlane(wl_); wh_ = __builtin_amdgcn_readfirstlane(wh_); ol_ = __builtin_amdgcn_readfirstlane(ol_); oh_ = __builtin_amdgcn_readfirstlane(oh_);
;       asm volatile("" : "+s"(wl_), "+s"(wh_), "+s"(ol_), "+s"(oh_));
;       p.ws = (char*)(((unsigned long long)wh_ << 32) | wl_); p.out = (float*)(((unsigned long long)oh_ << 32) | ol_);
;     }
; #pragma nounroll
;     for (int rep = 0; rep < (q == PROBE_Q ? 2 : 1); ++rep)
;     switch (q) {
.LBB0_431:
	s_setprio 0
	s_cmpk_gt_i32 s2, 0xff
	s_cbranch_scc0 .Lprio_done
	s_setprio 1

; template <int MI, int NI>
; DI void gemm256(f32x4 (&acc)[MI][NI], const u16* __restrict__ A, int lda, const u16* __restrict__ Bt, int ldb, int K, int m0, int n0, char* smem) {
;     ...
;   const int nk = K >> 5;
;   G256_ISSUE(0, 0);
;   if (nk > 1) G256_ISSUE(1, 32);
;   const int foff = lr * 64 + ((lq ^ ((lr >> 3) << 1)) * 16);
;   int st = 0;
;   for (int kt = 0; kt < nk; ++kt) {
;     if (kt + 1 < nk) asm volatile("s_waitcnt vmcnt(%0) lgkmcnt(0)" :: "n"(LPS) : "memory");
;     else asm volatile("s_waitcnt vmcnt(0) lgkmcnt(0)" ::: "memory");
;     __builtin_amdgcn_s_barrier();
;     __builtin_amdgcn_s_setprio(1);
;     const char* sb = smem + st * STAGE + foff;
;     bf16x8 af[MI], bfr[NI];
; #pragma unroll
;     for (int mi = 0; mi < MI; ++mi) af[mi] = *(const bf16x8*)(sb + (wr * MI + mi) * 1024);
; #pragma unroll
;     for (int ni = 0; ni < NI; ++ni) bfr[ni] = *(const bf16x8*)(sb + ABYTES + (wc * NI + ni) * 1024);
;     __builtin_amdgcn_sched_barrier(0x0);
;     if (kt + 2 < nk) { const int s2 = st >= 1 ? st - 1 : 2; G256_ISSUE(s2, (kt + 2) * 32); }
;     __builtin_amdgcn_s_setprio(0);
; #pragma unroll
;     for (int mi = 0; mi < MI; ++mi)
; #pragma unroll
;       for (int ni = 0; ni < NI; ++ni)
;         acc[mi][ni] = __builtin_amdgcn_mfma_f32_16x16x32_bf16(bfr[ni], af[mi], acc[mi][ni], 0, 0, 0);
;     st = st == 2 ? 0 : st + 1;
;   }
.Lpipe_mlp1:
	v_add_u32_e32 v160, s11, v143
	ds_read_b128 v[164:167], v160 offset:4096
	ds_read_b128 v[168:171], v160 offset:5120
	ds_read_b128 v[172:175], v160 offset:6144
	ds_read_b128 v[176:179], v160 offset:7168
	s_add_i32 s12, s11, 0xffffa000
	s_cmp_eq_u32 s11, 0
	s_cselect_b32 s12, 0xc000, s12
	s_add_i32 s13, s12, s14
	s_add_i32 s12, s12, s4
	s_mov_b32 m0, s13
	s_waitcnt lgkmcnt(7)
	v_mfma_f32_16x16x32_bf16 v[126:129], v[180:183], v[144:147], v[126:129]
	global_load_lds_dwordx4 v[198:199], off
	v_mfma_f32_16x16x32_bf16 v[110:113], v[180:183], v[148:151], v[110:113]
	v_lshl_add_u64 v[198:199], v[198:199], 0, s[98:99]
	s_add_i32 m0, s13, 0x400
	v_mfma_f32_16x16x32_bf16 v[94:97], v[180:183], v[152:155], v[94:97]
	global_load_lds_dwordx4 v[200:201], off
	v_mfma_f32_16x16x32_bf16 v[78:81], v[180:183], v[156:159], v[78:81]
	v_lshl_add_u64 v[200:201], v[200:201], 0, s[98:99]
	s_add_i32 m0, s13, 0x800
	s_waitcnt lgkmcnt(6)
	v_mfma_f32_16x16x32_bf16 v[122:125], v[184:187], v[144:147], v[122:125]
	global_load_lds_dwordx4 v[202:203], off
	v_mfma_f32_16x16x32_bf16 v[106:109], v[184:187], v[148:151], v[106:109]
	v_lshl_add_u64 v[202:203], v[202:203], 0, s[98:99]
	s_add_i32 m0, s13, 0xc00
	v_mfma_f32_16x16x32_bf16 v[90:93], v[184:187], v[152:155], v[90:93]
	global_load_lds_dwordx4 v[204:205], off
	v_mfma_f32_16x16x32_bf16 v[74:77], v[184:187], v[156:159], v[74:77]
	v_lshl_add_u64 v[204:205], v[204:205], 0, s[98:99]
	s_mov_b32 m0, s12
	s_waitcnt lgkmcnt(5)
	v_mfma_f32_16x16x32_bf16 v[118:121], v[188:191], v[144:147], v[118:121]
	global_load_lds_dwordx4 v[206:207], off
	v_mfma_f32_16x16x32_bf16 v[102:105], v[188:191], v[148:151], v[102:105]
	v_lshl_add_u64 v[206:207], v[206:207], 0, s[98:99]
	s_add_i32 m0, s12, 0x400
	v_mfma_f32_16x16x32_bf16 v[86:89], v[188:191], v[152:155], v[86:89]
	global_load_lds_dwordx4 v[208:209], off
	v_mfma_f32_16x16x32_bf16 v[70:73], v[188:191], v[156:159], v[70:73]
	v_lshl_add_u64 v[208:209], v[208:209], 0, s[98:99]
	s_waitcnt lgkmcnt(4)
	v_mfma_f32_16x16x32_bf16 v[114:117], v[192:195], v[144:147], v[114:117]
	v_mfma_f32_16x16x32_bf16 v[98:101], v[192:195], v[148:151], v[98:101]
	v_mfma_f32_16x16x32_bf16 v[82:85], v[192:195], v[152:155], v[82:85]
	v_mfma_f32_16x16x32_bf16 v[66:69], v[192:195], v[156:159], v[66:69]
	s_waitcnt vmcnt(6) lgkmcnt(0)
	s_barrier
	s_add_i32 s13, s11, 0x6000
	s_cmp_eq_u32 s11, 0xc000
	s_cselect_b32 s11, 0, s13
	v_add_u32_e32 v196, s11, v143
	v_add_u32_e32 v197, s11, v0
	v_mfma_f32_16x16x32_bf16 v[62:65], v[180:183], v[164:167], v[62:65]
	ds_read_b128 v[144:147], v196
	v_mfma_f32_16x16x32_bf16 v[46:49], v[180:183], v[168:171], v[46:49]
	ds_read_b128 v[148:151], v196 offset:1024
	v_mfma_f32_16x16x32_bf16 v[30:33], v[180:183], v[172:175], v[30:33]
	ds_read_b128 v[152:155], v196 offset:2048
	v_mfma_f32_16x16x32_bf16 v[14:17], v[180:183], v[176:179], v[14:17]
	ds_read_b128 v[156:159], v196 offset:3072
	ds_read_b128 v[180:183], v197 offset:16384
	v_mfma_f32_16x16x32_bf16 v[58:61], v[184:187], v[164:167], v[58:61]
	v_mfma_f32_16x16x32_bf16 v[42:45], v[184:187], v[168:171], v[42:45]
	v_mfma_f32_16x16x32_bf16 v[26:29], v[184:187], v[172:175], v[26:29]
	v_mfma_f32_16x16x32_bf16 v[10:13], v[184:187], v[176:179], v[10:13]
	ds_read_b128 v[184:187], v197 offset:17408
	v_mfma_f32_16x16x32_bf16 v[54:57], v[188:191], v[164:167], v[54:57]
	v_mfma_f32_16x16x32_bf16 v[38:41], v[188:191], v[168:171], v[38:41]
	v_mfma_f32_16x16x32_bf16 v[22:25], v[188:191], v[172:175], v[22:25]
	v_mfma_f32_16x16x32_bf16 v[6:9], v[188:191], v[176:179], v[6:9]
	ds_read_b128 v[188:191], v197 offset:18432
	v_mfma_f32_16x16x32_bf16 v[50:53], v[192:195], v[164:167], v[50:53]
	v_mfma_f32_16x16x32_bf16 v[34:37], v[192:195], v[168:171], v[34:37]
	v_mfma_f32_16x16x32_bf16 v[18:21], v[192:195], v[172:175], v[18:21]
	v_mfma_f32_16x16x32_bf16 v[2:5], v[192:195], v[176:179], v[2:5]
	ds_read_b128 v[192:195], v197 offset:19456
	s_sub_i32 s5, s5, 1
	s_cmp_lg_u32 s5, 0
	s_cbranch_scc1 .Lpipe_mlp1
	v_add_u32_e32 v160, s11, v143
	ds_read_b128 v[164:167], v160 offset:4096
	ds_read_b128 v[168:171], v160 offset:5120
	ds_read_b128 v[172:175], v160 offset:6144
	ds_read_b128 v[176:179], v160 offset:7168
	s_add_i32 s12, s11, 0xffffa000
	s_cmp_eq_u32 s11, 0
	s_cselect_b32 s12, 0xc000, s12
	s_add_i32 s13, s12, s14
	s_add_i32 s12, s12, s4
	s_mov_b32 m0, s13
	s_waitcnt lgkmcnt(7)
	v_mfma_f32_16x16x32_bf16 v[126:129], v[180:183], v[144:147], v[126:129]
	global_load_lds_dwordx4 v[198:199], off
	v_mfma_f32_16x16x32_bf16 v[110:113], v[180:183], v[148:151], v[110:113]
	v_lshl_add_u64 v[198:199], v[198:199], 0, s[98:99]
	s_add_i32 m0, s13, 0x400
	v_mfma_f32_16x16x32_bf16 v[94:97], v[180:183], v[152:155], v[94:97]
	global_load_lds_dwordx4 v[200:201], off
	v_mfma_f32_16x16x32_bf16 v[78:81], v[180:183], v[156:159], v[78:81]
	v_lshl_add_u64 v[200:201], v[200:201], 0, s[98:99]
	s_add_i32 m0, s13, 0x800
	s_waitcnt lgkmcnt(6)
	v_mfma_f32_16x16x32_bf16 v[122:125], v[184:187], v[144:147], v[122:125]
	global_load_lds_dwordx4 v[202:203], off
	v_mfma_f32_16x16x32_bf16 v[106:109], v[184:187], v[148:151], v[106:109]
	v_lshl_add_u64 v[202:203], v[202:203], 0, s[98:99]
	s_add_i32 m0, s13, 0xc00
	v_mfma_f32_16x16x32_bf16 v[90:93], v[184:187], v[152:155], v[90:93]
	global_load_lds_dwordx4 v[204:205], off
	v_mfma_f32_16x16x32_bf16 v[74:77], v[184:187], v[156:159], v[74:77]
	v_lshl_add_u64 v[204:205], v[204:205], 0, s[98:99]
	s_mov_b32 m0, s12
	s_waitcnt lgkmcnt(5)
; template <int MI, int NI>
; DI void gemm256(f32x4 (&acc)[MI][NI], const u16* __restrict__ A, int lda, const u16* __restrict__ Bt, int ldb, int K, int m0, int n0, char* smem) {
;     ...
;   for (int kt = 0; kt < nk; ++kt) {
;     if (kt + 1 < nk) asm volatile("s_waitcnt vmcnt(%0) lgkmcnt(0)" :: "n"(LPS) : "memory");
;     else asm volatile("s_waitcnt vmcnt(0) lgkmcnt(0)" ::: "memory");
;     __builtin_amdgcn_s_barrier();
;     __builtin_amdgcn_s_setprio(1);
;     const char* sb = smem + st * STAGE + foff;
;     bf16x8 af[MI], bfr[NI];
; #pragma unroll
;     for (int mi = 0; mi < MI; ++mi) af[mi] = *(const bf16x8*)(sb + (wr * MI + mi) * 1024);
; #pragma unroll
;     for (int ni = 0; ni < NI; ++ni) bfr[ni] = *(const bf16x8*)(sb + ABYTES + (wc * NI + ni) * 1024);
;     __builtin_amdgcn_sched_barrier(0x0);
;     if (kt + 2 < nk) { const int s2 = st >= 1 ? st - 1 : 2; G256_ISSUE(s2, (kt + 2) * 32); }
;     __builtin_amdgcn_s_setprio(0);
; #pragma unroll
;     for (int mi = 0; mi < MI; ++mi)
; #pragma unroll
;       for (int ni = 0; ni < NI; ++ni)
;         acc[mi][ni] = __builtin_amdgcn_mfma_f32_16x16x32_bf16(bfr[ni], af[mi], acc[mi][ni], 0, 0, 0);
;     st = st == 2 ? 0 : st + 1;
;   }
;   asm volatile("s_waitcnt lgkmcnt(0)" ::: "memory");
;   __builtin_amdgcn_s_barrier();
	v_mfma_f32_16x16x32_bf16 v[118:121], v[188:191], v[144:147], v[118:121]
	global_load_lds_dwordx4 v[206:207], off
	v_mfma_f32_16x16x32_bf16 v[102:105], v[188:191], v[148:151], v[102:105]
	v_lshl_add_u64 v[206:207], v[206:207], 0, s[98:99]
	s_add_i32 m0, s12, 0x400
	v_mfma_f32_16x16x32_bf16 v[86:89], v[188:191], v[152:155], v[86:89]
	global_load_lds_dwordx4 v[208:209], off
	v_mfma_f32_16x16x32_bf16 v[70:73], v[188:191], v[156:159], v[70:73]
	v_lshl_add_u64 v[208:209], v[208:209], 0, s[98:99]
	s_waitcnt lgkmcnt(4)
	v_mfma_f32_16x16x32_bf16 v[114:117], v[192:195], v[144:147], v[114:117]
	v_mfma_f32_16x16x32_bf16 v[98:101], v[192:195], v[148:151], v[98:101]
	v_mfma_f32_16x16x32_bf16 v[82:85], v[192:195], v[152:155], v[82:85]
	v_mfma_f32_16x16x32_bf16 v[66:69], v[192:195], v[156:159], v[66:69]
	s_waitcnt lgkmcnt(0)
	v_mfma_f32_16x16x32_bf16 v[62:65], v[180:183], v[164:167], v[62:65]
	v_mfma_f32_16x16x32_bf16 v[46:49], v[180:183], v[168:171], v[46:49]
	v_mfma_f32_16x16x32_bf16 v[30:33], v[180:183], v[172:175], v[30:33]
	v_mfma_f32_16x16x32_bf16 v[14:17], v[180:183], v[176:179], v[14:17]
	v_mfma_f32_16x16x32_bf16 v[58:61], v[184:187], v[164:167], v[58:61]
	v_mfma_f32_16x16x32_bf16 v[42:45], v[184:187], v[168:171], v[42:45]
	v_mfma_f32_16x16x32_bf16 v[26:29], v[184:187], v[172:175], v[26:29]
	v_mfma_f32_16x16x32_bf16 v[10:13], v[184:187], v[176:179], v[10:13]
	v_mfma_f32_16x16x32_bf16 v[54:57], v[188:191], v[164:167], v[54:57]
	v_mfma_f32_16x16x32_bf16 v[38:41], v[188:191], v[168:171], v[38:41]
	v_mfma_f32_16x16x32_bf16 v[22:25], v[188:191], v[172:175], v[22:25]
	v_mfma_f32_16x16x32_bf16 v[6:9], v[188:191], v[176:179], v[6:9]
	v_mfma_f32_16x16x32_bf16 v[50:53], v[192:195], v[164:167], v[50:53]
	v_mfma_f32_16x16x32_bf16 v[34:37], v[192:195], v[168:171], v[34:37]
	v_mfma_f32_16x16x32_bf16 v[18:21], v[192:195], v[172:175], v[18:21]
	v_mfma_f32_16x16x32_bf16 v[2:5], v[192:195], v[176:179], v[2:5]
	s_waitcnt vmcnt(6) lgkmcnt(0)
	s_barrier
	s_nop 0
	v_add_u32_e32 v0, v140, v142
	ds_read_b128 v[130:133], v0
	ds_read_b128 v[142:145], v0 offset:1024
	ds_read_b128 v[146:149], v0 offset:2048
	ds_read_b128 v[150:153], v0 offset:3072
	ds_read_b128 v[154:157], v0 offset:4096
	ds_read_b128 v[158:161], v0 offset:5120
	ds_read_b128 v[164:167], v0 offset:6144
	ds_read_b128 v[168:171], v0 offset:7168
	v_add_u32_e32 v212, v140, v141
	ds_read_b128 v[138:141], v212 offset:16384
	ds_read_b128 v[172:175], v212 offset:17408
	ds_read_b128 v[176:179], v212 offset:18432
	ds_read_b128 v[180:183], v212 offset:19456
	s_nop 0
	s_waitcnt vmcnt(0) lgkmcnt(0)
	s_waitcnt lgkmcnt(3)
	v_mfma_f32_16x16x32_bf16 v[126:129], v[138:141], v[130:133], v[126:129]
	s_barrier
	s_waitcnt lgkmcnt(2)
	v_mfma_f32_16x16x32_bf16 v[122:125], v[172:175], v[130:133], v[122:125]
	s_waitcnt lgkmcnt(1)
	v_mfma_f32_16x16x32_bf16 v[184:187], v[176:179], v[130:133], v[118:121]
	s_waitcnt lgkmcnt(0)
	v_mfma_f32_16x16x32_bf16 v[114:117], v[180:183], v[130:133], v[114:117]
	v_mfma_f32_16x16x32_bf16 v[130:133], v[138:141], v[142:145], v[110:113]
	v_mfma_f32_16x16x32_bf16 v[106:109], v[172:175], v[142:145], v[106:109]
	v_mfma_f32_16x16x32_bf16 v[188:191], v[176:179], v[142:145], v[102:105]
	v_mfma_f32_16x16x32_bf16 v[98:101], v[180:183], v[142:145], v[98:101]
	v_mfma_f32_16x16x32_bf16 v[94:97], v[138:141], v[146:149], v[94:97]
	v_mfma_f32_16x16x32_bf16 v[90:93], v[172:175], v[146:149], v[90:93]
	v_mfma_f32_16x16x32_bf16 v[142:145], v[176:179], v[146:149], v[86:89]
	v_mfma_f32_16x16x32_bf16 v[82:85], v[180:183], v[146:149], v[82:85]
	v_mfma_f32_16x16x32_bf16 v[146:149], v[138:141], v[150:153], v[78:81]
	v_mfma_f32_16x16x32_bf16 v[74:77], v[172:175], v[150:153], v[74:77]
	v_mfma_f32_16x16x32_bf16 v[192:195], v[176:179], v[150:153], v[70:73]
	v_mfma_f32_16x16x32_bf16 v[66:69], v[180:183], v[150:153], v[66:69]
	v_mfma_f32_16x16x32_bf16 v[62:65], v[138:141], v[154:157], v[62:65]
	v_mfma_f32_16x16x32_bf16 v[58:61], v[172:175], v[154:157], v[58:61]
	v_mfma_f32_16x16x32_bf16 v[150:153], v[176:179], v[154:157], v[54:57]
	v_mfma_f32_16x16x32_bf16 v[50:53], v[180:183], v[154:157], v[50:53]
	v_mfma_f32_16x16x32_bf16 v[154:157], v[138:141], v[158:161], v[46:49]
	v_mfma_f32_16x16x32_bf16 v[42:45], v[172:175], v[158:161], v[42:45]
	v_mfma_f32_16x16x32_bf16 v[196:199], v[176:179], v[158:161], v[38:41]
	v_mfma_f32_16x16x32_bf16 v[34:37], v[180:183], v[158:161], v[34:37]
	v_mfma_f32_16x16x32_bf16 v[30:33], v[138:141], v[164:167], v[30:33]
	v_mfma_f32_16x16x32_bf16 v[26:29], v[172:175], v[164:167], v[26:29]
	v_mfma_f32_16x16x32_bf16 v[158:161], v[176:179], v[164:167], v[22:25]
	v_mfma_f32_16x16x32_bf16 v[18:21], v[180:183], v[164:167], v[18:21]
	v_mfma_f32_16x16x32_bf16 v[138:141], v[138:141], v[168:171], v[14:17]
	v_mfma_f32_16x16x32_bf16 v[10:13], v[172:175], v[168:171], v[10:13]
	v_mfma_f32_16x16x32_bf16 v[164:167], v[176:179], v[168:171], v[6:9]
	v_mfma_f32_16x16x32_bf16 v[2:5], v[180:183], v[168:171], v[2:5]
	s_nop 0
	s_nop 0
	ds_read_b128 v[6:9], v0 offset:24576
	ds_read_b128 v[14:17], v0 offset:25600
	ds_read_b128 v[22:25], v0 offset:26624
	ds_read_b128 v[38:41], v0 offset:27648
	ds_read_b128 v[168:171], v0 offset:28672
	ds_read_b128 v[172:175], v0 offset:29696
	ds_read_b128 v[176:179], v0 offset:30720
	ds_read_b128 v[180:183], v0 offset:31744
	ds_read_b128 v[200:203], v212 offset:40960
	ds_read_b128 v[204:207], v212 offset:41984
	ds_read_b128 v[208:211], v212 offset:43008
	ds_read_b128 v[212:215], v212 offset:44032
	s_nop 0
	s_waitcnt lgkmcnt(3)
	v_mfma_f32_16x16x32_bf16 v[216:219], v[200:203], v[6:9], v[126:129]
	v_mov_b32_e32 v0, v136
	s_waitcnt lgkmcnt(0)
	s_barrier
; DI unsigned pack2(float a, float b) { float2_t v = {a, b}; bf16x2_t r = __builtin_convertvector(v, bf16x2_t); return __builtin_bit_cast(unsigned, r); }
; #define EPI_BEGIN const int lr1_ = launder_v(lr), lq1_ = launder_v(lq), wr1_ = launder_v(wr), wc1_ = launder_v(wc); { const int lr = lr1_, lq = lq1_, wr = wr1_, wc = wc1_; (void)lr; (void)lq; (void)wr; (void)wc;
; DI void phase_mlp1(const Params& p, int l, int Mout, char* smem) {
;     ...
;     EPI_BEGIN
; #pragma unroll
;     for (int mi = 0; mi < 8; mi += 2) {
;       const int m = m0 + wr * 128 + (mi + (lq & 1)) * 16 + lr;
; #pragma unroll
;       for (int ni = 0; ni < 4; ++ni) {
;         const int n = n0 + wc * 64 + ni * 16 + (lq >> 1) * 8;
;         float va[4], vb[4];
; #pragma unroll
;         for (int j = 0; j < 4; ++j) { const float a = fmaxf(acc[mi][ni][j], 0.f); va[j] = a * a; const float b = fmaxf(acc[mi + 1][ni][j], 0.f); vb[j] = b * b; }
;         *(uint4*)(U + (size_t)m * DFF + n) = widen16(make_uint2(pack2(va[0], va[1]), pack2(va[2], va[3])), make_uint2(pack2(vb[0], vb[1]), pack2(vb[2], vb[3])));
;       }
;       __builtin_amdgcn_sched_barrier(0);
;     }
	s_waitcnt lgkmcnt(2)
	v_mfma_f32_16x16x32_bf16 v[118:121], v[204:207], v[6:9], v[122:125]
	v_mov_b32_e32 v126, v137
	v_mov_b32_e32 v127, v134
	v_lshlrev_b32_e32 v129, 2, v126
	v_lshlrev_b32_e32 v126, 4, v126
	v_mfma_f32_16x16x32_bf16 v[122:125], v[200:203], v[14:17], v[130:133]
	v_mov_b32_e32 v128, v135
	v_lshlrev_b32_e32 v127, 7, v127
	v_add_u32_e32 v0, s10, v0
	v_and_b32_e32 v126, 16, v126
	v_add3_u32 v126, v0, v127, v126
	v_lshlrev_b32_e32 v128, 6, v128
	v_and_b32_e32 v129, -8, v129
	v_ashrrev_i32_e32 v127, 31, v126
	v_add3_u32 v132, v129, s9, v128
	v_and_b32_e32 v220, 1, v126
	v_lshrrev_b32_e32 v128, 1, v126
	v_mov_b32_e32 v129, 0
	v_lshlrev_b64 v[128:129], 14, v[128:129]
	v_lshl_or_b32 v128, v220, 6, v128
	v_max_f32_e32 v0, v216, v216
	v_mfma_f32_16x16x32_bf16 v[94:97], v[200:203], v[22:25], v[94:97]
	v_ashrrev_i32_e32 v133, 31, v132
	v_mfma_f32_16x16x32_bf16 v[86:89], v[204:207], v[22:25], v[90:93]
	s_waitcnt lgkmcnt(1)
	v_mfma_f32_16x16x32_bf16 v[78:81], v[208:211], v[22:25], v[142:145]
	s_waitcnt lgkmcnt(0)
	v_mfma_f32_16x16x32_bf16 v[70:73], v[212:215], v[22:25], v[82:85]
	v_mfma_f32_16x16x32_bf16 v[22:25], v[204:207], v[176:179], v[26:29]
	v_mfma_f32_16x16x32_bf16 v[26:29], v[200:203], v[180:183], v[138:141]
	s_nop 2
	v_lshl_add_u64 v[138:139], s[60:61], 0, v[128:129]
	v_max_f32_e32 v128, 0, v0
	v_max_f32_e32 v0, v122, v122
	v_max_f32_e32 v122, 0, v0
	v_max_f32_e32 v0, v217, v217
	v_max_f32_e32 v129, 0, v0
	v_max_f32_e32 v0, v123, v123
	v_max_f32_e32 v123, 0, v0
	v_max_f32_e32 v0, v218, v218
	v_mfma_f32_16x16x32_bf16 v[102:105], v[212:215], v[6:9], v[114:117]
	v_max_f32_e32 v130, 0, v0
	v_max_f32_e32 v0, v124, v124
	v_max_f32_e32 v124, 0, v0
	v_mfma_f32_16x16x32_bf16 v[114:117], v[204:207], v[14:17], v[106:109]
	v_max_f32_e32 v0, v219, v219
	v_max_f32_e32 v131, 0, v0
	v_max_f32_e32 v0, v125, v125
	v_max_f32_e32 v125, 0, v0
	v_max_f32_e32 v0, v118, v118
	v_max_f32_e32 v118, 0, v0
	s_nop 1
	v_max_f32_e32 v0, v114, v114
	v_pk_mul_f32 v[128:129], v[128:129], v[128:129]
	v_pk_mul_f32 v[122:123], v[122:123], v[122:123]
	v_pk_mul_f32 v[130:131], v[130:131], v[130:131]
	v_pk_mul_f32 v[124:125], v[124:125], v[124:125]
	v_max_f32_e32 v114, 0, v0
	v_max_f32_e32 v0, v119, v119
	v_cvt_pk_bf16_f32 v128, v128, v129
	v_cvt_pk_bf16_f32 v129, v130, v131
	v_cvt_pk_bf16_f32 v130, v122, v123
	v_cvt_pk_bf16_f32 v131, v124, v125
	v_and_b32_e32 v220, 31, v132
	v_lshrrev_b32_e32 v122, 5, v132
	v_lshlrev_b32_e32 v122, 7, v122
	v_lshl_or_b32 v122, v220, 1, v122
	v_mov_b32_e32 v123, 0
	v_max_f32_e32 v119, 0, v0
	v_max_f32_e32 v0, v115, v115
	v_mfma_f32_16x16x32_bf16 v[110:113], v[208:211], v[6:9], v[184:187]
	v_permlane16_swap_b32_e32 v128, v130
	v_permlane16_swap_b32_e32 v129, v131
	v_lshl_add_u64 v[124:125], v[138:139], 0, v[122:123]
	v_max_f32_e32 v115, 0, v0
	v_max_f32_e32 v0, v120, v120
	v_mfma_f32_16x16x32_bf16 v[106:109], v[208:211], v[14:17], v[188:191]
	flat_store_dwordx4 v[124:125], v[128:131]
	v_pk_mul_f32 v[118:119], v[118:119], v[118:119]
	s_nop 0
	v_pk_mul_f32 v[128:129], v[114:115], v[114:115]
	v_max_f32_e32 v114, 0, v0
	v_max_f32_e32 v0, v116, v116
	v_max_f32_e32 v116, 0, v0
	v_max_f32_e32 v0, v121, v121
	v_max_f32_e32 v115, 0, v0
	v_max_f32_e32 v0, v117, v117
	v_max_f32_e32 v117, 0, v0
	v_max_f32_e32 v0, v110, v110
	v_max_f32_e32 v110, 0, v0
	v_max_f32_e32 v0, v106, v106
	v_pk_mul_f32 v[120:121], v[114:115], v[114:115]
	v_pk_mul_f32 v[130:131], v[116:117], v[116:117]
	v_max_f32_e32 v106, 0, v0
	v_max_f32_e32 v0, v111, v111
	v_cvt_pk_bf16_f32 v114, v118, v119
	v_cvt_pk_bf16_f32 v115, v120, v121
	v_cvt_pk_bf16_f32 v116, v128, v129
	v_cvt_pk_bf16_f32 v117, v130, v131
	v_max_f32_e32 v111, 0, v0
	v_max_f32_e32 v0, v107, v107
	v_permlane16_swap_b32_e32 v114, v116
	v_permlane16_swap_b32_e32 v115, v117
	v_max_f32_e32 v107, 0, v0
	v_max_f32_e32 v0, v112, v112
	v_mfma_f32_16x16x32_bf16 v[98:101], v[212:215], v[14:17], v[98:101]
	flat_store_dwordx4 v[124:125], v[114:117] offset:32
	v_pk_mul_f32 v[110:111], v[110:111], v[110:111]
	s_nop 0
	v_pk_mul_f32 v[114:115], v[106:107], v[106:107]
	v_max_f32_e32 v106, 0, v0
	v_max_f32_e32 v0, v108, v108
	v_max_f32_e32 v108, 0, v0
	v_max_f32_e32 v0, v113, v113
	v_max_f32_e32 v107, 0, v0
	v_max_f32_e32 v0, v109, v109
	v_max_f32_e32 v109, 0, v0
	v_max_f32_e32 v0, v102, v102
	v_max_f32_e32 v102, 0, v0
	v_max_f32_e32 v0, v98, v98
	v_pk_mul_f32 v[112:113], v[106:107], v[106:107]
	v_pk_mul_f32 v[116:117], v[108:109], v[108:109]
	v_max_f32_e32 v98, 0, v0
	v_max_f32_e32 v0, v103, v103
	v_cvt_pk_bf16_f32 v106, v110, v111
	v_cvt_pk_bf16_f32 v107, v112, v113
	v_cvt_pk_bf16_f32 v108, v114, v115
	v_cvt_pk_bf16_f32 v109, v116, v117
	v_max_f32_e32 v103, 0, v0
	v_max_f32_e32 v0, v99, v99
	v_permlane16_swap_b32_e32 v106, v108
	v_permlane16_swap_b32_e32 v107, v109
	v_max_f32_e32 v99, 0, v0
	v_max_f32_e32 v0, v104, v104
	flat_store_dwordx4 v[124:125], v[106:109] offset:128
	v_pk_mul_f32 v[102:103], v[102:103], v[102:103]
	v_mfma_f32_16x16x32_bf16 v[90:93], v[200:203], v[38:41], v[146:149]
	v_mul_f32_e64 v106, v98, v98
	v_mul_f32_e64 v107, v99, v99
	v_max_f32_e32 v98, 0, v0
	v_max_f32_e32 v0, v100, v100
	v_max_f32_e32 v100, 0, v0
	v_max_f32_e32 v0, v105, v105
	v_max_f32_e32 v99, 0, v0
	v_max_f32_e32 v0, v101, v101
	v_max_f32_e32 v101, 0, v0
	v_pk_mul_f32 v[104:105], v[98:99], v[98:99]
	v_pk_mul_f32 v[108:109], v[100:101], v[100:101]
	v_cvt_pk_bf16_f32 v98, v102, v103
	v_cvt_pk_bf16_f32 v99, v104, v105
	v_cvt_pk_bf16_f32 v100, v106, v107
	v_cvt_pk_bf16_f32 v101, v108, v109
	s_nop 0
	v_permlane16_swap_b32_e32 v98, v100
	v_permlane16_swap_b32_e32 v99, v101
	v_mfma_f32_16x16x32_bf16 v[82:85], v[204:207], v[38:41], v[74:77]
; DI unsigned pack2(float a, float b) { float2_t v = {a, b}; bf16x2_t r = __builtin_convertvector(v, bf16x2_t); return __builtin_bit_cast(unsigned, r); }
; DI void phase_mlp1(const Params& p, int l, int Mout, char* smem) {
;     ...
;     for (int mi = 0; mi < 8; mi += 2) {
;       const int m = m0 + wr * 128 + (mi + (lq & 1)) * 16 + lr;
; #pragma unroll
;       for (int ni = 0; ni < 4; ++ni) {
;         const int n = n0 + wc * 64 + ni * 16 + (lq >> 1) * 8;
;         float va[4], vb[4];
; #pragma unroll
;         for (int j = 0; j < 4; ++j) { const float a = fmaxf(acc[mi][ni][j], 0.f); va[j] = a * a; const float b = fmaxf(acc[mi + 1][ni][j], 0.f); vb[j] = b * b; }
;         *(uint4*)(U + (size_t)m * DFF + n) = widen16(make_uint2(pack2(va[0], va[1]), pack2(va[2], va[3])), make_uint2(pack2(vb[0], vb[1]), pack2(vb[2], vb[3])));
;       }
;       __builtin_amdgcn_sched_barrier(0);
;     }
	flat_store_dwordx4 v[124:125], v[98:101] offset:160
	v_mfma_f32_16x16x32_bf16 v[74:77], v[208:211], v[38:41], v[192:195]
	v_mfma_f32_16x16x32_bf16 v[66:69], v[212:215], v[38:41], v[66:69]
	v_mfma_f32_16x16x32_bf16 v[62:65], v[200:203], v[168:171], v[62:65]
	v_mfma_f32_16x16x32_bf16 v[54:57], v[204:207], v[168:171], v[58:61]
	v_mfma_f32_16x16x32_bf16 v[46:49], v[208:211], v[168:171], v[150:153]
	v_mfma_f32_16x16x32_bf16 v[38:41], v[212:215], v[168:171], v[50:53]
	v_mfma_f32_16x16x32_bf16 v[58:61], v[200:203], v[172:175], v[154:157]
	v_mfma_f32_16x16x32_bf16 v[50:53], v[204:207], v[172:175], v[42:45]
	v_mfma_f32_16x16x32_bf16 v[42:45], v[208:211], v[172:175], v[196:199]
	v_mfma_f32_16x16x32_bf16 v[34:37], v[212:215], v[172:175], v[34:37]
	v_mfma_f32_16x16x32_bf16 v[30:33], v[200:203], v[176:179], v[30:33]
	v_mfma_f32_16x16x32_bf16 v[14:17], v[208:211], v[176:179], v[158:161]
	v_mfma_f32_16x16x32_bf16 v[6:9], v[212:215], v[176:179], v[18:21]
	v_mfma_f32_16x16x32_bf16 v[18:21], v[204:207], v[180:183], v[10:13]
	v_mfma_f32_16x16x32_bf16 v[10:13], v[208:211], v[180:183], v[164:167]
	v_mfma_f32_16x16x32_bf16 v[2:5], v[212:215], v[180:183], v[2:5]
	v_max_f32_e32 v0, v94, v94
	v_max_f32_e32 v94, 0, v0
	v_max_f32_e32 v0, v90, v90
	v_max_f32_e32 v90, 0, v0
	v_max_f32_e32 v0, v95, v95
	v_max_f32_e32 v95, 0, v0
	v_max_f32_e32 v0, v91, v91
	v_max_f32_e32 v91, 0, v0
	v_max_f32_e32 v0, v96, v96
	v_pk_mul_f32 v[100:101], v[90:91], v[90:91]
	v_max_f32_e32 v90, 0, v0
	v_max_f32_e32 v0, v92, v92
	v_max_f32_e32 v92, 0, v0
	v_max_f32_e32 v0, v97, v97
	v_max_f32_e32 v91, 0, v0
	v_max_f32_e32 v0, v93, v93
	v_add_u32_e32 v98, 32, v126
	v_max_f32_e32 v93, 0, v0
	v_max_f32_e32 v0, v86, v86
	v_ashrrev_i32_e32 v99, 31, v98
	v_max_f32_e32 v86, 0, v0
	v_max_f32_e32 v0, v82, v82
	v_and_b32_e32 v220, 1, v98
	v_lshrrev_b32_e32 v98, 1, v98
	v_mov_b32_e32 v99, 0
	v_lshlrev_b64 v[98:99], 14, v[98:99]
	v_lshl_or_b32 v98, v220, 6, v98
	v_pk_mul_f32 v[94:95], v[94:95], v[94:95]
	v_pk_mul_f32 v[96:97], v[90:91], v[90:91]
	v_pk_mul_f32 v[102:103], v[92:93], v[92:93]
	v_max_f32_e32 v82, 0, v0
	v_max_f32_e32 v0, v87, v87
	v_lshl_add_u64 v[98:99], s[60:61], 0, v[98:99]
	v_cvt_pk_bf16_f32 v90, v94, v95
	v_cvt_pk_bf16_f32 v91, v96, v97
	v_cvt_pk_bf16_f32 v92, v100, v101
	v_cvt_pk_bf16_f32 v93, v102, v103
	v_max_f32_e32 v87, 0, v0
	v_max_f32_e32 v0, v83, v83
	v_permlane16_swap_b32_e32 v90, v92
	v_permlane16_swap_b32_e32 v91, v93
	v_lshl_add_u64 v[94:95], v[98:99], 0, v[122:123]
	v_max_f32_e32 v83, 0, v0
	v_max_f32_e32 v0, v88, v88
	flat_store_dwordx4 v[94:95], v[90:93]
	v_pk_mul_f32 v[86:87], v[86:87], v[86:87]
	s_nop 0
	v_pk_mul_f32 v[90:91], v[82:83], v[82:83]
	v_max_f32_e32 v82, 0, v0
	v_max_f32_e32 v0, v84, v84
	v_max_f32_e32 v84, 0, v0
	v_max_f32_e32 v0, v89, v89
	v_max_f32_e32 v83, 0, v0
	v_max_f32_e32 v0, v85, v85
	v_max_f32_e32 v85, 0, v0
	v_max_f32_e32 v0, v78, v78
	v_max_f32_e32 v78, 0, v0
	v_max_f32_e32 v0, v74, v74
	v_pk_mul_f32 v[88:89], v[82:83], v[82:83]
	v_pk_mul_f32 v[92:93], v[84:85], v[84:85]
	v_max_f32_e32 v74, 0, v0
	v_max_f32_e32 v0, v79, v79
	v_cvt_pk_bf16_f32 v82, v86, v87
	v_cvt_pk_bf16_f32 v83, v88, v89
	v_cvt_pk_bf16_f32 v84, v90, v91
	v_cvt_pk_bf16_f32 v85, v92, v93
	v_max_f32_e32 v79, 0, v0
	v_max_f32_e32 v0, v75, v75
	v_permlane16_swap_b32_e32 v82, v84
	v_permlane16_swap_b32_e32 v83, v85
	v_max_f32_e32 v75, 0, v0
	v_max_f32_e32 v0, v80, v80
	flat_store_dwordx4 v[94:95], v[82:85] offset:32
	v_pk_mul_f32 v[78:79], v[78:79], v[78:79]
	s_nop 0
	v_pk_mul_f32 v[82:83], v[74:75], v[74:75]
	v_max_f32_e32 v74, 0, v0
	v_max_f32_e32 v0, v76, v76
	v_max_f32_e32 v76, 0, v0
	v_max_f32_e32 v0, v81, v81
	v_max_f32_e32 v75, 0, v0
	v_max_f32_e32 v0, v77, v77
	v_max_f32_e32 v77, 0, v0
	v_max_f32_e32 v0, v70, v70
	v_max_f32_e32 v70, 0, v0
	v_max_f32_e32 v0, v66, v66
	v_pk_mul_f32 v[80:81], v[74:75], v[74:75]
	v_pk_mul_f32 v[84:85], v[76:77], v[76:77]
	v_max_f32_e32 v66, 0, v0
	v_max_f32_e32 v0, v71, v71
	v_cvt_pk_bf16_f32 v74, v78, v79
	v_cvt_pk_bf16_f32 v75, v80, v81
	v_cvt_pk_bf16_f32 v76, v82, v83
	v_cvt_pk_bf16_f32 v77, v84, v85
	v_max_f32_e32 v71, 0, v0
	v_max_f32_e32 v0, v67, v67
	v_permlane16_swap_b32_e32 v74, v76
	v_permlane16_swap_b32_e32 v75, v77
	v_max_f32_e32 v67, 0, v0
	v_max_f32_e32 v0, v72, v72
	flat_store_dwordx4 v[94:95], v[74:77] offset:128
	v_pk_mul_f32 v[70:71], v[70:71], v[70:71]
	s_nop 0
	v_pk_mul_f32 v[74:75], v[66:67], v[66:67]
	v_max_f32_e32 v66, 0, v0
	v_max_f32_e32 v0, v68, v68
	v_max_f32_e32 v68, 0, v0
	v_max_f32_e32 v0, v73, v73
	v_max_f32_e32 v67, 0, v0
	v_max_f32_e32 v0, v69, v69
	v_max_f32_e32 v69, 0, v0
	v_pk_mul_f32 v[72:73], v[66:67], v[66:67]
	v_pk_mul_f32 v[76:77], v[68:69], v[68:69]
	v_cvt_pk_bf16_f32 v66, v70, v71
	v_cvt_pk_bf16_f32 v67, v72, v73
	v_cvt_pk_bf16_f32 v68, v74, v75
	v_cvt_pk_bf16_f32 v69, v76, v77
	s_nop 0
	v_permlane16_swap_b32_e32 v66, v68
	v_permlane16_swap_b32_e32 v67, v69
	flat_store_dwordx4 v[94:95], v[66:69] offset:160
	v_max_f32_e32 v0, v62, v62
	v_max_f32_e32 v62, 0, v0
	v_max_f32_e32 v0, v58, v58
	v_max_f32_e32 v58, 0, v0
	v_max_f32_e32 v0, v63, v63
	v_max_f32_e32 v63, 0, v0
	v_max_f32_e32 v0, v59, v59
	v_max_f32_e32 v59, 0, v0
	v_max_f32_e32 v0, v64, v64
	v_pk_mul_f32 v[68:69], v[58:59], v[58:59]
	v_max_f32_e32 v58, 0, v0
	v_max_f32_e32 v0, v60, v60
	v_max_f32_e32 v60, 0, v0
	v_max_f32_e32 v0, v65, v65
	v_max_f32_e32 v59, 0, v0
	v_max_f32_e32 v0, v61, v61
	v_add_u32_e32 v66, 64, v126
	v_max_f32_e32 v61, 0, v0
	v_max_f32_e32 v0, v54, v54
	v_ashrrev_i32_e32 v67, 31, v66
	v_max_f32_e32 v54, 0, v0
	v_max_f32_e32 v0, v50, v50
	v_and_b32_e32 v220, 1, v66
	v_lshrrev_b32_e32 v66, 1, v66
	v_mov_b32_e32 v67, 0
; DI unsigned pack2(float a, float b) { float2_t v = {a, b}; bf16x2_t r = __builtin_convertvector(v, bf16x2_t); return __builtin_bit_cast(unsigned, r); }
; DI void phase_mlp1(const Params& p, int l, int Mout, char* smem) {
;     ...
;     for (int mi = 0; mi < 8; mi += 2) {
;       const int m = m0 + wr * 128 + (mi + (lq & 1)) * 16 + lr;
; #pragma unroll
;       for (int ni = 0; ni < 4; ++ni) {
;         const int n = n0 + wc * 64 + ni * 16 + (lq >> 1) * 8;
;         float va[4], vb[4];
; #pragma unroll
;         for (int j = 0; j < 4; ++j) { const float a = fmaxf(acc[mi][ni][j], 0.f); va[j] = a * a; const float b = fmaxf(acc[mi + 1][ni][j], 0.f); vb[j] = b * b; }
;         *(uint4*)(U + (size_t)m * DFF + n) = widen16(make_uint2(pack2(va[0], va[1]), pack2(va[2], va[3])), make_uint2(pack2(vb[0], vb[1]), pack2(vb[2], vb[3])));
;       }
;       __builtin_amdgcn_sched_barrier(0);
;     }
;     EPI_END
;   }
	v_lshlrev_b64 v[66:67], 14, v[66:67]
	v_lshl_or_b32 v66, v220, 6, v66
	v_pk_mul_f32 v[62:63], v[62:63], v[62:63]
	v_pk_mul_f32 v[64:65], v[58:59], v[58:59]
	v_pk_mul_f32 v[70:71], v[60:61], v[60:61]
	v_max_f32_e32 v50, 0, v0
	v_max_f32_e32 v0, v55, v55
	v_lshl_add_u64 v[66:67], s[60:61], 0, v[66:67]
	v_cvt_pk_bf16_f32 v58, v62, v63
	v_cvt_pk_bf16_f32 v59, v64, v65
	v_cvt_pk_bf16_f32 v60, v68, v69
	v_cvt_pk_bf16_f32 v61, v70, v71
	v_max_f32_e32 v55, 0, v0
	v_max_f32_e32 v0, v51, v51
	v_permlane16_swap_b32_e32 v58, v60
	v_permlane16_swap_b32_e32 v59, v61
	v_lshl_add_u64 v[62:63], v[66:67], 0, v[122:123]
	v_max_f32_e32 v51, 0, v0
	v_max_f32_e32 v0, v56, v56
	flat_store_dwordx4 v[62:63], v[58:61]
	v_pk_mul_f32 v[54:55], v[54:55], v[54:55]
	s_nop 0
	v_pk_mul_f32 v[58:59], v[50:51], v[50:51]
	v_max_f32_e32 v50, 0, v0
	v_max_f32_e32 v0, v52, v52
	v_max_f32_e32 v52, 0, v0
	v_max_f32_e32 v0, v57, v57
	v_max_f32_e32 v51, 0, v0
	v_max_f32_e32 v0, v53, v53
	v_max_f32_e32 v53, 0, v0
	v_max_f32_e32 v0, v46, v46
	v_max_f32_e32 v46, 0, v0
	v_max_f32_e32 v0, v42, v42
	v_pk_mul_f32 v[56:57], v[50:51], v[50:51]
	v_pk_mul_f32 v[60:61], v[52:53], v[52:53]
	v_max_f32_e32 v42, 0, v0
	v_max_f32_e32 v0, v47, v47
	v_cvt_pk_bf16_f32 v50, v54, v55
	v_cvt_pk_bf16_f32 v51, v56, v57
	v_cvt_pk_bf16_f32 v52, v58, v59
	v_cvt_pk_bf16_f32 v53, v60, v61
	v_max_f32_e32 v47, 0, v0
	v_max_f32_e32 v0, v43, v43
	v_permlane16_swap_b32_e32 v50, v52
	v_permlane16_swap_b32_e32 v51, v53
	v_max_f32_e32 v43, 0, v0
	v_max_f32_e32 v0, v48, v48
	flat_store_dwordx4 v[62:63], v[50:53] offset:32
	v_pk_mul_f32 v[46:47], v[46:47], v[46:47]
	s_nop 0
	v_pk_mul_f32 v[50:51], v[42:43], v[42:43]
	v_max_f32_e32 v42, 0, v0
	v_max_f32_e32 v0, v44, v44
	v_max_f32_e32 v44, 0, v0
	v_max_f32_e32 v0, v49, v49
	v_max_f32_e32 v43, 0, v0
	v_max_f32_e32 v0, v45, v45
	v_max_f32_e32 v45, 0, v0
	v_max_f32_e32 v0, v38, v38
	v_max_f32_e32 v38, 0, v0
	v_max_f32_e32 v0, v34, v34
	v_pk_mul_f32 v[48:49], v[42:43], v[42:43]
	v_pk_mul_f32 v[52:53], v[44:45], v[44:45]
	v_max_f32_e32 v34, 0, v0
	v_max_f32_e32 v0, v39, v39
	v_cvt_pk_bf16_f32 v42, v46, v47
	v_cvt_pk_bf16_f32 v43, v48, v49
	v_cvt_pk_bf16_f32 v44, v50, v51
	v_cvt_pk_bf16_f32 v45, v52, v53
	v_max_f32_e32 v39, 0, v0
	v_max_f32_e32 v0, v35, v35
	v_permlane16_swap_b32_e32 v42, v44
	v_permlane16_swap_b32_e32 v43, v45
	v_max_f32_e32 v35, 0, v0
	v_max_f32_e32 v0, v40, v40
	flat_store_dwordx4 v[62:63], v[42:45] offset:128
	v_pk_mul_f32 v[38:39], v[38:39], v[38:39]
	s_nop 0
	v_pk_mul_f32 v[42:43], v[34:35], v[34:35]
	v_max_f32_e32 v34, 0, v0
	v_max_f32_e32 v0, v36, v36
	v_max_f32_e32 v36, 0, v0
	v_max_f32_e32 v0, v41, v41
	v_max_f32_e32 v35, 0, v0
	v_max_f32_e32 v0, v37, v37
	v_max_f32_e32 v37, 0, v0
	v_pk_mul_f32 v[40:41], v[34:35], v[34:35]
	v_pk_mul_f32 v[44:45], v[36:37], v[36:37]
	v_cvt_pk_bf16_f32 v34, v38, v39
	v_cvt_pk_bf16_f32 v35, v40, v41
	v_cvt_pk_bf16_f32 v36, v42, v43
	v_cvt_pk_bf16_f32 v37, v44, v45
	s_nop 0
	v_permlane16_swap_b32_e32 v34, v36
	v_permlane16_swap_b32_e32 v35, v37
	flat_store_dwordx4 v[62:63], v[34:37] offset:160
	v_max_f32_e32 v0, v30, v30
	v_max_f32_e32 v30, 0, v0
	v_max_f32_e32 v0, v26, v26
	v_max_f32_e32 v26, 0, v0
	v_max_f32_e32 v0, v31, v31
	v_max_f32_e32 v31, 0, v0
	v_max_f32_e32 v0, v27, v27
	v_max_f32_e32 v27, 0, v0
	v_max_f32_e32 v0, v32, v32
	v_pk_mul_f32 v[36:37], v[26:27], v[26:27]
	v_max_f32_e32 v26, 0, v0
	v_max_f32_e32 v0, v28, v28
	v_max_f32_e32 v28, 0, v0
	v_max_f32_e32 v0, v33, v33
	v_max_f32_e32 v27, 0, v0
	v_max_f32_e32 v0, v29, v29
	v_add_u32_e32 v34, 0x60, v126
	v_max_f32_e32 v29, 0, v0
	v_max_f32_e32 v0, v22, v22
	v_ashrrev_i32_e32 v35, 31, v34
	v_max_f32_e32 v22, 0, v0
	v_max_f32_e32 v0, v18, v18
	v_and_b32_e32 v220, 1, v34
	v_lshrrev_b32_e32 v34, 1, v34
	v_mov_b32_e32 v35, 0
	v_lshlrev_b64 v[34:35], 14, v[34:35]
	v_lshl_or_b32 v34, v220, 6, v34
	v_pk_mul_f32 v[30:31], v[30:31], v[30:31]
	v_pk_mul_f32 v[32:33], v[26:27], v[26:27]
	v_pk_mul_f32 v[38:39], v[28:29], v[28:29]
	v_max_f32_e32 v18, 0, v0
	v_max_f32_e32 v0, v23, v23
	v_lshl_add_u64 v[34:35], s[60:61], 0, v[34:35]
	v_cvt_pk_bf16_f32 v26, v30, v31
	v_cvt_pk_bf16_f32 v27, v32, v33
	v_cvt_pk_bf16_f32 v28, v36, v37
	v_cvt_pk_bf16_f32 v29, v38, v39
	v_max_f32_e32 v23, 0, v0
	v_max_f32_e32 v0, v19, v19
	v_permlane16_swap_b32_e32 v26, v28
	v_permlane16_swap_b32_e32 v27, v29
	v_lshl_add_u64 v[30:31], v[34:35], 0, v[122:123]
	v_max_f32_e32 v19, 0, v0
	v_max_f32_e32 v0, v24, v24
	flat_store_dwordx4 v[30:31], v[26:29]
	v_pk_mul_f32 v[22:23], v[22:23], v[22:23]
	s_nop 0
	v_pk_mul_f32 v[26:27], v[18:19], v[18:19]
	v_max_f32_e32 v18, 0, v0
	v_max_f32_e32 v0, v20, v20
	v_max_f32_e32 v20, 0, v0
	v_max_f32_e32 v0, v25, v25
	v_max_f32_e32 v19, 0, v0
	v_max_f32_e32 v0, v21, v21
	v_max_f32_e32 v21, 0, v0
	v_max_f32_e32 v0, v14, v14
	v_max_f32_e32 v14, 0, v0
	v_max_f32_e32 v0, v10, v10
	v_pk_mul_f32 v[24:25], v[18:19], v[18:19]
	v_pk_mul_f32 v[28:29], v[20:21], v[20:21]
	v_max_f32_e32 v10, 0, v0
	v_max_f32_e32 v0, v15, v15
	v_cvt_pk_bf16_f32 v18, v22, v23
	v_cvt_pk_bf16_f32 v19, v24, v25
	v_cvt_pk_bf16_f32 v20, v26, v27
	v_cvt_pk_bf16_f32 v21, v28, v29
	v_max_f32_e32 v15, 0, v0
	v_max_f32_e32 v0, v11, v11
	v_permlane16_swap_b32_e32 v18, v20
	v_permlane16_swap_b32_e32 v19, v21
	v_max_f32_e32 v11, 0, v0
	v_max_f32_e32 v0, v16, v16
	flat_store_dwordx4 v[30:31], v[18:21] offset:32
	v_pk_mul_f32 v[14:15], v[14:15], v[14:15]
	s_nop 0
	v_pk_mul_f32 v[18:19], v[10:11], v[10:11]
	v_max_f32_e32 v10, 0, v0
	v_max_f32_e32 v0, v12, v12
	v_max_f32_e32 v12, 0, v0
	v_max_f32_e32 v0, v17, v17
	v_max_f32_e32 v11, 0, v0
	v_max_f32_e32 v0, v13, v13
	v_max_f32_e32 v13, 0, v0
	v_max_f32_e32 v0, v6, v6
	v_max_f32_e32 v6, 0, v0
	v_max_f32_e32 v0, v2, v2
	v_pk_mul_f32 v[16:17], v[10:11], v[10:11]
	v_pk_mul_f32 v[20:21], v[12:13], v[12:13]
	v_max_f32_e32 v2, 0, v0
	v_max_f32_e32 v0, v7, v7
	v_cvt_pk_bf16_f32 v10, v14, v15
	v_cvt_pk_bf16_f32 v11, v16, v17
	v_cvt_pk_bf16_f32 v12, v18, v19
	v_cvt_pk_bf16_f32 v13, v20, v21
	v_max_f32_e32 v7, 0, v0
	v_max_f32_e32 v0, v3, v3
	v_permlane16_swap_b32_e32 v10, v12
	v_permlane16_swap_b32_e32 v11, v13
	v_max_f32_e32 v3, 0, v0
	v_max_f32_e32 v0, v8, v8
	flat_store_dwordx4 v[30:31], v[10:13] offset:128
	v_pk_mul_f32 v[6:7], v[6:7], v[6:7]
	s_nop 0
	v_pk_mul_f32 v[10:11], v[2:3], v[2:3]
	v_max_f32_e32 v2, 0, v0
	v_max_f32_e32 v0, v4, v4
	v_max_f32_e32 v4, 0, v0
	v_max_f32_e32 v0, v9, v9
	v_max_f32_e32 v3, 0, v0
	v_max_f32_e32 v0, v5, v5
	v_max_f32_e32 v5, 0, v0
	v_pk_mul_f32 v[8:9], v[2:3], v[2:3]
	v_pk_mul_f32 v[12:13], v[4:5], v[4:5]
	v_cvt_pk_bf16_f32 v2, v6, v7
	v_cvt_pk_bf16_f32 v3, v8, v9
	v_cvt_pk_bf16_f32 v4, v10, v11
	v_cvt_pk_bf16_f32 v5, v12, v13
	s_nop 0
	v_permlane16_swap_b32_e32 v2, v4
	v_permlane16_swap_b32_e32 v3, v5
	flat_store_dwordx4 v[30:31], v[2:5] offset:160
	s_add_i32 s8, s8, 1
	s_mul_i32 s4, s8, s39
	s_add_i32 s9, s4, s6
	v_readlane_b32 s4, v253, 41
	s_cmp_ge_i32 s9, s4
	s_cbranch_scc0 .LBB0_441

; template <int MI, int NI>
; DI void gemm256(f32x4 (&acc)[MI][NI], const u16* __restrict__ A, int lda, const u16* __restrict__ Bt, int ldb, int K, int m0, int n0, char* smem) {
;     ...
;   const int nk = K >> 5;
;   G256_ISSUE(0, 0);
;   if (nk > 1) G256_ISSUE(1, 32);
;   const int foff = lr * 64 + ((lq ^ ((lr >> 3) << 1)) * 16);
;   int st = 0;
;   for (int kt = 0; kt < nk; ++kt) {
;     if (kt + 1 < nk) asm volatile("s_waitcnt vmcnt(%0) lgkmcnt(0)" :: "n"(LPS) : "memory");
;     else asm volatile("s_waitcnt vmcnt(0) lgkmcnt(0)" ::: "memory");
;     __builtin_amdgcn_s_barrier();
;     __builtin_amdgcn_s_setprio(1);
;     const char* sb = smem + st * STAGE + foff;
;     bf16x8 af[MI], bfr[NI];
; #pragma unroll
;     for (int mi = 0; mi < MI; ++mi) af[mi] = *(const bf16x8*)(sb + (wr * MI + mi) * 1024);
; #pragma unroll
;     for (int ni = 0; ni < NI; ++ni) bfr[ni] = *(const bf16x8*)(sb + ABYTES + (wc * NI + ni) * 1024);
;     __builtin_amdgcn_sched_barrier(0x0);
;     if (kt + 2 < nk) { const int s2 = st >= 1 ? st - 1 : 2; G256_ISSUE(s2, (kt + 2) * 32); }
;     __builtin_amdgcn_s_setprio(0);
; #pragma unroll
;     for (int mi = 0; mi < MI; ++mi)
; #pragma unroll
;       for (int ni = 0; ni < NI; ++ni)
;         acc[mi][ni] = __builtin_amdgcn_mfma_f32_16x16x32_bf16(bfr[ni], af[mi], acc[mi][ni], 0, 0, 0);
;     st = st == 2 ? 0 : st + 1;
;   }
.Lpipe_wo:
	v_add_u32_e32 v161, s12, v160
	ds_read_b128 v[156:159], v161 offset:4096
	ds_read_b128 v[164:167], v161 offset:5120
	ds_read_b128 v[168:171], v161 offset:6144
	ds_read_b128 v[172:175], v161 offset:7168
	s_add_i32 s14, s12, 0xffffa000
	s_cmp_eq_u32 s12, 0
	s_cselect_b32 s14, 0xc000, s14
	s_add_i32 s15, s14, s13
	s_add_i32 s14, s14, s4
	s_mov_b32 m0, s15
	s_waitcnt lgkmcnt(7)
	v_mfma_f32_16x16x32_bf16 v[126:129], v[176:179], v[140:143], v[126:129]
	global_load_lds_dwordx4 v[196:197], off
	v_mfma_f32_16x16x32_bf16 v[110:113], v[176:179], v[144:147], v[110:113]
	v_lshl_add_u64 v[196:197], v[196:197], 0, s[98:99]
	s_add_i32 m0, s15, 0x400
	v_mfma_f32_16x16x32_bf16 v[94:97], v[176:179], v[148:151], v[94:97]
	global_load_lds_dwordx4 v[198:199], off
	v_mfma_f32_16x16x32_bf16 v[78:81], v[176:179], v[152:155], v[78:81]
	v_lshl_add_u64 v[198:199], v[198:199], 0, s[98:99]
	s_add_i32 m0, s15, 0x800
	s_waitcnt lgkmcnt(6)
	v_mfma_f32_16x16x32_bf16 v[122:125], v[180:183], v[140:143], v[122:125]
	global_load_lds_dwordx4 v[200:201], off
	v_mfma_f32_16x16x32_bf16 v[106:109], v[180:183], v[144:147], v[106:109]
	v_lshl_add_u64 v[200:201], v[200:201], 0, s[98:99]
	s_add_i32 m0, s15, 0xc00
	v_mfma_f32_16x16x32_bf16 v[90:93], v[180:183], v[148:151], v[90:93]
	global_load_lds_dwordx4 v[202:203], off
	v_mfma_f32_16x16x32_bf16 v[74:77], v[180:183], v[152:155], v[74:77]
	v_lshl_add_u64 v[202:203], v[202:203], 0, s[98:99]
	s_mov_b32 m0, s14
	s_waitcnt lgkmcnt(5)
	v_mfma_f32_16x16x32_bf16 v[118:121], v[184:187], v[140:143], v[118:121]
	global_load_lds_dwordx4 v[204:205], off
	v_mfma_f32_16x16x32_bf16 v[102:105], v[184:187], v[144:147], v[102:105]
	v_lshl_add_u64 v[204:205], v[204:205], 0, 64
	s_add_i32 m0, s14, 0x400
	v_mfma_f32_16x16x32_bf16 v[86:89], v[184:187], v[148:151], v[86:89]
	global_load_lds_dwordx4 v[206:207], off
	v_mfma_f32_16x16x32_bf16 v[70:73], v[184:187], v[152:155], v[70:73]
	v_lshl_add_u64 v[206:207], v[206:207], 0, 64
	s_waitcnt lgkmcnt(4)
	v_mfma_f32_16x16x32_bf16 v[114:117], v[188:191], v[140:143], v[114:117]
	v_mfma_f32_16x16x32_bf16 v[98:101], v[188:191], v[144:147], v[98:101]
	v_mfma_f32_16x16x32_bf16 v[82:85], v[188:191], v[148:151], v[82:85]
	v_mfma_f32_16x16x32_bf16 v[66:69], v[188:191], v[152:155], v[66:69]
	s_waitcnt vmcnt(6) lgkmcnt(0)
	s_barrier
	s_add_i32 s15, s12, 0x6000
	s_cmp_eq_u32 s12, 0xc000
	s_cselect_b32 s12, 0, s15
	v_add_u32_e32 v192, s12, v160
	v_add_u32_e32 v193, s12, v0
	v_mfma_f32_16x16x32_bf16 v[62:65], v[176:179], v[156:159], v[62:65]
	ds_read_b128 v[140:143], v192
	v_mfma_f32_16x16x32_bf16 v[46:49], v[176:179], v[164:167], v[46:49]
	ds_read_b128 v[144:147], v192 offset:1024
	v_mfma_f32_16x16x32_bf16 v[30:33], v[176:179], v[168:171], v[30:33]
	ds_read_b128 v[148:151], v192 offset:2048
	v_mfma_f32_16x16x32_bf16 v[14:17], v[176:179], v[172:175], v[14:17]
	ds_read_b128 v[152:155], v192 offset:3072
	ds_read_b128 v[176:179], v193 offset:16384
	v_mfma_f32_16x16x32_bf16 v[58:61], v[180:183], v[156:159], v[58:61]
	v_mfma_f32_16x16x32_bf16 v[42:45], v[180:183], v[164:167], v[42:45]
	v_mfma_f32_16x16x32_bf16 v[26:29], v[180:183], v[168:171], v[26:29]
	v_mfma_f32_16x16x32_bf16 v[10:13], v[180:183], v[172:175], v[10:13]
	ds_read_b128 v[180:183], v193 offset:17408
	v_mfma_f32_16x16x32_bf16 v[54:57], v[184:187], v[156:159], v[54:57]
	v_mfma_f32_16x16x32_bf16 v[38:41], v[184:187], v[164:167], v[38:41]
	v_mfma_f32_16x16x32_bf16 v[22:25], v[184:187], v[168:171], v[22:25]
	v_mfma_f32_16x16x32_bf16 v[6:9], v[184:187], v[172:175], v[6:9]
	ds_read_b128 v[184:187], v193 offset:18432
	v_mfma_f32_16x16x32_bf16 v[50:53], v[188:191], v[156:159], v[50:53]
	v_mfma_f32_16x16x32_bf16 v[34:37], v[188:191], v[164:167], v[34:37]
	v_mfma_f32_16x16x32_bf16 v[18:21], v[188:191], v[168:171], v[18:21]
	v_mfma_f32_16x16x32_bf16 v[2:5], v[188:191], v[172:175], v[2:5]
	ds_read_b128 v[188:191], v193 offset:19456
	s_sub_i32 s5, s5, 1
	s_cmp_lg_u32 s5, 0
	s_cbranch_scc1 .Lpipe_wo
	v_add_u32_e32 v161, s12, v160
	ds_read_b128 v[156:159], v161 offset:4096
	ds_read_b128 v[164:167], v161 offset:5120
	ds_read_b128 v[168:171], v161 offset:6144
	ds_read_b128 v[172:175], v161 offset:7168
	s_add_i32 s14, s12, 0xffffa000
	s_cmp_eq_u32 s12, 0
	s_cselect_b32 s14, 0xc000, s14
	s_add_i32 s15, s14, s13
	s_add_i32 s14, s14, s4
	s_mov_b32 m0, s15
	s_waitcnt lgkmcnt(7)
	v_mfma_f32_16x16x32_bf16 v[126:129], v[176:179], v[140:143], v[126:129]
	global_load_lds_dwordx4 v[196:197], off
	v_mfma_f32_16x16x32_bf16 v[110:113], v[176:179], v[144:147], v[110:113]
	v_lshl_add_u64 v[196:197], v[196:197], 0, s[98:99]
	s_add_i32 m0, s15, 0x400
	v_mfma_f32_16x16x32_bf16 v[94:97], v[176:179], v[148:151], v[94:97]
	global_load_lds_dwordx4 v[198:199], off
	v_mfma_f32_16x16x32_bf16 v[78:81], v[176:179], v[152:155], v[78:81]
	v_lshl_add_u64 v[198:199], v[198:199], 0, s[98:99]
	s_add_i32 m0, s15, 0x800
	s_waitcnt lgkmcnt(6)
	v_mfma_f32_16x16x32_bf16 v[122:125], v[180:183], v[140:143], v[122:125]
	global_load_lds_dwordx4 v[200:201], off
	v_mfma_f32_16x16x32_bf16 v[106:109], v[180:183], v[144:147], v[106:109]
	v_lshl_add_u64 v[200:201], v[200:201], 0, s[98:99]
	s_add_i32 m0, s15, 0xc00
	v_mfma_f32_16x16x32_bf16 v[90:93], v[180:183], v[148:151], v[90:93]
	global_load_lds_dwordx4 v[202:203], off
	v_mfma_f32_16x16x32_bf16 v[74:77], v[180:183], v[152:155], v[74:77]
	v_lshl_add_u64 v[202:203], v[202:203], 0, s[98:99]
	s_mov_b32 m0, s14
	s_waitcnt lgkmcnt(5)
; template <int MI, int NI>
; DI void gemm256(f32x4 (&acc)[MI][NI], const u16* __restrict__ A, int lda, const u16* __restrict__ Bt, int ldb, int K, int m0, int n0, char* smem) {
;     ...
;   for (int kt = 0; kt < nk; ++kt) {
;     if (kt + 1 < nk) asm volatile("s_waitcnt vmcnt(%0) lgkmcnt(0)" :: "n"(LPS) : "memory");
;     else asm volatile("s_waitcnt vmcnt(0) lgkmcnt(0)" ::: "memory");
;     __builtin_amdgcn_s_barrier();
;     __builtin_amdgcn_s_setprio(1);
;     const char* sb = smem + st * STAGE + foff;
;     bf16x8 af[MI], bfr[NI];
; #pragma unroll
;     for (int mi = 0; mi < MI; ++mi) af[mi] = *(const bf16x8*)(sb + (wr * MI + mi) * 1024);
; #pragma unroll
;     for (int ni = 0; ni < NI; ++ni) bfr[ni] = *(const bf16x8*)(sb + ABYTES + (wc * NI + ni) * 1024);
;     __builtin_amdgcn_sched_barrier(0x0);
;     if (kt + 2 < nk) { const int s2 = st >= 1 ? st - 1 : 2; G256_ISSUE(s2, (kt + 2) * 32); }
;     __builtin_amdgcn_s_setprio(0);
; #pragma unroll
;     for (int mi = 0; mi < MI; ++mi)
; #pragma unroll
;       for (int ni = 0; ni < NI; ++ni)
;         acc[mi][ni] = __builtin_amdgcn_mfma_f32_16x16x32_bf16(bfr[ni], af[mi], acc[mi][ni], 0, 0, 0);
;     st = st == 2 ? 0 : st + 1;
;   }
;   asm volatile("s_waitcnt lgkmcnt(0)" ::: "memory");
;   __builtin_amdgcn_s_barrier();
	v_mfma_f32_16x16x32_bf16 v[118:121], v[184:187], v[140:143], v[118:121]
	global_load_lds_dwordx4 v[204:205], off
	v_mfma_f32_16x16x32_bf16 v[102:105], v[184:187], v[144:147], v[102:105]
	v_lshl_add_u64 v[204:205], v[204:205], 0, 64
	s_add_i32 m0, s14, 0x400
	v_mfma_f32_16x16x32_bf16 v[86:89], v[184:187], v[148:151], v[86:89]
	global_load_lds_dwordx4 v[206:207], off
	v_mfma_f32_16x16x32_bf16 v[70:73], v[184:187], v[152:155], v[70:73]
	v_lshl_add_u64 v[206:207], v[206:207], 0, 64
	s_waitcnt lgkmcnt(4)
	v_mfma_f32_16x16x32_bf16 v[114:117], v[188:191], v[140:143], v[114:117]
	v_mfma_f32_16x16x32_bf16 v[98:101], v[188:191], v[144:147], v[98:101]
	v_mfma_f32_16x16x32_bf16 v[82:85], v[188:191], v[148:151], v[82:85]
	v_mfma_f32_16x16x32_bf16 v[66:69], v[188:191], v[152:155], v[66:69]
	s_waitcnt lgkmcnt(0)
	v_mfma_f32_16x16x32_bf16 v[62:65], v[176:179], v[156:159], v[62:65]
	v_mfma_f32_16x16x32_bf16 v[46:49], v[176:179], v[164:167], v[46:49]
	v_mfma_f32_16x16x32_bf16 v[30:33], v[176:179], v[168:171], v[30:33]
	v_mfma_f32_16x16x32_bf16 v[14:17], v[176:179], v[172:175], v[14:17]
	v_mfma_f32_16x16x32_bf16 v[58:61], v[180:183], v[156:159], v[58:61]
	v_mfma_f32_16x16x32_bf16 v[42:45], v[180:183], v[164:167], v[42:45]
	v_mfma_f32_16x16x32_bf16 v[26:29], v[180:183], v[168:171], v[26:29]
	v_mfma_f32_16x16x32_bf16 v[10:13], v[180:183], v[172:175], v[10:13]
	v_mfma_f32_16x16x32_bf16 v[54:57], v[184:187], v[156:159], v[54:57]
	v_mfma_f32_16x16x32_bf16 v[38:41], v[184:187], v[164:167], v[38:41]
	v_mfma_f32_16x16x32_bf16 v[22:25], v[184:187], v[168:171], v[22:25]
	v_mfma_f32_16x16x32_bf16 v[6:9], v[184:187], v[172:175], v[6:9]
	v_mfma_f32_16x16x32_bf16 v[50:53], v[188:191], v[156:159], v[50:53]
	v_mfma_f32_16x16x32_bf16 v[34:37], v[188:191], v[164:167], v[34:37]
	v_mfma_f32_16x16x32_bf16 v[18:21], v[188:191], v[168:171], v[18:21]
	v_mfma_f32_16x16x32_bf16 v[2:5], v[188:191], v[172:175], v[2:5]
	s_waitcnt vmcnt(6) lgkmcnt(0)
	s_barrier
	s_nop 0
	v_add_u32_e32 v0, v137, v139
	ds_read_b128 v[130:133], v0
	ds_read_b128 v[140:143], v0 offset:1024
	ds_read_b128 v[144:147], v0 offset:2048
	ds_read_b128 v[148:151], v0 offset:3072
	ds_read_b128 v[152:155], v0 offset:4096
	ds_read_b128 v[156:159], v0 offset:5120
	ds_read_b128 v[164:167], v0 offset:6144
	ds_read_b128 v[168:171], v0 offset:7168
	v_add_u32_e32 v184, v137, v138
	ds_read_b128 v[136:139], v184 offset:16384
	ds_read_b128 v[172:175], v184 offset:17408
	ds_read_b128 v[176:179], v184 offset:18432
	ds_read_b128 v[180:183], v184 offset:19456
	v_bfe_u32 v188, v134, 6, 1
	s_nop 0
	s_waitcnt vmcnt(0) lgkmcnt(0)
	s_waitcnt lgkmcnt(3)
	v_mfma_f32_16x16x32_bf16 v[126:129], v[136:139], v[130:133], v[126:129]
	v_ashrrev_i32_e32 v189, 7, v134
	v_and_b32_e32 v190, 15, v134
	v_bfe_u32 v191, v134, 4, 2
	s_waitcnt lgkmcnt(2)
	v_mfma_f32_16x16x32_bf16 v[122:125], v[172:175], v[130:133], v[122:125]
	s_barrier
	s_waitcnt lgkmcnt(1)
	v_mfma_f32_16x16x32_bf16 v[118:121], v[176:179], v[130:133], v[118:121]
	s_waitcnt lgkmcnt(0)
	v_mfma_f32_16x16x32_bf16 v[114:117], v[180:183], v[130:133], v[114:117]
	v_mfma_f32_16x16x32_bf16 v[110:113], v[136:139], v[140:143], v[110:113]
	v_mfma_f32_16x16x32_bf16 v[106:109], v[172:175], v[140:143], v[106:109]
	v_mfma_f32_16x16x32_bf16 v[102:105], v[176:179], v[140:143], v[102:105]
	v_mfma_f32_16x16x32_bf16 v[98:101], v[180:183], v[140:143], v[98:101]
	v_mfma_f32_16x16x32_bf16 v[94:97], v[136:139], v[144:147], v[94:97]
	v_mfma_f32_16x16x32_bf16 v[90:93], v[172:175], v[144:147], v[90:93]
	v_mfma_f32_16x16x32_bf16 v[86:89], v[176:179], v[144:147], v[86:89]
	v_mfma_f32_16x16x32_bf16 v[82:85], v[180:183], v[144:147], v[82:85]
	v_mfma_f32_16x16x32_bf16 v[78:81], v[136:139], v[148:151], v[78:81]
	v_mfma_f32_16x16x32_bf16 v[130:133], v[172:175], v[148:151], v[74:77]
	v_mfma_f32_16x16x32_bf16 v[70:73], v[176:179], v[148:151], v[70:73]
	v_mfma_f32_16x16x32_bf16 v[66:69], v[180:183], v[148:151], v[66:69]
	v_mfma_f32_16x16x32_bf16 v[62:65], v[136:139], v[152:155], v[62:65]
	v_mfma_f32_16x16x32_bf16 v[58:61], v[172:175], v[152:155], v[58:61]
	v_mfma_f32_16x16x32_bf16 v[54:57], v[176:179], v[152:155], v[54:57]
	v_mfma_f32_16x16x32_bf16 v[50:53], v[180:183], v[152:155], v[50:53]
	v_mfma_f32_16x16x32_bf16 v[46:49], v[136:139], v[156:159], v[46:49]
	v_mfma_f32_16x16x32_bf16 v[42:45], v[172:175], v[156:159], v[42:45]
	v_mfma_f32_16x16x32_bf16 v[38:41], v[176:179], v[156:159], v[38:41]
	v_mfma_f32_16x16x32_bf16 v[34:37], v[180:183], v[156:159], v[34:37]
	v_mfma_f32_16x16x32_bf16 v[30:33], v[136:139], v[164:167], v[30:33]
	v_mfma_f32_16x16x32_bf16 v[26:29], v[172:175], v[164:167], v[26:29]
	v_mfma_f32_16x16x32_bf16 v[22:25], v[176:179], v[164:167], v[22:25]
	v_mfma_f32_16x16x32_bf16 v[18:21], v[180:183], v[164:167], v[18:21]
	v_mfma_f32_16x16x32_bf16 v[14:17], v[136:139], v[168:171], v[14:17]
	v_mfma_f32_16x16x32_bf16 v[10:13], v[172:175], v[168:171], v[10:13]
	v_mfma_f32_16x16x32_bf16 v[6:9], v[176:179], v[168:171], v[6:9]
	v_mfma_f32_16x16x32_bf16 v[134:137], v[180:183], v[168:171], v[2:5]
	s_nop 0
	s_nop 1
	ds_read_b128 v[2:5], v0 offset:24576
	ds_read_b128 v[74:77], v0 offset:25600
	ds_read_b128 v[138:141], v0 offset:26624
	ds_read_b128 v[142:145], v0 offset:27648
	ds_read_b128 v[146:149], v0 offset:28672
	ds_read_b128 v[150:153], v0 offset:29696
	ds_read_b128 v[154:157], v0 offset:30720
	ds_read_b128 v[158:161], v0 offset:31744
	ds_read_b128 v[164:167], v184 offset:40960
	ds_read_b128 v[168:171], v184 offset:41984
	ds_read_b128 v[172:175], v184 offset:43008
	ds_read_b128 v[176:179], v184 offset:44032
	s_nop 0
	s_waitcnt lgkmcnt(0)
	s_barrier
; #define EPI_BEGIN const int lr1_ = launder_v(lr), lq1_ = launder_v(lq), wr1_ = launder_v(wr), wc1_ = launder_v(wc); { const int lr = lr1_, lq = lq1_, wr = wr1_, wc = wc1_; (void)lr; (void)lq; (void)wr; (void)wc;
; template <int MI, int NI>
; DI void resid_tile(const u16* A, int K, const u16* Bt, const float* gate, const float* xl_in, const float* xc_in, float* xl_out, float* xc_out,
;                    int m0, int n0, char* smem) {
;     ...
;   EPI_BEGIN
; #pragma unroll
;   for (int mi = 0; mi < MI; ++mi) {
;     const int m = m0 + wr * 16 * MI + mi * 16 + lr;
;     const int b9 = m < NTL ? m >> 12 : 8;
;     const float* xi = xrow(xl_in, xc_in, m);
;     float* xo = m < NTL ? xl_out + (size_t)m * D : xc_out + (size_t)(m - NTL) * D;
; #pragma unroll
;     for (int ni = 0; ni < NI; ++ni) {
;       const int n = n0 + wc * 16 * NI + ni * 16 + lq * 4;
;       const float4 g = *(const float4*)(gate + (size_t)b9 * 6144 + n);
;       const float4 xv = *(const float4*)(xi + n);
;       float4 ov;
;       ov.x = xv.x + g.x * acc[mi][ni][0]; ov.y = xv.y + g.y * acc[mi][ni][1]; ov.z = xv.z + g.z * acc[mi][ni][2]; ov.w = xv.w + g.w * acc[mi][ni][3];
;       *(float4*)(xo + n) = ov;
;     }
;     __builtin_amdgcn_sched_barrier(0);
;   }
;   EPI_END
; }
	v_readlane_b32 s4, v253, 55
	v_lshlrev_b32_e32 v0, 7, v189
	s_waitcnt lgkmcnt(3)
	v_mfma_f32_16x16x32_bf16 v[126:129], v[164:167], v[2:5], v[126:129]
	s_waitcnt lgkmcnt(2)
	v_mfma_f32_16x16x32_bf16 v[122:125], v[168:171], v[2:5], v[122:125]
	s_waitcnt lgkmcnt(1)
	v_mfma_f32_16x16x32_bf16 v[180:183], v[172:175], v[2:5], v[118:121]
	s_waitcnt lgkmcnt(0)
	v_mfma_f32_16x16x32_bf16 v[184:187], v[176:179], v[2:5], v[114:117]
	v_lshlrev_b32_e32 v2, 2, v191
	v_mov_b32_e32 v118, s4
	v_readlane_b32 s4, v253, 53
	v_add3_u32 v116, v190, s10, v0
	v_lshlrev_b32_e32 v0, 6, v188
	v_add3_u32 v2, v2, s11, v0
	v_min_i32_e32 v0, 0x8000, v116
	v_mov_b32_e32 v119, s4
	v_readlane_b32 s4, v253, 56
	v_mfma_f32_16x16x32_bf16 v[110:113], v[164:167], v[74:77], v[110:113]
	v_ashrrev_i32_e32 v117, 31, v116
	v_cmp_gt_i32_e32 vcc, s58, v116
	v_mov_b32_e32 v120, s4
	v_mfma_f32_16x16x32_bf16 v[106:109], v[168:171], v[74:77], v[106:109]
	v_readlane_b32 s4, v253, 54
	v_cndmask_b32_e32 v5, 0, v117, vcc
	v_cndmask_b32_e32 v115, v118, v119, vcc
	v_mfma_f32_16x16x32_bf16 v[102:105], v[172:175], v[74:77], v[102:105]
	v_mov_b32_e32 v121, s4
	v_cndmask_b32_e32 v114, v120, v121, vcc
	v_readlane_b32 s4, v253, 51
	v_mfma_f32_16x16x32_bf16 v[98:101], v[176:179], v[74:77], v[98:101]
	v_ashrrev_i32_e32 v3, 31, v2
	v_readlane_b32 s5, v253, 52
	v_mfma_f32_16x16x32_bf16 v[74:77], v[164:167], v[142:145], v[78:81]
	v_mfma_f32_16x16x32_bf16 v[78:81], v[168:171], v[142:145], v[130:133]
	s_nop 2
	v_ashrrev_i32_e32 v130, 12, v0
	v_add_u32_e32 v0, 0xffff8000, v116
	v_cndmask_b32_e32 v4, v0, v116, vcc
	v_lshlrev_b64 v[4:5], 12, v[4:5]
	v_lshl_add_u64 v[4:5], v[114:115], 0, v[4:5]
	v_mul_hi_i32_i24_e32 v115, 0x6000, v130
	v_mul_i32_i24_e32 v114, 0x6000, v130
	v_lshl_add_u64 v[130:131], s[4:5], 0, v[114:115]
	v_lshlrev_b64 v[114:115], 2, v[2:3]
	v_mfma_f32_16x16x32_bf16 v[94:97], v[164:167], v[138:141], v[94:97]
	v_mfma_f32_16x16x32_bf16 v[90:93], v[168:171], v[138:141], v[90:93]
	v_mfma_f32_16x16x32_bf16 v[86:89], v[172:175], v[138:141], v[86:89]
	v_mfma_f32_16x16x32_bf16 v[82:85], v[176:179], v[138:141], v[82:85]
	v_lshl_add_u64 v[138:139], v[130:131], 0, v[114:115]
	v_lshl_add_u64 v[140:141], v[4:5], 0, v[114:115]
	flat_load_dwordx4 v[2:5], v[138:139]
	flat_load_dwordx4 v[130:133], v[140:141]
	v_mfma_f32_16x16x32_bf16 v[70:73], v[172:175], v[142:145], v[70:73]
	s_waitcnt vmcnt(0) lgkmcnt(0)
	v_pk_fma_f32 v[2:3], v[126:127], v[2:3], v[130:131]
	v_mfma_f32_16x16x32_bf16 v[66:69], v[176:179], v[142:145], v[66:69]
	v_lshlrev_b64 v[142:143], 12, v[116:117]
	v_lshlrev_b64 v[144:145], 12, v[0:1]
	v_lshl_add_u64 v[142:143], s[48:49], 0, v[142:143]
	v_lshl_add_u64 v[144:145], s[94:95], 0, v[144:145]
	v_cndmask_b32_e32 v143, v145, v143, vcc
	v_cndmask_b32_e32 v142, v144, v142, vcc
	v_lshl_add_u64 v[142:143], v[142:143], 0, v[114:115]
	v_pk_fma_f32 v[4:5], v[128:129], v[4:5], v[132:133]
	flat_store_dwordx4 v[142:143], v[2:5]
	flat_load_dwordx4 v[126:129], v[138:139] offset:64
	flat_load_dwordx4 v[130:133], v[140:141] offset:64
	v_mfma_f32_16x16x32_bf16 v[2:5], v[168:171], v[158:161], v[10:13]
	v_mfma_f32_16x16x32_bf16 v[62:65], v[164:167], v[146:149], v[62:65]
	s_waitcnt vmcnt(0) lgkmcnt(0)
	s_nop 0
	v_pk_fma_f32 v[10:11], v[122:123], v[126:127], v[130:131]
	v_pk_fma_f32 v[12:13], v[124:125], v[128:129], v[132:133]
	flat_store_dwordx4 v[142:143], v[10:13] offset:64
	flat_load_dwordx4 v[10:13], v[138:139] offset:128
	s_nop 0
	flat_load_dwordx4 v[122:125], v[140:141] offset:128
	v_mfma_f32_16x16x32_bf16 v[58:61], v[168:171], v[146:149], v[58:61]
	s_waitcnt vmcnt(0) lgkmcnt(0)
	v_pk_fma_f32 v[10:11], v[180:181], v[10:11], v[122:123]
	v_pk_fma_f32 v[12:13], v[182:183], v[12:13], v[124:125]
	flat_store_dwordx4 v[142:143], v[10:13] offset:128
	flat_load_dwordx4 v[122:125], v[138:139] offset:192
	flat_load_dwordx4 v[126:129], v[140:141] offset:192
	v_mfma_f32_16x16x32_bf16 v[54:57], v[172:175], v[146:149], v[54:57]
	s_waitcnt vmcnt(0) lgkmcnt(0)
	v_pk_fma_f32 v[122:123], v[184:185], v[122:123], v[126:127]
	v_pk_fma_f32 v[124:125], v[186:187], v[124:125], v[128:129]
	v_mfma_f32_16x16x32_bf16 v[50:53], v[176:179], v[146:149], v[50:53]
	flat_store_dwordx4 v[142:143], v[122:125] offset:192
	v_mfma_f32_16x16x32_bf16 v[46:49], v[164:167], v[150:153], v[46:49]
	v_mfma_f32_16x16x32_bf16 v[42:45], v[168:171], v[150:153], v[42:45]
	v_mfma_f32_16x16x32_bf16 v[38:41], v[172:175], v[150:153], v[38:41]
	v_mfma_f32_16x16x32_bf16 v[34:37], v[176:179], v[150:153], v[34:37]
	v_mfma_f32_16x16x32_bf16 v[30:33], v[164:167], v[154:157], v[30:33]
	v_mfma_f32_16x16x32_bf16 v[26:29], v[168:171], v[154:157], v[26:29]
	v_mfma_f32_16x16x32_bf16 v[22:25], v[172:175], v[154:157], v[22:25]
	v_mfma_f32_16x16x32_bf16 v[18:21], v[176:179], v[154:157], v[18:21]
	v_mfma_f32_16x16x32_bf16 v[14:17], v[164:167], v[158:161], v[14:17]
	v_mfma_f32_16x16x32_bf16 v[6:9], v[172:175], v[158:161], v[6:9]
	v_mfma_f32_16x16x32_bf16 v[10:13], v[176:179], v[158:161], v[134:137]
	v_add_u32_e32 v122, 16, v116
	v_min_i32_e32 v0, 0x8000, v122
	v_cmp_gt_i32_e32 vcc, s58, v122
	v_ashrrev_i32_e32 v117, 12, v0
	v_add_u32_e32 v0, 0xffff8010, v116
	v_ashrrev_i32_e32 v123, 31, v122
	v_cndmask_b32_e32 v125, 0, v123, vcc
	v_cndmask_b32_e32 v124, v0, v122, vcc
	v_cndmask_b32_e32 v127, v118, v119, vcc
	v_cndmask_b32_e32 v126, v120, v121, vcc
	v_lshlrev_b64 v[124:125], 12, v[124:125]
	v_lshl_add_u64 v[124:125], v[126:127], 0, v[124:125]
	v_lshlrev_b64 v[122:123], 12, v[122:123]
	v_lshlrev_b64 v[126:127], 12, v[0:1]
	v_lshl_add_u64 v[122:123], s[48:49], 0, v[122:123]
	v_lshl_add_u64 v[126:127], s[94:95], 0, v[126:127]
	v_cndmask_b32_e32 v123, v127, v123, vcc
	v_cndmask_b32_e32 v122, v126, v122, vcc
	v_mul_hi_i32_i24_e32 v127, 0x6000, v117
	v_mul_i32_i24_e32 v126, 0x6000, v117
	v_lshl_add_u64 v[126:127], s[4:5], 0, v[126:127]
	v_lshl_add_u64 v[130:131], v[126:127], 0, v[114:115]
	v_lshl_add_u64 v[132:133], v[124:125], 0, v[114:115]
	v_lshl_add_u64 v[134:135], v[122:123], 0, v[114:115]
	global_load_dwordx4 v[156:159], v[130:131], off
	global_load_dwordx4 v[164:167], v[130:131], off offset:64
	global_load_dwordx4 v[168:171], v[130:131], off offset:128
	global_load_dwordx4 v[172:175], v[130:131], off offset:192
	global_load_dwordx4 v[140:143], v[132:133], off
	global_load_dwordx4 v[144:147], v[132:133], off offset:64
	global_load_dwordx4 v[148:151], v[132:133], off offset:128
	global_load_dwordx4 v[152:155], v[132:133], off offset:192
	v_mov_b32_e32 v216, 0x10000
	v_mov_b32_e32 v217, 0
	v_lshl_add_u64 v[212:213], v[132:133], 0, v[216:217]
	v_lshl_add_u64 v[214:215], v[134:135], 0, v[216:217]
	global_load_dwordx4 v[176:179], v[212:213], off
	global_load_dwordx4 v[180:183], v[212:213], off offset:64
	global_load_dwordx4 v[184:187], v[212:213], off offset:128
	global_load_dwordx4 v[188:191], v[212:213], off offset:192
	v_lshl_add_u64 v[212:213], v[212:213], 0, v[216:217]
	s_waitcnt vmcnt(4)
; template <int MI, int NI>
; DI void resid_tile(const u16* A, int K, const u16* Bt, const float* gate, const float* xl_in, const float* xc_in, float* xl_out, float* xc_out,
;                    int m0, int n0, char* smem) {
;     ...
; #pragma unroll
;   for (int mi = 0; mi < MI; ++mi) {
;     const int m = m0 + wr * 16 * MI + mi * 16 + lr;
;     const int b9 = m < NTL ? m >> 12 : 8;
;     const float* xi = xrow(xl_in, xc_in, m);
;     float* xo = m < NTL ? xl_out + (size_t)m * D : xc_out + (size_t)(m - NTL) * D;
; #pragma unroll
;     for (int ni = 0; ni < NI; ++ni) {
;       const int n = n0 + wc * 16 * NI + ni * 16 + lq * 4;
;       const float4 g = *(const float4*)(gate + (size_t)b9 * 6144 + n);
;       const float4 xv = *(const float4*)(xi + n);
;       float4 ov;
;       ov.x = xv.x + g.x * acc[mi][ni][0]; ov.y = xv.y + g.y * acc[mi][ni][1]; ov.z = xv.z + g.z * acc[mi][ni][2]; ov.w = xv.w + g.w * acc[mi][ni][3];
;       *(float4*)(xo + n) = ov;
;     }
;     __builtin_amdgcn_sched_barrier(0);
;   }
;   EPI_END
; }
; DI void phase_resid(const Params& p, const u16* A, int K, const u16* Bt, const float* gate  ,
;                     const float* xl_in, const float* xc_in, float* xl_out, float* xc_out, int Mout, char* smem) {
;     ...
;   for (int it = 0;; ++it) {
;     int tm, tn;
;     if (!tile_map(it, NTL / 256, 8, blk__, gridDim.x, tm, tn)) break;
;     resid_tile<8, 4>(A, K, Bt, gate, xl_in, xc_in, xl_out, xc_out, tm * 256, tn * 128, smem);
;   }
	v_pk_fma_f32 v[110:111], v[110:111], v[156:157], v[140:141]
	v_pk_fma_f32 v[112:113], v[112:113], v[158:159], v[142:143]
	v_pk_fma_f32 v[106:107], v[106:107], v[164:165], v[144:145]
	v_pk_fma_f32 v[108:109], v[108:109], v[166:167], v[146:147]
	v_pk_fma_f32 v[102:103], v[102:103], v[168:169], v[148:149]
	v_pk_fma_f32 v[104:105], v[104:105], v[170:171], v[150:151]
	v_pk_fma_f32 v[98:99], v[98:99], v[172:173], v[152:153]
	v_pk_fma_f32 v[100:101], v[100:101], v[174:175], v[154:155]
	global_store_dwordx4 v[134:135], v[110:113], off
	global_store_dwordx4 v[134:135], v[106:109], off offset:64
	global_store_dwordx4 v[134:135], v[102:105], off offset:128
	global_store_dwordx4 v[134:135], v[98:101], off offset:192
	global_load_dwordx4 v[140:143], v[212:213], off
	global_load_dwordx4 v[144:147], v[212:213], off offset:64
	global_load_dwordx4 v[148:151], v[212:213], off offset:128
	global_load_dwordx4 v[152:155], v[212:213], off offset:192
	v_lshl_add_u64 v[212:213], v[212:213], 0, v[216:217]
	s_waitcnt vmcnt(8)
	v_pk_fma_f32 v[94:95], v[94:95], v[156:157], v[176:177]
	v_pk_fma_f32 v[96:97], v[96:97], v[158:159], v[178:179]
	v_pk_fma_f32 v[90:91], v[90:91], v[164:165], v[180:181]
	v_pk_fma_f32 v[92:93], v[92:93], v[166:167], v[182:183]
	v_pk_fma_f32 v[86:87], v[86:87], v[168:169], v[184:185]
	v_pk_fma_f32 v[88:89], v[88:89], v[170:171], v[186:187]
	v_pk_fma_f32 v[82:83], v[82:83], v[172:173], v[188:189]
	v_pk_fma_f32 v[84:85], v[84:85], v[174:175], v[190:191]
	global_store_dwordx4 v[214:215], v[94:97], off
	global_store_dwordx4 v[214:215], v[90:93], off offset:64
	global_store_dwordx4 v[214:215], v[86:89], off offset:128
	global_store_dwordx4 v[214:215], v[82:85], off offset:192
	v_lshl_add_u64 v[214:215], v[214:215], 0, v[216:217]
	global_load_dwordx4 v[176:179], v[212:213], off
	global_load_dwordx4 v[180:183], v[212:213], off offset:64
	global_load_dwordx4 v[184:187], v[212:213], off offset:128
	global_load_dwordx4 v[188:191], v[212:213], off offset:192
	v_lshl_add_u64 v[212:213], v[212:213], 0, v[216:217]
	s_waitcnt vmcnt(8)
	v_pk_fma_f32 v[74:75], v[74:75], v[156:157], v[140:141]
	v_pk_fma_f32 v[76:77], v[76:77], v[158:159], v[142:143]
	v_pk_fma_f32 v[78:79], v[78:79], v[164:165], v[144:145]
	v_pk_fma_f32 v[80:81], v[80:81], v[166:167], v[146:147]
	v_pk_fma_f32 v[70:71], v[70:71], v[168:169], v[148:149]
	v_pk_fma_f32 v[72:73], v[72:73], v[170:171], v[150:151]
	v_pk_fma_f32 v[66:67], v[66:67], v[172:173], v[152:153]
	v_pk_fma_f32 v[68:69], v[68:69], v[174:175], v[154:155]
	global_store_dwordx4 v[214:215], v[74:77], off
	global_store_dwordx4 v[214:215], v[78:81], off offset:64
	global_store_dwordx4 v[214:215], v[70:73], off offset:128
	global_store_dwordx4 v[214:215], v[66:69], off offset:192
	v_lshl_add_u64 v[214:215], v[214:215], 0, v[216:217]
	global_load_dwordx4 v[140:143], v[212:213], off
	global_load_dwordx4 v[144:147], v[212:213], off offset:64
	global_load_dwordx4 v[148:151], v[212:213], off offset:128
	global_load_dwordx4 v[152:155], v[212:213], off offset:192
	v_lshl_add_u64 v[212:213], v[212:213], 0, v[216:217]
	s_waitcnt vmcnt(8)
	v_pk_fma_f32 v[62:63], v[62:63], v[156:157], v[176:177]
	v_pk_fma_f32 v[64:65], v[64:65], v[158:159], v[178:179]
	v_pk_fma_f32 v[58:59], v[58:59], v[164:165], v[180:181]
	v_pk_fma_f32 v[60:61], v[60:61], v[166:167], v[182:183]
	v_pk_fma_f32 v[54:55], v[54:55], v[168:169], v[184:185]
	v_pk_fma_f32 v[56:57], v[56:57], v[170:171], v[186:187]
	v_pk_fma_f32 v[50:51], v[50:51], v[172:173], v[188:189]
	v_pk_fma_f32 v[52:53], v[52:53], v[174:175], v[190:191]
	global_store_dwordx4 v[214:215], v[62:65], off
	global_store_dwordx4 v[214:215], v[58:61], off offset:64
	global_store_dwordx4 v[214:215], v[54:57], off offset:128
	global_store_dwordx4 v[214:215], v[50:53], off offset:192
	v_lshl_add_u64 v[214:215], v[214:215], 0, v[216:217]
	global_load_dwordx4 v[176:179], v[212:213], off
	global_load_dwordx4 v[180:183], v[212:213], off offset:64
	global_load_dwordx4 v[184:187], v[212:213], off offset:128
	global_load_dwordx4 v[188:191], v[212:213], off offset:192
	v_lshl_add_u64 v[212:213], v[212:213], 0, v[216:217]
	s_waitcnt vmcnt(8)
	v_pk_fma_f32 v[46:47], v[46:47], v[156:157], v[140:141]
	v_pk_fma_f32 v[48:49], v[48:49], v[158:159], v[142:143]
	v_pk_fma_f32 v[42:43], v[42:43], v[164:165], v[144:145]
	v_pk_fma_f32 v[44:45], v[44:45], v[166:167], v[146:147]
	v_pk_fma_f32 v[38:39], v[38:39], v[168:169], v[148:149]
	v_pk_fma_f32 v[40:41], v[40:41], v[170:171], v[150:151]
	v_pk_fma_f32 v[34:35], v[34:35], v[172:173], v[152:153]
	v_pk_fma_f32 v[36:37], v[36:37], v[174:175], v[154:155]
	global_store_dwordx4 v[214:215], v[46:49], off
	global_store_dwordx4 v[214:215], v[42:45], off offset:64
	global_store_dwordx4 v[214:215], v[38:41], off offset:128
	global_store_dwordx4 v[214:215], v[34:37], off offset:192
	v_lshl_add_u64 v[214:215], v[214:215], 0, v[216:217]
	global_load_dwordx4 v[140:143], v[212:213], off
	global_load_dwordx4 v[144:147], v[212:213], off offset:64
	global_load_dwordx4 v[148:151], v[212:213], off offset:128
	global_load_dwordx4 v[152:155], v[212:213], off offset:192
	s_waitcnt vmcnt(8)
	v_pk_fma_f32 v[30:31], v[30:31], v[156:157], v[176:177]
	v_pk_fma_f32 v[32:33], v[32:33], v[158:159], v[178:179]
	v_pk_fma_f32 v[26:27], v[26:27], v[164:165], v[180:181]
	v_pk_fma_f32 v[28:29], v[28:29], v[166:167], v[182:183]
	v_pk_fma_f32 v[22:23], v[22:23], v[168:169], v[184:185]
	v_pk_fma_f32 v[24:25], v[24:25], v[170:171], v[186:187]
	v_pk_fma_f32 v[18:19], v[18:19], v[172:173], v[188:189]
	v_pk_fma_f32 v[20:21], v[20:21], v[174:175], v[190:191]
	global_store_dwordx4 v[214:215], v[30:33], off
	global_store_dwordx4 v[214:215], v[26:29], off offset:64
	global_store_dwordx4 v[214:215], v[22:25], off offset:128
	global_store_dwordx4 v[214:215], v[18:21], off offset:192
	v_lshl_add_u64 v[214:215], v[214:215], 0, v[216:217]
	s_waitcnt vmcnt(4)
	v_pk_fma_f32 v[14:15], v[14:15], v[156:157], v[140:141]
	v_pk_fma_f32 v[16:17], v[16:17], v[158:159], v[142:143]
	v_pk_fma_f32 v[2:3], v[2:3], v[164:165], v[144:145]
	v_pk_fma_f32 v[4:5], v[4:5], v[166:167], v[146:147]
	v_pk_fma_f32 v[6:7], v[6:7], v[168:169], v[148:149]
	v_pk_fma_f32 v[8:9], v[8:9], v[170:171], v[150:151]
	v_pk_fma_f32 v[10:11], v[10:11], v[172:173], v[152:153]
	v_pk_fma_f32 v[12:13], v[12:13], v[174:175], v[154:155]
	global_store_dwordx4 v[214:215], v[14:17], off
	global_store_dwordx4 v[214:215], v[2:5], off offset:64
	global_store_dwordx4 v[214:215], v[6:9], off offset:128
	global_store_dwordx4 v[214:215], v[10:13], off offset:192
	s_add_i32 s9, s9, 1
	s_mul_i32 s4, s9, s39
	s_add_i32 s4, s4, s7
	s_cmpk_gt_i32 s4, 0x7f
	s_cbranch_scc0 .LBB0_461

; template <int MI, int NI>
; DI void gemm256(f32x4 (&acc)[MI][NI], const u16* __restrict__ A, int lda, const u16* __restrict__ Bt, int ldb, int K, int m0, int n0, char* smem) {
;     ...
;   for (int kt = 0; kt < nk; ++kt) {
;     if (kt + 1 < nk) asm volatile("s_waitcnt vmcnt(%0) lgkmcnt(0)" :: "n"(LPS) : "memory");
;     else asm volatile("s_waitcnt vmcnt(0) lgkmcnt(0)" ::: "memory");
;     __builtin_amdgcn_s_barrier();
;     __builtin_amdgcn_s_setprio(1);
;     const char* sb = smem + st * STAGE + foff;
;     bf16x8 af[MI], bfr[NI];
; #pragma unroll
;     for (int mi = 0; mi < MI; ++mi) af[mi] = *(const bf16x8*)(sb + (wr * MI + mi) * 1024);
; #pragma unroll
;     for (int ni = 0; ni < NI; ++ni) bfr[ni] = *(const bf16x8*)(sb + ABYTES + (wc * NI + ni) * 1024);
;     __builtin_amdgcn_sched_barrier(0x0);
;     if (kt + 2 < nk) { const int s2 = st >= 1 ? st - 1 : 2; G256_ISSUE(s2, (kt + 2) * 32); }
;     __builtin_amdgcn_s_setprio(0);
; #pragma unroll
;     for (int mi = 0; mi < MI; ++mi)
; #pragma unroll
;       for (int ni = 0; ni < NI; ++ni)
;         acc[mi][ni] = __builtin_amdgcn_mfma_f32_16x16x32_bf16(bfr[ni], af[mi], acc[mi][ni], 0, 0, 0);
;     st = st == 2 ? 0 : st + 1;
;   }
.LBB0_467:
	s_waitcnt vmcnt(2) lgkmcnt(0)
	s_barrier
	s_nop 0
	s_lshl_b32 s12, s11, 13
	v_or_b32_e32 v0, s12, v24
	v_add_u32_e32 v28, v0, v27
	v_add_u32_e32 v32, v0, v26
	v_add_u32_e32 v0, v0, v25
	ds_read_b128 v[28:31], v28
	ds_read_b128 v[32:35], v32
	ds_read_b128 v[36:39], v0 offset:4096
	ds_read_b128 v[40:43], v0 offset:5120
	s_addk_i32 s12, 0xe000
	s_cmp_gt_i32 s11, 0
	s_cselect_b32 s12, s12, 0x4000
	v_add_u32_e32 v0, s12, v23
	v_add_u32_e32 v52, 0x1000, v0
	v_lshl_add_u64 v[48:49], v[18:19], 0, s[4:5]
	v_lshl_add_u64 v[48:49], v[48:49], 0, s[4:5]
	v_readfirstlane_b32 s12, v0
	v_lshl_add_u64 v[44:45], v[20:21], 0, s[4:5]
	s_mov_b64 s[98:99], 0x47e1100
	v_lshl_add_u64 v[50:51], v[48:49], 0, s[98:99]
	s_mov_b32 m0, s12
	v_readfirstlane_b32 s12, v52
	v_lshl_add_u64 v[46:47], v[44:45], 0, s[86:87]
	global_load_lds_dwordx4 v[50:51], off
	s_mov_b32 m0, s12
	s_nop 0
	global_load_lds_dwordx4 v[46:47], off
	s_nop 0
	s_waitcnt lgkmcnt(0)
	v_mfma_f32_16x16x32_bf16 v[14:17], v[36:39], v[28:31], v[14:17]
	s_add_i32 s12, s11, 1
	s_waitcnt vmcnt(2) lgkmcnt(0)
	s_cmp_lg_u32 s11, 2
	v_mfma_f32_16x16x32_bf16 v[10:13], v[40:43], v[28:31], v[10:13]
	s_cselect_b32 s11, s12, 0
	s_barrier
	v_mfma_f32_16x16x32_bf16 v[2:5], v[36:39], v[32:35], v[2:5]
	v_mfma_f32_16x16x32_bf16 v[6:9], v[40:43], v[32:35], v[6:9]
	s_nop 0
	s_lshl_b32 s12, s11, 13
	v_or_b32_e32 v0, s12, v24
	v_add_u32_e32 v28, v0, v27
	v_add_u32_e32 v32, v0, v26
	v_add_u32_e32 v0, v0, v25
	ds_read_b128 v[28:31], v28
	ds_read_b128 v[32:35], v32
	ds_read_b128 v[36:39], v0 offset:4096
	ds_read_b128 v[40:43], v0 offset:5120
	s_addk_i32 s12, 0xe000
	s_cmp_gt_i32 s11, 0
	s_cselect_b32 s12, s12, 0x4000
	v_add_u32_e32 v0, s12, v23
	s_mov_b64 s[12:13], 0x16610c0
	v_add_u32_e32 v52, 0x1000, v0
	v_lshl_add_u64 v[46:47], v[44:45], 0, s[12:13]
	v_readfirstlane_b32 s12, v0
	s_mov_b64 s[98:99], 0x47e1180
	v_lshl_add_u64 v[50:51], v[48:49], 0, s[98:99]
	s_mov_b32 m0, s12
	v_readfirstlane_b32 s12, v52
	global_load_lds_dwordx4 v[50:51], off
	s_mov_b32 m0, s12
	s_nop 0
	global_load_lds_dwordx4 v[46:47], off
	s_nop 0
	s_waitcnt lgkmcnt(0)
	v_mfma_f32_16x16x32_bf16 v[14:17], v[36:39], v[28:31], v[14:17]
	s_add_i32 s12, s11, 1
	s_waitcnt vmcnt(2) lgkmcnt(0)
	s_cmp_lg_u32 s11, 2
	v_mfma_f32_16x16x32_bf16 v[10:13], v[40:43], v[28:31], v[10:13]
	s_cselect_b32 s11, s12, 0
	s_barrier
	v_mfma_f32_16x16x32_bf16 v[2:5], v[36:39], v[32:35], v[2:5]
	v_mfma_f32_16x16x32_bf16 v[6:9], v[40:43], v[32:35], v[6:9]
	s_nop 0
	s_lshl_b32 s12, s11, 13
	v_or_b32_e32 v0, s12, v24
	v_add_u32_e32 v28, v0, v27
	v_add_u32_e32 v32, v0, v26
	v_add_u32_e32 v0, v0, v25
	ds_read_b128 v[28:31], v28
	ds_read_b128 v[32:35], v32
	ds_read_b128 v[36:39], v0 offset:4096
	ds_read_b128 v[40:43], v0 offset:5120
	s_addk_i32 s12, 0xe000
	s_cmp_gt_i32 s11, 0
	s_cselect_b32 s12, s12, 0x4000
	v_add_u32_e32 v0, s12, v23
	s_mov_b64 s[12:13], 0x1661100
	v_add_u32_e32 v52, 0x1000, v0
	v_lshl_add_u64 v[46:47], v[44:45], 0, s[12:13]
	v_readfirstlane_b32 s12, v0
	s_mov_b64 s[98:99], 0x47e1200
	v_lshl_add_u64 v[50:51], v[48:49], 0, s[98:99]
	s_mov_b32 m0, s12
	v_readfirstlane_b32 s12, v52
	global_load_lds_dwordx4 v[50:51], off
	s_mov_b32 m0, s12
	s_nop 0
	global_load_lds_dwordx4 v[46:47], off
	s_nop 0
	s_waitcnt lgkmcnt(0)
	v_mfma_f32_16x16x32_bf16 v[14:17], v[36:39], v[28:31], v[14:17]
	s_add_i32 s12, s11, 1
	s_waitcnt vmcnt(2) lgkmcnt(0)
	s_cmp_lg_u32 s11, 2
	v_mfma_f32_16x16x32_bf16 v[10:13], v[40:43], v[28:31], v[10:13]
	s_cselect_b32 s11, s12, 0
	s_barrier
	v_mfma_f32_16x16x32_bf16 v[2:5], v[36:39], v[32:35], v[2:5]
	v_mfma_f32_16x16x32_bf16 v[6:9], v[40:43], v[32:35], v[6:9]
	s_nop 0
	s_lshl_b32 s12, s11, 13
	v_or_b32_e32 v0, s12, v24
	v_add_u32_e32 v28, v0, v27
	v_add_u32_e32 v32, v0, v26
	v_add_u32_e32 v0, v0, v25
	ds_read_b128 v[28:31], v28
	ds_read_b128 v[32:35], v32
	ds_read_b128 v[36:39], v0 offset:4096
	ds_read_b128 v[40:43], v0 offset:5120
	s_addk_i32 s12, 0xe000
	s_cmp_gt_i32 s11, 0
	s_cselect_b32 s12, s12, 0x4000
	v_add_u32_e32 v0, s12, v23
	s_mov_b64 s[12:13], 0x1661140
	v_lshl_add_u64 v[46:47], v[44:45], 0, s[12:13]
	s_mov_b64 s[12:13], 0x47e1140
	v_add_u32_e32 v52, 0x1000, v0
	s_mov_b64 s[98:99], 0x47e1280
	v_lshl_add_u64 v[50:51], v[48:49], 0, s[98:99]
	v_readfirstlane_b32 s12, v0
	s_mov_b32 m0, s12
	v_readfirstlane_b32 s12, v52
	global_load_lds_dwordx4 v[50:51], off
	s_mov_b32 m0, s12
	s_nop 0
	global_load_lds_dwordx4 v[46:47], off
	s_nop 0
	s_waitcnt lgkmcnt(0)
	v_mfma_f32_16x16x32_bf16 v[14:17], v[36:39], v[28:31], v[14:17]
	s_add_i32 s12, s11, 1
	s_waitcnt vmcnt(2) lgkmcnt(0)
	s_cmp_lg_u32 s11, 2
	v_mfma_f32_16x16x32_bf16 v[10:13], v[40:43], v[28:31], v[10:13]
	s_cselect_b32 s11, s12, 0
	s_barrier
	v_mfma_f32_16x16x32_bf16 v[2:5], v[36:39], v[32:35], v[2:5]
	v_mfma_f32_16x16x32_bf16 v[6:9], v[40:43], v[32:35], v[6:9]
	s_nop 0
	s_lshl_b32 s12, s11, 13
	v_or_b32_e32 v0, s12, v24
	v_add_u32_e32 v28, v0, v27
	v_add_u32_e32 v32, v0, v26
	v_add_u32_e32 v0, v0, v25
	ds_read_b128 v[28:31], v28
	ds_read_b128 v[32:35], v32
	ds_read_b128 v[36:39], v0 offset:4096
	ds_read_b128 v[40:43], v0 offset:5120
	s_addk_i32 s12, 0xe000
	s_cmp_gt_i32 s11, 0
	s_cselect_b32 s12, s12, 0x4000
	v_add_u32_e32 v0, s12, v23
	s_mov_b64 s[12:13], 0x1661180
	v_lshl_add_u64 v[44:45], v[44:45], 0, s[12:13]
	s_mov_b64 s[12:13], 0x47e1180
	v_add_u32_e32 v50, 0x1000, v0
	s_mov_b64 s[98:99], 0x47e1300
	v_lshl_add_u64 v[46:47], v[48:49], 0, s[98:99]
	v_readfirstlane_b32 s12, v0
	s_mov_b32 m0, s12
	v_readfirstlane_b32 s12, v50
	global_load_lds_dwordx4 v[46:47], off
	s_mov_b32 m0, s12
	s_nop 0
	global_load_lds_dwordx4 v[44:45], off
	s_nop 0
	s_add_i32 s12, s11, 1
	s_waitcnt lgkmcnt(0)
	v_mfma_f32_16x16x32_bf16 v[14:17], v[36:39], v[28:31], v[14:17]
	s_cmp_lg_u32 s11, 2
	s_cselect_b32 s11, s12, 0
	s_add_u32 s4, s4, 0x140
	v_mfma_f32_16x16x32_bf16 v[10:13], v[40:43], v[28:31], v[10:13]
	s_addc_u32 s5, s5, 0
	s_cmpk_eq_i32 s4, 0x780
	v_mfma_f32_16x16x32_bf16 v[2:5], v[36:39], v[32:35], v[2:5]
	v_mfma_f32_16x16x32_bf16 v[6:9], v[40:43], v[32:35], v[6:9]
	s_cbranch_scc0 .LBB0_467
; template <int MI, int NI>
; DI void gemm256(f32x4 (&acc)[MI][NI], const u16* __restrict__ A, int lda, const u16* __restrict__ Bt, int ldb, int K, int m0, int n0, char* smem) {
;     ...
;   for (int kt = 0; kt < nk; ++kt) {
;     if (kt + 1 < nk) asm volatile("s_waitcnt vmcnt(%0) lgkmcnt(0)" :: "n"(LPS) : "memory");
;     else asm volatile("s_waitcnt vmcnt(0) lgkmcnt(0)" ::: "memory");
;     __builtin_amdgcn_s_barrier();
;     __builtin_amdgcn_s_setprio(1);
;     const char* sb = smem + st * STAGE + foff;
;     bf16x8 af[MI], bfr[NI];
; #pragma unroll
;     for (int mi = 0; mi < MI; ++mi) af[mi] = *(const bf16x8*)(sb + (wr * MI + mi) * 1024);
; #pragma unroll
;     for (int ni = 0; ni < NI; ++ni) bfr[ni] = *(const bf16x8*)(sb + ABYTES + (wc * NI + ni) * 1024);
;     __builtin_amdgcn_sched_barrier(0x0);
;     if (kt + 2 < nk) { const int s2 = st >= 1 ? st - 1 : 2; G256_ISSUE(s2, (kt + 2) * 32); }
;     __builtin_amdgcn_s_setprio(0);
; #pragma unroll
;     for (int mi = 0; mi < MI; ++mi)
; #pragma unroll
;       for (int ni = 0; ni < NI; ++ni)
;         acc[mi][ni] = __builtin_amdgcn_mfma_f32_16x16x32_bf16(bfr[ni], af[mi], acc[mi][ni], 0, 0, 0);
;     st = st == 2 ? 0 : st + 1;
;   }
;   asm volatile("s_waitcnt lgkmcnt(0)" ::: "memory");
;   __builtin_amdgcn_s_barrier();
; template <int MI, int NI>
; DI void resid_tile(const u16* A, int K, const u16* Bt, const float* gate, const float* xl_in, const float* xc_in, float* xl_out, float* xc_out,
;                    int m0, int n0, char* smem) {
;     ...
;   EPI_BEGIN
; #pragma unroll
;   for (int mi = 0; mi < MI; ++mi) {
;     const int m = m0 + wr * 16 * MI + mi * 16 + lr;
;     const int b9 = m < NTL ? m >> 12 : 8;
;     const float* xi = xrow(xl_in, xc_in, m);
;     float* xo = m < NTL ? xl_out + (size_t)m * D : xc_out + (size_t)(m - NTL) * D;
; #pragma unroll
;     for (int ni = 0; ni < NI; ++ni) {
;       const int n = n0 + wc * 16 * NI + ni * 16 + lq * 4;
;       const float4 g = *(const float4*)(gate + (size_t)b9 * 6144 + n);
;       const float4 xv = *(const float4*)(xi + n);
;       float4 ov;
;       ov.x = xv.x + g.x * acc[mi][ni][0]; ov.y = xv.y + g.y * acc[mi][ni][1]; ov.z = xv.z + g.z * acc[mi][ni][2]; ov.w = xv.w + g.w * acc[mi][ni][3];
;       *(float4*)(xo + n) = ov;
;     }
;     __builtin_amdgcn_sched_barrier(0);
;   }
;   EPI_END
; }
	s_waitcnt vmcnt(2) lgkmcnt(0)
	s_barrier
	s_nop 0
	v_add_u32_e32 v0, v24, v27
	v_add_u32_e32 v38, v24, v25
	v_add_u32_e32 v23, v24, v26
	ds_read_b128 v[18:21], v0
	ds_read_b128 v[26:29], v23
	ds_read_b128 v[30:33], v38 offset:4096
	ds_read_b128 v[34:37], v38 offset:5120
	v_bfe_u32 v39, v22, 6, 1
	s_nop 0
	s_waitcnt vmcnt(0) lgkmcnt(0)
	s_waitcnt lgkmcnt(1)
	v_mfma_f32_16x16x32_bf16 v[14:17], v[30:33], v[18:21], v[14:17]
	v_ashrrev_i32_e32 v40, 7, v22
	v_and_b32_e32 v41, 15, v22
	v_bfe_u32 v42, v22, 4, 2
	s_waitcnt lgkmcnt(0)
	v_mfma_f32_16x16x32_bf16 v[10:13], v[34:37], v[18:21], v[10:13]
	s_barrier
	v_mfma_f32_16x16x32_bf16 v[2:5], v[30:33], v[26:29], v[2:5]
	v_mfma_f32_16x16x32_bf16 v[18:21], v[34:37], v[26:29], v[6:9]
	s_nop 0
	s_nop 1
	ds_read_b128 v[6:9], v0 offset:8192
	ds_read_b128 v[22:25], v23 offset:8192
	ds_read_b128 v[26:29], v38 offset:12288
	ds_read_b128 v[30:33], v38 offset:13312
	s_nop 0
	s_waitcnt lgkmcnt(0)
	s_barrier
	v_readlane_b32 s4, v253, 55
	v_lshlrev_b32_e32 v0, 5, v40
	s_waitcnt lgkmcnt(1)
	v_mfma_f32_16x16x32_bf16 v[14:17], v[26:29], v[6:9], v[14:17]
	v_mov_b32_e32 v36, s4
	v_readlane_b32 s4, v253, 53
	s_waitcnt lgkmcnt(0)
	v_mfma_f32_16x16x32_bf16 v[10:13], v[30:33], v[6:9], v[10:13]
	v_mov_b32_e32 v37, s4
	v_readlane_b32 s4, v253, 56
	v_mfma_f32_16x16x32_bf16 v[6:9], v[26:29], v[22:25], v[2:5]
	v_add3_u32 v26, v41, s10, v0
	v_lshlrev_b32_e32 v0, 5, v39
	v_cmp_gt_i32_e32 vcc, s58, v26
	v_mfma_f32_16x16x32_bf16 v[2:5], v[30:33], v[22:25], v[18:21]
	v_ashrrev_i32_e32 v27, 31, v26
	v_mov_b32_e32 v38, s4
	v_readlane_b32 s4, v253, 54
	v_lshlrev_b32_e32 v18, 2, v42
	v_add3_u32 v18, v18, s9, v0
	v_min_i32_e32 v0, 0x8000, v26
	v_ashrrev_i32_e32 v28, 12, v0
	v_add_u32_e32 v0, 0xffff8000, v26
	v_cndmask_b32_e32 v21, 0, v27, vcc
	v_cndmask_b32_e32 v20, v0, v26, vcc
	v_mov_b32_e32 v39, s4
	v_cndmask_b32_e32 v23, v36, v37, vcc
	v_cndmask_b32_e32 v22, v38, v39, vcc
	v_lshlrev_b64 v[20:21], 12, v[20:21]
	v_lshl_add_u64 v[20:21], v[22:23], 0, v[20:21]
	v_lshlrev_b64 v[22:23], 12, v[26:27]
	v_lshlrev_b64 v[24:25], 12, v[0:1]
	v_lshl_add_u64 v[22:23], s[48:49], 0, v[22:23]
	v_lshl_add_u64 v[24:25], s[94:95], 0, v[24:25]
	v_readlane_b32 s4, v253, 51
	v_ashrrev_i32_e32 v19, 31, v18
	v_cndmask_b32_e32 v23, v25, v23, vcc
	v_cndmask_b32_e32 v22, v24, v22, vcc
	v_mul_hi_i32_i24_e32 v25, 0x6000, v28
	v_mul_i32_i24_e32 v24, 0x6000, v28
	v_readlane_b32 s5, v253, 52
	v_lshlrev_b64 v[28:29], 2, v[18:19]
	v_lshl_add_u64 v[32:33], v[20:21], 0, v[28:29]
	v_lshl_add_u64 v[24:25], s[4:5], 0, v[24:25]
	v_lshl_add_u64 v[30:31], v[24:25], 0, v[28:29]
	v_lshl_add_u64 v[34:35], v[22:23], 0, v[28:29]
	flat_load_dwordx4 v[18:21], v[30:31]
	flat_load_dwordx4 v[22:25], v[32:33]
	s_waitcnt vmcnt(0) lgkmcnt(0)
	v_pk_fma_f32 v[14:15], v[14:15], v[18:19], v[22:23]
	v_pk_fma_f32 v[16:17], v[16:17], v[20:21], v[24:25]
	flat_store_dwordx4 v[34:35], v[14:17]
	flat_load_dwordx4 v[14:17], v[30:31] offset:64
	s_nop 0
	flat_load_dwordx4 v[18:21], v[32:33] offset:64
	s_waitcnt vmcnt(0) lgkmcnt(0)
	v_pk_fma_f32 v[10:11], v[10:11], v[14:15], v[18:19]
	v_pk_fma_f32 v[12:13], v[12:13], v[16:17], v[20:21]
	flat_store_dwordx4 v[34:35], v[10:13] offset:64
	s_nop 1
	v_add_u32_e32 v10, 16, v26
	v_min_i32_e32 v0, 0x8000, v10
	v_cmp_gt_i32_e32 vcc, s58, v10
	v_ashrrev_i32_e32 v16, 12, v0
	v_add_u32_e32 v0, 0xffff8010, v26
	v_ashrrev_i32_e32 v11, 31, v10
	v_cndmask_b32_e32 v13, 0, v11, vcc
	v_cndmask_b32_e32 v12, v0, v10, vcc
	v_cndmask_b32_e32 v15, v36, v37, vcc
	v_cndmask_b32_e32 v14, v38, v39, vcc
	v_lshlrev_b64 v[12:13], 12, v[12:13]
	v_lshl_add_u64 v[12:13], v[14:15], 0, v[12:13]
	v_lshlrev_b64 v[10:11], 12, v[10:11]
	v_lshlrev_b64 v[14:15], 12, v[0:1]
	v_lshl_add_u64 v[10:11], s[48:49], 0, v[10:11]
	v_lshl_add_u64 v[14:15], s[94:95], 0, v[14:15]
	v_cndmask_b32_e32 v11, v15, v11, vcc
	v_cndmask_b32_e32 v10, v14, v10, vcc
	v_mul_hi_i32_i24_e32 v15, 0x6000, v16
	v_mul_i32_i24_e32 v14, 0x6000, v16
	v_lshl_add_u64 v[14:15], s[4:5], 0, v[14:15]
	v_lshl_add_u64 v[18:19], v[14:15], 0, v[28:29]
	v_lshl_add_u64 v[20:21], v[12:13], 0, v[28:29]
	v_lshl_add_u64 v[22:23], v[10:11], 0, v[28:29]
	flat_load_dwordx4 v[10:13], v[18:19]
	flat_load_dwordx4 v[14:17], v[20:21]
	s_waitcnt vmcnt(0) lgkmcnt(0)
	v_pk_fma_f32 v[6:7], v[6:7], v[10:11], v[14:15]
	v_pk_fma_f32 v[8:9], v[8:9], v[12:13], v[16:17]
	flat_store_dwordx4 v[22:23], v[6:9]
	flat_load_dwordx4 v[6:9], v[18:19] offset:64
	s_nop 0
	flat_load_dwordx4 v[10:13], v[20:21] offset:64
	s_waitcnt vmcnt(0) lgkmcnt(0)
	v_pk_fma_f32 v[2:3], v[2:3], v[6:7], v[10:11]
	v_pk_fma_f32 v[4:5], v[4:5], v[8:9], v[12:13]
	flat_store_dwordx4 v[22:23], v[2:5] offset:64
	s_add_i32 s6, s6, s79
	s_add_i32 s7, s7, s40
	s_add_i32 s8, s8, s41
	s_cmpk_gt_i32 s6, 0x1ff
	s_cbranch_scc0 .LBB0_466

; DI unsigned pack2(float a, float b) { float2_t v = {a, b}; bf16x2_t r = __builtin_convertvector(v, bf16x2_t); return __builtin_bit_cast(unsigned, r); }
; DI float sigmoidf_(float x) { return 1.f / (1.f + __expf(-x)); }
; DI void phase_merge(const Params& p, int l, int Mout, char* smem) {
;     ...
; #pragma unroll
;         for (int mi = 0; mi < 4; ++mi)
; #pragma unroll
;           for (int ni = 0; ni < 4; ++ni) {
;             gpk[mi][ni][0] = pack2(sigmoidf_(ag[mi][ni][0]), sigmoidf_(ag[mi][ni][1]));
;             gpk[mi][ni][1] = pack2(sigmoidf_(ag[mi][ni][2]), sigmoidf_(ag[mi][ni][3]));
;           }
.LBB0_478:
	v_mul_f32_e32 v126, 0xbfb8aa3b, v126
	v_mul_f32_e32 v127, 0xbfb8aa3b, v127
	v_exp_f32_e32 v126, v126
	v_exp_f32_e32 v127, v127
	v_mul_f32_e32 v122, 0xbfb8aa3b, v122
	v_mul_f32_e32 v123, 0xbfb8aa3b, v123
	v_exp_f32_e32 v122, v122
	v_pk_add_f32 v[126:127], v[126:127], 1.0 op_sel_hi:[1,0]
	v_exp_f32_e32 v123, v123
	s_nop 0
	v_pk_add_f32 v[122:123], v[122:123], 1.0 op_sel_hi:[1,0]
	v_mul_f32_e32 v118, 0xbfb8aa3b, v118
	v_mul_f32_e32 v119, 0xbfb8aa3b, v119
	v_rcp_f32_e32 v127, v127
	v_exp_f32_e32 v118, v118
	v_exp_f32_e32 v119, v119
	v_mul_f32_e32 v114, 0xbfb8aa3b, v114
	v_rcp_f32_e32 v126, v126
	s_nop 0
	v_cvt_pk_bf16_f32 v126, v126, v127
	v_mul_f32_e32 v127, 0xbfb8aa3b, v128
	v_exp_f32_e32 v128, v127
	v_mul_f32_e32 v127, 0xbfb8aa3b, v129
	v_exp_f32_e32 v129, v127
	v_pk_add_f32 v[118:119], v[118:119], 1.0 op_sel_hi:[1,0]
	v_mul_f32_e32 v115, 0xbfb8aa3b, v115
	v_exp_f32_e32 v114, v114
	v_pk_add_f32 v[128:129], v[128:129], 1.0 op_sel_hi:[1,0]
	v_exp_f32_e32 v115, v115
	s_nop 0
	v_pk_add_f32 v[114:115], v[114:115], 1.0 op_sel_hi:[1,0]
	v_mul_f32_e32 v110, 0xbfb8aa3b, v110
	v_mul_f32_e32 v111, 0xbfb8aa3b, v111
	v_rcp_f32_e32 v127, v129
	v_exp_f32_e32 v110, v110
	v_exp_f32_e32 v111, v111
	v_mul_f32_e32 v106, 0xbfb8aa3b, v106
	v_rcp_f32_e32 v128, v128
	s_nop 0
	v_cvt_pk_bf16_f32 v127, v128, v127
	v_pk_add_f32 v[110:111], v[110:111], 1.0 op_sel_hi:[1,0]
	v_mul_f32_e32 v107, 0xbfb8aa3b, v107
	v_exp_f32_e32 v106, v106
	v_rcp_f32_e32 v123, v123
	v_exp_f32_e32 v107, v107
	v_mul_f32_e32 v102, 0xbfb8aa3b, v102
	v_mul_f32_e32 v103, 0xbfb8aa3b, v103
	v_rcp_f32_e32 v122, v122
	s_nop 0
	v_cvt_pk_bf16_f32 v122, v122, v123
	v_mul_f32_e32 v123, 0xbfb8aa3b, v124
	v_exp_f32_e32 v124, v123
	v_mul_f32_e32 v123, 0xbfb8aa3b, v125
	v_exp_f32_e32 v125, v123
	v_pk_add_f32 v[106:107], v[106:107], 1.0 op_sel_hi:[1,0]
	v_exp_f32_e32 v102, v102
	v_exp_f32_e32 v103, v103
	v_pk_add_f32 v[124:125], v[124:125], 1.0 op_sel_hi:[1,0]
	v_mul_f32_e32 v98, 0xbfb8aa3b, v98
	v_pk_add_f32 v[102:103], v[102:103], 1.0 op_sel_hi:[1,0]
	v_mul_f32_e32 v99, 0xbfb8aa3b, v99
	v_exp_f32_e32 v98, v98
	v_rcp_f32_e32 v123, v125
	v_exp_f32_e32 v99, v99
	v_mul_f32_e32 v94, 0xbfb8aa3b, v94
	v_mul_f32_e32 v95, 0xbfb8aa3b, v95
	v_rcp_f32_e32 v124, v124
	s_nop 0
	v_cvt_pk_bf16_f32 v123, v124, v123
	v_pk_add_f32 v[98:99], v[98:99], 1.0 op_sel_hi:[1,0]
	v_exp_f32_e32 v94, v94
	v_exp_f32_e32 v95, v95
	v_rcp_f32_e32 v119, v119
	v_pk_add_f32 v[94:95], v[94:95], 1.0 op_sel_hi:[1,0]
	v_mul_f32_e32 v90, 0xbfb8aa3b, v90
	v_mul_f32_e32 v91, 0xbfb8aa3b, v91
	v_rcp_f32_e32 v118, v118
	s_nop 0
	v_cvt_pk_bf16_f32 v118, v118, v119
	v_mul_f32_e32 v119, 0xbfb8aa3b, v120
	v_exp_f32_e32 v120, v119
	v_mul_f32_e32 v119, 0xbfb8aa3b, v121
	v_exp_f32_e32 v121, v119
	v_exp_f32_e32 v90, v90
	v_exp_f32_e32 v91, v91
	v_mul_f32_e32 v86, 0xbfb8aa3b, v86
	v_pk_add_f32 v[120:121], v[120:121], 1.0 op_sel_hi:[1,0]
	v_mul_f32_e32 v87, 0xbfb8aa3b, v87
	v_pk_add_f32 v[90:91], v[90:91], 1.0 op_sel_hi:[1,0]
	v_exp_f32_e32 v86, v86
	v_exp_f32_e32 v87, v87
	v_rcp_f32_e32 v119, v121
	v_pk_add_f32 v[86:87], v[86:87], 1.0 op_sel_hi:[1,0]
	v_mul_f32_e32 v82, 0xbfb8aa3b, v82
	v_mul_f32_e32 v83, 0xbfb8aa3b, v83
	v_rcp_f32_e32 v120, v120
	s_nop 0
	v_cvt_pk_bf16_f32 v119, v120, v119
	v_exp_f32_e32 v82, v82
	v_exp_f32_e32 v83, v83
	v_mul_f32_e32 v78, 0xbfb8aa3b, v78
	v_rcp_f32_e32 v115, v115
	v_pk_add_f32 v[82:83], v[82:83], 1.0 op_sel_hi:[1,0]
	v_mul_f32_e32 v79, 0xbfb8aa3b, v79
	v_exp_f32_e32 v78, v78
	v_rcp_f32_e32 v114, v114
	s_nop 0
	v_cvt_pk_bf16_f32 v114, v114, v115
	v_mul_f32_e32 v115, 0xbfb8aa3b, v116
	v_exp_f32_e32 v116, v115
	v_mul_f32_e32 v115, 0xbfb8aa3b, v117
	v_exp_f32_e32 v117, v115
	v_exp_f32_e32 v79, v79
	v_mul_f32_e32 v74, 0xbfb8aa3b, v74
	v_mul_f32_e32 v75, 0xbfb8aa3b, v75
	v_pk_add_f32 v[116:117], v[116:117], 1.0 op_sel_hi:[1,0]
	v_pk_add_f32 v[78:79], v[78:79], 1.0 op_sel_hi:[1,0]
	v_exp_f32_e32 v74, v74
	v_exp_f32_e32 v75, v75
	v_mul_f32_e32 v70, 0xbfb8aa3b, v70
	v_rcp_f32_e32 v115, v117
	v_pk_add_f32 v[74:75], v[74:75], 1.0 op_sel_hi:[1,0]
	v_mul_f32_e32 v71, 0xbfb8aa3b, v71
	v_exp_f32_e32 v70, v70
	v_rcp_f32_e32 v116, v116
	s_nop 0
	v_cvt_pk_bf16_f32 v115, v116, v115
	v_exp_f32_e32 v71, v71
	v_mul_f32_e32 v66, 0xbfb8aa3b, v66
	v_mul_f32_e32 v67, 0xbfb8aa3b, v67
	v_rcp_f32_e32 v111, v111
	v_pk_add_f32 v[70:71], v[70:71], 1.0 op_sel_hi:[1,0]
	v_exp_f32_e32 v66, v66
	v_exp_f32_e32 v67, v67
	v_rcp_f32_e32 v110, v110
	s_nop 0
	v_cvt_pk_bf16_f32 v110, v110, v111
	v_mul_f32_e32 v111, 0xbfb8aa3b, v112
	v_exp_f32_e32 v112, v111
	v_mul_f32_e32 v111, 0xbfb8aa3b, v113
	v_exp_f32_e32 v113, v111
	v_pk_add_f32 v[66:67], v[66:67], 1.0 op_sel_hi:[1,0]
	s_waitcnt vmcnt(0) lgkmcnt(0)
	s_barrier
; DI unsigned pack2(float a, float b) { float2_t v = {a, b}; bf16x2_t r = __builtin_convertvector(v, bf16x2_t); return __builtin_bit_cast(unsigned, r); }
; DI float sigmoidf_(float x) { return 1.f / (1.f + __expf(-x)); }
; template <int MI, int NI>
; DI void gemm256(f32x4 (&acc)[MI][NI], const u16* __restrict__ A, int lda, const u16* __restrict__ Bt, int ldb, int K, int m0, int n0, char* smem) {
;     ...
;   for (int kt = 0; kt < nk; ++kt) {
;     if (kt + 1 < nk) asm volatile("s_waitcnt vmcnt(%0) lgkmcnt(0)" :: "n"(LPS) : "memory");
;     else asm volatile("s_waitcnt vmcnt(0) lgkmcnt(0)" ::: "memory");
;     __builtin_amdgcn_s_barrier();
;     __builtin_amdgcn_s_setprio(1);
;     const char* sb = smem + st * STAGE + foff;
;     bf16x8 af[MI], bfr[NI];
; #pragma unroll
;     for (int mi = 0; mi < MI; ++mi) af[mi] = *(const bf16x8*)(sb + (wr * MI + mi) * 1024);
; #pragma unroll
;     for (int ni = 0; ni < NI; ++ni) bfr[ni] = *(const bf16x8*)(sb + ABYTES + (wc * NI + ni) * 1024);
;     __builtin_amdgcn_sched_barrier(0x0);
;     if (kt + 2 < nk) { const int s2 = st >= 1 ? st - 1 : 2; G256_ISSUE(s2, (kt + 2) * 32); }
;     __builtin_amdgcn_s_setprio(0);
; DI void phase_merge(const Params& p, int l, int Mout, char* smem) {
;     ...
; #pragma unroll
;         for (int mi = 0; mi < 4; ++mi)
; #pragma unroll
;           for (int ni = 0; ni < 4; ++ni) {
;             gpk[mi][ni][0] = pack2(sigmoidf_(ag[mi][ni][0]), sigmoidf_(ag[mi][ni][1]));
;             gpk[mi][ni][1] = pack2(sigmoidf_(ag[mi][ni][2]), sigmoidf_(ag[mi][ni][3]));
;           }
	v_pk_add_f32 v[112:113], v[112:113], 1.0 op_sel_hi:[1,0]
	s_nop 0
	s_nop 0
	v_rcp_f32_e32 v111, v113
	s_nop 0
	v_rcp_f32_e32 v112, v112
	s_nop 0
	v_cvt_pk_bf16_f32 v111, v112, v111
	s_nop 0
	v_rcp_f32_e32 v107, v107
	s_nop 0
	v_rcp_f32_e32 v106, v106
	s_nop 0
	v_cvt_pk_bf16_f32 v106, v106, v107
	v_mul_f32_e32 v107, 0xbfb8aa3b, v108
	v_exp_f32_e32 v108, v107
	v_mul_f32_e32 v107, 0xbfb8aa3b, v109
	v_exp_f32_e32 v109, v107
	s_nop 0
	v_pk_add_f32 v[108:109], v[108:109], 1.0 op_sel_hi:[1,0]
	s_nop 0
	s_nop 0
	v_rcp_f32_e32 v107, v109
	s_nop 0
	v_rcp_f32_e32 v108, v108
	s_nop 0
	v_cvt_pk_bf16_f32 v107, v108, v107
	s_nop 0
	v_rcp_f32_e32 v103, v103
	s_nop 0
	v_rcp_f32_e32 v102, v102
	s_nop 0
	v_cvt_pk_bf16_f32 v102, v102, v103
	v_mul_f32_e32 v103, 0xbfb8aa3b, v104
	v_exp_f32_e32 v104, v103
	v_mul_f32_e32 v103, 0xbfb8aa3b, v105
	v_exp_f32_e32 v105, v103
	s_nop 0
	v_pk_add_f32 v[104:105], v[104:105], 1.0 op_sel_hi:[1,0]
	s_nop 0
	s_nop 0
	v_rcp_f32_e32 v103, v105
	s_nop 0
	v_rcp_f32_e32 v104, v104
	s_nop 0
	v_cvt_pk_bf16_f32 v103, v104, v103
	s_nop 0
	v_rcp_f32_e32 v99, v99
	s_nop 0
	v_rcp_f32_e32 v98, v98
	s_nop 0
	v_cvt_pk_bf16_f32 v98, v98, v99
	v_mul_f32_e32 v99, 0xbfb8aa3b, v100
	v_exp_f32_e32 v100, v99
	v_mul_f32_e32 v99, 0xbfb8aa3b, v101
	v_exp_f32_e32 v101, v99
	s_nop 0
	v_pk_add_f32 v[100:101], v[100:101], 1.0 op_sel_hi:[1,0]
	s_nop 0
	s_nop 0
	v_rcp_f32_e32 v99, v101
	s_nop 0
	v_rcp_f32_e32 v100, v100
	s_nop 0
	v_cvt_pk_bf16_f32 v99, v100, v99
	s_nop 0
	v_rcp_f32_e32 v95, v95
	s_nop 0
	v_rcp_f32_e32 v94, v94
	s_nop 0
	v_cvt_pk_bf16_f32 v94, v94, v95
	v_mul_f32_e32 v95, 0xbfb8aa3b, v96
	v_exp_f32_e32 v96, v95
	v_mul_f32_e32 v95, 0xbfb8aa3b, v97
	v_exp_f32_e32 v97, v95
	s_nop 0
	v_pk_add_f32 v[96:97], v[96:97], 1.0 op_sel_hi:[1,0]
	s_nop 0
	s_nop 0
	v_rcp_f32_e32 v95, v97
	s_nop 0
	v_rcp_f32_e32 v96, v96
	s_nop 0
	v_cvt_pk_bf16_f32 v95, v96, v95
	s_nop 0
	v_rcp_f32_e32 v91, v91
	s_nop 0
	v_rcp_f32_e32 v90, v90
	s_nop 0
	v_cvt_pk_bf16_f32 v90, v90, v91
	v_mul_f32_e32 v91, 0xbfb8aa3b, v92
	v_exp_f32_e32 v92, v91
	v_mul_f32_e32 v91, 0xbfb8aa3b, v93
	v_exp_f32_e32 v93, v91
	s_nop 0
	v_pk_add_f32 v[92:93], v[92:93], 1.0 op_sel_hi:[1,0]
	s_nop 0
	s_nop 0
	v_rcp_f32_e32 v91, v93
	s_nop 0
	v_rcp_f32_e32 v92, v92
	s_nop 0
	v_cvt_pk_bf16_f32 v91, v92, v91
	s_nop 0
	v_rcp_f32_e32 v87, v87
	s_nop 0
	v_rcp_f32_e32 v86, v86
	s_nop 0
	v_cvt_pk_bf16_f32 v86, v86, v87
	v_mul_f32_e32 v87, 0xbfb8aa3b, v88
	v_exp_f32_e32 v88, v87
	v_mul_f32_e32 v87, 0xbfb8aa3b, v89
	v_exp_f32_e32 v89, v87
	s_nop 0
	v_pk_add_f32 v[88:89], v[88:89], 1.0 op_sel_hi:[1,0]
	s_nop 0
	s_nop 0
	v_rcp_f32_e32 v87, v89
	s_nop 0
	v_rcp_f32_e32 v88, v88
	s_nop 0
	v_cvt_pk_bf16_f32 v87, v88, v87
	s_nop 0
	v_rcp_f32_e32 v83, v83
	s_nop 0
	v_rcp_f32_e32 v82, v82
	s_nop 0
	v_cvt_pk_bf16_f32 v82, v82, v83
	v_mul_f32_e32 v83, 0xbfb8aa3b, v84
	v_exp_f32_e32 v84, v83
	v_mul_f32_e32 v83, 0xbfb8aa3b, v85
	v_exp_f32_e32 v85, v83
	s_nop 0
	v_pk_add_f32 v[84:85], v[84:85], 1.0 op_sel_hi:[1,0]
	s_nop 0
	s_nop 0
	v_rcp_f32_e32 v83, v85
	s_nop 0
	v_rcp_f32_e32 v84, v84
	s_nop 0
	v_cvt_pk_bf16_f32 v83, v84, v83
	s_nop 0
	v_rcp_f32_e32 v79, v79
	s_nop 0
	v_rcp_f32_e32 v78, v78
	s_nop 0
	v_cvt_pk_bf16_f32 v78, v78, v79
	v_mul_f32_e32 v79, 0xbfb8aa3b, v80
	v_exp_f32_e32 v80, v79
	v_mul_f32_e32 v79, 0xbfb8aa3b, v81
	v_exp_f32_e32 v81, v79
	s_nop 0
	v_pk_add_f32 v[80:81], v[80:81], 1.0 op_sel_hi:[1,0]
	s_nop 0
	s_nop 0
	v_rcp_f32_e32 v79, v81
	s_nop 0
	v_rcp_f32_e32 v80, v80
	s_nop 0
	v_cvt_pk_bf16_f32 v79, v80, v79
	s_nop 0
	v_rcp_f32_e32 v75, v75
	s_nop 0
	v_rcp_f32_e32 v74, v74
	s_nop 0
	v_cvt_pk_bf16_f32 v74, v74, v75
	v_mul_f32_e32 v75, 0xbfb8aa3b, v76
	v_exp_f32_e32 v76, v75
	v_mul_f32_e32 v75, 0xbfb8aa3b, v77
	v_exp_f32_e32 v77, v75
	s_nop 0
	v_pk_add_f32 v[76:77], v[76:77], 1.0 op_sel_hi:[1,0]
	s_nop 0
	s_nop 0
	v_rcp_f32_e32 v75, v77
	s_nop 0
	v_rcp_f32_e32 v76, v76
	s_nop 0
	v_cvt_pk_bf16_f32 v75, v76, v75
	s_nop 0
	v_rcp_f32_e32 v71, v71
	s_nop 0
	v_rcp_f32_e32 v70, v70
	s_nop 0
	v_cvt_pk_bf16_f32 v70, v70, v71
	v_mul_f32_e32 v71, 0xbfb8aa3b, v72
	v_exp_f32_e32 v72, v71
	v_mul_f32_e32 v71, 0xbfb8aa3b, v73
	v_exp_f32_e32 v73, v71
	s_nop 0
	v_pk_add_f32 v[72:73], v[72:73], 1.0 op_sel_hi:[1,0]
	s_nop 0
	s_nop 0
	v_rcp_f32_e32 v71, v73
	s_nop 0
	v_rcp_f32_e32 v72, v72
	s_nop 0
	v_cvt_pk_bf16_f32 v71, v72, v71
	s_nop 0
	v_rcp_f32_e32 v67, v67
	s_nop 0
	v_rcp_f32_e32 v66, v66
	s_nop 0
	v_cvt_pk_bf16_f32 v76, v66, v67
	v_mul_f32_e32 v66, 0xbfb8aa3b, v68
	v_mul_f32_e32 v67, 0xbfb8aa3b, v69
	v_exp_f32_e32 v66, v66
	v_exp_f32_e32 v67, v67
	s_nop 0
	v_pk_add_f32 v[66:67], v[66:67], 1.0 op_sel_hi:[1,0]
	s_nop 0
	s_nop 0
	v_rcp_f32_e32 v67, v67
	s_nop 0
	v_rcp_f32_e32 v66, v66
	s_nop 0
	v_cvt_pk_bf16_f32 v77, v66, v67
	s_nop 0
	v_lshl_or_b32 v72, s15, 14, v248
	v_add_u32_e32 v73, v72, v249
	v_add_u32_e32 v0, v72, v0
	s_waitcnt vmcnt(0)
	ds_read_b128 v[66:69], v73
	ds_read_b128 v[128:131], v73 offset:1024
	ds_read_b128 v[132:135], v73 offset:2048
	ds_read_b128 v[136:139], v73 offset:3072
	ds_read_b128 v[140:143], v0 offset:8192
	ds_read_b128 v[144:147], v0 offset:9216
	ds_read_b128 v[148:151], v0 offset:10240
	ds_read_b128 v[152:155], v0 offset:11264
	s_nop 0
	s_waitcnt lgkmcnt(3)
	v_mfma_f32_16x16x32_bf16 v[62:65], v[140:143], v[66:69], v[62:65]
	v_lshlrev_b32_e32 v72, 16, v126
	v_and_b32_e32 v73, 0xffff0000, v126
	s_waitcnt lgkmcnt(0)
	s_waitcnt lgkmcnt(2)
	v_mfma_f32_16x16x32_bf16 v[58:61], v[144:147], v[66:69], v[58:61]
	s_barrier
; DI float bflo(unsigned u) { return __uint_as_float(u << 16); }
; DI float bfhi(unsigned u) { return __uint_as_float(u & 0xffff0000u); }
; DI void phase_merge(const Params& p, int l, int Mout, char* smem) {
;     ...
; #pragma unroll
;       for (int mi = 0; mi < 4; ++mi)
; #pragma unroll
;         for (int ni = 0; ni < 4; ++ni) {
;           msum[mi][ni][0] += bflo(gpk[mi][ni][0]) * ab[mi][ni][0];
;           msum[mi][ni][1] += bfhi(gpk[mi][ni][0]) * ab[mi][ni][1];
;           msum[mi][ni][2] += bflo(gpk[mi][ni][1]) * ab[mi][ni][2];
;           msum[mi][ni][3] += bfhi(gpk[mi][ni][1]) * ab[mi][ni][3];
;         }
;       __builtin_amdgcn_sched_barrier(0);
;     }
	s_nop 2
	v_pk_fma_f32 v[220:221], v[62:63], v[72:73], v[220:221]
	v_lshlrev_b32_e32 v62, 16, v127
	v_and_b32_e32 v63, 0xffff0000, v127
	s_waitcnt lgkmcnt(1)
	v_mfma_f32_16x16x32_bf16 v[54:57], v[148:151], v[66:69], v[54:57]
	v_fma_f32 v222, v64, v62, v222
	v_fma_f32 v223, v65, v63, v223
	v_lshlrev_b32_e32 v62, 16, v122
	v_and_b32_e32 v63, 0xffff0000, v122
	v_pk_fma_f32 v[208:209], v[58:59], v[62:63], v[208:209]
	s_waitcnt lgkmcnt(0)
	v_mfma_f32_16x16x32_bf16 v[50:53], v[152:155], v[66:69], v[50:53]
	v_lshlrev_b32_e32 v58, 16, v123
	v_and_b32_e32 v59, 0xffff0000, v123
	v_pk_fma_f32 v[210:211], v[60:61], v[58:59], v[210:211]
	v_lshlrev_b32_e32 v58, 16, v118
	v_and_b32_e32 v59, 0xffff0000, v118
	v_mfma_f32_16x16x32_bf16 v[46:49], v[140:143], v[128:131], v[46:49]
	v_fma_f32 v196, v54, v58, v196
	v_fma_f32 v197, v55, v59, v197
	v_lshlrev_b32_e32 v54, 16, v119
	v_and_b32_e32 v55, 0xffff0000, v119
	v_pk_fma_f32 v[198:199], v[56:57], v[54:55], v[198:199]
	v_lshlrev_b32_e32 v54, 16, v114
	v_and_b32_e32 v55, 0xffff0000, v114
	v_mfma_f32_16x16x32_bf16 v[42:45], v[144:147], v[128:131], v[42:45]
	v_fma_f32 v186, v50, v54, v186
	v_fma_f32 v187, v51, v55, v187
	v_lshlrev_b32_e32 v50, 16, v115
	v_and_b32_e32 v51, 0xffff0000, v115
	v_pk_fma_f32 v[190:191], v[52:53], v[50:51], v[190:191]
	v_lshlrev_b32_e32 v50, 16, v110
	v_and_b32_e32 v51, 0xffff0000, v110
	v_mfma_f32_16x16x32_bf16 v[38:41], v[148:151], v[128:131], v[38:41]
	v_fma_f32 v224, v46, v50, v224
	v_fma_f32 v225, v47, v51, v225
	v_lshlrev_b32_e32 v46, 16, v111
	v_and_b32_e32 v47, 0xffff0000, v111
	v_pk_fma_f32 v[226:227], v[48:49], v[46:47], v[226:227]
	v_lshlrev_b32_e32 v46, 16, v106
	v_and_b32_e32 v47, 0xffff0000, v106
	v_mfma_f32_16x16x32_bf16 v[34:37], v[152:155], v[128:131], v[34:37]
	v_fma_f32 v216, v42, v46, v216
	v_fma_f32 v217, v43, v47, v217
	v_lshlrev_b32_e32 v42, 16, v107
	v_and_b32_e32 v43, 0xffff0000, v107
	v_pk_fma_f32 v[218:219], v[44:45], v[42:43], v[218:219]
	v_lshlrev_b32_e32 v42, 16, v102
	v_and_b32_e32 v43, 0xffff0000, v102
	v_mfma_f32_16x16x32_bf16 v[30:33], v[140:143], v[132:135], v[30:33]
	v_fma_f32 v212, v38, v42, v212
	v_fma_f32 v213, v39, v43, v213
	v_lshlrev_b32_e32 v38, 16, v103
	v_and_b32_e32 v39, 0xffff0000, v103
	v_pk_fma_f32 v[214:215], v[40:41], v[38:39], v[214:215]
	v_lshlrev_b32_e32 v38, 16, v98
	v_and_b32_e32 v39, 0xffff0000, v98
	v_mfma_f32_16x16x32_bf16 v[26:29], v[144:147], v[132:135], v[26:29]
	v_fma_f32 v202, v34, v38, v202
	v_fma_f32 v203, v35, v39, v203
	v_lshlrev_b32_e32 v34, 16, v99
	v_and_b32_e32 v35, 0xffff0000, v99
	v_pk_fma_f32 v[206:207], v[36:37], v[34:35], v[206:207]
	v_lshlrev_b32_e32 v34, 16, v94
	v_and_b32_e32 v35, 0xffff0000, v94
	v_mfma_f32_16x16x32_bf16 v[22:25], v[148:151], v[132:135], v[22:25]
	v_fma_f32 v184, v30, v34, v184
	v_fma_f32 v185, v31, v35, v185
	v_lshlrev_b32_e32 v30, 16, v95
	v_and_b32_e32 v31, 0xffff0000, v95
	v_pk_fma_f32 v[188:189], v[32:33], v[30:31], v[188:189]
	v_lshlrev_b32_e32 v30, 16, v90
	v_and_b32_e32 v31, 0xffff0000, v90
	v_mfma_f32_16x16x32_bf16 v[18:21], v[152:155], v[132:135], v[18:21]
	v_fma_f32 v176, v26, v30, v176
	v_fma_f32 v177, v27, v31, v177
	v_lshlrev_b32_e32 v26, 16, v91
	v_and_b32_e32 v27, 0xffff0000, v91
	v_pk_fma_f32 v[178:179], v[28:29], v[26:27], v[178:179]
	v_lshlrev_b32_e32 v26, 16, v86
	v_and_b32_e32 v27, 0xffff0000, v86
	v_mfma_f32_16x16x32_bf16 v[14:17], v[140:143], v[136:139], v[14:17]
	v_fma_f32 v168, v22, v26, v168
	v_fma_f32 v169, v23, v27, v169
	v_lshlrev_b32_e32 v22, 16, v87
	v_and_b32_e32 v23, 0xffff0000, v87
	v_pk_fma_f32 v[170:171], v[24:25], v[22:23], v[170:171]
	v_lshlrev_b32_e32 v22, 16, v82
	v_and_b32_e32 v23, 0xffff0000, v82
	v_mfma_f32_16x16x32_bf16 v[10:13], v[144:147], v[136:139], v[10:13]
	v_fma_f32 v164, v18, v22, v164
	v_fma_f32 v165, v19, v23, v165
	v_lshlrev_b32_e32 v18, 16, v83
	v_and_b32_e32 v19, 0xffff0000, v83
	v_pk_fma_f32 v[166:167], v[20:21], v[18:19], v[166:167]
	v_lshlrev_b32_e32 v18, 16, v78
	v_and_b32_e32 v19, 0xffff0000, v78
	v_mfma_f32_16x16x32_bf16 v[6:9], v[148:151], v[136:139], v[6:9]
	v_fma_f32 v200, v14, v18, v200
	v_fma_f32 v201, v15, v19, v201
	v_lshlrev_b32_e32 v14, 16, v79
	v_and_b32_e32 v15, 0xffff0000, v79
	v_pk_fma_f32 v[204:205], v[16:17], v[14:15], v[204:205]
	v_lshlrev_b32_e32 v14, 16, v74
	v_and_b32_e32 v15, 0xffff0000, v74
	v_mfma_f32_16x16x32_bf16 v[2:5], v[152:155], v[136:139], v[2:5]
	v_fma_f32 v192, v10, v14, v192
	v_fma_f32 v193, v11, v15, v193
	v_lshlrev_b32_e32 v10, 16, v75
	v_and_b32_e32 v11, 0xffff0000, v75
	v_pk_fma_f32 v[194:195], v[12:13], v[10:11], v[194:195]
	v_lshlrev_b32_e32 v10, 16, v70
	v_and_b32_e32 v11, 0xffff0000, v70
	v_pk_fma_f32 v[180:181], v[6:7], v[10:11], v[180:181]
	v_lshlrev_b32_e32 v6, 16, v71
	v_and_b32_e32 v7, 0xffff0000, v71
	v_pk_fma_f32 v[182:183], v[8:9], v[6:7], v[182:183]
	v_lshlrev_b32_e32 v6, 16, v76
	v_and_b32_e32 v7, 0xffff0000, v76
	v_pk_fma_f32 v[172:173], v[2:3], v[6:7], v[172:173]
	v_lshlrev_b32_e32 v2, 16, v77
	v_and_b32_e32 v3, 0xffff0000, v77
	v_pk_fma_f32 v[174:175], v[4:5], v[2:3], v[174:175]
	s_add_i32 s11, s11, 1
	s_add_u32 s4, s4, 0x200000
	s_addc_u32 s5, s5, 0
	s_cmp_eq_u32 s11, 3
	s_cbranch_scc1 .LBB0_473

; template <int MI, int NI>
; DI void gemm256(f32x4 (&acc)[MI][NI], const u16* __restrict__ A, int lda, const u16* __restrict__ Bt, int ldb, int K, int m0, int n0, char* smem) {
;     ...
;   for (int kt = 0; kt < nk; ++kt) {
;     if (kt + 1 < nk) asm volatile("s_waitcnt vmcnt(%0) lgkmcnt(0)" :: "n"(LPS) : "memory");
;     else asm volatile("s_waitcnt vmcnt(0) lgkmcnt(0)" ::: "memory");
;     __builtin_amdgcn_s_barrier();
;     __builtin_amdgcn_s_setprio(1);
;     const char* sb = smem + st * STAGE + foff;
;     bf16x8 af[MI], bfr[NI];
; #pragma unroll
;     for (int mi = 0; mi < MI; ++mi) af[mi] = *(const bf16x8*)(sb + (wr * MI + mi) * 1024);
; #pragma unroll
;     for (int ni = 0; ni < NI; ++ni) bfr[ni] = *(const bf16x8*)(sb + ABYTES + (wc * NI + ni) * 1024);
;     __builtin_amdgcn_sched_barrier(0x0);
;     if (kt + 2 < nk) { const int s2 = st >= 1 ? st - 1 : 2; G256_ISSUE(s2, (kt + 2) * 32); }
;     __builtin_amdgcn_s_setprio(0);
; #pragma unroll
;     for (int mi = 0; mi < MI; ++mi)
; #pragma unroll
;       for (int ni = 0; ni < NI; ++ni)
;         acc[mi][ni] = __builtin_amdgcn_mfma_f32_16x16x32_bf16(bfr[ni], af[mi], acc[mi][ni], 0, 0, 0);
;     st = st == 2 ? 0 : st + 1;
;   }
.LBB0_480:
	s_waitcnt vmcnt(4) lgkmcnt(0)
	s_barrier
	s_nop 0
	s_lshl_b32 s16, s15, 14
	v_or_b32_e32 v0, s16, v71
	v_add_u32_e32 v86, v0, v73
	v_add_u32_e32 v0, v0, v72
	ds_read_b128 v[74:77], v86
	ds_read_b128 v[78:81], v86 offset:1024
	ds_read_b128 v[82:85], v86 offset:2048
	ds_read_b128 v[86:89], v86 offset:3072
	ds_read_b128 v[90:93], v0 offset:8192
	ds_read_b128 v[94:97], v0 offset:9216
	ds_read_b128 v[98:101], v0 offset:10240
	ds_read_b128 v[102:105], v0 offset:11264
	s_add_i32 s18, s16, 0xffffc000
	s_cmp_gt_i32 s15, 0
	v_lshl_add_u64 v[106:107], v[68:69], 0, s[6:7]
	v_lshl_add_u64 v[106:107], v[106:107], 0, s[6:7]
	s_mov_b64 s[16:17], 0x8be1100
	v_lshl_add_u64 v[108:109], v[106:107], 0, s[16:17]
	s_cselect_b32 s16, s18, 0x8000
	v_add_u32_e32 v0, s16, v70
	v_add_u32_e32 v110, 0x400, v0
	v_readfirstlane_b32 s16, v0
	s_mov_b32 m0, s16
	s_mov_b64 s[16:17], 0x8be9100
	global_load_lds_dwordx4 v[108:109], off
	v_lshl_add_u64 v[108:109], v[106:107], 0, s[16:17]
	v_readfirstlane_b32 s16, v110
	s_mov_b32 m0, s16
	s_mov_b64 s[16:17], 0xd51100
	global_load_lds_dwordx4 v[108:109], off
	v_lshl_add_u64 v[108:109], v[66:67], 0, s[6:7]
	v_lshl_add_u64 v[108:109], v[108:109], 0, s[6:7]
	v_add_u32_e32 v112, 0x2000, v0
	v_lshl_add_u64 v[110:111], v[108:109], 0, s[16:17]
	v_readfirstlane_b32 s16, v112
	s_mov_b32 m0, s16
	s_mov_b64 s[16:17], 0xd59100
	v_add_u32_e32 v0, 0x2400, v0
	global_load_lds_dwordx4 v[110:111], off
	v_lshl_add_u64 v[110:111], v[108:109], 0, s[16:17]
	v_readfirstlane_b32 s16, v0
	s_mov_b32 m0, s16
	s_nop 0
	global_load_lds_dwordx4 v[110:111], off
	s_nop 0
	s_waitcnt lgkmcnt(0)
	v_mfma_f32_16x16x32_bf16 v[62:65], v[90:93], v[74:77], v[62:65]
	s_add_i32 s16, s15, 1
	s_waitcnt vmcnt(4) lgkmcnt(0)
	s_cmp_lg_u32 s15, 2
	v_mfma_f32_16x16x32_bf16 v[58:61], v[94:97], v[74:77], v[58:61]
	s_cselect_b32 s15, s16, 0
	s_barrier
	v_mfma_f32_16x16x32_bf16 v[54:57], v[98:101], v[74:77], v[54:57]
	v_mfma_f32_16x16x32_bf16 v[46:49], v[102:105], v[74:77], v[46:49]
	v_mfma_f32_16x16x32_bf16 v[42:45], v[90:93], v[78:81], v[42:45]
	v_mfma_f32_16x16x32_bf16 v[38:41], v[94:97], v[78:81], v[38:41]
	v_mfma_f32_16x16x32_bf16 v[34:37], v[98:101], v[78:81], v[34:37]
	v_mfma_f32_16x16x32_bf16 v[30:33], v[102:105], v[78:81], v[30:33]
	v_mfma_f32_16x16x32_bf16 v[26:29], v[90:93], v[82:85], v[26:29]
	v_mfma_f32_16x16x32_bf16 v[22:25], v[94:97], v[82:85], v[22:25]
	v_mfma_f32_16x16x32_bf16 v[18:21], v[98:101], v[82:85], v[18:21]
	v_mfma_f32_16x16x32_bf16 v[14:17], v[102:105], v[82:85], v[14:17]
	v_mfma_f32_16x16x32_bf16 v[10:13], v[90:93], v[86:89], v[10:13]
	v_mfma_f32_16x16x32_bf16 v[6:9], v[94:97], v[86:89], v[6:9]
	v_mfma_f32_16x16x32_bf16 v[2:5], v[98:101], v[86:89], v[2:5]
	v_mfma_f32_16x16x32_bf16 v[50:53], v[102:105], v[86:89], v[50:53]
	s_nop 0
	s_lshl_b32 s16, s15, 14
	v_or_b32_e32 v0, s16, v71
	v_add_u32_e32 v86, v0, v73
	v_add_u32_e32 v0, v0, v72
	ds_read_b128 v[74:77], v86
	ds_read_b128 v[78:81], v86 offset:1024
	ds_read_b128 v[82:85], v86 offset:2048
	ds_read_b128 v[86:89], v86 offset:3072
	ds_read_b128 v[90:93], v0 offset:8192
	ds_read_b128 v[94:97], v0 offset:9216
	ds_read_b128 v[98:101], v0 offset:10240
	ds_read_b128 v[102:105], v0 offset:11264
	s_add_i32 s18, s16, 0xffffc000
	s_cmp_gt_i32 s15, 0
	s_mov_b64 s[16:17], 0x8be1180
	v_lshl_add_u64 v[110:111], v[106:107], 0, s[16:17]
	s_cselect_b32 s16, s18, 0x8000
	v_add_u32_e32 v0, s16, v70
	s_nop 0
	v_readfirstlane_b32 s16, v0
	s_mov_b32 m0, s16
	s_mov_b64 s[16:17], 0x8be9180
	global_load_lds_dwordx4 v[110:111], off
	v_add_u32_e32 v110, 0x400, v0
	v_lshl_add_u64 v[106:107], v[106:107], 0, s[16:17]
	v_readfirstlane_b32 s16, v110
	s_mov_b32 m0, s16
	s_mov_b64 s[16:17], 0xd51180
	v_add_u32_e32 v110, 0x2000, v0
	global_load_lds_dwordx4 v[106:107], off
	v_lshl_add_u64 v[106:107], v[108:109], 0, s[16:17]
	v_readfirstlane_b32 s16, v110
	s_mov_b32 m0, s16
	s_mov_b64 s[16:17], 0xd59180
	v_add_u32_e32 v0, 0x2400, v0
	global_load_lds_dwordx4 v[106:107], off
	v_lshl_add_u64 v[106:107], v[108:109], 0, s[16:17]
	v_readfirstlane_b32 s16, v0
	s_mov_b32 m0, s16
	s_nop 0
	global_load_lds_dwordx4 v[106:107], off
	s_nop 0
	s_add_i32 s16, s15, 1
	s_waitcnt lgkmcnt(0)
	v_mfma_f32_16x16x32_bf16 v[62:65], v[90:93], v[74:77], v[62:65]
	s_cmp_lg_u32 s15, 2
	s_cselect_b32 s15, s16, 0
	s_add_u32 s6, s6, 0x80
	v_mfma_f32_16x16x32_bf16 v[58:61], v[94:97], v[74:77], v[58:61]
	s_addc_u32 s7, s7, 0
	s_cmpk_eq_i32 s6, 0x780
	v_mfma_f32_16x16x32_bf16 v[54:57], v[98:101], v[74:77], v[54:57]
	v_mfma_f32_16x16x32_bf16 v[46:49], v[102:105], v[74:77], v[46:49]
	v_mfma_f32_16x16x32_bf16 v[42:45], v[90:93], v[78:81], v[42:45]
	v_mfma_f32_16x16x32_bf16 v[38:41], v[94:97], v[78:81], v[38:41]
	v_mfma_f32_16x16x32_bf16 v[34:37], v[98:101], v[78:81], v[34:37]
	v_mfma_f32_16x16x32_bf16 v[30:33], v[102:105], v[78:81], v[30:33]
	v_mfma_f32_16x16x32_bf16 v[26:29], v[90:93], v[82:85], v[26:29]
	v_mfma_f32_16x16x32_bf16 v[22:25], v[94:97], v[82:85], v[22:25]
	v_mfma_f32_16x16x32_bf16 v[18:21], v[98:101], v[82:85], v[18:21]
	v_mfma_f32_16x16x32_bf16 v[14:17], v[102:105], v[82:85], v[14:17]
	v_mfma_f32_16x16x32_bf16 v[10:13], v[90:93], v[86:89], v[10:13]
	v_mfma_f32_16x16x32_bf16 v[6:9], v[94:97], v[86:89], v[6:9]
	v_mfma_f32_16x16x32_bf16 v[2:5], v[98:101], v[86:89], v[2:5]
	v_mfma_f32_16x16x32_bf16 v[50:53], v[102:105], v[86:89], v[50:53]
	s_cbranch_scc0 .LBB0_480
	s_waitcnt vmcnt(4) lgkmcnt(0)
	s_barrier
; template <int MI, int NI>
; DI void gemm256(f32x4 (&acc)[MI][NI], const u16* __restrict__ A, int lda, const u16* __restrict__ Bt, int ldb, int K, int m0, int n0, char* smem) {
;     ...
;   const int srow = lane >> 2, scol = ((lane & 3) ^ ((lane >> 5) << 1)) * 8;
;   const u16* Ag = A + (size_t)(m0 + wave * NAW * 16 + srow) * lda + scol;
;   const u16* Bg = Bt + (size_t)(n0 + wave * NBW * 16 + srow) * ldb + scol;
;   char* la = smem + (wave * NAW) * 1024 + lane * 16;
;   char* lb = smem + ABYTES + (wave * NBW) * 1024 + lane * 16;
;     ...
;   const int nk = K >> 5;
;   G256_ISSUE(0, 0);
;   if (nk > 1) G256_ISSUE(1, 32);
;   const int foff = lr * 64 + ((lq ^ ((lr >> 3) << 1)) * 16);
;   int st = 0;
;   for (int kt = 0; kt < nk; ++kt) {
;     if (kt + 1 < nk) asm volatile("s_waitcnt vmcnt(%0) lgkmcnt(0)" :: "n"(LPS) : "memory");
;     else asm volatile("s_waitcnt vmcnt(0) lgkmcnt(0)" ::: "memory");
;     __builtin_amdgcn_s_barrier();
;     __builtin_amdgcn_s_setprio(1);
;     const char* sb = smem + st * STAGE + foff;
;     bf16x8 af[MI], bfr[NI];
; #pragma unroll
;     for (int mi = 0; mi < MI; ++mi) af[mi] = *(const bf16x8*)(sb + (wr * MI + mi) * 1024);
; #pragma unroll
;     for (int ni = 0; ni < NI; ++ni) bfr[ni] = *(const bf16x8*)(sb + ABYTES + (wc * NI + ni) * 1024);
;     __builtin_amdgcn_sched_barrier(0x0);
;     if (kt + 2 < nk) { const int s2 = st >= 1 ? st - 1 : 2; G256_ISSUE(s2, (kt + 2) * 32); }
;     __builtin_amdgcn_s_setprio(0);
; #pragma unroll
;     for (int mi = 0; mi < MI; ++mi)
; #pragma unroll
;       for (int ni = 0; ni < NI; ++ni)
;         acc[mi][ni] = __builtin_amdgcn_mfma_f32_16x16x32_bf16(bfr[ni], af[mi], acc[mi][ni], 0, 0, 0);
; DI void phase_merge(const Params& p, int l, int Mout, char* smem) {
;     ...
;       {
;         const int Kb = br == 1 ? 512 : 256;
;         const u16* Ab = br == 0 ? opool : br == 1 ? omla : orw;
;         const u16* Wb = (const u16*)(wl + (br == 0 ? WO_BRP : br == 1 ? WO_BRM : WO_BRR));
;         gemm256<4, 4>(ab, Ab, Kb, Wb, Kb, Kb, m0, n0, smem);
	s_nop 0
	v_add_u32_e32 v0, v71, v73
	v_add_u32_e32 v98, v71, v72
	ds_read_b128 v[66:69], v0
	ds_read_b128 v[74:77], v0 offset:1024
	ds_read_b128 v[78:81], v0 offset:2048
	ds_read_b128 v[82:85], v0 offset:3072
	ds_read_b128 v[70:73], v98 offset:8192
	ds_read_b128 v[86:89], v98 offset:9216
	ds_read_b128 v[90:93], v98 offset:10240
	ds_read_b128 v[94:97], v98 offset:11264
	s_nop 0
	s_waitcnt lgkmcnt(3)
	v_mfma_f32_16x16x32_bf16 v[62:65], v[70:73], v[66:69], v[62:65]
	s_waitcnt vmcnt(0) lgkmcnt(0)
	s_barrier
	s_waitcnt lgkmcnt(2)
	v_mfma_f32_16x16x32_bf16 v[58:61], v[86:89], v[66:69], v[58:61]
	s_waitcnt lgkmcnt(1)
	v_mfma_f32_16x16x32_bf16 v[54:57], v[90:93], v[66:69], v[54:57]
	s_waitcnt lgkmcnt(0)
	v_mfma_f32_16x16x32_bf16 v[46:49], v[94:97], v[66:69], v[46:49]
	v_mfma_f32_16x16x32_bf16 v[42:45], v[70:73], v[74:77], v[42:45]
	v_mfma_f32_16x16x32_bf16 v[38:41], v[86:89], v[74:77], v[38:41]
	v_mfma_f32_16x16x32_bf16 v[34:37], v[90:93], v[74:77], v[34:37]
	v_mfma_f32_16x16x32_bf16 v[30:33], v[94:97], v[74:77], v[30:33]
	v_mfma_f32_16x16x32_bf16 v[26:29], v[70:73], v[78:81], v[26:29]
	v_mfma_f32_16x16x32_bf16 v[22:25], v[86:89], v[78:81], v[22:25]
	v_mfma_f32_16x16x32_bf16 v[18:21], v[90:93], v[78:81], v[18:21]
	v_mfma_f32_16x16x32_bf16 v[14:17], v[94:97], v[78:81], v[14:17]
	v_mfma_f32_16x16x32_bf16 v[10:13], v[70:73], v[82:85], v[10:13]
	v_mfma_f32_16x16x32_bf16 v[6:9], v[86:89], v[82:85], v[6:9]
	v_mfma_f32_16x16x32_bf16 v[2:5], v[90:93], v[82:85], v[2:5]
	v_mfma_f32_16x16x32_bf16 v[50:53], v[94:97], v[82:85], v[50:53]
	s_nop 0
	ds_read_b128 v[66:69], v0 offset:16384
	ds_read_b128 v[70:73], v0 offset:17408
	ds_read_b128 v[74:77], v0 offset:18432
	ds_read_b128 v[130:133], v0 offset:19456
	ds_read_b128 v[78:81], v98 offset:24576
	ds_read_b128 v[134:137], v98 offset:25600
	ds_read_b128 v[138:141], v98 offset:26624
	ds_read_b128 v[142:145], v98 offset:27648
	s_nop 0
	s_waitcnt lgkmcnt(3)
	v_mfma_f32_16x16x32_bf16 v[126:129], v[78:81], v[66:69], v[62:65]
	s_waitcnt lgkmcnt(0)
	s_barrier
	s_waitcnt lgkmcnt(2)
	v_mfma_f32_16x16x32_bf16 v[122:125], v[134:137], v[66:69], v[58:61]
	s_waitcnt lgkmcnt(1)
	v_mfma_f32_16x16x32_bf16 v[118:121], v[138:141], v[66:69], v[54:57]
	s_waitcnt lgkmcnt(0)
	v_mfma_f32_16x16x32_bf16 v[114:117], v[142:145], v[66:69], v[46:49]
	v_mfma_f32_16x16x32_bf16 v[110:113], v[78:81], v[70:73], v[42:45]
	v_mfma_f32_16x16x32_bf16 v[106:109], v[134:137], v[70:73], v[38:41]
	v_mfma_f32_16x16x32_bf16 v[102:105], v[138:141], v[70:73], v[34:37]
	v_mfma_f32_16x16x32_bf16 v[98:101], v[142:145], v[70:73], v[30:33]
	v_mfma_f32_16x16x32_bf16 v[94:97], v[78:81], v[74:77], v[26:29]
	v_mfma_f32_16x16x32_bf16 v[90:93], v[134:137], v[74:77], v[22:25]
	v_mfma_f32_16x16x32_bf16 v[86:89], v[138:141], v[74:77], v[18:21]
	v_mfma_f32_16x16x32_bf16 v[82:85], v[142:145], v[74:77], v[14:17]
	v_mfma_f32_16x16x32_bf16 v[78:81], v[78:81], v[130:133], v[10:13]
	v_mfma_f32_16x16x32_bf16 v[74:77], v[134:137], v[130:133], v[6:9]
	v_mfma_f32_16x16x32_bf16 v[70:73], v[138:141], v[130:133], v[2:5]
	v_mfma_f32_16x16x32_bf16 v[66:69], v[142:145], v[130:133], v[50:53]
	s_cmp_eq_u32 s11, 1
	s_movk_i32 s6, 0x200
	v_mov_b32_e32 v8, v163
	s_cselect_b32 s18, s6, 0x100
	s_mov_b32 s6, 0x1caa1000
	s_mov_b32 s7, 0xba0000
	s_cselect_b32 s6, s6, 0x18481000
	v_ashrrev_i32_e32 v9, 6, v8
	v_bfe_u32 v0, v8, 2, 4
	s_cselect_b32 s7, s7, 0xca0000
	s_cselect_b32 s15, 9, 8
	s_cmp_eq_u32 s11, 0
	v_and_b32_e32 v2, 3, v8
	v_lshrrev_b32_e32 v3, 4, v8
	v_lshl_or_b32 v6, v9, 5, v0
	s_cselect_b32 s6, 0x1b781000, s6
	v_bitop3_b32 v5, v3, v2, 2 bitop3:0x6c
	v_add_u32_e32 v2, s13, v6
	s_cselect_b32 s16, 0xb20000, s7
	s_add_u32 s6, s62, s6
	v_ashrrev_i32_e32 v3, 31, v2
	s_addc_u32 s7, s63, 0
	v_lshlrev_b64 v[2:3], s15, v[2:3]
	v_and_b32_e32 v4, 63, v8
	v_lshl_add_u64 v[2:3], v[2:3], 1, s[6:7]
	v_lshlrev_b32_e32 v0, 4, v5
	s_mov_b32 s17, s2
	v_lshl_add_u64 v[228:229], v[2:3], 0, v[0:1]
	v_add_u32_e32 v2, s12, v6
	v_lshlrev_b32_e32 v4, 4, v4
	s_add_u32 s16, s44, s16
	v_ashrrev_i32_e32 v3, 31, v2
	v_lshl_or_b32 v250, v9, 11, v4
	s_addc_u32 s17, s45, 0
	v_lshlrev_b64 v[2:3], s15, v[2:3]
	v_readfirstlane_b32 s6, v250
	v_or_b32_e32 v7, 0x400, v250
	v_lshl_add_u64 v[2:3], v[2:3], 1, s[16:17]
	v_add_u32_e32 v6, 0x2000, v250
	s_mov_b32 m0, s6
	s_lshl_b32 s64, s18, 5
	v_readfirstlane_b32 s6, v7
	global_load_lds_dwordx4 v[228:229], off
	v_lshl_add_u64 v[4:5], v[228:229], 0, s[64:65]
	s_mov_b32 m0, s6
	v_lshl_add_u64 v[230:231], v[2:3], 0, v[0:1]
	v_readfirstlane_b32 s6, v6
	v_add_u32_e32 v0, 0x2400, v250
	global_load_lds_dwordx4 v[4:5], off
	s_mov_b32 m0, s6
	v_readfirstlane_b32 s6, v0
	v_add_u32_e32 v0, 0x4000, v250
	global_load_lds_dwordx4 v[230:231], off
	v_lshl_add_u64 v[2:3], v[230:231], 0, s[64:65]
	s_mov_b32 m0, s6
	v_readfirstlane_b32 s6, v0
	v_add_u32_e32 v0, 0x4400, v250
	global_load_lds_dwordx4 v[2:3], off
	v_lshl_add_u64 v[6:7], v[228:229], 0, 64
	s_mov_b32 m0, s6
	v_readfirstlane_b32 s6, v0
	v_add_u32_e32 v0, 0x6000, v250
	global_load_lds_dwordx4 v[6:7], off
; template <int MI, int NI>
; DI void gemm256(f32x4 (&acc)[MI][NI], const u16* __restrict__ A, int lda, const u16* __restrict__ Bt, int ldb, int K, int m0, int n0, char* smem) {
;     ...
;   const int srow = lane >> 2, scol = ((lane & 3) ^ ((lane >> 5) << 1)) * 8;
;   const u16* Ag = A + (size_t)(m0 + wave * NAW * 16 + srow) * lda + scol;
;   const u16* Bg = Bt + (size_t)(n0 + wave * NBW * 16 + srow) * ldb + scol;
;   char* la = smem + (wave * NAW) * 1024 + lane * 16;
;   char* lb = smem + ABYTES + (wave * NBW) * 1024 + lane * 16;
;     ...
;   const int nk = K >> 5;
;   G256_ISSUE(0, 0);
;   if (nk > 1) G256_ISSUE(1, 32);
;   const int foff = lr * 64 + ((lq ^ ((lr >> 3) << 1)) * 16);
;   int st = 0;
;   for (int kt = 0; kt < nk; ++kt) {
;     if (kt + 1 < nk) asm volatile("s_waitcnt vmcnt(%0) lgkmcnt(0)" :: "n"(LPS) : "memory");
;     else asm volatile("s_waitcnt vmcnt(0) lgkmcnt(0)" ::: "memory");
;     __builtin_amdgcn_s_barrier();
;     __builtin_amdgcn_s_setprio(1);
;     const char* sb = smem + st * STAGE + foff;
;     bf16x8 af[MI], bfr[NI];
; #pragma unroll
;     for (int mi = 0; mi < MI; ++mi) af[mi] = *(const bf16x8*)(sb + (wr * MI + mi) * 1024);
; #pragma unroll
;     for (int ni = 0; ni < NI; ++ni) bfr[ni] = *(const bf16x8*)(sb + ABYTES + (wc * NI + ni) * 1024);
;     __builtin_amdgcn_sched_barrier(0x0);
;     if (kt + 2 < nk) { const int s2 = st >= 1 ? st - 1 : 2; G256_ISSUE(s2, (kt + 2) * 32); }
;     __builtin_amdgcn_s_setprio(0);
; #pragma unroll
;     for (int mi = 0; mi < MI; ++mi)
; #pragma unroll
;       for (int ni = 0; ni < NI; ++ni)
;         acc[mi][ni] = __builtin_amdgcn_mfma_f32_16x16x32_bf16(bfr[ni], af[mi], acc[mi][ni], 0, 0, 0);
;     st = st == 2 ? 0 : st + 1;
;   }
	v_lshl_add_u64 v[4:5], v[4:5], 0, 64
	s_mov_b32 m0, s6
	v_readfirstlane_b32 s6, v0
	v_add_u32_e32 v0, 0x6400, v250
	global_load_lds_dwordx4 v[4:5], off
	v_lshl_add_u64 v[4:5], v[230:231], 0, 64
	s_mov_b32 m0, s6
	v_readfirstlane_b32 s6, v0
	global_load_lds_dwordx4 v[4:5], off
	v_lshl_add_u64 v[2:3], v[2:3], 0, 64
	s_mov_b32 m0, s6
	v_lshlrev_b32_e32 v0, 6, v8
	global_load_lds_dwordx4 v[2:3], off
	v_lshlrev_b32_e32 v2, 2, v8
	v_and_b32_e32 v3, 48, v8
	v_bitop3_b32 v2, v2, v3, 32 bitop3:0x6c
	v_and_or_b32 v248, v0, s59, v2
	v_lshlrev_b32_e32 v2, 5, v8
	s_lshl_b32 s6, s18, 4
	v_lshlrev_b32_e32 v0, 12, v9
	v_and_b32_e32 v249, 0xfffff000, v2
	v_mov_b32_e32 v2, 0
	s_mov_b32 s16, 1
	s_mov_b32 s15, 0
	s_lshr_b32 s17, s18, 5
	v_and_b32_e32 v0, 0x1000, v0
	s_mov_b32 s64, 64
	s_lshl_b32 s6, s6, 1
	v_mov_b32_e32 v3, v2
	v_mov_b32_e32 v4, v2
	v_mov_b32_e32 v5, v2
	v_mov_b32_e32 v6, v2
	v_mov_b32_e32 v7, v2
	v_mov_b32_e32 v8, v2
	v_mov_b32_e32 v9, v2
	v_mov_b32_e32 v10, v2
	v_mov_b32_e32 v11, v2
	v_mov_b32_e32 v12, v2
	v_mov_b32_e32 v13, v2
	v_mov_b32_e32 v14, v2
	v_mov_b32_e32 v15, v2
	v_mov_b32_e32 v16, v2
	v_mov_b32_e32 v17, v2
	v_mov_b32_e32 v18, v2
	v_mov_b32_e32 v19, v2
	v_mov_b32_e32 v20, v2
	v_mov_b32_e32 v21, v2
	v_mov_b32_e32 v22, v2
	v_mov_b32_e32 v23, v2
	v_mov_b32_e32 v24, v2
	v_mov_b32_e32 v25, v2
	v_mov_b32_e32 v26, v2
	v_mov_b32_e32 v27, v2
	v_mov_b32_e32 v28, v2
	v_mov_b32_e32 v29, v2
	v_mov_b32_e32 v30, v2
	v_mov_b32_e32 v31, v2
	v_mov_b32_e32 v32, v2
	v_mov_b32_e32 v33, v2
	v_mov_b32_e32 v34, v2
	v_mov_b32_e32 v35, v2
	v_mov_b32_e32 v36, v2
	v_mov_b32_e32 v37, v2
	v_mov_b32_e32 v38, v2
	v_mov_b32_e32 v39, v2
	v_mov_b32_e32 v40, v2
	v_mov_b32_e32 v41, v2
	v_mov_b32_e32 v42, v2
	v_mov_b32_e32 v43, v2
	v_mov_b32_e32 v44, v2
	v_mov_b32_e32 v45, v2
	v_mov_b32_e32 v46, v2
	v_mov_b32_e32 v47, v2
	v_mov_b32_e32 v48, v2
	v_mov_b32_e32 v49, v2
	v_mov_b32_e32 v50, v2
	v_mov_b32_e32 v51, v2
	v_mov_b32_e32 v52, v2
	v_mov_b32_e32 v53, v2
	v_mov_b32_e32 v54, v2
	v_mov_b32_e32 v55, v2
	v_mov_b32_e32 v56, v2
	v_mov_b32_e32 v57, v2
	v_mov_b32_e32 v58, v2
	v_mov_b32_e32 v59, v2
	v_mov_b32_e32 v60, v2
	v_mov_b32_e32 v61, v2
	v_mov_b32_e32 v62, v2
	v_mov_b32_e32 v63, v2
	v_mov_b32_e32 v64, v2
	v_mov_b32_e32 v65, v2
	s_branch .LBB0_483
.LBB0_482:
	s_nop 0
	s_waitcnt lgkmcnt(0)
	v_mfma_f32_16x16x32_bf16 v[62:65], v[146:149], v[158:161], v[62:65]
	s_add_i32 s7, s15, 1
	s_cmp_lg_u32 s15, 2
	s_cselect_b32 s15, s7, 0
	v_mfma_f32_16x16x32_bf16 v[58:61], v[150:153], v[158:161], v[58:61]
	s_add_i32 s64, s64, 32
	s_cmp_eq_u32 s17, s16
	v_mfma_f32_16x16x32_bf16 v[54:57], v[138:141], v[158:161], v[54:57]
	v_mfma_f32_16x16x32_bf16 v[50:53], v[134:137], v[158:161], v[50:53]
	v_mfma_f32_16x16x32_bf16 v[46:49], v[146:149], v[154:157], v[46:49]
	v_mfma_f32_16x16x32_bf16 v[42:45], v[150:153], v[154:157], v[42:45]
	v_mfma_f32_16x16x32_bf16 v[38:41], v[138:141], v[154:157], v[38:41]
	v_mfma_f32_16x16x32_bf16 v[34:37], v[134:137], v[154:157], v[34:37]
	v_mfma_f32_16x16x32_bf16 v[30:33], v[146:149], v[142:145], v[30:33]
	v_mfma_f32_16x16x32_bf16 v[26:29], v[150:153], v[142:145], v[26:29]
	v_mfma_f32_16x16x32_bf16 v[22:25], v[138:141], v[142:145], v[22:25]
	v_mfma_f32_16x16x32_bf16 v[18:21], v[134:137], v[142:145], v[18:21]
	v_mfma_f32_16x16x32_bf16 v[14:17], v[146:149], v[130:133], v[14:17]
	v_mfma_f32_16x16x32_bf16 v[10:13], v[150:153], v[130:133], v[10:13]
	v_mfma_f32_16x16x32_bf16 v[6:9], v[138:141], v[130:133], v[6:9]
	v_mfma_f32_16x16x32_bf16 v[2:5], v[134:137], v[130:133], v[2:5]
	s_cbranch_scc1 .LBB0_478
.LBB0_483:
	s_waitcnt vmcnt(4) lgkmcnt(0)
	s_barrier
	s_nop 0
	s_lshl_b32 s7, s15, 14
	v_or_b32_e32 v134, s7, v248
	v_add_u32_e32 v130, v134, v249
	v_add_u32_e32 v134, v134, v0
	ds_read_b128 v[158:161], v130
	ds_read_b128 v[154:157], v130 offset:1024
	ds_read_b128 v[142:145], v130 offset:2048
	ds_read_b128 v[130:133], v130 offset:3072
	ds_read_b128 v[146:149], v134 offset:8192
	ds_read_b128 v[150:153], v134 offset:9216
	ds_read_b128 v[138:141], v134 offset:10240
	ds_read_b128 v[134:137], v134 offset:11264
	s_add_i32 s16, s16, 1
	s_cmp_ge_u32 s16, s17
	s_cbranch_scc1 .LBB0_482
	s_lshl_b64 s[18:19], s[64:65], 1
	s_addk_i32 s7, 0xc000
	s_cmp_gt_i32 s15, 0
	s_cselect_b32 s7, s7, 0x8000
	v_add_u32_e32 v240, s7, v250
	v_add_u32_e32 v241, 0x400, v240
	v_readfirstlane_b32 s7, v240
	v_lshl_add_u64 v[238:239], v[228:229], 0, s[18:19]
	s_mov_b32 m0, s7
	s_mov_b32 s7, s65
	v_readfirstlane_b32 s20, v241
	global_load_lds_dwordx4 v[238:239], off
	v_lshl_add_u64 v[238:239], v[238:239], 0, s[6:7]
	s_mov_b32 m0, s20
	v_add_u32_e32 v241, 0x2000, v240
	global_load_lds_dwordx4 v[238:239], off
	v_lshl_add_u64 v[238:239], v[230:231], 0, s[18:19]
	v_readfirstlane_b32 s18, v241
	s_mov_b32 m0, s18
	v_add_u32_e32 v240, 0x2400, v240
	global_load_lds_dwordx4 v[238:239], off
	v_lshl_add_u64 v[238:239], v[238:239], 0, s[6:7]
	v_readfirstlane_b32 s7, v240
	s_mov_b32 m0, s7
	s_nop 0
	global_load_lds_dwordx4 v[238:239], off
	s_branch .LBB0_482

; #define LAUNDER_IDS const int tid__ = launder_v((int)threadIdx.x); const int blk__ = launder_s((int)blockIdx.x); (void)tid__; (void)blk__;
; DI void attn_item(const Params& p, int item, char* smem) {
;   LAUNDER_IDS
;   const int tid = tid__, lane = tid & 63, wave = tid >> 6, r32 = lane & 31, hi = lane >> 5;
;   int bh, qpos0, key0, nkt, orow0;
;   if (item < 2048) { bh = item >> 5; const int qb = item & 31; qpos0 = qb * 128; key0 = 0; nkt = LK / 64; orow0 = (bh >> 3) * L + qpos0; }
;   else { const int it = item - 2048; bh = it >> 1; const int qb = it & 1; qpos0 = 4096 + qb * 128; key0 = 4096; nkt = LC / 64; orow0 = NTL + (bh >> 3) * LC + qb * 128; }
;   const int h = bh & 7;
;   const u16* Qp = (const u16*)(p.ws + OFF_R1) + ((size_t)bh * LK + qpos0 + wave * 32 + r32) * 96 + hi * 8;
;   const u16* Kp = (const u16*)(p.ws + OFF_R1 + SZ_Q) + ((size_t)bh * LK + key0) * 96;
;   const u16* Vp = (const u16*)(p.ws + OFF_R1 + 2 * SZ_Q) + (size_t)bh * 64 * LK + key0;
; DI void phase_attn(const Params& p, int l, char* smem) {
;   LAUNDER_IDS
;   __shared__ int qslot_sh;
;   const int nattn = (l == 0) ? 2048 + 128 : 2048;
;   unsigned* ctr = (unsigned*)(p.ws + OFF_BAR) + 16 + l * 16;
;   for (;;) {
;     __syncthreads();
;     if (tid__ == 0) qslot_sh = (int)__hip_atomic_fetch_add(ctr, 1u, __ATOMIC_RELAXED, __HIP_MEMORY_SCOPE_AGENT);
;     __syncthreads();
;     const int it = qslot_sh;
;     if (it >= nattn) break;
;     attn_item(p, it, smem);
.LBB0_517:
	s_setprio 0
	s_add_u32 s22, s62, 0x7ae7000
	s_addc_u32 s23, s63, 0
	s_add_u32 s24, s62, 0x7aea000
	s_addc_u32 s25, s63, 0
	s_add_u32 s26, s62, 0xade1000
	s_addc_u32 s27, s63, 0
	s_add_u32 s28, s62, 0xae25000
	s_addc_u32 s29, s63, 0
	v_mov_b32_e32 v0, v163
	s_mov_b32 s0, s2
	s_nop 0
	v_cmp_eq_u32_e64 s[0:1], 0, v0
	s_branch .LBB0_520

; template <int MI, int NI>
; DI void gemm256(f32x4 (&acc)[MI][NI], const u16* __restrict__ A, int lda, const u16* __restrict__ Bt, int ldb, int K, int m0, int n0, char* smem) {
;     ...
;   const int srow = lane >> 2, scol = ((lane & 3) ^ ((lane >> 5) << 1)) * 8;
;   const u16* Ag = A + (size_t)(m0 + wave * NAW * 16 + srow) * lda + scol;
;   const u16* Bg = Bt + (size_t)(n0 + wave * NBW * 16 + srow) * ldb + scol;
;   char* la = smem + (wave * NAW) * 1024 + lane * 16;
;   char* lb = smem + ABYTES + (wave * NBW) * 1024 + lane * 16;
;     ...
;   const int nk = K >> 5;
;   G256_ISSUE(0, 0);
;   if (nk > 1) G256_ISSUE(1, 32);
;   const int foff = lr * 64 + ((lq ^ ((lr >> 3) << 1)) * 16);
;   int st = 0;
;   for (int kt = 0; kt < nk; ++kt) {
;     if (kt + 1 < nk) asm volatile("s_waitcnt vmcnt(%0) lgkmcnt(0)" :: "n"(LPS) : "memory");
;     else asm volatile("s_waitcnt vmcnt(0) lgkmcnt(0)" ::: "memory");
;     __builtin_amdgcn_s_barrier();
;     __builtin_amdgcn_s_setprio(1);
;     const char* sb = smem + st * STAGE + foff;
;     bf16x8 af[MI], bfr[NI];
; #pragma unroll
;     for (int mi = 0; mi < MI; ++mi) af[mi] = *(const bf16x8*)(sb + (wr * MI + mi) * 1024);
; #pragma unroll
;     for (int ni = 0; ni < NI; ++ni) bfr[ni] = *(const bf16x8*)(sb + ABYTES + (wc * NI + ni) * 1024);
;     __builtin_amdgcn_sched_barrier(0x0);
;     if (kt + 2 < nk) { const int s2 = st >= 1 ? st - 1 : 2; G256_ISSUE(s2, (kt + 2) * 32); }
;     __builtin_amdgcn_s_setprio(0);
; #pragma unroll
;     for (int mi = 0; mi < MI; ++mi)
; #pragma unroll
;       for (int ni = 0; ni < NI; ++ni)
;         acc[mi][ni] = __builtin_amdgcn_mfma_f32_16x16x32_bf16(bfr[ni], af[mi], acc[mi][ni], 0, 0, 0);
.LBB0_551:
	s_andn2_b64 vcc, exec, s[0:1]
	s_mov_b64 s[0:1], -1
	s_cbranch_vccnz .LBB0_545
	s_waitcnt vmcnt(0)
	v_mov_b32_e32 v8, v163
	s_mov_b32 s4, s2
	s_lshl_b32 s0, s13, 8
	v_and_b32_e32 v0, 3, v8
	v_lshrrev_b32_e32 v2, 4, v8
	v_bitop3_b32 v0, v2, v0, 2 bitop3:0x6c
	v_and_b32_e32 v2, 0xffffffc0, v8
	v_readlane_b32 s4, v254, 27
	v_bfe_u32 v4, v8, 2, 4
	v_add_u32_e32 v2, s0, v2
	v_readlane_b32 s5, v254, 28
	v_or_b32_e32 v5, v2, v4
	s_lshl_b32 s1, s14, 7
	v_mov_b64_e32 v[2:3], s[4:5]
	s_movk_i32 s4, 0x740
	v_mad_i64_i32 v[2:3], s[4:5], v5, s4, v[2:3]
	v_ashrrev_i32_e32 v7, 6, v8
	v_readlane_b32 s4, v254, 29
	v_lshl_add_u32 v5, v7, 5, s1
	v_readlane_b32 s5, v254, 30
	v_and_b32_e32 v6, 63, v8
	v_or_b32_e32 v9, v5, v4
	v_mov_b64_e32 v[4:5], s[4:5]
	v_mad_i64_i32 v[4:5], s[4:5], v9, s27, v[4:5]
	v_lshlrev_b32_e32 v9, 12, v7
	v_lshlrev_b32_e32 v6, 4, v6
	v_or_b32_e32 v24, v9, v6
	v_lshlrev_b32_e32 v0, 4, v0
	v_readfirstlane_b32 s22, v24
	v_or_b32_e32 v25, 0x400, v24
	v_lshl_add_u64 v[2:3], v[2:3], 0, v[0:1]
	s_mov_b32 m0, s22
	s_mov_b64 s[4:5], 0x7400
	v_readfirstlane_b32 s21, v25
	s_waitcnt lgkmcnt(0)
	v_or_b32_e32 v26, 0x800, v24
	v_lshl_or_b32 v12, v7, 11, v6
	global_load_lds_dwordx4 v[2:3], off
	v_lshl_add_u64 v[6:7], v[2:3], 0, s[4:5]
	s_mov_b32 m0, s21
	s_mov_b64 s[4:5], 0xe800
	v_readfirstlane_b32 s23, v26
	v_or_b32_e32 v27, 0xc00, v24
	v_add_u32_e32 v23, 0x4000, v12
	global_load_lds_dwordx4 v[6:7], off
	v_lshl_add_u64 v[6:7], v[2:3], 0, s[4:5]
	s_mov_b32 m0, s23
	s_mov_b64 s[4:5], 0x15c00
	v_readfirstlane_b32 s24, v27
	global_load_lds_dwordx4 v[6:7], off
	v_lshl_add_u64 v[6:7], v[2:3], 0, s[4:5]
	s_mov_b32 m0, s24
	v_readfirstlane_b32 s25, v23
	v_add_u32_e32 v28, 0x4400, v12
	global_load_lds_dwordx4 v[6:7], off
	v_lshl_add_u64 v[4:5], v[4:5], 0, v[0:1]
	s_mov_b32 m0, s25
	s_mov_b64 s[4:5], 0x3000
	v_readfirstlane_b32 s26, v28
	v_add_u32_e32 v13, 0x6000, v24
	global_load_lds_dwordx4 v[4:5], off
	v_lshl_add_u64 v[6:7], v[4:5], 0, s[4:5]
	s_mov_b32 m0, s26
	v_readfirstlane_b32 s16, v13
	v_add_u32_e32 v14, 0x6400, v24
	global_load_lds_dwordx4 v[6:7], off
	v_lshl_add_u64 v[6:7], v[2:3], 0, 64
	s_mov_b32 m0, s16
	s_mov_b64 s[4:5], 0x7440
	v_readfirstlane_b32 s15, v14
	v_add_u32_e32 v15, 0x6800, v24
	global_load_lds_dwordx4 v[6:7], off
	v_lshl_add_u64 v[6:7], v[2:3], 0, s[4:5]
	s_mov_b32 m0, s15
	s_mov_b64 s[4:5], 0xe840
	v_readfirstlane_b32 s17, v15
	v_add_u32_e32 v17, 0x6c00, v24
	global_load_lds_dwordx4 v[6:7], off
	v_lshl_add_u64 v[6:7], v[2:3], 0, s[4:5]
	s_mov_b32 m0, s17
	s_mov_b64 s[4:5], 0x15c40
	v_readfirstlane_b32 s18, v17
	v_add_u32_e32 v16, 0xa000, v12
	global_load_lds_dwordx4 v[6:7], off
	v_lshl_add_u64 v[6:7], v[2:3], 0, s[4:5]
	s_mov_b32 m0, s18
	v_readfirstlane_b32 s19, v16
	v_add_u32_e32 v18, 0xa400, v12
	global_load_lds_dwordx4 v[6:7], off
	v_lshl_add_u64 v[6:7], v[4:5], 0, 64
	s_mov_b32 m0, s19
	s_mov_b64 s[4:5], 0x3040
	v_readfirstlane_b32 s20, v18
	global_load_lds_dwordx4 v[6:7], off
	v_lshl_add_u64 v[6:7], v[4:5], 0, s[4:5]
	s_mov_b32 m0, s20
	v_lshlrev_b32_e32 v0, 6, v8
	global_load_lds_dwordx4 v[6:7], off
	v_lshlrev_b32_e32 v6, 2, v8
	v_and_b32_e32 v7, 48, v8
	s_waitcnt vmcnt(6) lgkmcnt(0)
	v_bitop3_b32 v6, v6, v7, 32 bitop3:0x6c
	v_and_or_b32 v6, v0, s59, v6
	s_barrier
	s_nop 0
	v_and_or_b32 v0, v0, s46, v6
	ds_read_b128 v[30:33], v0
	ds_read_b128 v[34:37], v0 offset:1024
	ds_read_b128 v[38:41], v0 offset:2048
	ds_read_b128 v[42:45], v0 offset:3072
	ds_read_b128 v[46:49], v0 offset:4096
	ds_read_b128 v[50:53], v0 offset:5120
	ds_read_b128 v[54:57], v0 offset:6144
	ds_read_b128 v[58:61], v0 offset:7168
	v_and_or_b32 v6, v9, s97, v6
	ds_read_b128 v[62:65], v6 offset:16384
	ds_read_b128 v[66:69], v6 offset:17408
	ds_read_b128 v[70:73], v6 offset:18432
	ds_read_b128 v[74:77], v6 offset:19456
	v_add_u32_e32 v7, 0xc000, v24
	s_mov_b64 s[8:9], 0x80
	v_readfirstlane_b32 s6, v7
	v_lshl_add_u64 v[8:9], v[2:3], 0, s[8:9]
	s_mov_b32 m0, s6
	s_mov_b64 s[4:5], 0x7480
	global_load_lds_dwordx4 v[8:9], off
	v_add_u32_e32 v8, 0xc400, v24
	v_lshl_add_u64 v[10:11], v[2:3], 0, s[4:5]
	v_readfirstlane_b32 s4, v8
	v_add_u32_e32 v9, 0xc800, v24
	s_mov_b32 m0, s4
	s_mov_b64 s[28:29], 0xe880
	v_readfirstlane_b32 s5, v9
	global_load_lds_dwordx4 v[10:11], off
	v_lshl_add_u64 v[10:11], v[2:3], 0, s[28:29]
	s_mov_b32 m0, s5
	s_mov_b64 s[28:29], 0x15c80
	global_load_lds_dwordx4 v[10:11], off
	v_add_u32_e32 v10, 0xcc00, v24
	v_lshl_add_u64 v[20:21], v[2:3], 0, s[28:29]
	v_readfirstlane_b32 s7, v10
	s_mov_b32 m0, s7
	v_add_u32_e32 v11, 0x10000, v12
	global_load_lds_dwordx4 v[20:21], off
	v_lshl_add_u64 v[20:21], v[4:5], 0, s[8:9]
	v_readfirstlane_b32 s8, v11
	v_add_u32_e32 v12, 0x10400, v12
	s_mov_b32 m0, s8
	s_mov_b64 s[28:29], 0x3080
	v_readfirstlane_b32 s9, v12
	global_load_lds_dwordx4 v[20:21], off
	v_lshl_add_u64 v[20:21], v[4:5], 0, s[28:29]
	s_mov_b32 m0, s9
	s_nop 0
	global_load_lds_dwordx4 v[20:21], off
	s_nop 0
	s_waitcnt lgkmcnt(0)
	v_mfma_f32_16x16x32_bf16 v[78:81], v[62:65], v[30:33], 0
	s_waitcnt vmcnt(6) lgkmcnt(0)
	s_barrier
; template <int MI, int NI>
; DI void gemm256(f32x4 (&acc)[MI][NI], const u16* __restrict__ A, int lda, const u16* __restrict__ Bt, int ldb, int K, int m0, int n0, char* smem) {
;     ...
;     const char* sb = smem + st * STAGE + foff;
;     bf16x8 af[MI], bfr[NI];
; #pragma unroll
;     for (int mi = 0; mi < MI; ++mi) af[mi] = *(const bf16x8*)(sb + (wr * MI + mi) * 1024);
; #pragma unroll
;     for (int ni = 0; ni < NI; ++ni) bfr[ni] = *(const bf16x8*)(sb + ABYTES + (wc * NI + ni) * 1024);
;     __builtin_amdgcn_sched_barrier(0x0);
;     if (kt + 2 < nk) { const int s2 = st >= 1 ? st - 1 : 2; G256_ISSUE(s2, (kt + 2) * 32); }
;     __builtin_amdgcn_s_setprio(0);
; #pragma unroll
;     for (int mi = 0; mi < MI; ++mi)
; #pragma unroll
;       for (int ni = 0; ni < NI; ++ni)
;         acc[mi][ni] = __builtin_amdgcn_mfma_f32_16x16x32_bf16(bfr[ni], af[mi], acc[mi][ni], 0, 0, 0);
	v_mfma_f32_16x16x32_bf16 v[82:85], v[66:69], v[30:33], 0
	v_mfma_f32_16x16x32_bf16 v[86:89], v[70:73], v[30:33], 0
	v_mfma_f32_16x16x32_bf16 v[30:33], v[74:77], v[30:33], 0
	v_mfma_f32_16x16x32_bf16 v[90:93], v[62:65], v[34:37], 0
	v_mfma_f32_16x16x32_bf16 v[94:97], v[66:69], v[34:37], 0
	v_mfma_f32_16x16x32_bf16 v[98:101], v[70:73], v[34:37], 0
	v_mfma_f32_16x16x32_bf16 v[34:37], v[74:77], v[34:37], 0
	v_mfma_f32_16x16x32_bf16 v[102:105], v[62:65], v[38:41], 0
	v_mfma_f32_16x16x32_bf16 v[106:109], v[66:69], v[38:41], 0
	v_mfma_f32_16x16x32_bf16 v[110:113], v[70:73], v[38:41], 0
	v_mfma_f32_16x16x32_bf16 v[38:41], v[74:77], v[38:41], 0
	v_mfma_f32_16x16x32_bf16 v[114:117], v[62:65], v[42:45], 0
	v_mfma_f32_16x16x32_bf16 v[118:121], v[66:69], v[42:45], 0
	v_mfma_f32_16x16x32_bf16 v[122:125], v[70:73], v[42:45], 0
	v_mfma_f32_16x16x32_bf16 v[42:45], v[74:77], v[42:45], 0
	v_mfma_f32_16x16x32_bf16 v[126:129], v[62:65], v[46:49], 0
	v_mfma_f32_16x16x32_bf16 v[130:133], v[66:69], v[46:49], 0
	v_mfma_f32_16x16x32_bf16 v[134:137], v[70:73], v[46:49], 0
	v_mfma_f32_16x16x32_bf16 v[46:49], v[74:77], v[46:49], 0
	v_mfma_f32_16x16x32_bf16 v[138:141], v[62:65], v[50:53], 0
	v_mfma_f32_16x16x32_bf16 v[142:145], v[66:69], v[50:53], 0
	v_mfma_f32_16x16x32_bf16 v[146:149], v[70:73], v[50:53], 0
	v_mfma_f32_16x16x32_bf16 v[50:53], v[74:77], v[50:53], 0
	v_mfma_f32_16x16x32_bf16 v[150:153], v[62:65], v[54:57], 0
	v_mfma_f32_16x16x32_bf16 v[154:157], v[66:69], v[54:57], 0
	v_mfma_f32_16x16x32_bf16 v[164:167], v[70:73], v[54:57], 0
	v_mfma_f32_16x16x32_bf16 v[54:57], v[74:77], v[54:57], 0
	v_mfma_f32_16x16x32_bf16 v[62:65], v[62:65], v[58:61], 0
	v_mfma_f32_16x16x32_bf16 v[66:69], v[66:69], v[58:61], 0
	v_mfma_f32_16x16x32_bf16 v[70:73], v[70:73], v[58:61], 0
	v_mfma_f32_16x16x32_bf16 v[58:61], v[74:77], v[58:61], 0
	s_nop 0
	ds_read_b128 v[74:77], v0 offset:24576
	ds_read_b128 v[168:171], v0 offset:25600
	ds_read_b128 v[172:175], v0 offset:26624
	ds_read_b128 v[176:179], v0 offset:27648
	ds_read_b128 v[180:183], v0 offset:28672
	ds_read_b128 v[184:187], v0 offset:29696
	ds_read_b128 v[188:191], v0 offset:30720
	ds_read_b128 v[192:195], v0 offset:31744
	ds_read_b128 v[196:199], v6 offset:40960
	ds_read_b128 v[200:203], v6 offset:41984
	ds_read_b128 v[204:207], v6 offset:43008
	ds_read_b128 v[208:211], v6 offset:44032
	s_mov_b64 s[28:29], 0xc0
	s_mov_b32 m0, s22
	v_lshl_add_u64 v[20:21], v[2:3], 0, s[28:29]
	s_mov_b64 s[34:35], 0x74c0
	global_load_lds_dwordx4 v[20:21], off
	v_lshl_add_u64 v[20:21], v[2:3], 0, s[34:35]
	s_mov_b32 m0, s21
	s_mov_b64 s[34:35], 0xe8c0
	global_load_lds_dwordx4 v[20:21], off
	v_lshl_add_u64 v[20:21], v[2:3], 0, s[34:35]
	s_mov_b32 m0, s23
	s_mov_b64 s[34:35], 0x15cc0
	global_load_lds_dwordx4 v[20:21], off
	v_lshl_add_u64 v[20:21], v[2:3], 0, s[34:35]
	s_mov_b32 m0, s24
	s_nop 0
	global_load_lds_dwordx4 v[20:21], off
	v_lshl_add_u64 v[20:21], v[4:5], 0, s[28:29]
	s_mov_b32 m0, s25
	s_mov_b64 s[28:29], 0x30c0
	global_load_lds_dwordx4 v[20:21], off
	v_lshl_add_u64 v[20:21], v[4:5], 0, s[28:29]
	s_mov_b32 m0, s26
	s_nop 0
	global_load_lds_dwordx4 v[20:21], off
	s_nop 0
	s_waitcnt lgkmcnt(0)
	v_mfma_f32_16x16x32_bf16 v[78:81], v[196:199], v[74:77], v[78:81]
	s_waitcnt vmcnt(6) lgkmcnt(0)
	s_barrier
	v_mfma_f32_16x16x32_bf16 v[82:85], v[200:203], v[74:77], v[82:85]
	v_mfma_f32_16x16x32_bf16 v[86:89], v[204:207], v[74:77], v[86:89]
	v_mfma_f32_16x16x32_bf16 v[30:33], v[208:211], v[74:77], v[30:33]
	v_mfma_f32_16x16x32_bf16 v[74:77], v[196:199], v[168:171], v[90:93]
	v_mfma_f32_16x16x32_bf16 v[90:93], v[200:203], v[168:171], v[94:97]
	v_mfma_f32_16x16x32_bf16 v[94:97], v[204:207], v[168:171], v[98:101]
	v_mfma_f32_16x16x32_bf16 v[34:37], v[208:211], v[168:171], v[34:37]
	v_mfma_f32_16x16x32_bf16 v[98:101], v[196:199], v[172:175], v[102:105]
	v_mfma_f32_16x16x32_bf16 v[102:105], v[200:203], v[172:175], v[106:109]
	v_mfma_f32_16x16x32_bf16 v[106:109], v[204:207], v[172:175], v[110:113]
	v_mfma_f32_16x16x32_bf16 v[38:41], v[208:211], v[172:175], v[38:41]
	v_mfma_f32_16x16x32_bf16 v[110:113], v[196:199], v[176:179], v[114:117]
	v_mfma_f32_16x16x32_bf16 v[114:117], v[200:203], v[176:179], v[118:121]
	v_mfma_f32_16x16x32_bf16 v[118:121], v[204:207], v[176:179], v[122:125]
	v_mfma_f32_16x16x32_bf16 v[42:45], v[208:211], v[176:179], v[42:45]
	v_mfma_f32_16x16x32_bf16 v[122:125], v[196:199], v[180:183], v[126:129]
	v_mfma_f32_16x16x32_bf16 v[126:129], v[200:203], v[180:183], v[130:133]
	v_mfma_f32_16x16x32_bf16 v[130:133], v[204:207], v[180:183], v[134:137]
	v_mfma_f32_16x16x32_bf16 v[46:49], v[208:211], v[180:183], v[46:49]
	v_mfma_f32_16x16x32_bf16 v[134:137], v[196:199], v[184:187], v[138:141]
	v_mfma_f32_16x16x32_bf16 v[138:141], v[200:203], v[184:187], v[142:145]
	v_mfma_f32_16x16x32_bf16 v[142:145], v[204:207], v[184:187], v[146:149]
	v_mfma_f32_16x16x32_bf16 v[50:53], v[208:211], v[184:187], v[50:53]
	v_mfma_f32_16x16x32_bf16 v[146:149], v[196:199], v[188:191], v[150:153]
	v_mfma_f32_16x16x32_bf16 v[54:57], v[208:211], v[188:191], v[54:57]
	v_mfma_f32_16x16x32_bf16 v[62:65], v[196:199], v[192:195], v[62:65]
	v_mfma_f32_16x16x32_bf16 v[66:69], v[200:203], v[192:195], v[66:69]
	v_mfma_f32_16x16x32_bf16 v[70:73], v[204:207], v[192:195], v[70:73]
	v_mfma_f32_16x16x32_bf16 v[58:61], v[208:211], v[192:195], v[58:61]
	v_mfma_f32_16x16x32_bf16 v[150:153], v[200:203], v[188:191], v[154:157]
	v_mfma_f32_16x16x32_bf16 v[154:157], v[204:207], v[188:191], v[164:167]
	s_nop 0
	s_nop 0
	ds_read_b128 v[164:167], v0 offset:49152
	ds_read_b128 v[168:171], v0 offset:50176
	ds_read_b128 v[172:175], v0 offset:51200
	ds_read_b128 v[176:179], v0 offset:52224
	ds_read_b128 v[180:183], v0 offset:53248
	ds_read_b128 v[184:187], v0 offset:54272
	ds_read_b128 v[188:191], v0 offset:55296
	ds_read_b128 v[192:195], v0 offset:56320
	v_or_b32_e32 v19, 0x10000, v6
	v_or_b32_e32 v21, 0x10800, v6
	v_or_b32_e32 v20, 0x10400, v6
	ds_read_b128 v[196:199], v19
	ds_read_b128 v[200:203], v20
	v_or_b32_e32 v22, 0x10c00, v6
	ds_read_b128 v[204:207], v21
	ds_read_b128 v[208:211], v22
	s_mov_b64 s[28:29], 0x100
	s_mov_b32 m0, s16
	v_lshl_add_u64 v[212:213], v[2:3], 0, s[28:29]
	s_mov_b64 s[34:35], 0x7500
	global_load_lds_dwordx4 v[212:213], off
	v_lshl_add_u64 v[212:213], v[2:3], 0, s[34:35]
	s_mov_b32 m0, s15
	s_mov_b64 s[34:35], 0xe900
	global_load_lds_dwordx4 v[212:213], off
	v_lshl_add_u64 v[212:213], v[2:3], 0, s[34:35]
	s_mov_b32 m0, s17
	s_mov_b64 s[34:35], 0x15d00
	global_load_lds_dwordx4 v[212:213], off
	v_lshl_add_u64 v[212:213], v[2:3], 0, s[34:35]
	s_mov_b32 m0, s18
	s_mov_b64 s[50:51], 0x100
	global_load_lds_dwordx4 v[212:213], off
	v_lshl_add_u64 v[212:213], v[4:5], 0, s[28:29]
	s_mov_b32 m0, s19
	s_mov_b64 s[28:29], 0x3100
	global_load_lds_dwordx4 v[212:213], off
	v_lshl_add_u64 v[212:213], v[4:5], 0, s[28:29]
	s_mov_b32 m0, s20
	s_nop 0
	global_load_lds_dwordx4 v[212:213], off
	s_nop 0
	s_waitcnt lgkmcnt(0)
	v_mfma_f32_16x16x32_bf16 v[78:81], v[196:199], v[164:167], v[78:81]
	s_waitcnt vmcnt(6) lgkmcnt(0)
	s_barrier
; template <int MI, int NI>
; DI void gemm256(f32x4 (&acc)[MI][NI], const u16* __restrict__ A, int lda, const u16* __restrict__ Bt, int ldb, int K, int m0, int n0, char* smem) {
;     ...
;     const char* sb = smem + st * STAGE + foff;
;     bf16x8 af[MI], bfr[NI];
; #pragma unroll
;     for (int mi = 0; mi < MI; ++mi) af[mi] = *(const bf16x8*)(sb + (wr * MI + mi) * 1024);
; #pragma unroll
;     for (int ni = 0; ni < NI; ++ni) bfr[ni] = *(const bf16x8*)(sb + ABYTES + (wc * NI + ni) * 1024);
;     __builtin_amdgcn_sched_barrier(0x0);
;     if (kt + 2 < nk) { const int s2 = st >= 1 ? st - 1 : 2; G256_ISSUE(s2, (kt + 2) * 32); }
;     __builtin_amdgcn_s_setprio(0);
; #pragma unroll
;     for (int mi = 0; mi < MI; ++mi)
; #pragma unroll
;       for (int ni = 0; ni < NI; ++ni)
;         acc[mi][ni] = __builtin_amdgcn_mfma_f32_16x16x32_bf16(bfr[ni], af[mi], acc[mi][ni], 0, 0, 0);
	v_mfma_f32_16x16x32_bf16 v[82:85], v[200:203], v[164:167], v[82:85]
	v_mfma_f32_16x16x32_bf16 v[86:89], v[204:207], v[164:167], v[86:89]
	v_mfma_f32_16x16x32_bf16 v[30:33], v[208:211], v[164:167], v[30:33]
	v_mfma_f32_16x16x32_bf16 v[74:77], v[196:199], v[168:171], v[74:77]
	v_mfma_f32_16x16x32_bf16 v[90:93], v[200:203], v[168:171], v[90:93]
	v_mfma_f32_16x16x32_bf16 v[94:97], v[204:207], v[168:171], v[94:97]
	v_mfma_f32_16x16x32_bf16 v[34:37], v[208:211], v[168:171], v[34:37]
	v_mfma_f32_16x16x32_bf16 v[98:101], v[196:199], v[172:175], v[98:101]
	v_mfma_f32_16x16x32_bf16 v[102:105], v[200:203], v[172:175], v[102:105]
	v_mfma_f32_16x16x32_bf16 v[106:109], v[204:207], v[172:175], v[106:109]
	v_mfma_f32_16x16x32_bf16 v[38:41], v[208:211], v[172:175], v[38:41]
	v_mfma_f32_16x16x32_bf16 v[110:113], v[196:199], v[176:179], v[110:113]
	v_mfma_f32_16x16x32_bf16 v[114:117], v[200:203], v[176:179], v[114:117]
	v_mfma_f32_16x16x32_bf16 v[118:121], v[204:207], v[176:179], v[118:121]
	v_mfma_f32_16x16x32_bf16 v[42:45], v[208:211], v[176:179], v[42:45]
	v_mfma_f32_16x16x32_bf16 v[122:125], v[196:199], v[180:183], v[122:125]
	v_mfma_f32_16x16x32_bf16 v[126:129], v[200:203], v[180:183], v[126:129]
	v_mfma_f32_16x16x32_bf16 v[130:133], v[204:207], v[180:183], v[130:133]
	v_mfma_f32_16x16x32_bf16 v[46:49], v[208:211], v[180:183], v[46:49]
	v_mfma_f32_16x16x32_bf16 v[134:137], v[196:199], v[184:187], v[134:137]
	v_mfma_f32_16x16x32_bf16 v[138:141], v[200:203], v[184:187], v[138:141]
	v_mfma_f32_16x16x32_bf16 v[142:145], v[204:207], v[184:187], v[142:145]
	v_mfma_f32_16x16x32_bf16 v[50:53], v[208:211], v[184:187], v[50:53]
	v_mfma_f32_16x16x32_bf16 v[146:149], v[196:199], v[188:191], v[146:149]
	v_mfma_f32_16x16x32_bf16 v[54:57], v[208:211], v[188:191], v[54:57]
	v_mfma_f32_16x16x32_bf16 v[62:65], v[196:199], v[192:195], v[62:65]
	v_mfma_f32_16x16x32_bf16 v[66:69], v[200:203], v[192:195], v[66:69]
	v_mfma_f32_16x16x32_bf16 v[70:73], v[204:207], v[192:195], v[70:73]
	v_mfma_f32_16x16x32_bf16 v[58:61], v[208:211], v[192:195], v[58:61]
	v_mfma_f32_16x16x32_bf16 v[150:153], v[200:203], v[188:191], v[150:153]
	v_mfma_f32_16x16x32_bf16 v[154:157], v[204:207], v[188:191], v[154:157]
	s_nop 0
	ds_read_b128 v[164:167], v0
	ds_read_b128 v[168:171], v0 offset:1024
	ds_read_b128 v[172:175], v0 offset:2048
	ds_read_b128 v[176:179], v0 offset:3072
	ds_read_b128 v[180:183], v0 offset:4096
	ds_read_b128 v[184:187], v0 offset:5120
	ds_read_b128 v[188:191], v0 offset:6144
	ds_read_b128 v[192:195], v0 offset:7168
	ds_read_b128 v[196:199], v6 offset:16384
	ds_read_b128 v[200:203], v6 offset:17408
	ds_read_b128 v[204:207], v6 offset:18432
	ds_read_b128 v[208:211], v6 offset:19456
	s_mov_b64 s[28:29], 0x140
	s_mov_b32 m0, s6
	v_lshl_add_u64 v[212:213], v[2:3], 0, s[28:29]
	s_mov_b64 s[34:35], 0x7540
	global_load_lds_dwordx4 v[212:213], off
	v_lshl_add_u64 v[212:213], v[2:3], 0, s[34:35]
	s_mov_b32 m0, s4
	s_mov_b64 s[34:35], 0xe940
	global_load_lds_dwordx4 v[212:213], off
	v_lshl_add_u64 v[212:213], v[2:3], 0, s[34:35]
	s_mov_b32 m0, s5
	s_mov_b64 s[34:35], 0x15d40
	global_load_lds_dwordx4 v[212:213], off
	v_lshl_add_u64 v[212:213], v[2:3], 0, s[34:35]
	s_mov_b32 m0, s7
	s_nop 0
	global_load_lds_dwordx4 v[212:213], off
	v_lshl_add_u64 v[212:213], v[4:5], 0, s[28:29]
	s_mov_b32 m0, s8
	s_mov_b64 s[28:29], 0x3140
	global_load_lds_dwordx4 v[212:213], off
	v_lshl_add_u64 v[212:213], v[4:5], 0, s[28:29]
	s_mov_b32 m0, s9
	s_nop 0
	global_load_lds_dwordx4 v[212:213], off
	s_nop 0
	s_waitcnt lgkmcnt(0)
	v_mfma_f32_16x16x32_bf16 v[78:81], v[196:199], v[164:167], v[78:81]
	s_waitcnt vmcnt(6) lgkmcnt(0)
	s_barrier
	v_mfma_f32_16x16x32_bf16 v[82:85], v[200:203], v[164:167], v[82:85]
	v_mfma_f32_16x16x32_bf16 v[86:89], v[204:207], v[164:167], v[86:89]
	v_mfma_f32_16x16x32_bf16 v[30:33], v[208:211], v[164:167], v[30:33]
	v_mfma_f32_16x16x32_bf16 v[74:77], v[196:199], v[168:171], v[74:77]
	v_mfma_f32_16x16x32_bf16 v[90:93], v[200:203], v[168:171], v[90:93]
	v_mfma_f32_16x16x32_bf16 v[94:97], v[204:207], v[168:171], v[94:97]
	v_mfma_f32_16x16x32_bf16 v[34:37], v[208:211], v[168:171], v[34:37]
	v_mfma_f32_16x16x32_bf16 v[98:101], v[196:199], v[172:175], v[98:101]
	v_mfma_f32_16x16x32_bf16 v[102:105], v[200:203], v[172:175], v[102:105]
	v_mfma_f32_16x16x32_bf16 v[106:109], v[204:207], v[172:175], v[106:109]
	v_mfma_f32_16x16x32_bf16 v[38:41], v[208:211], v[172:175], v[38:41]
	v_mfma_f32_16x16x32_bf16 v[110:113], v[196:199], v[176:179], v[110:113]
	v_mfma_f32_16x16x32_bf16 v[114:117], v[200:203], v[176:179], v[114:117]
	v_mfma_f32_16x16x32_bf16 v[118:121], v[204:207], v[176:179], v[118:121]
	v_mfma_f32_16x16x32_bf16 v[42:45], v[208:211], v[176:179], v[42:45]
	v_mfma_f32_16x16x32_bf16 v[122:125], v[196:199], v[180:183], v[122:125]
	v_mfma_f32_16x16x32_bf16 v[126:129], v[200:203], v[180:183], v[126:129]
	v_mfma_f32_16x16x32_bf16 v[130:133], v[204:207], v[180:183], v[130:133]
	v_mfma_f32_16x16x32_bf16 v[46:49], v[208:211], v[180:183], v[46:49]
	v_mfma_f32_16x16x32_bf16 v[134:137], v[196:199], v[184:187], v[134:137]
	v_mfma_f32_16x16x32_bf16 v[138:141], v[200:203], v[184:187], v[138:141]
	v_mfma_f32_16x16x32_bf16 v[142:145], v[204:207], v[184:187], v[142:145]
	v_mfma_f32_16x16x32_bf16 v[50:53], v[208:211], v[184:187], v[50:53]
	v_mfma_f32_16x16x32_bf16 v[146:149], v[196:199], v[188:191], v[146:149]
	v_mfma_f32_16x16x32_bf16 v[54:57], v[208:211], v[188:191], v[54:57]
	v_mfma_f32_16x16x32_bf16 v[62:65], v[196:199], v[192:195], v[62:65]
	v_mfma_f32_16x16x32_bf16 v[66:69], v[200:203], v[192:195], v[66:69]
	v_mfma_f32_16x16x32_bf16 v[70:73], v[204:207], v[192:195], v[70:73]
; template <int MI, int NI>
; DI void gemm256(f32x4 (&acc)[MI][NI], const u16* __restrict__ A, int lda, const u16* __restrict__ Bt, int ldb, int K, int m0, int n0, char* smem) {
;     ...
;     const char* sb = smem + st * STAGE + foff;
;     bf16x8 af[MI], bfr[NI];
; #pragma unroll
;     for (int mi = 0; mi < MI; ++mi) af[mi] = *(const bf16x8*)(sb + (wr * MI + mi) * 1024);
; #pragma unroll
;     for (int ni = 0; ni < NI; ++ni) bfr[ni] = *(const bf16x8*)(sb + ABYTES + (wc * NI + ni) * 1024);
;     __builtin_amdgcn_sched_barrier(0x0);
;     if (kt + 2 < nk) { const int s2 = st >= 1 ? st - 1 : 2; G256_ISSUE(s2, (kt + 2) * 32); }
;     __builtin_amdgcn_s_setprio(0);
; #pragma unroll
;     for (int mi = 0; mi < MI; ++mi)
; #pragma unroll
;       for (int ni = 0; ni < NI; ++ni)
;         acc[mi][ni] = __builtin_amdgcn_mfma_f32_16x16x32_bf16(bfr[ni], af[mi], acc[mi][ni], 0, 0, 0);
	v_mfma_f32_16x16x32_bf16 v[58:61], v[208:211], v[192:195], v[58:61]
	v_mfma_f32_16x16x32_bf16 v[150:153], v[200:203], v[188:191], v[150:153]
	v_mfma_f32_16x16x32_bf16 v[154:157], v[204:207], v[188:191], v[154:157]
	s_nop 0
	ds_read_b128 v[164:167], v0 offset:24576
	ds_read_b128 v[168:171], v0 offset:25600
	ds_read_b128 v[172:175], v0 offset:26624
	ds_read_b128 v[176:179], v0 offset:27648
	ds_read_b128 v[180:183], v0 offset:28672
	ds_read_b128 v[184:187], v0 offset:29696
	ds_read_b128 v[188:191], v0 offset:30720
	ds_read_b128 v[192:195], v0 offset:31744
	ds_read_b128 v[196:199], v6 offset:40960
	ds_read_b128 v[200:203], v6 offset:41984
	ds_read_b128 v[204:207], v6 offset:43008
	ds_read_b128 v[208:211], v6 offset:44032
	s_mov_b64 s[28:29], 0x180
	s_mov_b32 m0, s22
	v_lshl_add_u64 v[212:213], v[2:3], 0, s[28:29]
	s_mov_b64 s[34:35], 0x7580
	global_load_lds_dwordx4 v[212:213], off
	v_lshl_add_u64 v[212:213], v[2:3], 0, s[34:35]
	s_mov_b32 m0, s21
	s_mov_b64 s[34:35], 0xe980
	global_load_lds_dwordx4 v[212:213], off
	v_lshl_add_u64 v[212:213], v[2:3], 0, s[34:35]
	s_mov_b32 m0, s23
	s_mov_b64 s[22:23], 0x15d80
	global_load_lds_dwordx4 v[212:213], off
	v_lshl_add_u64 v[212:213], v[2:3], 0, s[22:23]
	s_mov_b32 m0, s24
	s_mov_b64 s[22:23], 0x3180
	global_load_lds_dwordx4 v[212:213], off
	v_lshl_add_u64 v[212:213], v[4:5], 0, s[28:29]
	s_mov_b32 m0, s25
	s_nop 0
	global_load_lds_dwordx4 v[212:213], off
	v_lshl_add_u64 v[212:213], v[4:5], 0, s[22:23]
	s_mov_b32 m0, s26
	s_nop 0
	global_load_lds_dwordx4 v[212:213], off
	s_nop 0
	s_waitcnt lgkmcnt(0)
	v_mfma_f32_16x16x32_bf16 v[78:81], v[196:199], v[164:167], v[78:81]
	s_waitcnt vmcnt(6) lgkmcnt(0)
	s_barrier
	v_mfma_f32_16x16x32_bf16 v[82:85], v[200:203], v[164:167], v[82:85]
	v_mfma_f32_16x16x32_bf16 v[86:89], v[204:207], v[164:167], v[86:89]
	v_mfma_f32_16x16x32_bf16 v[30:33], v[208:211], v[164:167], v[30:33]
	v_mfma_f32_16x16x32_bf16 v[74:77], v[196:199], v[168:171], v[74:77]
	v_mfma_f32_16x16x32_bf16 v[90:93], v[200:203], v[168:171], v[90:93]
	v_mfma_f32_16x16x32_bf16 v[94:97], v[204:207], v[168:171], v[94:97]
	v_mfma_f32_16x16x32_bf16 v[34:37], v[208:211], v[168:171], v[34:37]
	v_mfma_f32_16x16x32_bf16 v[98:101], v[196:199], v[172:175], v[98:101]
	v_mfma_f32_16x16x32_bf16 v[102:105], v[200:203], v[172:175], v[102:105]
	v_mfma_f32_16x16x32_bf16 v[106:109], v[204:207], v[172:175], v[106:109]
	v_mfma_f32_16x16x32_bf16 v[38:41], v[208:211], v[172:175], v[38:41]
	v_mfma_f32_16x16x32_bf16 v[110:113], v[196:199], v[176:179], v[110:113]
	v_mfma_f32_16x16x32_bf16 v[114:117], v[200:203], v[176:179], v[114:117]
	v_mfma_f32_16x16x32_bf16 v[118:121], v[204:207], v[176:179], v[118:121]
	v_mfma_f32_16x16x32_bf16 v[42:45], v[208:211], v[176:179], v[42:45]
	v_mfma_f32_16x16x32_bf16 v[122:125], v[196:199], v[180:183], v[122:125]
	v_mfma_f32_16x16x32_bf16 v[126:129], v[200:203], v[180:183], v[126:129]
	v_mfma_f32_16x16x32_bf16 v[130:133], v[204:207], v[180:183], v[130:133]
	v_mfma_f32_16x16x32_bf16 v[46:49], v[208:211], v[180:183], v[46:49]
	v_mfma_f32_16x16x32_bf16 v[134:137], v[196:199], v[184:187], v[134:137]
	v_mfma_f32_16x16x32_bf16 v[138:141], v[200:203], v[184:187], v[138:141]
	v_mfma_f32_16x16x32_bf16 v[142:145], v[204:207], v[184:187], v[142:145]
	v_mfma_f32_16x16x32_bf16 v[50:53], v[208:211], v[184:187], v[50:53]
	v_mfma_f32_16x16x32_bf16 v[146:149], v[196:199], v[188:191], v[146:149]
	v_mfma_f32_16x16x32_bf16 v[54:57], v[208:211], v[188:191], v[54:57]
	v_mfma_f32_16x16x32_bf16 v[62:65], v[196:199], v[192:195], v[62:65]
	v_mfma_f32_16x16x32_bf16 v[66:69], v[200:203], v[192:195], v[66:69]
	v_mfma_f32_16x16x32_bf16 v[70:73], v[204:207], v[192:195], v[70:73]
	v_mfma_f32_16x16x32_bf16 v[58:61], v[208:211], v[192:195], v[58:61]
	v_mfma_f32_16x16x32_bf16 v[150:153], v[200:203], v[188:191], v[150:153]
	v_mfma_f32_16x16x32_bf16 v[154:157], v[204:207], v[188:191], v[154:157]
	s_nop 0
	ds_read_b128 v[164:167], v0 offset:49152
	ds_read_b128 v[168:171], v0 offset:50176
	ds_read_b128 v[172:175], v0 offset:51200
	ds_read_b128 v[176:179], v0 offset:52224
	ds_read_b128 v[180:183], v0 offset:53248
	ds_read_b128 v[184:187], v0 offset:54272
	ds_read_b128 v[188:191], v0 offset:55296
	ds_read_b128 v[192:195], v0 offset:56320
	ds_read_b128 v[196:199], v19
	ds_read_b128 v[200:203], v20
	ds_read_b128 v[204:207], v21
	ds_read_b128 v[208:211], v22
	s_mov_b64 s[22:23], 0x1c0
	s_mov_b32 m0, s16
	v_lshl_add_u64 v[212:213], v[2:3], 0, s[22:23]
	s_mov_b64 s[24:25], 0x75c0
	global_load_lds_dwordx4 v[212:213], off
	v_lshl_add_u64 v[212:213], v[2:3], 0, s[24:25]
	s_mov_b32 m0, s15
	s_mov_b64 s[24:25], 0xe9c0
	global_load_lds_dwordx4 v[212:213], off
	v_lshl_add_u64 v[212:213], v[2:3], 0, s[24:25]
	s_mov_b32 m0, s17
	s_mov_b64 s[16:17], 0x15dc0
	global_load_lds_dwordx4 v[212:213], off
	v_lshl_add_u64 v[212:213], v[2:3], 0, s[16:17]
	s_mov_b32 m0, s18
	s_mov_b64 s[16:17], 0x31c0
	global_load_lds_dwordx4 v[212:213], off
	v_lshl_add_u64 v[212:213], v[4:5], 0, s[22:23]
	s_mov_b32 m0, s19
	s_nop 0
	global_load_lds_dwordx4 v[212:213], off
	v_lshl_add_u64 v[212:213], v[4:5], 0, s[16:17]
	s_mov_b32 m0, s20
	s_nop 0
	global_load_lds_dwordx4 v[212:213], off
	s_nop 0
	s_waitcnt lgkmcnt(0)
	v_mfma_f32_16x16x32_bf16 v[78:81], v[196:199], v[164:167], v[78:81]
	s_waitcnt vmcnt(6) lgkmcnt(0)
	s_barrier
; template <int MI, int NI>
; DI void gemm256(f32x4 (&acc)[MI][NI], const u16* __restrict__ A, int lda, const u16* __restrict__ Bt, int ldb, int K, int m0, int n0, char* smem) {
;     ...
;     const char* sb = smem + st * STAGE + foff;
;     bf16x8 af[MI], bfr[NI];
; #pragma unroll
;     for (int mi = 0; mi < MI; ++mi) af[mi] = *(const bf16x8*)(sb + (wr * MI + mi) * 1024);
; #pragma unroll
;     for (int ni = 0; ni < NI; ++ni) bfr[ni] = *(const bf16x8*)(sb + ABYTES + (wc * NI + ni) * 1024);
;     __builtin_amdgcn_sched_barrier(0x0);
;     if (kt + 2 < nk) { const int s2 = st >= 1 ? st - 1 : 2; G256_ISSUE(s2, (kt + 2) * 32); }
;     __builtin_amdgcn_s_setprio(0);
; #pragma unroll
;     for (int mi = 0; mi < MI; ++mi)
; #pragma unroll
;       for (int ni = 0; ni < NI; ++ni)
;         acc[mi][ni] = __builtin_amdgcn_mfma_f32_16x16x32_bf16(bfr[ni], af[mi], acc[mi][ni], 0, 0, 0);
	v_mfma_f32_16x16x32_bf16 v[82:85], v[200:203], v[164:167], v[82:85]
	v_mfma_f32_16x16x32_bf16 v[86:89], v[204:207], v[164:167], v[86:89]
	v_mfma_f32_16x16x32_bf16 v[30:33], v[208:211], v[164:167], v[30:33]
	v_mfma_f32_16x16x32_bf16 v[74:77], v[196:199], v[168:171], v[74:77]
	v_mfma_f32_16x16x32_bf16 v[90:93], v[200:203], v[168:171], v[90:93]
	v_mfma_f32_16x16x32_bf16 v[94:97], v[204:207], v[168:171], v[94:97]
	v_mfma_f32_16x16x32_bf16 v[34:37], v[208:211], v[168:171], v[34:37]
	v_mfma_f32_16x16x32_bf16 v[98:101], v[196:199], v[172:175], v[98:101]
	v_mfma_f32_16x16x32_bf16 v[102:105], v[200:203], v[172:175], v[102:105]
	v_mfma_f32_16x16x32_bf16 v[106:109], v[204:207], v[172:175], v[106:109]
	v_mfma_f32_16x16x32_bf16 v[38:41], v[208:211], v[172:175], v[38:41]
	v_mfma_f32_16x16x32_bf16 v[110:113], v[196:199], v[176:179], v[110:113]
	v_mfma_f32_16x16x32_bf16 v[114:117], v[200:203], v[176:179], v[114:117]
	v_mfma_f32_16x16x32_bf16 v[118:121], v[204:207], v[176:179], v[118:121]
	v_mfma_f32_16x16x32_bf16 v[42:45], v[208:211], v[176:179], v[42:45]
	v_mfma_f32_16x16x32_bf16 v[122:125], v[196:199], v[180:183], v[122:125]
	v_mfma_f32_16x16x32_bf16 v[126:129], v[200:203], v[180:183], v[126:129]
	v_mfma_f32_16x16x32_bf16 v[130:133], v[204:207], v[180:183], v[130:133]
	v_mfma_f32_16x16x32_bf16 v[46:49], v[208:211], v[180:183], v[46:49]
	v_mfma_f32_16x16x32_bf16 v[134:137], v[196:199], v[184:187], v[134:137]
	v_mfma_f32_16x16x32_bf16 v[138:141], v[200:203], v[184:187], v[138:141]
	v_mfma_f32_16x16x32_bf16 v[142:145], v[204:207], v[184:187], v[142:145]
	v_mfma_f32_16x16x32_bf16 v[50:53], v[208:211], v[184:187], v[50:53]
	v_mfma_f32_16x16x32_bf16 v[146:149], v[196:199], v[188:191], v[146:149]
	v_mfma_f32_16x16x32_bf16 v[54:57], v[208:211], v[188:191], v[54:57]
	v_mfma_f32_16x16x32_bf16 v[62:65], v[196:199], v[192:195], v[62:65]
	v_mfma_f32_16x16x32_bf16 v[66:69], v[200:203], v[192:195], v[66:69]
	v_mfma_f32_16x16x32_bf16 v[70:73], v[204:207], v[192:195], v[70:73]
	v_mfma_f32_16x16x32_bf16 v[58:61], v[208:211], v[192:195], v[58:61]
	v_mfma_f32_16x16x32_bf16 v[150:153], v[200:203], v[188:191], v[150:153]
	v_mfma_f32_16x16x32_bf16 v[154:157], v[204:207], v[188:191], v[154:157]
	s_nop 0
	ds_read_b128 v[164:167], v0
	ds_read_b128 v[168:171], v0 offset:1024
	ds_read_b128 v[172:175], v0 offset:2048
	ds_read_b128 v[176:179], v0 offset:3072
	ds_read_b128 v[180:183], v0 offset:4096
	ds_read_b128 v[184:187], v0 offset:5120
	ds_read_b128 v[188:191], v0 offset:6144
	ds_read_b128 v[192:195], v0 offset:7168
	ds_read_b128 v[196:199], v6 offset:16384
	ds_read_b128 v[200:203], v6 offset:17408
	ds_read_b128 v[204:207], v6 offset:18432
	ds_read_b128 v[208:211], v6 offset:19456
	s_mov_b64 s[18:19], 0x200
	s_mov_b32 m0, s6
	v_lshl_add_u64 v[212:213], v[2:3], 0, s[18:19]
	s_mov_b64 s[16:17], 0x7600
	global_load_lds_dwordx4 v[212:213], off
	v_lshl_add_u64 v[212:213], v[2:3], 0, s[16:17]
	s_mov_b32 m0, s4
	s_mov_b64 s[16:17], 0xea00
	global_load_lds_dwordx4 v[212:213], off
	v_lshl_add_u64 v[212:213], v[2:3], 0, s[16:17]
	s_mov_b32 m0, s5
	s_mov_b64 s[4:5], 0x15e00
	global_load_lds_dwordx4 v[212:213], off
	v_lshl_add_u64 v[212:213], v[2:3], 0, s[4:5]
	s_mov_b32 m0, s7
	s_mov_b64 s[4:5], 0x3200
	global_load_lds_dwordx4 v[212:213], off
	v_lshl_add_u64 v[212:213], v[4:5], 0, s[18:19]
	s_mov_b32 m0, s8
	s_nop 0
	global_load_lds_dwordx4 v[212:213], off
	v_lshl_add_u64 v[212:213], v[4:5], 0, s[4:5]
	s_mov_b32 m0, s9
	s_nop 0
	global_load_lds_dwordx4 v[212:213], off
	s_nop 0
	s_waitcnt lgkmcnt(0)
	v_mfma_f32_16x16x32_bf16 v[78:81], v[196:199], v[164:167], v[78:81]
	s_waitcnt vmcnt(6) lgkmcnt(0)
	s_barrier
	v_mfma_f32_16x16x32_bf16 v[82:85], v[200:203], v[164:167], v[82:85]
	v_mfma_f32_16x16x32_bf16 v[86:89], v[204:207], v[164:167], v[86:89]
	v_mfma_f32_16x16x32_bf16 v[30:33], v[208:211], v[164:167], v[30:33]
	v_mfma_f32_16x16x32_bf16 v[74:77], v[196:199], v[168:171], v[74:77]
	v_mfma_f32_16x16x32_bf16 v[90:93], v[200:203], v[168:171], v[90:93]
	v_mfma_f32_16x16x32_bf16 v[94:97], v[204:207], v[168:171], v[94:97]
	v_mfma_f32_16x16x32_bf16 v[34:37], v[208:211], v[168:171], v[34:37]
	v_mfma_f32_16x16x32_bf16 v[98:101], v[196:199], v[172:175], v[98:101]
	v_mfma_f32_16x16x32_bf16 v[102:105], v[200:203], v[172:175], v[102:105]
	v_mfma_f32_16x16x32_bf16 v[106:109], v[204:207], v[172:175], v[106:109]
	v_mfma_f32_16x16x32_bf16 v[38:41], v[208:211], v[172:175], v[38:41]
	v_mfma_f32_16x16x32_bf16 v[110:113], v[196:199], v[176:179], v[110:113]
	v_mfma_f32_16x16x32_bf16 v[114:117], v[200:203], v[176:179], v[114:117]
	v_mfma_f32_16x16x32_bf16 v[118:121], v[204:207], v[176:179], v[118:121]
	v_mfma_f32_16x16x32_bf16 v[42:45], v[208:211], v[176:179], v[42:45]
	v_mfma_f32_16x16x32_bf16 v[122:125], v[196:199], v[180:183], v[122:125]
	v_mfma_f32_16x16x32_bf16 v[126:129], v[200:203], v[180:183], v[126:129]
	v_mfma_f32_16x16x32_bf16 v[130:133], v[204:207], v[180:183], v[130:133]
	v_mfma_f32_16x16x32_bf16 v[46:49], v[208:211], v[180:183], v[46:49]
	v_mfma_f32_16x16x32_bf16 v[134:137], v[196:199], v[184:187], v[134:137]
	v_mfma_f32_16x16x32_bf16 v[138:141], v[200:203], v[184:187], v[138:141]
	v_mfma_f32_16x16x32_bf16 v[142:145], v[204:207], v[184:187], v[142:145]
	v_mfma_f32_16x16x32_bf16 v[50:53], v[208:211], v[184:187], v[50:53]
	v_mfma_f32_16x16x32_bf16 v[146:149], v[196:199], v[188:191], v[146:149]
	v_mfma_f32_16x16x32_bf16 v[54:57], v[208:211], v[188:191], v[54:57]
	v_mfma_f32_16x16x32_bf16 v[62:65], v[196:199], v[192:195], v[62:65]
	v_mfma_f32_16x16x32_bf16 v[66:69], v[200:203], v[192:195], v[66:69]
	v_mfma_f32_16x16x32_bf16 v[70:73], v[204:207], v[192:195], v[70:73]
; template <int MI, int NI>
; DI void gemm256(f32x4 (&acc)[MI][NI], const u16* __restrict__ A, int lda, const u16* __restrict__ Bt, int ldb, int K, int m0, int n0, char* smem) {
;     ...
;     const char* sb = smem + st * STAGE + foff;
;     bf16x8 af[MI], bfr[NI];
; #pragma unroll
;     for (int mi = 0; mi < MI; ++mi) af[mi] = *(const bf16x8*)(sb + (wr * MI + mi) * 1024);
; #pragma unroll
;     for (int ni = 0; ni < NI; ++ni) bfr[ni] = *(const bf16x8*)(sb + ABYTES + (wc * NI + ni) * 1024);
;     __builtin_amdgcn_sched_barrier(0x0);
;     if (kt + 2 < nk) { const int s2 = st >= 1 ? st - 1 : 2; G256_ISSUE(s2, (kt + 2) * 32); }
;     __builtin_amdgcn_s_setprio(0);
; #pragma unroll
;     for (int mi = 0; mi < MI; ++mi)
; #pragma unroll
;       for (int ni = 0; ni < NI; ++ni)
;         acc[mi][ni] = __builtin_amdgcn_mfma_f32_16x16x32_bf16(bfr[ni], af[mi], acc[mi][ni], 0, 0, 0);
	v_mfma_f32_16x16x32_bf16 v[58:61], v[208:211], v[192:195], v[58:61]
	v_mfma_f32_16x16x32_bf16 v[150:153], v[200:203], v[188:191], v[150:153]
	v_mfma_f32_16x16x32_bf16 v[154:157], v[204:207], v[188:191], v[154:157]
	s_nop 0
	ds_read_b128 v[164:167], v0 offset:24576
	ds_read_b128 v[168:171], v0 offset:25600
	ds_read_b128 v[172:175], v0 offset:26624
	ds_read_b128 v[176:179], v0 offset:27648
	ds_read_b128 v[180:183], v0 offset:28672
	ds_read_b128 v[184:187], v0 offset:29696
	ds_read_b128 v[188:191], v0 offset:30720
	ds_read_b128 v[192:195], v0 offset:31744
	ds_read_b128 v[196:199], v6 offset:40960
	ds_read_b128 v[200:203], v6 offset:41984
	ds_read_b128 v[204:207], v6 offset:43008
	ds_read_b128 v[208:211], v6 offset:44032
	s_mov_b64 s[6:7], 0x240
	v_readfirstlane_b32 s4, v24
	v_lshl_add_u64 v[212:213], v[2:3], 0, s[6:7]
	s_mov_b32 m0, s4
	s_mov_b64 s[4:5], 0x7640
	global_load_lds_dwordx4 v[212:213], off
	v_lshl_add_u64 v[212:213], v[2:3], 0, s[4:5]
	v_readfirstlane_b32 s4, v25
	s_mov_b32 m0, s4
	s_mov_b64 s[4:5], 0xea40
	v_lshl_add_u64 v[24:25], v[2:3], 0, s[4:5]
	v_readfirstlane_b32 s4, v26
	global_load_lds_dwordx4 v[212:213], off
	s_mov_b32 m0, s4
	s_mov_b64 s[4:5], 0x15e40
	global_load_lds_dwordx4 v[24:25], off
	v_lshl_add_u64 v[24:25], v[2:3], 0, s[4:5]
	v_readfirstlane_b32 s4, v27
	s_mov_b32 m0, s4
	v_readfirstlane_b32 s4, v23
	global_load_lds_dwordx4 v[24:25], off
	v_lshl_add_u64 v[24:25], v[4:5], 0, s[6:7]
	s_mov_b32 m0, s4
	s_mov_b64 s[4:5], 0x3240
	global_load_lds_dwordx4 v[24:25], off
	v_lshl_add_u64 v[24:25], v[4:5], 0, s[4:5]
	v_readfirstlane_b32 s4, v28
	s_mov_b32 m0, s4
	s_nop 0
	global_load_lds_dwordx4 v[24:25], off
	s_nop 0
	s_waitcnt lgkmcnt(0)
	v_mfma_f32_16x16x32_bf16 v[24:27], v[196:199], v[164:167], v[78:81]
	s_waitcnt vmcnt(6) lgkmcnt(0)
	s_barrier
	v_mfma_f32_16x16x32_bf16 v[78:81], v[200:203], v[164:167], v[82:85]
	v_mfma_f32_16x16x32_bf16 v[82:85], v[204:207], v[164:167], v[86:89]
	v_mfma_f32_16x16x32_bf16 v[28:31], v[208:211], v[164:167], v[30:33]
	v_mfma_f32_16x16x32_bf16 v[74:77], v[196:199], v[168:171], v[74:77]
	v_mfma_f32_16x16x32_bf16 v[86:89], v[200:203], v[168:171], v[90:93]
	v_mfma_f32_16x16x32_bf16 v[90:93], v[204:207], v[168:171], v[94:97]
	v_mfma_f32_16x16x32_bf16 v[32:35], v[208:211], v[168:171], v[34:37]
	v_mfma_f32_16x16x32_bf16 v[94:97], v[196:199], v[172:175], v[98:101]
	v_mfma_f32_16x16x32_bf16 v[98:101], v[200:203], v[172:175], v[102:105]
	v_mfma_f32_16x16x32_bf16 v[102:105], v[204:207], v[172:175], v[106:109]
	v_mfma_f32_16x16x32_bf16 v[36:39], v[208:211], v[172:175], v[38:41]
	v_mfma_f32_16x16x32_bf16 v[106:109], v[196:199], v[176:179], v[110:113]
	v_mfma_f32_16x16x32_bf16 v[110:113], v[200:203], v[176:179], v[114:117]
	v_mfma_f32_16x16x32_bf16 v[114:117], v[204:207], v[176:179], v[118:121]
	v_mfma_f32_16x16x32_bf16 v[40:43], v[208:211], v[176:179], v[42:45]
	v_mfma_f32_16x16x32_bf16 v[118:121], v[196:199], v[180:183], v[122:125]
	v_mfma_f32_16x16x32_bf16 v[122:125], v[200:203], v[180:183], v[126:129]
	v_mfma_f32_16x16x32_bf16 v[126:129], v[204:207], v[180:183], v[130:133]
	v_mfma_f32_16x16x32_bf16 v[44:47], v[208:211], v[180:183], v[46:49]
	v_mfma_f32_16x16x32_bf16 v[130:133], v[196:199], v[184:187], v[134:137]
	v_mfma_f32_16x16x32_bf16 v[134:137], v[200:203], v[184:187], v[138:141]
	v_mfma_f32_16x16x32_bf16 v[138:141], v[204:207], v[184:187], v[142:145]
	v_mfma_f32_16x16x32_bf16 v[48:51], v[208:211], v[184:187], v[50:53]
	v_mfma_f32_16x16x32_bf16 v[142:145], v[196:199], v[188:191], v[146:149]
	v_mfma_f32_16x16x32_bf16 v[146:149], v[200:203], v[188:191], v[150:153]
	v_mfma_f32_16x16x32_bf16 v[52:55], v[208:211], v[188:191], v[54:57]
	v_mfma_f32_16x16x32_bf16 v[62:65], v[196:199], v[192:195], v[62:65]
	v_mfma_f32_16x16x32_bf16 v[66:69], v[200:203], v[192:195], v[66:69]
	v_mfma_f32_16x16x32_bf16 v[70:73], v[204:207], v[192:195], v[70:73]
	v_mfma_f32_16x16x32_bf16 v[56:59], v[208:211], v[192:195], v[58:61]
	v_mfma_f32_16x16x32_bf16 v[150:153], v[204:207], v[188:191], v[154:157]
	s_nop 0
	s_nop 0
	ds_read_b128 v[154:157], v0 offset:49152
	ds_read_b128 v[164:167], v0 offset:50176
	ds_read_b128 v[168:171], v0 offset:51200
	ds_read_b128 v[172:175], v0 offset:52224
	ds_read_b128 v[176:179], v0 offset:53248
	ds_read_b128 v[180:183], v0 offset:54272
	ds_read_b128 v[184:187], v0 offset:55296
	ds_read_b128 v[188:191], v0 offset:56320
	ds_read_b128 v[192:195], v19
	ds_read_b128 v[196:199], v20
	ds_read_b128 v[200:203], v21
	ds_read_b128 v[204:207], v22
	s_mov_b64 s[6:7], 0x280
	v_readfirstlane_b32 s4, v13
	v_lshl_add_u64 v[60:61], v[2:3], 0, s[6:7]
	s_mov_b32 m0, s4
	s_mov_b64 s[4:5], 0x7680
	global_load_lds_dwordx4 v[60:61], off
	v_lshl_add_u64 v[60:61], v[2:3], 0, s[4:5]
	v_readfirstlane_b32 s4, v14
	s_mov_b32 m0, s4
	s_mov_b64 s[4:5], 0xea80
	global_load_lds_dwordx4 v[60:61], off
	v_lshl_add_u64 v[60:61], v[2:3], 0, s[4:5]
	v_readfirstlane_b32 s4, v15
	s_mov_b32 m0, s4
	s_mov_b64 s[4:5], 0x15e80
	v_lshl_add_u64 v[14:15], v[2:3], 0, s[4:5]
	v_readfirstlane_b32 s4, v17
	global_load_lds_dwordx4 v[60:61], off
	s_mov_b32 m0, s4
	v_readfirstlane_b32 s4, v16
	global_load_lds_dwordx4 v[14:15], off
	v_lshl_add_u64 v[14:15], v[4:5], 0, s[6:7]
	s_mov_b32 m0, s4
	s_mov_b64 s[4:5], 0x3280
	global_load_lds_dwordx4 v[14:15], off
	v_lshl_add_u64 v[14:15], v[4:5], 0, s[4:5]
	v_readfirstlane_b32 s4, v18
	s_mov_b32 m0, s4
	s_nop 0
	global_load_lds_dwordx4 v[14:15], off
	s_nop 0
	s_waitcnt lgkmcnt(0)
	v_mfma_f32_16x16x32_bf16 v[14:17], v[192:195], v[154:157], v[24:27]
	s_waitcnt vmcnt(6) lgkmcnt(0)
	s_barrier
; template <int MI, int NI>
; DI void gemm256(f32x4 (&acc)[MI][NI], const u16* __restrict__ A, int lda, const u16* __restrict__ Bt, int ldb, int K, int m0, int n0, char* smem) {
;     ...
;     const char* sb = smem + st * STAGE + foff;
;     bf16x8 af[MI], bfr[NI];
; #pragma unroll
;     for (int mi = 0; mi < MI; ++mi) af[mi] = *(const bf16x8*)(sb + (wr * MI + mi) * 1024);
; #pragma unroll
;     for (int ni = 0; ni < NI; ++ni) bfr[ni] = *(const bf16x8*)(sb + ABYTES + (wc * NI + ni) * 1024);
;     __builtin_amdgcn_sched_barrier(0x0);
;     if (kt + 2 < nk) { const int s2 = st >= 1 ? st - 1 : 2; G256_ISSUE(s2, (kt + 2) * 32); }
;     __builtin_amdgcn_s_setprio(0);
; #pragma unroll
;     for (int mi = 0; mi < MI; ++mi)
; #pragma unroll
;       for (int ni = 0; ni < NI; ++ni)
;         acc[mi][ni] = __builtin_amdgcn_mfma_f32_16x16x32_bf16(bfr[ni], af[mi], acc[mi][ni], 0, 0, 0);
	v_mfma_f32_16x16x32_bf16 v[24:27], v[196:199], v[154:157], v[78:81]
	v_mfma_f32_16x16x32_bf16 v[78:81], v[200:203], v[154:157], v[82:85]
	v_mfma_f32_16x16x32_bf16 v[28:31], v[204:207], v[154:157], v[28:31]
	v_mfma_f32_16x16x32_bf16 v[74:77], v[192:195], v[164:167], v[74:77]
	v_mfma_f32_16x16x32_bf16 v[82:85], v[196:199], v[164:167], v[86:89]
	v_mfma_f32_16x16x32_bf16 v[86:89], v[200:203], v[164:167], v[90:93]
	v_mfma_f32_16x16x32_bf16 v[32:35], v[204:207], v[164:167], v[32:35]
	v_mfma_f32_16x16x32_bf16 v[90:93], v[192:195], v[168:171], v[94:97]
	v_mfma_f32_16x16x32_bf16 v[94:97], v[196:199], v[168:171], v[98:101]
	v_mfma_f32_16x16x32_bf16 v[98:101], v[200:203], v[168:171], v[102:105]
	v_mfma_f32_16x16x32_bf16 v[36:39], v[204:207], v[168:171], v[36:39]
	v_mfma_f32_16x16x32_bf16 v[102:105], v[192:195], v[172:175], v[106:109]
	v_mfma_f32_16x16x32_bf16 v[106:109], v[196:199], v[172:175], v[110:113]
	v_mfma_f32_16x16x32_bf16 v[110:113], v[200:203], v[172:175], v[114:117]
	v_mfma_f32_16x16x32_bf16 v[40:43], v[204:207], v[172:175], v[40:43]
	v_mfma_f32_16x16x32_bf16 v[114:117], v[192:195], v[176:179], v[118:121]
	v_mfma_f32_16x16x32_bf16 v[118:121], v[196:199], v[176:179], v[122:125]
	v_mfma_f32_16x16x32_bf16 v[122:125], v[200:203], v[176:179], v[126:129]
	v_mfma_f32_16x16x32_bf16 v[44:47], v[204:207], v[176:179], v[44:47]
	v_mfma_f32_16x16x32_bf16 v[126:129], v[192:195], v[180:183], v[130:133]
	v_mfma_f32_16x16x32_bf16 v[130:133], v[196:199], v[180:183], v[134:137]
	v_mfma_f32_16x16x32_bf16 v[134:137], v[200:203], v[180:183], v[138:141]
	v_mfma_f32_16x16x32_bf16 v[48:51], v[204:207], v[180:183], v[48:51]
	v_mfma_f32_16x16x32_bf16 v[138:141], v[192:195], v[184:187], v[142:145]
	v_mfma_f32_16x16x32_bf16 v[142:145], v[196:199], v[184:187], v[146:149]
	v_mfma_f32_16x16x32_bf16 v[146:149], v[200:203], v[184:187], v[150:153]
	v_mfma_f32_16x16x32_bf16 v[52:55], v[204:207], v[184:187], v[52:55]
	v_mfma_f32_16x16x32_bf16 v[60:63], v[192:195], v[188:191], v[62:65]
	v_mfma_f32_16x16x32_bf16 v[64:67], v[196:199], v[188:191], v[66:69]
	v_mfma_f32_16x16x32_bf16 v[68:71], v[200:203], v[188:191], v[70:73]
	v_mfma_f32_16x16x32_bf16 v[56:59], v[204:207], v[188:191], v[56:59]
	s_nop 0
	ds_read_b128 v[150:153], v0
	ds_read_b128 v[154:157], v0 offset:1024
	ds_read_b128 v[164:167], v0 offset:2048
	ds_read_b128 v[168:171], v0 offset:3072
	ds_read_b128 v[172:175], v0 offset:4096
	ds_read_b128 v[176:179], v0 offset:5120
	ds_read_b128 v[180:183], v0 offset:6144
	ds_read_b128 v[184:187], v0 offset:7168
	ds_read_b128 v[188:191], v6 offset:16384
	ds_read_b128 v[192:195], v6 offset:17408
	ds_read_b128 v[196:199], v6 offset:18432
	ds_read_b128 v[200:203], v6 offset:19456
	s_mov_b64 s[6:7], 0x2c0
	v_readfirstlane_b32 s4, v7
	v_lshl_add_u64 v[72:73], v[2:3], 0, s[6:7]
	s_mov_b32 m0, s4
	s_mov_b64 s[4:5], 0x76c0
	global_load_lds_dwordx4 v[72:73], off
	v_lshl_add_u64 v[72:73], v[2:3], 0, s[4:5]
	v_readfirstlane_b32 s4, v8
	s_mov_b32 m0, s4
	s_mov_b64 s[4:5], 0xeac0
	global_load_lds_dwordx4 v[72:73], off
	v_lshl_add_u64 v[72:73], v[2:3], 0, s[4:5]
	v_readfirstlane_b32 s4, v9
	s_mov_b32 m0, s4
	s_mov_b64 s[4:5], 0x15ec0
	v_lshl_add_u64 v[2:3], v[2:3], 0, s[4:5]
	v_readfirstlane_b32 s4, v10
	global_load_lds_dwordx4 v[72:73], off
	s_mov_b32 m0, s4
	v_readfirstlane_b32 s4, v11
	global_load_lds_dwordx4 v[2:3], off
	v_lshl_add_u64 v[2:3], v[4:5], 0, s[6:7]
	s_mov_b32 m0, s4
	s_mov_b64 s[4:5], 0x32c0
	global_load_lds_dwordx4 v[2:3], off
	v_lshl_add_u64 v[2:3], v[4:5], 0, s[4:5]
	v_readfirstlane_b32 s4, v12
	s_mov_b32 m0, s4
	s_nop 0
	global_load_lds_dwordx4 v[2:3], off
	s_nop 0
	s_waitcnt lgkmcnt(0)
	v_mfma_f32_16x16x32_bf16 v[2:5], v[188:191], v[150:153], v[14:17]
	s_waitcnt vmcnt(6) lgkmcnt(0)
	s_barrier
	v_mfma_f32_16x16x32_bf16 v[8:11], v[192:195], v[150:153], v[24:27]
	v_mfma_f32_16x16x32_bf16 v[12:15], v[196:199], v[150:153], v[78:81]
	v_mfma_f32_16x16x32_bf16 v[24:27], v[200:203], v[150:153], v[28:31]
	v_mfma_f32_16x16x32_bf16 v[28:31], v[188:191], v[154:157], v[74:77]
	v_mfma_f32_16x16x32_bf16 v[72:75], v[192:195], v[154:157], v[82:85]
	v_mfma_f32_16x16x32_bf16 v[76:79], v[196:199], v[154:157], v[86:89]
	v_mfma_f32_16x16x32_bf16 v[32:35], v[200:203], v[154:157], v[32:35]
	v_mfma_f32_16x16x32_bf16 v[80:83], v[188:191], v[164:167], v[90:93]
	v_mfma_f32_16x16x32_bf16 v[84:87], v[192:195], v[164:167], v[94:97]
	v_mfma_f32_16x16x32_bf16 v[88:91], v[196:199], v[164:167], v[98:101]
	v_mfma_f32_16x16x32_bf16 v[36:39], v[200:203], v[164:167], v[36:39]
	v_mfma_f32_16x16x32_bf16 v[92:95], v[188:191], v[168:171], v[102:105]
	v_mfma_f32_16x16x32_bf16 v[96:99], v[192:195], v[168:171], v[106:109]
	v_mfma_f32_16x16x32_bf16 v[100:103], v[196:199], v[168:171], v[110:113]
	v_mfma_f32_16x16x32_bf16 v[40:43], v[200:203], v[168:171], v[40:43]
	v_mfma_f32_16x16x32_bf16 v[104:107], v[188:191], v[172:175], v[114:117]
	v_mfma_f32_16x16x32_bf16 v[108:111], v[192:195], v[172:175], v[118:121]
	v_mfma_f32_16x16x32_bf16 v[112:115], v[196:199], v[172:175], v[122:125]
	v_mfma_f32_16x16x32_bf16 v[44:47], v[200:203], v[172:175], v[44:47]
	v_mfma_f32_16x16x32_bf16 v[116:119], v[188:191], v[176:179], v[126:129]
	v_mfma_f32_16x16x32_bf16 v[120:123], v[192:195], v[176:179], v[130:133]
	v_mfma_f32_16x16x32_bf16 v[124:127], v[196:199], v[176:179], v[134:137]
	v_mfma_f32_16x16x32_bf16 v[48:51], v[200:203], v[176:179], v[48:51]
	v_mfma_f32_16x16x32_bf16 v[128:131], v[188:191], v[180:183], v[138:141]
	v_mfma_f32_16x16x32_bf16 v[132:135], v[192:195], v[180:183], v[142:145]
	v_mfma_f32_16x16x32_bf16 v[136:139], v[196:199], v[180:183], v[146:149]
	v_mfma_f32_16x16x32_bf16 v[52:55], v[200:203], v[180:183], v[52:55]
	v_mfma_f32_16x16x32_bf16 v[60:63], v[188:191], v[184:187], v[60:63]
	v_mfma_f32_16x16x32_bf16 v[64:67], v[192:195], v[184:187], v[64:67]
	v_mfma_f32_16x16x32_bf16 v[68:71], v[196:199], v[184:187], v[68:71]
	v_mfma_f32_16x16x32_bf16 v[56:59], v[200:203], v[184:187], v[56:59]
	s_nop 0
	ds_read_b128 v[140:143], v0 offset:24576
	ds_read_b128 v[144:147], v0 offset:25600
	ds_read_b128 v[148:151], v0 offset:26624
	ds_read_b128 v[152:155], v0 offset:27648
	ds_read_b128 v[164:167], v0 offset:28672
	ds_read_b128 v[168:171], v0 offset:29696
	ds_read_b128 v[172:175], v0 offset:30720
	ds_read_b128 v[176:179], v0 offset:31744
	ds_read_b128 v[180:183], v6 offset:40960
	ds_read_b128 v[184:187], v6 offset:41984
	ds_read_b128 v[188:191], v6 offset:43008
	ds_read_b128 v[192:195], v6 offset:44032
	s_nop 0
	s_waitcnt lgkmcnt(3)
	v_mfma_f32_16x16x32_bf16 v[2:5], v[180:183], v[140:143], v[2:5]
	s_waitcnt vmcnt(0) lgkmcnt(0)
	s_barrier
; template <int MI, int NI>
; DI void gemm256(f32x4 (&acc)[MI][NI], const u16* __restrict__ A, int lda, const u16* __restrict__ Bt, int ldb, int K, int m0, int n0, char* smem) {
;     ...
;     const char* sb = smem + st * STAGE + foff;
;     bf16x8 af[MI], bfr[NI];
; #pragma unroll
;     for (int mi = 0; mi < MI; ++mi) af[mi] = *(const bf16x8*)(sb + (wr * MI + mi) * 1024);
; #pragma unroll
;     for (int ni = 0; ni < NI; ++ni) bfr[ni] = *(const bf16x8*)(sb + ABYTES + (wc * NI + ni) * 1024);
;     __builtin_amdgcn_sched_barrier(0x0);
;     if (kt + 2 < nk) { const int s2 = st >= 1 ? st - 1 : 2; G256_ISSUE(s2, (kt + 2) * 32); }
;     __builtin_amdgcn_s_setprio(0);
; #pragma unroll
;     for (int mi = 0; mi < MI; ++mi)
; #pragma unroll
;       for (int ni = 0; ni < NI; ++ni)
;         acc[mi][ni] = __builtin_amdgcn_mfma_f32_16x16x32_bf16(bfr[ni], af[mi], acc[mi][ni], 0, 0, 0);
	s_waitcnt lgkmcnt(2)
	v_mfma_f32_16x16x32_bf16 v[6:9], v[184:187], v[140:143], v[8:11]
	s_waitcnt lgkmcnt(1)
	v_mfma_f32_16x16x32_bf16 v[10:13], v[188:191], v[140:143], v[12:15]
	s_waitcnt lgkmcnt(0)
	v_mfma_f32_16x16x32_bf16 v[14:17], v[192:195], v[140:143], v[24:27]
	v_mfma_f32_16x16x32_bf16 v[24:27], v[180:183], v[144:147], v[28:31]
	v_mfma_f32_16x16x32_bf16 v[28:31], v[184:187], v[144:147], v[72:75]
	v_mfma_f32_16x16x32_bf16 v[72:75], v[188:191], v[144:147], v[76:79]
	v_mfma_f32_16x16x32_bf16 v[32:35], v[192:195], v[144:147], v[32:35]
	v_mfma_f32_16x16x32_bf16 v[76:79], v[180:183], v[148:151], v[80:83]
	v_mfma_f32_16x16x32_bf16 v[80:83], v[184:187], v[148:151], v[84:87]
	v_mfma_f32_16x16x32_bf16 v[84:87], v[188:191], v[148:151], v[88:91]
	v_mfma_f32_16x16x32_bf16 v[36:39], v[192:195], v[148:151], v[36:39]
	v_mfma_f32_16x16x32_bf16 v[140:143], v[180:183], v[152:155], v[92:95]
	v_mfma_f32_16x16x32_bf16 v[144:147], v[184:187], v[152:155], v[96:99]
	v_mfma_f32_16x16x32_bf16 v[148:151], v[188:191], v[152:155], v[100:103]
	v_mfma_f32_16x16x32_bf16 v[40:43], v[192:195], v[152:155], v[40:43]
	v_mfma_f32_16x16x32_bf16 v[152:155], v[180:183], v[164:167], v[104:107]
	v_mfma_f32_16x16x32_bf16 v[196:199], v[184:187], v[164:167], v[108:111]
	v_mfma_f32_16x16x32_bf16 v[200:203], v[188:191], v[164:167], v[112:115]
	v_mfma_f32_16x16x32_bf16 v[44:47], v[192:195], v[164:167], v[44:47]
	v_mfma_f32_16x16x32_bf16 v[164:167], v[180:183], v[168:171], v[116:119]
	v_mfma_f32_16x16x32_bf16 v[212:215], v[180:183], v[172:175], v[128:131]
	v_mfma_f32_16x16x32_bf16 v[130:133], v[184:187], v[172:175], v[132:135]
	v_mfma_f32_16x16x32_bf16 v[134:137], v[188:191], v[172:175], v[136:139]
	v_mfma_f32_16x16x32_bf16 v[204:207], v[184:187], v[168:171], v[120:123]
	v_mfma_f32_16x16x32_bf16 v[208:211], v[188:191], v[168:171], v[124:127]
	v_mfma_f32_16x16x32_bf16 v[168:171], v[192:195], v[168:171], v[48:51]
	v_mfma_f32_16x16x32_bf16 v[172:175], v[192:195], v[172:175], v[52:55]
	v_mfma_f32_16x16x32_bf16 v[180:183], v[180:183], v[176:179], v[60:63]
	v_mfma_f32_16x16x32_bf16 v[184:187], v[184:187], v[176:179], v[64:67]
	v_mfma_f32_16x16x32_bf16 v[188:191], v[188:191], v[176:179], v[68:71]
	v_mfma_f32_16x16x32_bf16 v[176:179], v[192:195], v[176:179], v[56:59]
	s_nop 0
	ds_read_b128 v[48:51], v0 offset:49152
	ds_read_b128 v[52:55], v0 offset:50176
	ds_read_b128 v[56:59], v0 offset:51200
	ds_read_b128 v[60:63], v0 offset:52224
	ds_read_b128 v[192:195], v0 offset:53248
	ds_read_b128 v[216:219], v0 offset:54272
	ds_read_b128 v[220:223], v0 offset:55296
	ds_read_b128 v[224:227], v0 offset:56320
	ds_read_b128 v[228:231], v19
	ds_read_b128 v[244:247], v20
	ds_read_b128 v[248:251], v21
	ds_read_b128 v[238:241], v22
	s_nop 0
	v_readlane_b32 s4, v254, 25
	v_readlane_b32 s5, v254, 26
	s_waitcnt lgkmcnt(3)
	v_mfma_f32_16x16x32_bf16 v[126:129], v[228:231], v[48:51], v[2:5]
	s_waitcnt lgkmcnt(0)
	s_barrier
; template <int MI, int NI>
; DI void gemm256(f32x4 (&acc)[MI][NI], const u16* __restrict__ A, int lda, const u16* __restrict__ Bt, int ldb, int K, int m0, int n0, char* smem) {
;     ...
;     for (int mi = 0; mi < MI; ++mi)
; #pragma unroll
;       for (int ni = 0; ni < NI; ++ni)
;         acc[mi][ni] = __builtin_amdgcn_mfma_f32_16x16x32_bf16(bfr[ni], af[mi], acc[mi][ni], 0, 0, 0);
; DI void phase_qkv(const Params& p, int l, char* smem) {
;     ...
;       const int nw = n0 + wc * 64;
; #pragma unroll
;       for (int mi = 0; mi < 8; ++mi) {
;         __builtin_amdgcn_sched_barrier(0);
;         const int m = m0 + wr * 128 + mi * 16 + lr;
;         const float rs = rsq[m];
;         if (nw < 512) {
;           const int h = nw >> 6;
;           float ss = 0.f;
; #pragma unroll
;           for (int ni = 0; ni < 4; ++ni)
; #pragma unroll
;             for (int j = 0; j < 4; ++j) { const float v = acc[mi][ni][j] * rs; ss += v * v; }
;           ss += __shfl_xor(ss, 16, 64); ss += __shfl_xor(ss, 32, 64);
;           const float f = rs * rsqrtf(ss * (1.f / 64.f) + 1e-6f) * QS;
;           u16* dst = Qb + qk_index(m, h);
; #pragma unroll
;           for (int ni = 0; ni < 4; ++ni) {
;             const int d = ni * 16 + lq * 4;
;             const float4 g = *(const float4*)(gq + d);
	v_mov_b32_e32 v0, v158
	v_mfma_f32_16x16x32_bf16 v[94:97], v[228:231], v[56:59], v[76:79]
	v_mov_b64_e32 v[2:3], s[4:5]
	v_readlane_b32 s4, v254, 23
	v_readlane_b32 s5, v254, 24
	s_waitcnt lgkmcnt(2)
	v_mfma_f32_16x16x32_bf16 v[90:93], v[244:247], v[56:59], v[80:83]
	v_mov_b32_e32 v4, v159
	v_mfma_f32_16x16x32_bf16 v[78:81], v[228:231], v[60:63], v[140:143]
	s_nop 2
	v_mov_b64_e32 v[142:143], s[4:5]
	v_readlane_b32 s4, v254, 21
	v_mfma_f32_16x16x32_bf16 v[122:125], v[244:247], v[48:51], v[6:9]
	v_readlane_b32 s5, v254, 22
	s_waitcnt lgkmcnt(1)
	v_mfma_f32_16x16x32_bf16 v[118:121], v[248:251], v[48:51], v[10:13]
	s_waitcnt lgkmcnt(0)
	v_mfma_f32_16x16x32_bf16 v[114:117], v[238:241], v[48:51], v[14:17]
	v_mfma_f32_16x16x32_bf16 v[110:113], v[228:231], v[52:55], v[24:27]
	v_mfma_f32_16x16x32_bf16 v[106:109], v[244:247], v[52:55], v[28:31]
	v_mfma_f32_16x16x32_bf16 v[102:105], v[248:251], v[52:55], v[72:75]
	v_mfma_f32_16x16x32_bf16 v[98:101], v[238:241], v[52:55], v[32:35]
	v_mfma_f32_16x16x32_bf16 v[50:53], v[238:241], v[192:195], v[44:47]
	v_mfma_f32_16x16x32_bf16 v[46:49], v[228:231], v[216:219], v[164:167]
	s_nop 2
	v_mov_b32_e32 v166, v160
	v_mov_b32_e32 v164, v161
	v_mfma_f32_16x16x32_bf16 v[26:29], v[244:247], v[220:223], v[130:133]
	v_mfma_f32_16x16x32_bf16 v[86:89], v[248:251], v[56:59], v[84:87]
	v_lshlrev_b32_e32 v138, 2, v164
	s_nop 0
	v_mov_b64_e32 v[130:131], s[4:5]
	v_ashrrev_i32_e32 v139, 31, v138
	v_mfma_f32_16x16x32_bf16 v[82:85], v[238:241], v[56:59], v[36:39]
	v_lshl_add_u32 v167, v4, 6, s1
	v_lshl_add_u64 v[140:141], v[138:139], 2, v[2:3]
	v_lshlrev_b32_e32 v0, 7, v0
	v_mfma_f32_16x16x32_bf16 v[74:77], v[244:247], v[60:63], v[144:147]
	v_mfma_f32_16x16x32_bf16 v[70:73], v[248:251], v[60:63], v[148:151]
	s_nop 1
	v_add3_u32 v144, v166, s0, v0
	s_movk_i32 s0, 0x1ff
	v_add_u32_e32 v0, 0xfffffe00, v167
	v_mfma_f32_16x16x32_bf16 v[66:69], v[238:241], v[60:63], v[40:43]
	v_cmp_lt_i32_e32 vcc, s0, v167
	v_lshrrev_b32_e32 v165, 5, v0
	v_mfma_f32_16x16x32_bf16 v[62:65], v[228:231], v[192:195], v[152:155]
	v_mfma_f32_16x16x32_bf16 v[58:61], v[244:247], v[192:195], v[196:199]
	v_mfma_f32_16x16x32_bf16 v[54:57], v[248:251], v[192:195], v[200:203]
	v_mfma_f32_16x16x32_bf16 v[42:45], v[244:247], v[216:219], v[204:207]
	v_mfma_f32_16x16x32_bf16 v[38:41], v[248:251], v[216:219], v[208:211]
	v_mfma_f32_16x16x32_bf16 v[34:37], v[238:241], v[216:219], v[168:171]
	v_mfma_f32_16x16x32_bf16 v[30:33], v[228:231], v[220:223], v[212:215]
	v_mfma_f32_16x16x32_bf16 v[22:25], v[248:251], v[220:223], v[134:137]
	v_mfma_f32_16x16x32_bf16 v[18:21], v[238:241], v[220:223], v[172:175]
	v_mfma_f32_16x16x32_bf16 v[14:17], v[228:231], v[224:227], v[180:183]
	v_mfma_f32_16x16x32_bf16 v[10:13], v[244:247], v[224:227], v[184:187]
	v_mfma_f32_16x16x32_bf16 v[6:9], v[248:251], v[224:227], v[188:191]
	v_mfma_f32_16x16x32_bf16 v[2:5], v[238:241], v[224:227], v[176:179]
	v_ashrrev_i32_e32 v145, 31, v144
	v_lshl_add_u64 v[146:147], v[144:145], 2, v[130:131]
	flat_load_dword v148, v[146:147]
	s_and_saveexec_b64 s[0:1], vcc
	s_xor_b64 s[6:7], exec, s[0:1]
	s_cbranch_execz .LBB0_570
	v_and_b32_e32 v130, 64, v237
	v_xor_b32_e32 v0, 16, v237
	v_add_u32_e32 v130, 64, v130
	v_cmp_lt_i32_e64 s[4:5], v0, v130
	v_cmp_gt_i32_e64 s[0:1], s58, v144
	v_lshrrev_b32_e32 v145, 6, v144
	v_cndmask_b32_e64 v0, v237, v0, s[4:5]
	v_lshlrev_b32_e32 v168, 2, v0
	v_xor_b32_e32 v0, 32, v237
	v_cmp_lt_i32_e64 s[4:5], v0, v130
	s_nop 1
	v_cndmask_b32_e64 v0, v237, v0, s[4:5]
	v_lshlrev_b32_e32 v169, 2, v0
	s_waitcnt vmcnt(0) lgkmcnt(0)
	v_pk_mul_f32 v[130:131], v[126:127], v[148:149] op_sel_hi:[1,0]
	v_pk_mul_f32 v[132:133], v[128:129], v[148:149] op_sel_hi:[1,0]
	v_pk_mul_f32 v[130:131], v[130:131], v[130:131]
	v_pk_mul_f32 v[132:133], v[132:133], v[132:133]
	v_add_f32_e32 v0, v130, v131
	v_pk_mul_f32 v[134:135], v[122:123], v[148:149] op_sel_hi:[1,0]
	v_add_f32_e32 v0, v132, v0
	v_pk_mul_f32 v[134:135], v[134:135], v[134:135]
	v_add_f32_e32 v0, v133, v0
	v_pk_mul_f32 v[136:137], v[124:125], v[148:149] op_sel_hi:[1,0]
	v_add_f32_e32 v0, v134, v0
	v_pk_mul_f32 v[136:137], v[136:137], v[136:137]
	v_add_f32_e32 v0, v135, v0
	v_add_f32_e32 v0, v136, v0
	v_add_f32_e32 v0, v137, v0
	ds_bpermute_b32 v130, v168, v0
	v_mov_b32_e32 v153, 0
	v_mov_b32_e32 v152, 1.0
	v_mov_b32_e32 v150, 1.0
	v_mov_b32_e32 v151, 0
	s_waitcnt lgkmcnt(0)
	v_add_f32_e32 v149, v0, v130
	flat_load_dwordx4 v[134:137], v[140:141] offset:256
	flat_load_dwordx4 v[130:133], v[140:141] offset:320
	ds_bpermute_b32 v170, v169, v149
	s_and_saveexec_b64 s[8:9], s[0:1]
	s_cbranch_execz .LBB0_555
	v_cmp_gt_i32_e64 s[4:5], 2, v164
	v_and_b32_e32 v150, 4, v138
	s_nop 0
	v_cndmask_b32_e64 v0, v166, v145, s[4:5]
	v_lshlrev_b32_e32 v0, 3, v0
	s_movk_i32 s4, 0x1f8
	v_and_or_b32 v0, v0, s4, v150
	v_lshlrev_b32_e32 v0, 3, v0
	v_lshl_add_u64 v[150:151], v[142:143], 0, v[0:1]
	flat_load_dwordx2 v[150:151], v[150:151]

; template <int MI, int NI>
; DI void gemm256(f32x4 (&acc)[MI][NI], const u16* __restrict__ A, int lda, const u16* __restrict__ Bt, int ldb, int K, int m0, int n0, char* smem) {
;     ...
;   const int srow = lane >> 2, scol = ((lane & 3) ^ ((lane >> 5) << 1)) * 8;
;   const u16* Ag = A + (size_t)(m0 + wave * NAW * 16 + srow) * lda + scol;
;   const u16* Bg = Bt + (size_t)(n0 + wave * NBW * 16 + srow) * ldb + scol;
;   char* la = smem + (wave * NAW) * 1024 + lane * 16;
;   char* lb = smem + ABYTES + (wave * NBW) * 1024 + lane * 16;
;     ...
;   const int nk = K >> 5;
;   G256_ISSUE(0, 0);
;   if (nk > 1) G256_ISSUE(1, 32);
;   const int foff = lr * 64 + ((lq ^ ((lr >> 3) << 1)) * 16);
;   int st = 0;
;   for (int kt = 0; kt < nk; ++kt) {
;     if (kt + 1 < nk) asm volatile("s_waitcnt vmcnt(%0) lgkmcnt(0)" :: "n"(LPS) : "memory");
;     else asm volatile("s_waitcnt vmcnt(0) lgkmcnt(0)" ::: "memory");
;     __builtin_amdgcn_s_barrier();
;     __builtin_amdgcn_s_setprio(1);
;     const char* sb = smem + st * STAGE + foff;
;     bf16x8 af[MI], bfr[NI];
; #pragma unroll
;     for (int mi = 0; mi < MI; ++mi) af[mi] = *(const bf16x8*)(sb + (wr * MI + mi) * 1024);
; #pragma unroll
;     for (int ni = 0; ni < NI; ++ni) bfr[ni] = *(const bf16x8*)(sb + ABYTES + (wc * NI + ni) * 1024);
;     __builtin_amdgcn_sched_barrier(0x0);
;     if (kt + 2 < nk) { const int s2 = st >= 1 ? st - 1 : 2; G256_ISSUE(s2, (kt + 2) * 32); }
;     __builtin_amdgcn_s_setprio(0);
; #pragma unroll
;     for (int mi = 0; mi < MI; ++mi)
; #pragma unroll
;       for (int ni = 0; ni < NI; ++ni)
;         acc[mi][ni] = __builtin_amdgcn_mfma_f32_16x16x32_bf16(bfr[ni], af[mi], acc[mi][ni], 0, 0, 0);
.LBB0_721:
	s_waitcnt vmcnt(0)
	v_mov_b32_e32 v7, v163
	s_mov_b32 s0, s2
	v_lshlrev_b32_e32 v6, 8, v145
	v_and_b32_e32 v0, 3, v7
	v_lshrrev_b32_e32 v2, 4, v7
	v_bitop3_b32 v0, v2, v0, 2 bitop3:0x6c
	v_and_b32_e32 v2, 0xffffffc0, v7
	v_readlane_b32 s0, v254, 35
	s_waitcnt lgkmcnt(0)
	v_lshlrev_b32_e32 v4, 7, v148
	v_ashrrev_i32_e32 v9, 6, v7
	v_bfe_u32 v5, v7, 2, 4
	v_add_u32_e32 v2, v2, v6
	v_readlane_b32 s1, v254, 36
	v_and_b32_e32 v8, 63, v7
	v_or_b32_e32 v10, v2, v5
	v_mov_b64_e32 v[2:3], s[0:1]
	s_movk_i32 s0, 0x740
	v_lshl_add_u32 v4, v9, 5, v4
	v_mad_i64_i32 v[2:3], s[0:1], v10, s0, v[2:3]
	v_or_b32_e32 v4, v4, v5
	v_lshlrev_b32_e32 v40, 12, v9
	v_lshlrev_b32_e32 v8, 4, v8
	v_ashrrev_i32_e32 v5, 31, v4
	v_readlane_b32 s0, v254, 37
	v_or_b32_e32 v58, v40, v8
	v_lshlrev_b32_e32 v0, 4, v0
	v_lshlrev_b64 v[4:5], 9, v[4:5]
	v_readlane_b32 s1, v254, 38
	v_readfirstlane_b32 s9, v58
	v_or_b32_e32 v11, 0x400, v58
	v_lshl_add_u64 v[2:3], v[2:3], 0, v[0:1]
	v_lshl_add_u64 v[4:5], s[0:1], 0, v[4:5]
	s_mov_b32 m0, s9
	s_mov_b64 s[0:1], 0x7400
	v_readfirstlane_b32 s8, v11
	v_or_b32_e32 v11, 0x800, v58
	v_lshl_or_b32 v59, v9, 11, v8
	global_load_lds_dwordx4 v[2:3], off
	v_lshl_add_u64 v[8:9], v[2:3], 0, s[0:1]
	s_mov_b32 m0, s8
	s_mov_b64 s[0:1], 0xe800
	v_readfirstlane_b32 s12, v11
	v_or_b32_e32 v11, 0xc00, v58
	v_add_u32_e32 v10, 0x4000, v59
	global_load_lds_dwordx4 v[8:9], off
	v_lshl_add_u64 v[8:9], v[2:3], 0, s[0:1]
	s_mov_b32 m0, s12
	s_mov_b64 s[0:1], 0x15c00
	v_readfirstlane_b32 s13, v11
	global_load_lds_dwordx4 v[8:9], off
	v_lshl_add_u64 v[8:9], v[2:3], 0, s[0:1]
	s_mov_b32 m0, s13
	v_lshl_add_u64 v[4:5], v[4:5], 0, v[0:1]
	v_readfirstlane_b32 s14, v10
	v_add_u32_e32 v0, 0x4400, v59
	global_load_lds_dwordx4 v[8:9], off
	s_mov_b32 m0, s14
	s_mov_b64 s[0:1], 0x2000
	v_readfirstlane_b32 s15, v0
	v_add_u32_e32 v0, 0x6000, v58
	global_load_lds_dwordx4 v[4:5], off
	v_lshl_add_u64 v[8:9], v[4:5], 0, s[0:1]
	s_mov_b32 m0, s15
	v_readfirstlane_b32 s1, v0
	v_add_u32_e32 v0, 0x6400, v58
	global_load_lds_dwordx4 v[8:9], off
	v_lshl_add_u64 v[8:9], v[2:3], 0, 64
	s_mov_b32 m0, s1
	s_mov_b64 s[4:5], 0x7440
	v_readfirstlane_b32 s0, v0
	global_load_lds_dwordx4 v[8:9], off
	v_lshl_add_u64 v[8:9], v[2:3], 0, s[4:5]
	s_mov_b32 m0, s0
	s_mov_b64 s[4:5], 0xe840
	v_add_u32_e32 v0, 0x6800, v58
	global_load_lds_dwordx4 v[8:9], off
	v_lshl_add_u64 v[8:9], v[2:3], 0, s[4:5]
	v_readfirstlane_b32 s4, v0
	v_add_u32_e32 v0, 0x6c00, v58
	s_mov_b32 m0, s4
	s_mov_b64 s[6:7], 0x15c40
	v_readfirstlane_b32 s5, v0
	v_add_u32_e32 v0, 0xa000, v59
	global_load_lds_dwordx4 v[8:9], off
	v_lshl_add_u64 v[8:9], v[2:3], 0, s[6:7]
	s_mov_b32 m0, s5
	v_readfirstlane_b32 s6, v0
	v_add_u32_e32 v0, 0xa400, v59
	global_load_lds_dwordx4 v[8:9], off
	v_lshl_add_u64 v[8:9], v[4:5], 0, 64
	s_mov_b32 m0, s6
	s_mov_b64 s[16:17], 0x2040
	v_readfirstlane_b32 s7, v0
	global_load_lds_dwordx4 v[8:9], off
	v_lshl_add_u64 v[8:9], v[4:5], 0, s[16:17]
	s_mov_b32 m0, s7
	v_lshlrev_b32_e32 v0, 6, v7
	global_load_lds_dwordx4 v[8:9], off
	v_lshlrev_b32_e32 v8, 2, v7
	v_and_b32_e32 v7, 48, v7
	s_waitcnt vmcnt(6) lgkmcnt(0)
	v_bitop3_b32 v7, v8, v7, 32 bitop3:0x6c
	v_and_or_b32 v7, v0, s59, v7
	s_barrier
	s_nop 0
	v_and_or_b32 v0, v0, s46, v7
	ds_read_b128 v[8:11], v0
	ds_read_b128 v[12:15], v0 offset:1024
	ds_read_b128 v[16:19], v0 offset:2048
	ds_read_b128 v[20:23], v0 offset:3072
	ds_read_b128 v[24:27], v0 offset:4096
	ds_read_b128 v[28:31], v0 offset:5120
	ds_read_b128 v[32:35], v0 offset:6144
	ds_read_b128 v[36:39], v0 offset:7168
	v_and_or_b32 v7, v40, s97, v7
	ds_read_b128 v[40:43], v7 offset:16384
	ds_read_b128 v[44:47], v7 offset:17408
	ds_read_b128 v[48:51], v7 offset:18432
	ds_read_b128 v[52:55], v7 offset:19456
	v_add_u32_e32 v60, 0xc000, v58
	s_mov_b64 s[20:21], 0x80
	v_readfirstlane_b32 s17, v60
	v_add_u32_e32 v60, 0xc400, v58
	v_lshl_add_u64 v[56:57], v[2:3], 0, s[20:21]
	s_mov_b32 m0, s17
	s_mov_b64 s[18:19], 0x7480
	v_readfirstlane_b32 s16, v60
	global_load_lds_dwordx4 v[56:57], off
	v_lshl_add_u64 v[56:57], v[2:3], 0, s[18:19]
	s_mov_b32 m0, s16
	s_mov_b64 s[18:19], 0xe880
	v_add_u32_e32 v60, 0xc800, v58
	global_load_lds_dwordx4 v[56:57], off
	v_lshl_add_u64 v[56:57], v[2:3], 0, s[18:19]
	v_readfirstlane_b32 s18, v60
	v_add_u32_e32 v58, 0xcc00, v58
	s_mov_b32 m0, s18
	s_mov_b64 s[22:23], 0x15c80
	v_readfirstlane_b32 s19, v58
	global_load_lds_dwordx4 v[56:57], off
	v_lshl_add_u64 v[56:57], v[2:3], 0, s[22:23]
	s_mov_b32 m0, s19
	v_add_u32_e32 v58, 0x10000, v59
	global_load_lds_dwordx4 v[56:57], off
	v_lshl_add_u64 v[56:57], v[4:5], 0, s[20:21]
	v_readfirstlane_b32 s20, v58
	v_add_u32_e32 v58, 0x10400, v59
	s_mov_b32 m0, s20
	s_mov_b64 s[22:23], 0x2080
	v_readfirstlane_b32 s21, v58
	global_load_lds_dwordx4 v[56:57], off
	v_lshl_add_u64 v[56:57], v[4:5], 0, s[22:23]
	s_mov_b32 m0, s21
	s_nop 0
	global_load_lds_dwordx4 v[56:57], off
	s_nop 0
	s_waitcnt lgkmcnt(0)
	v_mfma_f32_16x16x32_bf16 v[56:59], v[40:43], v[8:11], 0
	s_waitcnt vmcnt(6) lgkmcnt(0)
	s_barrier
; template <int MI, int NI>
; DI void gemm256(f32x4 (&acc)[MI][NI], const u16* __restrict__ A, int lda, const u16* __restrict__ Bt, int ldb, int K, int m0, int n0, char* smem) {
;     ...
;     const char* sb = smem + st * STAGE + foff;
;     bf16x8 af[MI], bfr[NI];
; #pragma unroll
;     for (int mi = 0; mi < MI; ++mi) af[mi] = *(const bf16x8*)(sb + (wr * MI + mi) * 1024);
; #pragma unroll
;     for (int ni = 0; ni < NI; ++ni) bfr[ni] = *(const bf16x8*)(sb + ABYTES + (wc * NI + ni) * 1024);
;     __builtin_amdgcn_sched_barrier(0x0);
;     if (kt + 2 < nk) { const int s2 = st >= 1 ? st - 1 : 2; G256_ISSUE(s2, (kt + 2) * 32); }
;     __builtin_amdgcn_s_setprio(0);
; #pragma unroll
;     for (int mi = 0; mi < MI; ++mi)
; #pragma unroll
;       for (int ni = 0; ni < NI; ++ni)
;         acc[mi][ni] = __builtin_amdgcn_mfma_f32_16x16x32_bf16(bfr[ni], af[mi], acc[mi][ni], 0, 0, 0);
	v_mfma_f32_16x16x32_bf16 v[60:63], v[44:47], v[8:11], 0
	v_mfma_f32_16x16x32_bf16 v[64:67], v[48:51], v[8:11], 0
	v_mfma_f32_16x16x32_bf16 v[8:11], v[52:55], v[8:11], 0
	v_mfma_f32_16x16x32_bf16 v[68:71], v[40:43], v[12:15], 0
	v_mfma_f32_16x16x32_bf16 v[72:75], v[44:47], v[12:15], 0
	v_mfma_f32_16x16x32_bf16 v[76:79], v[48:51], v[12:15], 0
	v_mfma_f32_16x16x32_bf16 v[12:15], v[52:55], v[12:15], 0
	v_mfma_f32_16x16x32_bf16 v[80:83], v[40:43], v[16:19], 0
	v_mfma_f32_16x16x32_bf16 v[84:87], v[44:47], v[16:19], 0
	v_mfma_f32_16x16x32_bf16 v[88:91], v[48:51], v[16:19], 0
	v_mfma_f32_16x16x32_bf16 v[16:19], v[52:55], v[16:19], 0
	v_mfma_f32_16x16x32_bf16 v[92:95], v[40:43], v[20:23], 0
	v_mfma_f32_16x16x32_bf16 v[96:99], v[44:47], v[20:23], 0
	v_mfma_f32_16x16x32_bf16 v[100:103], v[48:51], v[20:23], 0
	v_mfma_f32_16x16x32_bf16 v[20:23], v[52:55], v[20:23], 0
	v_mfma_f32_16x16x32_bf16 v[104:107], v[40:43], v[24:27], 0
	v_mfma_f32_16x16x32_bf16 v[108:111], v[44:47], v[24:27], 0
	v_mfma_f32_16x16x32_bf16 v[112:115], v[48:51], v[24:27], 0
	v_mfma_f32_16x16x32_bf16 v[24:27], v[52:55], v[24:27], 0
	v_mfma_f32_16x16x32_bf16 v[116:119], v[40:43], v[28:31], 0
	v_mfma_f32_16x16x32_bf16 v[120:123], v[44:47], v[28:31], 0
	v_mfma_f32_16x16x32_bf16 v[124:127], v[48:51], v[28:31], 0
	v_mfma_f32_16x16x32_bf16 v[28:31], v[52:55], v[28:31], 0
	v_mfma_f32_16x16x32_bf16 v[128:131], v[40:43], v[32:35], 0
	v_mfma_f32_16x16x32_bf16 v[132:135], v[44:47], v[32:35], 0
	v_mfma_f32_16x16x32_bf16 v[136:139], v[48:51], v[32:35], 0
	v_mfma_f32_16x16x32_bf16 v[32:35], v[52:55], v[32:35], 0
	v_mfma_f32_16x16x32_bf16 v[40:43], v[40:43], v[36:39], 0
	v_mfma_f32_16x16x32_bf16 v[44:47], v[44:47], v[36:39], 0
	v_mfma_f32_16x16x32_bf16 v[48:51], v[48:51], v[36:39], 0
	v_mfma_f32_16x16x32_bf16 v[36:39], v[52:55], v[36:39], 0
	s_nop 0
	ds_read_b128 v[52:55], v0 offset:24576
	ds_read_b128 v[140:143], v0 offset:25600
	ds_read_b128 v[150:153], v0 offset:26624
	ds_read_b128 v[154:157], v0 offset:27648
	ds_read_b128 v[164:167], v0 offset:28672
	ds_read_b128 v[168:171], v0 offset:29696
	ds_read_b128 v[172:175], v0 offset:30720
	ds_read_b128 v[176:179], v0 offset:31744
	ds_read_b128 v[180:183], v7 offset:40960
	ds_read_b128 v[184:187], v7 offset:41984
	ds_read_b128 v[188:191], v7 offset:43008
	ds_read_b128 v[192:195], v7 offset:44032
	s_mov_b64 s[22:23], 0xc0
	s_mov_b32 m0, s9
	v_lshl_add_u64 v[146:147], v[2:3], 0, s[22:23]
	s_mov_b64 s[24:25], 0x74c0
	global_load_lds_dwordx4 v[146:147], off
	v_lshl_add_u64 v[146:147], v[2:3], 0, s[24:25]
	s_mov_b32 m0, s8
	s_mov_b64 s[24:25], 0xe8c0
	global_load_lds_dwordx4 v[146:147], off
	v_lshl_add_u64 v[146:147], v[2:3], 0, s[24:25]
	s_mov_b32 m0, s12
	s_mov_b64 s[24:25], 0x15cc0
	global_load_lds_dwordx4 v[146:147], off
	v_lshl_add_u64 v[146:147], v[2:3], 0, s[24:25]
	s_mov_b32 m0, s13
	s_nop 0
	global_load_lds_dwordx4 v[146:147], off
	v_lshl_add_u64 v[146:147], v[4:5], 0, s[22:23]
	s_mov_b32 m0, s14
	s_mov_b64 s[22:23], 0x20c0
	global_load_lds_dwordx4 v[146:147], off
	v_lshl_add_u64 v[146:147], v[4:5], 0, s[22:23]
	s_mov_b32 m0, s15
	s_nop 0
	global_load_lds_dwordx4 v[146:147], off
	s_nop 0
	s_waitcnt lgkmcnt(0)
	v_mfma_f32_16x16x32_bf16 v[56:59], v[180:183], v[52:55], v[56:59]
	s_waitcnt vmcnt(6) lgkmcnt(0)
	s_barrier
	v_mfma_f32_16x16x32_bf16 v[60:63], v[184:187], v[52:55], v[60:63]
	v_mfma_f32_16x16x32_bf16 v[64:67], v[188:191], v[52:55], v[64:67]
	v_mfma_f32_16x16x32_bf16 v[8:11], v[192:195], v[52:55], v[8:11]
	v_mfma_f32_16x16x32_bf16 v[52:55], v[180:183], v[140:143], v[68:71]
	v_mfma_f32_16x16x32_bf16 v[68:71], v[184:187], v[140:143], v[72:75]
	v_mfma_f32_16x16x32_bf16 v[72:75], v[188:191], v[140:143], v[76:79]
	v_mfma_f32_16x16x32_bf16 v[12:15], v[192:195], v[140:143], v[12:15]
	v_mfma_f32_16x16x32_bf16 v[76:79], v[180:183], v[150:153], v[80:83]
	v_mfma_f32_16x16x32_bf16 v[80:83], v[184:187], v[150:153], v[84:87]
	v_mfma_f32_16x16x32_bf16 v[84:87], v[188:191], v[150:153], v[88:91]
	v_mfma_f32_16x16x32_bf16 v[16:19], v[192:195], v[150:153], v[16:19]
	v_mfma_f32_16x16x32_bf16 v[88:91], v[180:183], v[154:157], v[92:95]
	v_mfma_f32_16x16x32_bf16 v[92:95], v[184:187], v[154:157], v[96:99]
	v_mfma_f32_16x16x32_bf16 v[96:99], v[188:191], v[154:157], v[100:103]
	v_mfma_f32_16x16x32_bf16 v[20:23], v[192:195], v[154:157], v[20:23]
	v_mfma_f32_16x16x32_bf16 v[100:103], v[180:183], v[164:167], v[104:107]
	v_mfma_f32_16x16x32_bf16 v[104:107], v[184:187], v[164:167], v[108:111]
	v_mfma_f32_16x16x32_bf16 v[108:111], v[188:191], v[164:167], v[112:115]
	v_mfma_f32_16x16x32_bf16 v[24:27], v[192:195], v[164:167], v[24:27]
	v_mfma_f32_16x16x32_bf16 v[112:115], v[180:183], v[168:171], v[116:119]
	v_mfma_f32_16x16x32_bf16 v[116:119], v[184:187], v[168:171], v[120:123]
	v_mfma_f32_16x16x32_bf16 v[120:123], v[188:191], v[168:171], v[124:127]
	v_mfma_f32_16x16x32_bf16 v[28:31], v[192:195], v[168:171], v[28:31]
	v_mfma_f32_16x16x32_bf16 v[124:127], v[180:183], v[172:175], v[128:131]
	v_mfma_f32_16x16x32_bf16 v[128:131], v[184:187], v[172:175], v[132:135]
	v_mfma_f32_16x16x32_bf16 v[132:135], v[188:191], v[172:175], v[136:139]
	v_mfma_f32_16x16x32_bf16 v[32:35], v[192:195], v[172:175], v[32:35]
	v_mfma_f32_16x16x32_bf16 v[40:43], v[180:183], v[176:179], v[40:43]
	v_mfma_f32_16x16x32_bf16 v[44:47], v[184:187], v[176:179], v[44:47]
	v_mfma_f32_16x16x32_bf16 v[48:51], v[188:191], v[176:179], v[48:51]
	v_mfma_f32_16x16x32_bf16 v[36:39], v[192:195], v[176:179], v[36:39]
	s_nop 0
	ds_read_b128 v[136:139], v0 offset:49152
	ds_read_b128 v[140:143], v0 offset:50176
	ds_read_b128 v[150:153], v0 offset:51200
	ds_read_b128 v[154:157], v0 offset:52224
	ds_read_b128 v[164:167], v0 offset:53248
	ds_read_b128 v[168:171], v0 offset:54272
	ds_read_b128 v[172:175], v0 offset:55296
	ds_read_b128 v[176:179], v0 offset:56320
	v_or_b32_e32 v144, 0x10000, v7
	v_or_b32_e32 v196, 0x10800, v7
	v_or_b32_e32 v149, 0x10400, v7
	ds_read_b128 v[180:183], v144
	ds_read_b128 v[184:187], v149
	v_or_b32_e32 v197, 0x10c00, v7
	ds_read_b128 v[188:191], v196
	ds_read_b128 v[192:195], v197
	s_mov_b64 s[22:23], 0x100
	s_mov_b32 m0, s1
	v_lshl_add_u64 v[146:147], v[2:3], 0, s[22:23]
	s_mov_b64 s[24:25], 0x7500
	global_load_lds_dwordx4 v[146:147], off
	v_lshl_add_u64 v[146:147], v[2:3], 0, s[24:25]
	s_mov_b32 m0, s0
	s_mov_b64 s[24:25], 0xe900
	global_load_lds_dwordx4 v[146:147], off
	v_lshl_add_u64 v[146:147], v[2:3], 0, s[24:25]
	s_mov_b32 m0, s4
	s_mov_b64 s[24:25], 0x15d00
	global_load_lds_dwordx4 v[146:147], off
	v_lshl_add_u64 v[146:147], v[2:3], 0, s[24:25]
	s_mov_b32 m0, s5
	s_mov_b64 s[50:51], 0x100
	global_load_lds_dwordx4 v[146:147], off
	v_lshl_add_u64 v[146:147], v[4:5], 0, s[22:23]
	s_mov_b32 m0, s6
	s_mov_b64 s[22:23], 0x2100
	global_load_lds_dwordx4 v[146:147], off
	v_lshl_add_u64 v[146:147], v[4:5], 0, s[22:23]
	s_mov_b32 m0, s7
	s_nop 0
	global_load_lds_dwordx4 v[146:147], off
	s_nop 0
	s_waitcnt lgkmcnt(0)
	v_mfma_f32_16x16x32_bf16 v[56:59], v[180:183], v[136:139], v[56:59]
	s_waitcnt vmcnt(6) lgkmcnt(0)
	s_barrier
; template <int MI, int NI>
; DI void gemm256(f32x4 (&acc)[MI][NI], const u16* __restrict__ A, int lda, const u16* __restrict__ Bt, int ldb, int K, int m0, int n0, char* smem) {
;     ...
;     const char* sb = smem + st * STAGE + foff;
;     bf16x8 af[MI], bfr[NI];
; #pragma unroll
;     for (int mi = 0; mi < MI; ++mi) af[mi] = *(const bf16x8*)(sb + (wr * MI + mi) * 1024);
; #pragma unroll
;     for (int ni = 0; ni < NI; ++ni) bfr[ni] = *(const bf16x8*)(sb + ABYTES + (wc * NI + ni) * 1024);
;     __builtin_amdgcn_sched_barrier(0x0);
;     if (kt + 2 < nk) { const int s2 = st >= 1 ? st - 1 : 2; G256_ISSUE(s2, (kt + 2) * 32); }
;     __builtin_amdgcn_s_setprio(0);
; #pragma unroll
;     for (int mi = 0; mi < MI; ++mi)
; #pragma unroll
;       for (int ni = 0; ni < NI; ++ni)
;         acc[mi][ni] = __builtin_amdgcn_mfma_f32_16x16x32_bf16(bfr[ni], af[mi], acc[mi][ni], 0, 0, 0);
	v_mfma_f32_16x16x32_bf16 v[60:63], v[184:187], v[136:139], v[60:63]
	v_mfma_f32_16x16x32_bf16 v[64:67], v[188:191], v[136:139], v[64:67]
	v_mfma_f32_16x16x32_bf16 v[8:11], v[192:195], v[136:139], v[8:11]
	v_mfma_f32_16x16x32_bf16 v[52:55], v[180:183], v[140:143], v[52:55]
	v_mfma_f32_16x16x32_bf16 v[68:71], v[184:187], v[140:143], v[68:71]
	v_mfma_f32_16x16x32_bf16 v[72:75], v[188:191], v[140:143], v[72:75]
	v_mfma_f32_16x16x32_bf16 v[12:15], v[192:195], v[140:143], v[12:15]
	v_mfma_f32_16x16x32_bf16 v[76:79], v[180:183], v[150:153], v[76:79]
	v_mfma_f32_16x16x32_bf16 v[80:83], v[184:187], v[150:153], v[80:83]
	v_mfma_f32_16x16x32_bf16 v[84:87], v[188:191], v[150:153], v[84:87]
	v_mfma_f32_16x16x32_bf16 v[16:19], v[192:195], v[150:153], v[16:19]
	v_mfma_f32_16x16x32_bf16 v[88:91], v[180:183], v[154:157], v[88:91]
	v_mfma_f32_16x16x32_bf16 v[92:95], v[184:187], v[154:157], v[92:95]
	v_mfma_f32_16x16x32_bf16 v[96:99], v[188:191], v[154:157], v[96:99]
	v_mfma_f32_16x16x32_bf16 v[20:23], v[192:195], v[154:157], v[20:23]
	v_mfma_f32_16x16x32_bf16 v[100:103], v[180:183], v[164:167], v[100:103]
	v_mfma_f32_16x16x32_bf16 v[104:107], v[184:187], v[164:167], v[104:107]
	v_mfma_f32_16x16x32_bf16 v[108:111], v[188:191], v[164:167], v[108:111]
	v_mfma_f32_16x16x32_bf16 v[24:27], v[192:195], v[164:167], v[24:27]
	v_mfma_f32_16x16x32_bf16 v[112:115], v[180:183], v[168:171], v[112:115]
	v_mfma_f32_16x16x32_bf16 v[116:119], v[184:187], v[168:171], v[116:119]
	v_mfma_f32_16x16x32_bf16 v[120:123], v[188:191], v[168:171], v[120:123]
	v_mfma_f32_16x16x32_bf16 v[28:31], v[192:195], v[168:171], v[28:31]
	v_mfma_f32_16x16x32_bf16 v[124:127], v[180:183], v[172:175], v[124:127]
	v_mfma_f32_16x16x32_bf16 v[128:131], v[184:187], v[172:175], v[128:131]
	v_mfma_f32_16x16x32_bf16 v[132:135], v[188:191], v[172:175], v[132:135]
	v_mfma_f32_16x16x32_bf16 v[32:35], v[192:195], v[172:175], v[32:35]
	v_mfma_f32_16x16x32_bf16 v[40:43], v[180:183], v[176:179], v[40:43]
	v_mfma_f32_16x16x32_bf16 v[44:47], v[184:187], v[176:179], v[44:47]
	v_mfma_f32_16x16x32_bf16 v[48:51], v[188:191], v[176:179], v[48:51]
	v_mfma_f32_16x16x32_bf16 v[36:39], v[192:195], v[176:179], v[36:39]
	s_nop 0
	ds_read_b128 v[136:139], v0
	ds_read_b128 v[140:143], v0 offset:1024
	ds_read_b128 v[150:153], v0 offset:2048
	ds_read_b128 v[154:157], v0 offset:3072
	ds_read_b128 v[164:167], v0 offset:4096
	ds_read_b128 v[168:171], v0 offset:5120
	ds_read_b128 v[172:175], v0 offset:6144
	ds_read_b128 v[176:179], v0 offset:7168
	ds_read_b128 v[180:183], v7 offset:16384
	ds_read_b128 v[184:187], v7 offset:17408
	ds_read_b128 v[188:191], v7 offset:18432
	ds_read_b128 v[192:195], v7 offset:19456
	s_mov_b64 s[22:23], 0x140
	s_mov_b32 m0, s17
	v_lshl_add_u64 v[146:147], v[2:3], 0, s[22:23]
	s_mov_b64 s[24:25], 0x7540
	global_load_lds_dwordx4 v[146:147], off
	v_lshl_add_u64 v[146:147], v[2:3], 0, s[24:25]
	s_mov_b32 m0, s16
	s_mov_b64 s[16:17], 0xe940
	global_load_lds_dwordx4 v[146:147], off
	v_lshl_add_u64 v[146:147], v[2:3], 0, s[16:17]
	s_mov_b32 m0, s18
	s_mov_b64 s[16:17], 0x15d40
	global_load_lds_dwordx4 v[146:147], off
	v_lshl_add_u64 v[146:147], v[2:3], 0, s[16:17]
	s_mov_b32 m0, s19
	s_mov_b64 s[16:17], 0x2140
	global_load_lds_dwordx4 v[146:147], off
	v_lshl_add_u64 v[146:147], v[4:5], 0, s[22:23]
	s_mov_b32 m0, s20
	s_nop 0
	global_load_lds_dwordx4 v[146:147], off
	v_lshl_add_u64 v[146:147], v[4:5], 0, s[16:17]
	s_mov_b32 m0, s21
	s_nop 0
	global_load_lds_dwordx4 v[146:147], off
	s_nop 0
	s_waitcnt lgkmcnt(0)
	v_mfma_f32_16x16x32_bf16 v[56:59], v[180:183], v[136:139], v[56:59]
	s_waitcnt vmcnt(6) lgkmcnt(0)
	s_barrier
	v_mfma_f32_16x16x32_bf16 v[60:63], v[184:187], v[136:139], v[60:63]
	v_mfma_f32_16x16x32_bf16 v[64:67], v[188:191], v[136:139], v[64:67]
	v_mfma_f32_16x16x32_bf16 v[8:11], v[192:195], v[136:139], v[8:11]
	v_mfma_f32_16x16x32_bf16 v[52:55], v[180:183], v[140:143], v[52:55]
	v_mfma_f32_16x16x32_bf16 v[68:71], v[184:187], v[140:143], v[68:71]
	v_mfma_f32_16x16x32_bf16 v[72:75], v[188:191], v[140:143], v[72:75]
	v_mfma_f32_16x16x32_bf16 v[12:15], v[192:195], v[140:143], v[12:15]
	v_mfma_f32_16x16x32_bf16 v[76:79], v[180:183], v[150:153], v[76:79]
	v_mfma_f32_16x16x32_bf16 v[80:83], v[184:187], v[150:153], v[80:83]
	v_mfma_f32_16x16x32_bf16 v[84:87], v[188:191], v[150:153], v[84:87]
	v_mfma_f32_16x16x32_bf16 v[16:19], v[192:195], v[150:153], v[16:19]
	v_mfma_f32_16x16x32_bf16 v[88:91], v[180:183], v[154:157], v[88:91]
	v_mfma_f32_16x16x32_bf16 v[92:95], v[184:187], v[154:157], v[92:95]
	v_mfma_f32_16x16x32_bf16 v[96:99], v[188:191], v[154:157], v[96:99]
	v_mfma_f32_16x16x32_bf16 v[20:23], v[192:195], v[154:157], v[20:23]
	v_mfma_f32_16x16x32_bf16 v[100:103], v[180:183], v[164:167], v[100:103]
	v_mfma_f32_16x16x32_bf16 v[104:107], v[184:187], v[164:167], v[104:107]
	v_mfma_f32_16x16x32_bf16 v[108:111], v[188:191], v[164:167], v[108:111]
	v_mfma_f32_16x16x32_bf16 v[24:27], v[192:195], v[164:167], v[24:27]
	v_mfma_f32_16x16x32_bf16 v[112:115], v[180:183], v[168:171], v[112:115]
	v_mfma_f32_16x16x32_bf16 v[116:119], v[184:187], v[168:171], v[116:119]
	v_mfma_f32_16x16x32_bf16 v[120:123], v[188:191], v[168:171], v[120:123]
	v_mfma_f32_16x16x32_bf16 v[28:31], v[192:195], v[168:171], v[28:31]
	v_mfma_f32_16x16x32_bf16 v[124:127], v[180:183], v[172:175], v[124:127]
	v_mfma_f32_16x16x32_bf16 v[128:131], v[184:187], v[172:175], v[128:131]
	v_mfma_f32_16x16x32_bf16 v[132:135], v[188:191], v[172:175], v[132:135]
	v_mfma_f32_16x16x32_bf16 v[32:35], v[192:195], v[172:175], v[32:35]
	v_mfma_f32_16x16x32_bf16 v[40:43], v[180:183], v[176:179], v[40:43]
	v_mfma_f32_16x16x32_bf16 v[44:47], v[184:187], v[176:179], v[44:47]
; template <int MI, int NI>
; DI void gemm256(f32x4 (&acc)[MI][NI], const u16* __restrict__ A, int lda, const u16* __restrict__ Bt, int ldb, int K, int m0, int n0, char* smem) {
;     ...
;     const char* sb = smem + st * STAGE + foff;
;     bf16x8 af[MI], bfr[NI];
; #pragma unroll
;     for (int mi = 0; mi < MI; ++mi) af[mi] = *(const bf16x8*)(sb + (wr * MI + mi) * 1024);
; #pragma unroll
;     for (int ni = 0; ni < NI; ++ni) bfr[ni] = *(const bf16x8*)(sb + ABYTES + (wc * NI + ni) * 1024);
;     __builtin_amdgcn_sched_barrier(0x0);
;     if (kt + 2 < nk) { const int s2 = st >= 1 ? st - 1 : 2; G256_ISSUE(s2, (kt + 2) * 32); }
;     __builtin_amdgcn_s_setprio(0);
; #pragma unroll
;     for (int mi = 0; mi < MI; ++mi)
; #pragma unroll
;       for (int ni = 0; ni < NI; ++ni)
;         acc[mi][ni] = __builtin_amdgcn_mfma_f32_16x16x32_bf16(bfr[ni], af[mi], acc[mi][ni], 0, 0, 0);
	v_mfma_f32_16x16x32_bf16 v[48:51], v[188:191], v[176:179], v[48:51]
	v_mfma_f32_16x16x32_bf16 v[36:39], v[192:195], v[176:179], v[36:39]
	s_nop 0
	ds_read_b128 v[136:139], v0 offset:24576
	ds_read_b128 v[140:143], v0 offset:25600
	ds_read_b128 v[150:153], v0 offset:26624
	ds_read_b128 v[154:157], v0 offset:27648
	ds_read_b128 v[164:167], v0 offset:28672
	ds_read_b128 v[168:171], v0 offset:29696
	ds_read_b128 v[172:175], v0 offset:30720
	ds_read_b128 v[176:179], v0 offset:31744
	ds_read_b128 v[180:183], v7 offset:40960
	ds_read_b128 v[184:187], v7 offset:41984
	ds_read_b128 v[188:191], v7 offset:43008
	ds_read_b128 v[192:195], v7 offset:44032
	s_mov_b64 s[16:17], 0x180
	s_mov_b32 m0, s9
	v_lshl_add_u64 v[146:147], v[2:3], 0, s[16:17]
	s_mov_b64 s[18:19], 0x7580
	global_load_lds_dwordx4 v[146:147], off
	v_lshl_add_u64 v[146:147], v[2:3], 0, s[18:19]
	s_mov_b32 m0, s8
	s_mov_b64 s[8:9], 0xe980
	global_load_lds_dwordx4 v[146:147], off
	v_lshl_add_u64 v[146:147], v[2:3], 0, s[8:9]
	s_mov_b32 m0, s12
	s_mov_b64 s[8:9], 0x15d80
	global_load_lds_dwordx4 v[146:147], off
	v_lshl_add_u64 v[146:147], v[2:3], 0, s[8:9]
	s_mov_b32 m0, s13
	s_mov_b64 s[8:9], 0x2180
	global_load_lds_dwordx4 v[146:147], off
	v_lshl_add_u64 v[146:147], v[4:5], 0, s[16:17]
	s_mov_b32 m0, s14
	s_nop 0
	global_load_lds_dwordx4 v[146:147], off
	v_lshl_add_u64 v[146:147], v[4:5], 0, s[8:9]
	s_mov_b32 m0, s15
	s_nop 0
	global_load_lds_dwordx4 v[146:147], off
	s_nop 0
	s_waitcnt lgkmcnt(0)
	v_mfma_f32_16x16x32_bf16 v[56:59], v[180:183], v[136:139], v[56:59]
	s_waitcnt vmcnt(6) lgkmcnt(0)
	s_barrier
	v_mfma_f32_16x16x32_bf16 v[60:63], v[184:187], v[136:139], v[60:63]
	v_mfma_f32_16x16x32_bf16 v[64:67], v[188:191], v[136:139], v[64:67]
	v_mfma_f32_16x16x32_bf16 v[8:11], v[192:195], v[136:139], v[8:11]
	v_mfma_f32_16x16x32_bf16 v[52:55], v[180:183], v[140:143], v[52:55]
	v_mfma_f32_16x16x32_bf16 v[68:71], v[184:187], v[140:143], v[68:71]
	v_mfma_f32_16x16x32_bf16 v[72:75], v[188:191], v[140:143], v[72:75]
	v_mfma_f32_16x16x32_bf16 v[12:15], v[192:195], v[140:143], v[12:15]
	v_mfma_f32_16x16x32_bf16 v[76:79], v[180:183], v[150:153], v[76:79]
	v_mfma_f32_16x16x32_bf16 v[80:83], v[184:187], v[150:153], v[80:83]
	v_mfma_f32_16x16x32_bf16 v[84:87], v[188:191], v[150:153], v[84:87]
	v_mfma_f32_16x16x32_bf16 v[16:19], v[192:195], v[150:153], v[16:19]
	v_mfma_f32_16x16x32_bf16 v[88:91], v[180:183], v[154:157], v[88:91]
	v_mfma_f32_16x16x32_bf16 v[92:95], v[184:187], v[154:157], v[92:95]
	v_mfma_f32_16x16x32_bf16 v[96:99], v[188:191], v[154:157], v[96:99]
	v_mfma_f32_16x16x32_bf16 v[20:23], v[192:195], v[154:157], v[20:23]
	v_mfma_f32_16x16x32_bf16 v[100:103], v[180:183], v[164:167], v[100:103]
	v_mfma_f32_16x16x32_bf16 v[104:107], v[184:187], v[164:167], v[104:107]
	v_mfma_f32_16x16x32_bf16 v[108:111], v[188:191], v[164:167], v[108:111]
	v_mfma_f32_16x16x32_bf16 v[24:27], v[192:195], v[164:167], v[24:27]
	v_mfma_f32_16x16x32_bf16 v[112:115], v[180:183], v[168:171], v[112:115]
	v_mfma_f32_16x16x32_bf16 v[116:119], v[184:187], v[168:171], v[116:119]
	v_mfma_f32_16x16x32_bf16 v[120:123], v[188:191], v[168:171], v[120:123]
	v_mfma_f32_16x16x32_bf16 v[28:31], v[192:195], v[168:171], v[28:31]
	v_mfma_f32_16x16x32_bf16 v[124:127], v[180:183], v[172:175], v[124:127]
	v_mfma_f32_16x16x32_bf16 v[128:131], v[184:187], v[172:175], v[128:131]
	v_mfma_f32_16x16x32_bf16 v[132:135], v[188:191], v[172:175], v[132:135]
	v_mfma_f32_16x16x32_bf16 v[32:35], v[192:195], v[172:175], v[32:35]
	v_mfma_f32_16x16x32_bf16 v[40:43], v[180:183], v[176:179], v[40:43]
	v_mfma_f32_16x16x32_bf16 v[44:47], v[184:187], v[176:179], v[44:47]
	v_mfma_f32_16x16x32_bf16 v[48:51], v[188:191], v[176:179], v[48:51]
	v_mfma_f32_16x16x32_bf16 v[36:39], v[192:195], v[176:179], v[36:39]
	s_nop 0
	ds_read_b128 v[136:139], v0 offset:49152
	ds_read_b128 v[140:143], v0 offset:50176
	ds_read_b128 v[150:153], v0 offset:51200
	ds_read_b128 v[154:157], v0 offset:52224
	ds_read_b128 v[164:167], v0 offset:53248
	ds_read_b128 v[168:171], v0 offset:54272
	ds_read_b128 v[172:175], v0 offset:55296
	ds_read_b128 v[176:179], v0 offset:56320
	ds_read_b128 v[180:183], v144
	ds_read_b128 v[184:187], v149
	ds_read_b128 v[188:191], v196
	ds_read_b128 v[192:195], v197
	s_mov_b64 s[8:9], 0x1c0
	s_mov_b32 m0, s1
	v_lshl_add_u64 v[146:147], v[2:3], 0, s[8:9]
	s_mov_b64 s[12:13], 0x75c0
	global_load_lds_dwordx4 v[146:147], off
	v_lshl_add_u64 v[146:147], v[2:3], 0, s[12:13]
	s_mov_b32 m0, s0
	s_mov_b64 s[0:1], 0xe9c0
	global_load_lds_dwordx4 v[146:147], off
	v_lshl_add_u64 v[146:147], v[2:3], 0, s[0:1]
	s_mov_b32 m0, s4
	s_mov_b64 s[0:1], 0x15dc0
	global_load_lds_dwordx4 v[146:147], off
	v_lshl_add_u64 v[2:3], v[2:3], 0, s[0:1]
	s_mov_b32 m0, s5
	s_mov_b64 s[0:1], 0x21c0
	global_load_lds_dwordx4 v[2:3], off
	v_lshl_add_u64 v[2:3], v[4:5], 0, s[8:9]
	s_mov_b32 m0, s6
	s_nop 0
	global_load_lds_dwordx4 v[2:3], off
	v_lshl_add_u64 v[2:3], v[4:5], 0, s[0:1]
	s_mov_b32 m0, s7
	s_nop 0
	global_load_lds_dwordx4 v[2:3], off
	s_nop 0
	s_waitcnt lgkmcnt(0)
	v_mfma_f32_16x16x32_bf16 v[2:5], v[180:183], v[136:139], v[56:59]
	s_waitcnt vmcnt(6) lgkmcnt(0)
	s_barrier
; template <int MI, int NI>
; DI void gemm256(f32x4 (&acc)[MI][NI], const u16* __restrict__ A, int lda, const u16* __restrict__ Bt, int ldb, int K, int m0, int n0, char* smem) {
;     ...
;     const char* sb = smem + st * STAGE + foff;
;     bf16x8 af[MI], bfr[NI];
; #pragma unroll
;     for (int mi = 0; mi < MI; ++mi) af[mi] = *(const bf16x8*)(sb + (wr * MI + mi) * 1024);
; #pragma unroll
;     for (int ni = 0; ni < NI; ++ni) bfr[ni] = *(const bf16x8*)(sb + ABYTES + (wc * NI + ni) * 1024);
;     __builtin_amdgcn_sched_barrier(0x0);
;     if (kt + 2 < nk) { const int s2 = st >= 1 ? st - 1 : 2; G256_ISSUE(s2, (kt + 2) * 32); }
;     __builtin_amdgcn_s_setprio(0);
; #pragma unroll
;     for (int mi = 0; mi < MI; ++mi)
; #pragma unroll
;       for (int ni = 0; ni < NI; ++ni)
;         acc[mi][ni] = __builtin_amdgcn_mfma_f32_16x16x32_bf16(bfr[ni], af[mi], acc[mi][ni], 0, 0, 0);
	v_mfma_f32_16x16x32_bf16 v[56:59], v[184:187], v[136:139], v[60:63]
	v_mfma_f32_16x16x32_bf16 v[60:63], v[188:191], v[136:139], v[64:67]
	v_mfma_f32_16x16x32_bf16 v[8:11], v[192:195], v[136:139], v[8:11]
	v_mfma_f32_16x16x32_bf16 v[52:55], v[180:183], v[140:143], v[52:55]
	v_mfma_f32_16x16x32_bf16 v[64:67], v[184:187], v[140:143], v[68:71]
	v_mfma_f32_16x16x32_bf16 v[68:71], v[188:191], v[140:143], v[72:75]
	v_mfma_f32_16x16x32_bf16 v[12:15], v[192:195], v[140:143], v[12:15]
	v_mfma_f32_16x16x32_bf16 v[72:75], v[180:183], v[150:153], v[76:79]
	v_mfma_f32_16x16x32_bf16 v[76:79], v[184:187], v[150:153], v[80:83]
	v_mfma_f32_16x16x32_bf16 v[80:83], v[188:191], v[150:153], v[84:87]
	v_mfma_f32_16x16x32_bf16 v[16:19], v[192:195], v[150:153], v[16:19]
	v_mfma_f32_16x16x32_bf16 v[84:87], v[180:183], v[154:157], v[88:91]
	v_mfma_f32_16x16x32_bf16 v[88:91], v[184:187], v[154:157], v[92:95]
	v_mfma_f32_16x16x32_bf16 v[92:95], v[188:191], v[154:157], v[96:99]
	v_mfma_f32_16x16x32_bf16 v[20:23], v[192:195], v[154:157], v[20:23]
	v_mfma_f32_16x16x32_bf16 v[96:99], v[180:183], v[164:167], v[100:103]
	v_mfma_f32_16x16x32_bf16 v[100:103], v[184:187], v[164:167], v[104:107]
	v_mfma_f32_16x16x32_bf16 v[104:107], v[188:191], v[164:167], v[108:111]
	v_mfma_f32_16x16x32_bf16 v[24:27], v[192:195], v[164:167], v[24:27]
	v_mfma_f32_16x16x32_bf16 v[108:111], v[180:183], v[168:171], v[112:115]
	v_mfma_f32_16x16x32_bf16 v[112:115], v[184:187], v[168:171], v[116:119]
	v_mfma_f32_16x16x32_bf16 v[116:119], v[188:191], v[168:171], v[120:123]
	v_mfma_f32_16x16x32_bf16 v[28:31], v[192:195], v[168:171], v[28:31]
	v_mfma_f32_16x16x32_bf16 v[120:123], v[180:183], v[172:175], v[124:127]
	v_mfma_f32_16x16x32_bf16 v[124:127], v[184:187], v[172:175], v[128:131]
	v_mfma_f32_16x16x32_bf16 v[128:131], v[188:191], v[172:175], v[132:135]
	v_mfma_f32_16x16x32_bf16 v[32:35], v[192:195], v[172:175], v[32:35]
	v_mfma_f32_16x16x32_bf16 v[40:43], v[180:183], v[176:179], v[40:43]
	v_mfma_f32_16x16x32_bf16 v[44:47], v[184:187], v[176:179], v[44:47]
	v_mfma_f32_16x16x32_bf16 v[48:51], v[188:191], v[176:179], v[48:51]
	v_mfma_f32_16x16x32_bf16 v[36:39], v[192:195], v[176:179], v[36:39]
	s_nop 0
	ds_read_b128 v[132:135], v0
	ds_read_b128 v[136:139], v0 offset:1024
	ds_read_b128 v[140:143], v0 offset:2048
	ds_read_b128 v[150:153], v0 offset:3072
	ds_read_b128 v[154:157], v0 offset:4096
	ds_read_b128 v[164:167], v0 offset:5120
	ds_read_b128 v[168:171], v0 offset:6144
	ds_read_b128 v[172:175], v0 offset:7168
	ds_read_b128 v[176:179], v7 offset:16384
	ds_read_b128 v[180:183], v7 offset:17408
	ds_read_b128 v[184:187], v7 offset:18432
	ds_read_b128 v[188:191], v7 offset:19456
	s_nop 0
	s_waitcnt lgkmcnt(3)
	v_mfma_f32_16x16x32_bf16 v[2:5], v[176:179], v[132:135], v[2:5]
	s_waitcnt vmcnt(0) lgkmcnt(0)
	s_barrier
	s_waitcnt lgkmcnt(2)
	v_mfma_f32_16x16x32_bf16 v[56:59], v[180:183], v[132:135], v[56:59]
	s_waitcnt lgkmcnt(1)
	v_mfma_f32_16x16x32_bf16 v[60:63], v[184:187], v[132:135], v[60:63]
	s_waitcnt lgkmcnt(0)
	v_mfma_f32_16x16x32_bf16 v[8:11], v[188:191], v[132:135], v[8:11]
	v_mfma_f32_16x16x32_bf16 v[52:55], v[176:179], v[136:139], v[52:55]
	v_mfma_f32_16x16x32_bf16 v[64:67], v[180:183], v[136:139], v[64:67]
	v_mfma_f32_16x16x32_bf16 v[68:71], v[184:187], v[136:139], v[68:71]
	v_mfma_f32_16x16x32_bf16 v[12:15], v[188:191], v[136:139], v[12:15]
	v_mfma_f32_16x16x32_bf16 v[72:75], v[176:179], v[140:143], v[72:75]
	v_mfma_f32_16x16x32_bf16 v[76:79], v[180:183], v[140:143], v[76:79]
	v_mfma_f32_16x16x32_bf16 v[80:83], v[184:187], v[140:143], v[80:83]
	v_mfma_f32_16x16x32_bf16 v[16:19], v[188:191], v[140:143], v[16:19]
	v_mfma_f32_16x16x32_bf16 v[132:135], v[176:179], v[150:153], v[84:87]
	v_mfma_f32_16x16x32_bf16 v[136:139], v[180:183], v[150:153], v[88:91]
	v_mfma_f32_16x16x32_bf16 v[140:143], v[184:187], v[150:153], v[92:95]
	v_mfma_f32_16x16x32_bf16 v[20:23], v[188:191], v[150:153], v[20:23]
	v_mfma_f32_16x16x32_bf16 v[150:153], v[176:179], v[154:157], v[96:99]
	v_mfma_f32_16x16x32_bf16 v[192:195], v[180:183], v[154:157], v[100:103]
	v_mfma_f32_16x16x32_bf16 v[196:199], v[184:187], v[154:157], v[104:107]
	v_mfma_f32_16x16x32_bf16 v[24:27], v[188:191], v[154:157], v[24:27]
	v_mfma_f32_16x16x32_bf16 v[154:157], v[176:179], v[164:167], v[108:111]
	v_mfma_f32_16x16x32_bf16 v[28:31], v[188:191], v[164:167], v[28:31]
	v_mfma_f32_16x16x32_bf16 v[200:203], v[180:183], v[164:167], v[112:115]
	v_mfma_f32_16x16x32_bf16 v[204:207], v[184:187], v[164:167], v[116:119]
	v_mfma_f32_16x16x32_bf16 v[164:167], v[176:179], v[168:171], v[120:123]
	v_mfma_f32_16x16x32_bf16 v[208:211], v[180:183], v[168:171], v[124:127]
	v_mfma_f32_16x16x32_bf16 v[212:215], v[184:187], v[168:171], v[128:131]
	v_mfma_f32_16x16x32_bf16 v[168:171], v[188:191], v[168:171], v[32:35]
	v_mfma_f32_16x16x32_bf16 v[176:179], v[176:179], v[172:175], v[40:43]
	v_mfma_f32_16x16x32_bf16 v[180:183], v[180:183], v[172:175], v[44:47]
	v_mfma_f32_16x16x32_bf16 v[184:187], v[184:187], v[172:175], v[48:51]
	v_mfma_f32_16x16x32_bf16 v[172:175], v[188:191], v[172:175], v[36:39]
	s_nop 0
	ds_read_b128 v[32:35], v0 offset:24576
	s_nop 0
	ds_read_b128 v[36:39], v0 offset:25600
	ds_read_b128 v[40:43], v0 offset:26624
	ds_read_b128 v[44:47], v0 offset:27648
	ds_read_b128 v[48:51], v0 offset:28672
	ds_read_b128 v[188:191], v0 offset:29696
	ds_read_b128 v[216:219], v0 offset:30720
	ds_read_b128 v[220:223], v0 offset:31744
	ds_read_b128 v[224:227], v7 offset:40960
	ds_read_b128 v[228:231], v7 offset:41984
	ds_read_b128 v[238:241], v7 offset:43008
	ds_read_b128 v[244:247], v7 offset:44032
	s_nop 0
	v_readlane_b32 s0, v254, 33
	s_waitcnt lgkmcnt(3)
	v_mfma_f32_16x16x32_bf16 v[126:129], v[224:227], v[32:35], v[2:5]
	v_mov_b32_e32 v0, v160
	v_mov_b32_e32 v130, v161
	v_readlane_b32 s1, v254, 34
	v_mov_b32_e32 v2, v158
	v_mfma_f32_16x16x32_bf16 v[94:97], v[224:227], v[40:43], v[72:75]
	s_waitcnt lgkmcnt(0)
	s_barrier
; DI unsigned pack2(float a, float b) { float2_t v = {a, b}; bf16x2_t r = __builtin_convertvector(v, bf16x2_t); return __builtin_bit_cast(unsigned, r); }
; DI u16 f2bf(float a) { return (u16)(pack2(a, 0.f) & 0xffffu); }
; DI void phase_qkv(const Params& p, int l, char* smem) {
;     ...
;       for (int mi = 0; mi < 8; ++mi) {
;         __builtin_amdgcn_sched_barrier(0);
;         const int m = m0 + wr * 128 + mi * 16 + lr;
;         const float rs = rskv[m];
;         if (wc == 0) {
;           float ss = 0.f;
; #pragma unroll
;           for (int ni = 0; ni < 4; ++ni)
; #pragma unroll
;             for (int j = 0; j < 4; ++j) { const float v = acc[mi][ni][j] * rs; ss += v * v; }
;           ss += __shfl_xor(ss, 16, 64); ss += __shfl_xor(ss, 32, 64);
;           const float f = rs * rsqrtf(ss * (1.f / 64.f) + 1e-6f);
;           u16* dst = Kb + qk_index(m, h);
; #pragma unroll
;           for (int ni = 0; ni < 4; ++ni) {
;             const int d = ni * 16 + lq * 4;
;             const float4 g = *(const float4*)(gk + d);
;             *(uint2*)(dst + d) = make_uint2(pack2(acc[mi][ni][0] * f * g.x, acc[mi][ni][1] * f * g.y), pack2(acc[mi][ni][2] * f * g.z, acc[mi][ni][3] * f * g.w));
;           }
;           *(uint4*)(dst + 64 + lq * 8) = *(const uint4*)((const u16*)(p.ws + OFF_KR) + (size_t)m * 32 + lq * 8);
;         } else {
;           const bool lat = m < NTL;
;           const int b = lat ? m >> 12 : (m - NTL) >> 8;
;           const int pos = lat ? m & 4095 : 4096 + ((m - NTL) & 255);
;           u16* dst = Vt + (size_t)(b * 8 + h) * 64 * LK + pos + (size_t)(lq * 4) * LK;
; #pragma unroll
;           for (int ni = 0; ni < 4; ++ni) {
;             asm volatile("" : "+v"(dst));
; #pragma unroll
;             for (int j = 0; j < 4; ++j) dst[j * LK] = f2bf(acc[mi][ni][j] * rs);
;             dst += 16 * LK;
;           }
	s_waitcnt lgkmcnt(2)
	v_mfma_f32_16x16x32_bf16 v[90:93], v[228:231], v[40:43], v[76:79]
	v_mov_b32_e32 v3, v159
	v_mfma_f32_16x16x32_bf16 v[74:77], v[228:231], v[44:47], v[136:139]
	v_lshlrev_b32_e32 v2, 7, v2
	s_movk_i32 s4, 0x2200
	v_mfma_f32_16x16x32_bf16 v[122:125], v[228:231], v[32:35], v[56:59]
	v_mov_b64_e32 v[136:137], s[0:1]
	v_readlane_b32 s0, v254, 31
	v_readlane_b32 s1, v254, 32
	s_waitcnt lgkmcnt(1)
	v_mfma_f32_16x16x32_bf16 v[118:121], v[238:241], v[32:35], v[60:63]
	s_waitcnt lgkmcnt(0)
	v_mfma_f32_16x16x32_bf16 v[114:117], v[244:247], v[32:35], v[8:11]
	v_mfma_f32_16x16x32_bf16 v[110:113], v[224:227], v[36:39], v[52:55]
	v_mfma_f32_16x16x32_bf16 v[106:109], v[228:231], v[36:39], v[64:67]
	v_mfma_f32_16x16x32_bf16 v[102:105], v[238:241], v[36:39], v[68:71]
	v_mfma_f32_16x16x32_bf16 v[98:101], v[244:247], v[36:39], v[12:15]
	v_mfma_f32_16x16x32_bf16 v[86:89], v[238:241], v[40:43], v[80:83]
	v_mfma_f32_16x16x32_bf16 v[82:85], v[244:247], v[40:43], v[16:19]
	v_mfma_f32_16x16x32_bf16 v[78:81], v[224:227], v[44:47], v[132:135]
	v_mfma_f32_16x16x32_bf16 v[70:73], v[238:241], v[44:47], v[140:143]
	s_nop 1
	v_mov_b64_e32 v[134:135], s[0:1]
	v_cmp_ne_u32_e64 s[0:1], 0, v3
	v_lshlrev_b32_e32 v132, 2, v130
	v_mfma_f32_16x16x32_bf16 v[66:69], v[244:247], v[44:47], v[20:23]
	v_add3_u32 v140, v0, v6, v2
	v_mad_i64_i32 v[138:139], s[4:5], v132, s4, 0
	v_mfma_f32_16x16x32_bf16 v[62:65], v[224:227], v[48:51], v[150:153]
	v_mfma_f32_16x16x32_bf16 v[58:61], v[228:231], v[48:51], v[192:195]
	v_mfma_f32_16x16x32_bf16 v[54:57], v[238:241], v[48:51], v[196:199]
	v_mfma_f32_16x16x32_bf16 v[50:53], v[244:247], v[48:51], v[24:27]
	v_mfma_f32_16x16x32_bf16 v[46:49], v[224:227], v[188:191], v[154:157]
	v_mfma_f32_16x16x32_bf16 v[42:45], v[228:231], v[188:191], v[200:203]
	v_mfma_f32_16x16x32_bf16 v[38:41], v[238:241], v[188:191], v[204:207]
	v_mfma_f32_16x16x32_bf16 v[34:37], v[244:247], v[188:191], v[28:31]
	v_mfma_f32_16x16x32_bf16 v[30:33], v[224:227], v[216:219], v[164:167]
	v_mfma_f32_16x16x32_bf16 v[26:29], v[228:231], v[216:219], v[208:211]
	v_mfma_f32_16x16x32_bf16 v[22:25], v[238:241], v[216:219], v[212:215]
	v_mfma_f32_16x16x32_bf16 v[18:21], v[244:247], v[216:219], v[168:171]
	v_mfma_f32_16x16x32_bf16 v[14:17], v[224:227], v[220:223], v[176:179]
	v_mfma_f32_16x16x32_bf16 v[10:13], v[228:231], v[220:223], v[180:183]
	v_mfma_f32_16x16x32_bf16 v[6:9], v[238:241], v[220:223], v[184:187]
	v_mfma_f32_16x16x32_bf16 v[2:5], v[244:247], v[220:223], v[172:175]
	v_ashrrev_i32_e32 v141, 31, v140
	v_lshl_add_u64 v[142:143], v[140:141], 2, v[134:135]
	flat_load_dword v144, v[142:143]
	v_ashrrev_i32_e32 v0, 12, v140
	v_add_u32_e32 v149, 0xffff8000, v140
	v_and_b32_e32 v146, 0xfff, v140
	v_or_b32_sdwa v147, v140, s97 dst_sel:DWORD dst_unused:UNUSED_PAD src0_sel:BYTE_0 src1_sel:DWORD
	s_waitcnt vmcnt(0) lgkmcnt(0)
	v_mul_f32_e32 v156, v126, v144
	v_mul_f32_e32 v157, v127, v144
	v_mul_f32_e32 v155, v128, v144
	v_mul_f32_e32 v154, v129, v144
	v_mul_f32_e32 v153, v122, v144
	v_mul_f32_e32 v152, v123, v144
	v_mul_f32_e32 v151, v124, v144
	v_mul_f32_e32 v150, v125, v144
	s_and_saveexec_b64 s[4:5], s[0:1]
	v_readlane_b32 s8, v254, 15
	s_xor_b64 s[4:5], exec, s[4:5]
	v_readlane_b32 s9, v254, 16
	s_cbranch_execz .LBB0_723
	v_lshrrev_b32_e32 v122, 8, v149
	v_cmp_gt_i32_e32 vcc, s58, v140
	s_mov_b32 s6, 0x88000
	s_nop 0
	v_cndmask_b32_e32 v0, v122, v0, vcc
	v_cndmask_b32_e32 v124, v147, v146, vcc
	v_lshl_add_u32 v0, v0, 3, v148
	v_mov_b64_e32 v[122:123], s[8:9]
	v_mad_i64_i32 v[122:123], s[6:7], v0, s6, v[122:123]
	v_lshlrev_b32_e32 v0, 1, v124
	v_lshl_add_u64 v[122:123], v[122:123], 0, v[0:1]
	v_lshl_add_u64 v[122:123], v[122:123], 0, v[138:139]
	v_cvt_pk_bf16_f32 v0, v156, s0
	v_add_co_u32_e32 v124, vcc, s47, v122
	flat_store_short v[122:123], v0
	v_cvt_pk_bf16_f32 v0, v157, s0
	v_addc_co_u32_e32 v125, vcc, 0, v123, vcc
	flat_store_short v[124:125], v0 offset:512
	v_add_co_u32_e32 v124, vcc, s42, v122
	v_cvt_pk_bf16_f32 v0, v155, s0
	s_nop 0
	v_addc_co_u32_e32 v125, vcc, 0, v123, vcc
	flat_store_short v[124:125], v0 offset:1024
	v_add_co_u32_e32 v124, vcc, s43, v122
	s_mov_b64 s[6:7], 0x22000
	v_cvt_pk_bf16_f32 v0, v154, s0
	v_addc_co_u32_e32 v125, vcc, 0, v123, vcc
	v_lshl_add_u64 v[122:123], v[122:123], 0, s[6:7]
	flat_store_short v[124:125], v0 offset:1536
	v_cvt_pk_bf16_f32 v0, v153, s0
	v_add_co_u32_e32 v124, vcc, s47, v122
	flat_store_short v[122:123], v0
	v_cvt_pk_bf16_f32 v0, v152, s0
	v_addc_co_u32_e32 v125, vcc, 0, v123, vcc
	flat_store_short v[124:125], v0 offset:512
	v_add_co_u32_e32 v124, vcc, s42, v122
	v_cvt_pk_bf16_f32 v0, v151, s0
	s_nop 0
	v_addc_co_u32_e32 v125, vcc, 0, v123, vcc
	flat_store_short v[124:125], v0 offset:1024
	v_add_co_u32_e32 v124, vcc, s43, v122
	v_cvt_pk_bf16_f32 v0, v150, s0
	s_nop 0
	v_addc_co_u32_e32 v125, vcc, 0, v123, vcc
	flat_store_short v[124:125], v0 offset:1536
	v_mul_f32_e32 v0, v118, v144
	v_lshl_add_u64 v[122:123], v[122:123], 0, s[6:7]
	v_cvt_pk_bf16_f32 v0, v0, s0
	flat_store_short v[122:123], v0
	v_mul_f32_e32 v0, v119, v144
	v_add_co_u32_e32 v118, vcc, s47, v122
	v_cvt_pk_bf16_f32 v0, v0, s0
	s_nop 0
	v_addc_co_u32_e32 v119, vcc, 0, v123, vcc
	flat_store_short v[118:119], v0 offset:512
	v_mul_f32_e32 v0, v120, v144
	v_add_co_u32_e32 v118, vcc, s42, v122
	v_cvt_pk_bf16_f32 v0, v0, s0
	s_nop 0
	v_addc_co_u32_e32 v119, vcc, 0, v123, vcc
	flat_store_short v[118:119], v0 offset:1024
	v_mul_f32_e32 v0, v121, v144
	v_add_co_u32_e32 v118, vcc, s43, v122
	v_cvt_pk_bf16_f32 v0, v0, s0
	s_nop 0
	v_addc_co_u32_e32 v119, vcc, 0, v123, vcc
	flat_store_short v[118:119], v0 offset:1536
	v_mul_f32_e32 v0, v114, v144
	v_lshl_add_u64 v[118:119], v[122:123], 0, s[6:7]
	v_cvt_pk_bf16_f32 v0, v0, s0
	flat_store_short v[118:119], v0
	v_mul_f32_e32 v0, v115, v144
	v_add_co_u32_e32 v114, vcc, 0x2000, v118
	v_cvt_pk_bf16_f32 v0, v0, s0
	s_nop 0
	v_addc_co_u32_e32 v115, vcc, 0, v119, vcc
	flat_store_short v[114:115], v0 offset:512
	v_mul_f32_e32 v0, v116, v144
	v_add_co_u32_e32 v114, vcc, 0x4000, v118
	v_cvt_pk_bf16_f32 v0, v0, s0
	s_nop 0
	v_addc_co_u32_e32 v115, vcc, 0, v119, vcc
	flat_store_short v[114:115], v0 offset:1024
	v_mul_f32_e32 v0, v117, v144
	v_add_co_u32_e32 v114, vcc, 0x6000, v118
	v_cvt_pk_bf16_f32 v0, v0, s0
	s_nop 0
	v_addc_co_u32_e32 v115, vcc, 0, v119, vcc
	flat_store_short v[114:115], v0 offset:1536

; template <int MI, int NI>
; DI void gemm256(f32x4 (&acc)[MI][NI], const u16* __restrict__ A, int lda, const u16* __restrict__ Bt, int ldb, int K, int m0, int n0, char* smem) {
;     ...
;   for (int kt = 0; kt < nk; ++kt) {
;     if (kt + 1 < nk) asm volatile("s_waitcnt vmcnt(%0) lgkmcnt(0)" :: "n"(LPS) : "memory");
;     else asm volatile("s_waitcnt vmcnt(0) lgkmcnt(0)" ::: "memory");
;     __builtin_amdgcn_s_barrier();
;     __builtin_amdgcn_s_setprio(1);
;     const char* sb = smem + st * STAGE + foff;
;     bf16x8 af[MI], bfr[NI];
; #pragma unroll
;     for (int mi = 0; mi < MI; ++mi) af[mi] = *(const bf16x8*)(sb + (wr * MI + mi) * 1024);
; #pragma unroll
;     for (int ni = 0; ni < NI; ++ni) bfr[ni] = *(const bf16x8*)(sb + ABYTES + (wc * NI + ni) * 1024);
;     __builtin_amdgcn_sched_barrier(0x0);
;     if (kt + 2 < nk) { const int s2 = st >= 1 ? st - 1 : 2; G256_ISSUE(s2, (kt + 2) * 32); }
;     __builtin_amdgcn_s_setprio(0);
; #pragma unroll
;     for (int mi = 0; mi < MI; ++mi)
; #pragma unroll
;       for (int ni = 0; ni < NI; ++ni)
;         acc[mi][ni] = __builtin_amdgcn_mfma_f32_16x16x32_bf16(bfr[ni], af[mi], acc[mi][ni], 0, 0, 0);
;     st = st == 2 ? 0 : st + 1;
;   }
.Lpipe_zgemm:
	v_add_u32_e32 v160, s6, v143
	ds_read_b128 v[164:167], v160 offset:4096
	ds_read_b128 v[168:171], v160 offset:5120
	ds_read_b128 v[172:175], v160 offset:6144
	ds_read_b128 v[176:179], v160 offset:7168
	s_add_i32 s8, s6, 0xffffa000
	s_cmp_eq_u32 s6, 0
	s_cselect_b32 s8, 0xc000, s8
	s_add_i32 s9, s8, s7
	s_add_i32 s8, s8, s0
	s_mov_b32 m0, s9
	s_waitcnt lgkmcnt(7)
	v_mfma_f32_16x16x32_bf16 v[126:129], v[180:183], v[144:147], v[126:129]
	global_load_lds_dwordx4 v[198:199], off
	v_mfma_f32_16x16x32_bf16 v[110:113], v[180:183], v[148:151], v[110:113]
	v_lshl_add_u64 v[198:199], v[198:199], 0, s[98:99]
	s_add_i32 m0, s9, 0x400
	v_mfma_f32_16x16x32_bf16 v[94:97], v[180:183], v[152:155], v[94:97]
	global_load_lds_dwordx4 v[200:201], off
	v_mfma_f32_16x16x32_bf16 v[78:81], v[180:183], v[156:159], v[78:81]
	v_lshl_add_u64 v[200:201], v[200:201], 0, s[98:99]
	s_add_i32 m0, s9, 0x800
	s_waitcnt lgkmcnt(6)
	v_mfma_f32_16x16x32_bf16 v[122:125], v[184:187], v[144:147], v[122:125]
	global_load_lds_dwordx4 v[202:203], off
	v_mfma_f32_16x16x32_bf16 v[106:109], v[184:187], v[148:151], v[106:109]
	v_lshl_add_u64 v[202:203], v[202:203], 0, s[98:99]
	s_add_i32 m0, s9, 0xc00
	v_mfma_f32_16x16x32_bf16 v[90:93], v[184:187], v[152:155], v[90:93]
	global_load_lds_dwordx4 v[204:205], off
	v_mfma_f32_16x16x32_bf16 v[74:77], v[184:187], v[156:159], v[74:77]
	v_lshl_add_u64 v[204:205], v[204:205], 0, s[98:99]
	s_mov_b32 m0, s8
	s_waitcnt lgkmcnt(5)
	v_mfma_f32_16x16x32_bf16 v[118:121], v[188:191], v[144:147], v[118:121]
	global_load_lds_dwordx4 v[206:207], off
	v_mfma_f32_16x16x32_bf16 v[102:105], v[188:191], v[148:151], v[102:105]
	v_lshl_add_u64 v[206:207], v[206:207], 0, s[98:99]
	s_add_i32 m0, s8, 0x400
	v_mfma_f32_16x16x32_bf16 v[86:89], v[188:191], v[152:155], v[86:89]
	global_load_lds_dwordx4 v[208:209], off
	v_mfma_f32_16x16x32_bf16 v[70:73], v[188:191], v[156:159], v[70:73]
	v_lshl_add_u64 v[208:209], v[208:209], 0, s[98:99]
	s_waitcnt lgkmcnt(4)
	v_mfma_f32_16x16x32_bf16 v[114:117], v[192:195], v[144:147], v[114:117]
	v_mfma_f32_16x16x32_bf16 v[98:101], v[192:195], v[148:151], v[98:101]
	v_mfma_f32_16x16x32_bf16 v[82:85], v[192:195], v[152:155], v[82:85]
	v_mfma_f32_16x16x32_bf16 v[66:69], v[192:195], v[156:159], v[66:69]
	s_waitcnt vmcnt(6) lgkmcnt(0)
	s_barrier
	s_add_i32 s9, s6, 0x6000
	s_cmp_eq_u32 s6, 0xc000
	s_cselect_b32 s6, 0, s9
	v_add_u32_e32 v196, s6, v143
	v_add_u32_e32 v197, s6, v0
	v_mfma_f32_16x16x32_bf16 v[62:65], v[180:183], v[164:167], v[62:65]
	ds_read_b128 v[144:147], v196
	v_mfma_f32_16x16x32_bf16 v[46:49], v[180:183], v[168:171], v[46:49]
	ds_read_b128 v[148:151], v196 offset:1024
	v_mfma_f32_16x16x32_bf16 v[30:33], v[180:183], v[172:175], v[30:33]
	ds_read_b128 v[152:155], v196 offset:2048
	v_mfma_f32_16x16x32_bf16 v[14:17], v[180:183], v[176:179], v[14:17]
	ds_read_b128 v[156:159], v196 offset:3072
	ds_read_b128 v[180:183], v197 offset:16384
	v_mfma_f32_16x16x32_bf16 v[58:61], v[184:187], v[164:167], v[58:61]
	v_mfma_f32_16x16x32_bf16 v[42:45], v[184:187], v[168:171], v[42:45]
	v_mfma_f32_16x16x32_bf16 v[26:29], v[184:187], v[172:175], v[26:29]
	v_mfma_f32_16x16x32_bf16 v[10:13], v[184:187], v[176:179], v[10:13]
	ds_read_b128 v[184:187], v197 offset:17408
	v_mfma_f32_16x16x32_bf16 v[54:57], v[188:191], v[164:167], v[54:57]
	v_mfma_f32_16x16x32_bf16 v[38:41], v[188:191], v[168:171], v[38:41]
	v_mfma_f32_16x16x32_bf16 v[22:25], v[188:191], v[172:175], v[22:25]
	v_mfma_f32_16x16x32_bf16 v[6:9], v[188:191], v[176:179], v[6:9]
	ds_read_b128 v[188:191], v197 offset:18432
	v_mfma_f32_16x16x32_bf16 v[50:53], v[192:195], v[164:167], v[50:53]
	v_mfma_f32_16x16x32_bf16 v[34:37], v[192:195], v[168:171], v[34:37]
	v_mfma_f32_16x16x32_bf16 v[18:21], v[192:195], v[172:175], v[18:21]
	v_mfma_f32_16x16x32_bf16 v[2:5], v[192:195], v[176:179], v[2:5]
	ds_read_b128 v[192:195], v197 offset:19456
	s_sub_i32 s1, s1, 1
	s_cmp_lg_u32 s1, 0
	s_cbranch_scc1 .Lpipe_zgemm
	v_add_u32_e32 v160, s6, v143
	ds_read_b128 v[164:167], v160 offset:4096
	ds_read_b128 v[168:171], v160 offset:5120
	ds_read_b128 v[172:175], v160 offset:6144
	ds_read_b128 v[176:179], v160 offset:7168
	s_add_i32 s8, s6, 0xffffa000
	s_cmp_eq_u32 s6, 0
	s_cselect_b32 s8, 0xc000, s8
	s_add_i32 s9, s8, s7
	s_add_i32 s8, s8, s0
	s_mov_b32 m0, s9
	s_waitcnt lgkmcnt(7)
	v_mfma_f32_16x16x32_bf16 v[126:129], v[180:183], v[144:147], v[126:129]
	global_load_lds_dwordx4 v[198:199], off
	v_mfma_f32_16x16x32_bf16 v[110:113], v[180:183], v[148:151], v[110:113]
	v_lshl_add_u64 v[198:199], v[198:199], 0, s[98:99]
	s_add_i32 m0, s9, 0x400
	v_mfma_f32_16x16x32_bf16 v[94:97], v[180:183], v[152:155], v[94:97]
	global_load_lds_dwordx4 v[200:201], off
	v_mfma_f32_16x16x32_bf16 v[78:81], v[180:183], v[156:159], v[78:81]
	v_lshl_add_u64 v[200:201], v[200:201], 0, s[98:99]
	s_add_i32 m0, s9, 0x800
	s_waitcnt lgkmcnt(6)
	v_mfma_f32_16x16x32_bf16 v[122:125], v[184:187], v[144:147], v[122:125]
	global_load_lds_dwordx4 v[202:203], off
	v_mfma_f32_16x16x32_bf16 v[106:109], v[184:187], v[148:151], v[106:109]
	v_lshl_add_u64 v[202:203], v[202:203], 0, s[98:99]
	s_add_i32 m0, s9, 0xc00
	v_mfma_f32_16x16x32_bf16 v[90:93], v[184:187], v[152:155], v[90:93]
	global_load_lds_dwordx4 v[204:205], off
	v_mfma_f32_16x16x32_bf16 v[74:77], v[184:187], v[156:159], v[74:77]
	v_lshl_add_u64 v[204:205], v[204:205], 0, s[98:99]
	s_mov_b32 m0, s8
	s_waitcnt lgkmcnt(5)
	v_mfma_f32_16x16x32_bf16 v[118:121], v[188:191], v[144:147], v[118:121]
	global_load_lds_dwordx4 v[206:207], off
	v_mfma_f32_16x16x32_bf16 v[102:105], v[188:191], v[148:151], v[102:105]
	v_lshl_add_u64 v[206:207], v[206:207], 0, s[98:99]
	s_add_i32 m0, s8, 0x400
	v_mfma_f32_16x16x32_bf16 v[86:89], v[188:191], v[152:155], v[86:89]
	global_load_lds_dwordx4 v[208:209], off
	v_mfma_f32_16x16x32_bf16 v[70:73], v[188:191], v[156:159], v[70:73]
	v_lshl_add_u64 v[208:209], v[208:209], 0, s[98:99]
	s_waitcnt lgkmcnt(4)
; template <int MI, int NI>
; DI void gemm256(f32x4 (&acc)[MI][NI], const u16* __restrict__ A, int lda, const u16* __restrict__ Bt, int ldb, int K, int m0, int n0, char* smem) {
;     ...
;     const char* sb = smem + st * STAGE + foff;
;     bf16x8 af[MI], bfr[NI];
; #pragma unroll
;     for (int mi = 0; mi < MI; ++mi) af[mi] = *(const bf16x8*)(sb + (wr * MI + mi) * 1024);
; #pragma unroll
;     for (int ni = 0; ni < NI; ++ni) bfr[ni] = *(const bf16x8*)(sb + ABYTES + (wc * NI + ni) * 1024);
;     __builtin_amdgcn_sched_barrier(0x0);
;     if (kt + 2 < nk) { const int s2 = st >= 1 ? st - 1 : 2; G256_ISSUE(s2, (kt + 2) * 32); }
;     __builtin_amdgcn_s_setprio(0);
; #pragma unroll
;     for (int mi = 0; mi < MI; ++mi)
; #pragma unroll
;       for (int ni = 0; ni < NI; ++ni)
;         acc[mi][ni] = __builtin_amdgcn_mfma_f32_16x16x32_bf16(bfr[ni], af[mi], acc[mi][ni], 0, 0, 0);
	v_mfma_f32_16x16x32_bf16 v[114:117], v[192:195], v[144:147], v[114:117]
	v_mfma_f32_16x16x32_bf16 v[98:101], v[192:195], v[148:151], v[98:101]
	v_mfma_f32_16x16x32_bf16 v[82:85], v[192:195], v[152:155], v[82:85]
	v_mfma_f32_16x16x32_bf16 v[66:69], v[192:195], v[156:159], v[66:69]
	s_waitcnt lgkmcnt(0)
	v_mfma_f32_16x16x32_bf16 v[62:65], v[180:183], v[164:167], v[62:65]
	v_mfma_f32_16x16x32_bf16 v[46:49], v[180:183], v[168:171], v[46:49]
	v_mfma_f32_16x16x32_bf16 v[30:33], v[180:183], v[172:175], v[30:33]
	v_mfma_f32_16x16x32_bf16 v[14:17], v[180:183], v[176:179], v[14:17]
	v_mfma_f32_16x16x32_bf16 v[58:61], v[184:187], v[164:167], v[58:61]
	v_mfma_f32_16x16x32_bf16 v[42:45], v[184:187], v[168:171], v[42:45]
	v_mfma_f32_16x16x32_bf16 v[26:29], v[184:187], v[172:175], v[26:29]
	v_mfma_f32_16x16x32_bf16 v[10:13], v[184:187], v[176:179], v[10:13]
	v_mfma_f32_16x16x32_bf16 v[54:57], v[188:191], v[164:167], v[54:57]
	v_mfma_f32_16x16x32_bf16 v[38:41], v[188:191], v[168:171], v[38:41]
	v_mfma_f32_16x16x32_bf16 v[22:25], v[188:191], v[172:175], v[22:25]
	v_mfma_f32_16x16x32_bf16 v[6:9], v[188:191], v[176:179], v[6:9]
	v_mfma_f32_16x16x32_bf16 v[50:53], v[192:195], v[164:167], v[50:53]
	v_mfma_f32_16x16x32_bf16 v[34:37], v[192:195], v[168:171], v[34:37]
	v_mfma_f32_16x16x32_bf16 v[18:21], v[192:195], v[172:175], v[18:21]
	v_mfma_f32_16x16x32_bf16 v[2:5], v[192:195], v[176:179], v[2:5]
	s_waitcnt vmcnt(6) lgkmcnt(0)
	s_barrier
	s_nop 0
	v_add_u32_e32 v0, v140, v142
	ds_read_b128 v[130:133], v0
	ds_read_b128 v[142:145], v0 offset:1024
	ds_read_b128 v[146:149], v0 offset:2048
	ds_read_b128 v[150:153], v0 offset:3072
	ds_read_b128 v[154:157], v0 offset:4096
	ds_read_b128 v[158:161], v0 offset:5120
	ds_read_b128 v[164:167], v0 offset:6144
	ds_read_b128 v[168:171], v0 offset:7168
	v_add_u32_e32 v220, v140, v141
	ds_read_b128 v[138:141], v220 offset:16384
	ds_read_b128 v[172:175], v220 offset:17408
	ds_read_b128 v[176:179], v220 offset:18432
	ds_read_b128 v[180:183], v220 offset:19456
	s_nop 0
	s_waitcnt lgkmcnt(3)
	v_mfma_f32_16x16x32_bf16 v[126:129], v[138:141], v[130:133], v[126:129]
	s_waitcnt vmcnt(0) lgkmcnt(0)
	s_barrier
	s_waitcnt lgkmcnt(2)
	v_mfma_f32_16x16x32_bf16 v[122:125], v[172:175], v[130:133], v[122:125]
	s_waitcnt lgkmcnt(1)
	v_mfma_f32_16x16x32_bf16 v[118:121], v[176:179], v[130:133], v[118:121]
	s_waitcnt lgkmcnt(0)
	v_mfma_f32_16x16x32_bf16 v[130:133], v[180:183], v[130:133], v[114:117]
	v_mfma_f32_16x16x32_bf16 v[110:113], v[138:141], v[142:145], v[110:113]
	v_mfma_f32_16x16x32_bf16 v[102:105], v[176:179], v[142:145], v[102:105]
	v_mfma_f32_16x16x32_bf16 v[94:97], v[138:141], v[146:149], v[94:97]
	v_mfma_f32_16x16x32_bf16 v[86:89], v[176:179], v[146:149], v[86:89]
	v_mfma_f32_16x16x32_bf16 v[78:81], v[138:141], v[150:153], v[78:81]
	v_mfma_f32_16x16x32_bf16 v[70:73], v[176:179], v[150:153], v[70:73]
	v_mfma_f32_16x16x32_bf16 v[62:65], v[138:141], v[154:157], v[62:65]
	v_mfma_f32_16x16x32_bf16 v[54:57], v[176:179], v[154:157], v[54:57]
	v_mfma_f32_16x16x32_bf16 v[46:49], v[138:141], v[158:161], v[46:49]
	v_mfma_f32_16x16x32_bf16 v[38:41], v[176:179], v[158:161], v[38:41]
	v_mfma_f32_16x16x32_bf16 v[30:33], v[138:141], v[164:167], v[30:33]
	v_mfma_f32_16x16x32_bf16 v[22:25], v[176:179], v[164:167], v[22:25]
	v_mfma_f32_16x16x32_bf16 v[14:17], v[138:141], v[168:171], v[14:17]
	v_mfma_f32_16x16x32_bf16 v[6:9], v[176:179], v[168:171], v[6:9]
	v_mfma_f32_16x16x32_bf16 v[184:187], v[172:175], v[142:145], v[106:109]
	v_mfma_f32_16x16x32_bf16 v[142:145], v[180:183], v[142:145], v[98:101]
	v_mfma_f32_16x16x32_bf16 v[188:191], v[172:175], v[146:149], v[90:93]
	v_mfma_f32_16x16x32_bf16 v[146:149], v[180:183], v[146:149], v[82:85]
	v_mfma_f32_16x16x32_bf16 v[192:195], v[172:175], v[150:153], v[74:77]
	v_mfma_f32_16x16x32_bf16 v[150:153], v[180:183], v[150:153], v[66:69]
	v_mfma_f32_16x16x32_bf16 v[196:199], v[172:175], v[154:157], v[58:61]
	v_mfma_f32_16x16x32_bf16 v[154:157], v[180:183], v[154:157], v[50:53]
	v_mfma_f32_16x16x32_bf16 v[200:203], v[172:175], v[158:161], v[42:45]
	v_mfma_f32_16x16x32_bf16 v[158:161], v[180:183], v[158:161], v[34:37]
	v_mfma_f32_16x16x32_bf16 v[204:207], v[172:175], v[164:167], v[26:29]
	v_mfma_f32_16x16x32_bf16 v[164:167], v[180:183], v[164:167], v[18:21]
	v_mfma_f32_16x16x32_bf16 v[138:141], v[172:175], v[168:171], v[10:13]
	v_mfma_f32_16x16x32_bf16 v[168:171], v[180:183], v[168:171], v[2:5]
	s_nop 0
	s_nop 1
	ds_read_b128 v[2:5], v0 offset:24576
	ds_read_b128 v[10:13], v0 offset:25600
	ds_read_b128 v[18:21], v0 offset:26624
	ds_read_b128 v[26:29], v0 offset:27648
	ds_read_b128 v[34:37], v0 offset:28672
	ds_read_b128 v[172:175], v0 offset:29696
	ds_read_b128 v[176:179], v0 offset:30720
	ds_read_b128 v[180:183], v0 offset:31744
	ds_read_b128 v[208:211], v220 offset:40960
	ds_read_b128 v[212:215], v220 offset:41984
	ds_read_b128 v[216:219], v220 offset:43008
	ds_read_b128 v[220:223], v220 offset:44032
	s_nop 0
	s_waitcnt lgkmcnt(3)
	v_mfma_f32_16x16x32_bf16 v[224:227], v[208:211], v[2:5], v[126:129]
	v_mov_b32_e32 v0, v136
	s_waitcnt lgkmcnt(0)
	s_barrier
; DI unsigned pack2(float a, float b) { float2_t v = {a, b}; bf16x2_t r = __builtin_convertvector(v, bf16x2_t); return __builtin_bit_cast(unsigned, r); }
; #define EPI_BEGIN const int lr1_ = launder_v(lr), lq1_ = launder_v(lq), wr1_ = launder_v(wr), wc1_ = launder_v(wc); { const int lr = lr1_, lq = lq1_, wr = wr1_, wc = wc1_; (void)lr; (void)lq; (void)wr; (void)wc;
; DI void phase_zgemm(const Params& p, int l, char* smem) {
;     ...
;     EPI_BEGIN
; #pragma unroll
;     for (int mi = 0; mi < 8; mi += 2) {
;       const int m = m0 + wr * 128 + (mi + (lq & 1)) * 16 + lr;
; #pragma unroll
;       for (int ni = 0; ni < 4; ++ni) {
;         const int n = n0 + wc * 64 + ni * 16 + (lq >> 1) * 8;
;         const uint4 v = widen16(make_uint2(pack2(acc[mi][ni][0], acc[mi][ni][1]), pack2(acc[mi][ni][2], acc[mi][ni][3])),
;                                 make_uint2(pack2(acc[mi + 1][ni][0], acc[mi + 1][ni][1]), pack2(acc[mi + 1][ni][2], acc[mi + 1][ni][3])));
;         if (n < ZA) *(uint4*)(za + (size_t)m * ZA + n) = v;
;         else if (n < ZA + ZR) *(uint4*)(zr + (size_t)m * ZR + (n - ZA)) = v;
;       }
	s_waitcnt lgkmcnt(2)
	v_mfma_f32_16x16x32_bf16 v[114:117], v[212:215], v[2:5], v[122:125]
	s_movk_i32 s0, 0x900
	s_waitcnt lgkmcnt(1)
	v_mfma_f32_16x16x32_bf16 v[106:109], v[216:219], v[2:5], v[118:121]
	s_nop 0
	v_cvt_pk_bf16_f32 v122, v224, v225
	v_cvt_pk_bf16_f32 v123, v226, v227
	s_waitcnt lgkmcnt(0)
	v_mfma_f32_16x16x32_bf16 v[98:101], v[220:223], v[2:5], v[130:133]
	v_mov_b32_e32 v2, v137
	v_mov_b32_e32 v3, v134
	v_mov_b32_e32 v4, v135
	v_lshlrev_b32_e32 v3, 7, v3
	v_add3_u32 v132, v0, s5, v3
	v_lshlrev_b32_e32 v3, 2, v2
	v_and_b32_e32 v3, -8, v3
	v_lshlrev_b32_e32 v0, 6, v4
	v_add3_u32 v126, v3, s4, v0
	v_lshlrev_b32_e32 v0, 4, v2
	v_mfma_f32_16x16x32_bf16 v[228:231], v[208:211], v[10:13], v[110:113]
	v_and_b32_e32 v133, 16, v0
	v_add_u32_e32 v0, v132, v133
	v_mfma_f32_16x16x32_bf16 v[118:121], v[212:215], v[10:13], v[184:187]
	v_mfma_f32_16x16x32_bf16 v[110:113], v[216:219], v[10:13], v[102:105]
	s_nop 3
	v_cvt_pk_bf16_f32 v124, v228, v229
	v_cvt_pk_bf16_f32 v125, v230, v231
	s_nop 0
	v_permlane16_swap_b32_e32 v122, v124
	v_mfma_f32_16x16x32_bf16 v[102:105], v[220:223], v[10:13], v[142:145]
	v_permlane16_swap_b32_e32 v123, v125
	v_mfma_f32_16x16x32_bf16 v[10:13], v[216:219], v[176:179], v[22:25]
	s_nop 2
	v_mov_b64_e32 v[22:23], s[62:63]
	v_mfma_f32_16x16x32_bf16 v[90:93], v[208:211], v[18:21], v[94:97]
	v_mad_i64_i32 v[128:129], s[0:1], v0, s0, v[22:23]
	s_movk_i32 s0, 0x39f
	v_mfma_f32_16x16x32_bf16 v[82:85], v[212:215], v[18:21], v[188:191]
	v_cmp_lt_i32_e64 s[0:1], s0, v126
	v_mfma_f32_16x16x32_bf16 v[74:77], v[216:219], v[18:21], v[86:89]
	v_mfma_f32_16x16x32_bf16 v[66:69], v[220:223], v[18:21], v[146:149]
	v_mfma_f32_16x16x32_bf16 v[94:97], v[208:211], v[26:29], v[78:81]
	v_mfma_f32_16x16x32_bf16 v[86:89], v[212:215], v[26:29], v[192:195]
	v_mfma_f32_16x16x32_bf16 v[78:81], v[216:219], v[26:29], v[70:73]
	v_mfma_f32_16x16x32_bf16 v[70:73], v[220:223], v[26:29], v[150:153]
	v_mfma_f32_16x16x32_bf16 v[58:61], v[208:211], v[34:37], v[62:65]
	v_mfma_f32_16x16x32_bf16 v[50:53], v[212:215], v[34:37], v[196:199]
	v_mfma_f32_16x16x32_bf16 v[42:45], v[216:219], v[34:37], v[54:57]
	v_mfma_f32_16x16x32_bf16 v[34:37], v[220:223], v[34:37], v[154:157]
	v_mfma_f32_16x16x32_bf16 v[62:65], v[208:211], v[172:175], v[46:49]
	v_mfma_f32_16x16x32_bf16 v[54:57], v[212:215], v[172:175], v[200:203]
	v_mfma_f32_16x16x32_bf16 v[46:49], v[216:219], v[172:175], v[38:41]
	v_mfma_f32_16x16x32_bf16 v[38:41], v[220:223], v[172:175], v[158:161]
	v_mfma_f32_16x16x32_bf16 v[26:29], v[208:211], v[176:179], v[30:33]
	v_mfma_f32_16x16x32_bf16 v[18:21], v[212:215], v[176:179], v[204:207]
	v_mfma_f32_16x16x32_bf16 v[2:5], v[220:223], v[176:179], v[164:167]
	v_mfma_f32_16x16x32_bf16 v[30:33], v[208:211], v[180:183], v[14:17]
	v_mfma_f32_16x16x32_bf16 v[22:25], v[212:215], v[180:183], v[138:141]
	v_mfma_f32_16x16x32_bf16 v[14:17], v[216:219], v[180:183], v[6:9]
	v_mfma_f32_16x16x32_bf16 v[6:9], v[220:223], v[180:183], v[168:171]
	s_and_saveexec_b64 s[4:5], s[0:1]
	s_xor_b64 s[4:5], exec, s[4:5]
	s_cbranch_execz .LBB0_862
	s_movk_i32 s6, 0x820
	v_cmp_gt_u32_e32 vcc, s6, v126
	s_and_saveexec_b64 s[6:7], vcc
	s_cbranch_execz .LBB0_861
	v_mov_b32_e32 v127, v1
	v_lshl_add_u64 v[130:131], v[126:127], 1, v[128:129]
	v_add_co_u32_e32 v130, vcc, 0x47e0000, v130
	s_nop 1
	v_addc_co_u32_e32 v131, vcc, 0, v131, vcc
	flat_store_dwordx4 v[130:131], v[122:125] offset:2240

; template <int MI, int NI>
; DI void gemm256(f32x4 (&acc)[MI][NI], const u16* __restrict__ A, int lda, const u16* __restrict__ Bt, int ldb, int K, int m0, int n0, char* smem) {
;     ...
;   for (int kt = 0; kt < nk; ++kt) {
;     if (kt + 1 < nk) asm volatile("s_waitcnt vmcnt(%0) lgkmcnt(0)" :: "n"(LPS) : "memory");
;     else asm volatile("s_waitcnt vmcnt(0) lgkmcnt(0)" ::: "memory");
;     __builtin_amdgcn_s_barrier();
;     __builtin_amdgcn_s_setprio(1);
;     const char* sb = smem + st * STAGE + foff;
;     bf16x8 af[MI], bfr[NI];
; #pragma unroll
;     for (int mi = 0; mi < MI; ++mi) af[mi] = *(const bf16x8*)(sb + (wr * MI + mi) * 1024);
; #pragma unroll
;     for (int ni = 0; ni < NI; ++ni) bfr[ni] = *(const bf16x8*)(sb + ABYTES + (wc * NI + ni) * 1024);
;     __builtin_amdgcn_sched_barrier(0x0);
;     if (kt + 2 < nk) { const int s2 = st >= 1 ? st - 1 : 2; G256_ISSUE(s2, (kt + 2) * 32); }
;     __builtin_amdgcn_s_setprio(0);
; #pragma unroll
;     for (int mi = 0; mi < MI; ++mi)
; #pragma unroll
;       for (int ni = 0; ni < NI; ++ni)
;         acc[mi][ni] = __builtin_amdgcn_mfma_f32_16x16x32_bf16(bfr[ni], af[mi], acc[mi][ni], 0, 0, 0);
;     st = st == 2 ? 0 : st + 1;
;   }
.Lpipe_mlp2:
	v_add_u32_e32 v161, s11, v160
	ds_read_b128 v[156:159], v161 offset:4096
	ds_read_b128 v[164:167], v161 offset:5120
	ds_read_b128 v[168:171], v161 offset:6144
	ds_read_b128 v[172:175], v161 offset:7168
	s_add_i32 s12, s11, 0xffffa000
	s_cmp_eq_u32 s11, 0
	s_cselect_b32 s12, 0xc000, s12
	s_add_i32 s13, s12, s0
	s_add_i32 s12, s12, s1
	s_mov_b32 m0, s13
	s_waitcnt lgkmcnt(7)
	v_mfma_f32_16x16x32_bf16 v[126:129], v[176:179], v[140:143], v[126:129]
	global_load_lds_dwordx4 v[196:197], off
	v_mfma_f32_16x16x32_bf16 v[110:113], v[176:179], v[144:147], v[110:113]
	v_lshl_add_u64 v[196:197], v[196:197], 0, s[98:99]
	s_add_i32 m0, s13, 0x400
	v_mfma_f32_16x16x32_bf16 v[94:97], v[176:179], v[148:151], v[94:97]
	global_load_lds_dwordx4 v[198:199], off
	v_mfma_f32_16x16x32_bf16 v[78:81], v[176:179], v[152:155], v[78:81]
	v_lshl_add_u64 v[198:199], v[198:199], 0, s[98:99]
	s_add_i32 m0, s13, 0x800
	s_waitcnt lgkmcnt(6)
	v_mfma_f32_16x16x32_bf16 v[122:125], v[180:183], v[140:143], v[122:125]
	global_load_lds_dwordx4 v[200:201], off
	v_mfma_f32_16x16x32_bf16 v[106:109], v[180:183], v[144:147], v[106:109]
	v_lshl_add_u64 v[200:201], v[200:201], 0, s[98:99]
	s_add_i32 m0, s13, 0xc00
	v_mfma_f32_16x16x32_bf16 v[90:93], v[180:183], v[148:151], v[90:93]
	global_load_lds_dwordx4 v[202:203], off
	v_mfma_f32_16x16x32_bf16 v[74:77], v[180:183], v[152:155], v[74:77]
	v_lshl_add_u64 v[202:203], v[202:203], 0, s[98:99]
	s_mov_b32 m0, s12
	s_waitcnt lgkmcnt(5)
	v_mfma_f32_16x16x32_bf16 v[118:121], v[184:187], v[140:143], v[118:121]
	global_load_lds_dwordx4 v[204:205], off
	v_mfma_f32_16x16x32_bf16 v[102:105], v[184:187], v[144:147], v[102:105]
	v_lshl_add_u64 v[204:205], v[204:205], 0, s[98:99]
	s_add_i32 m0, s12, 0x400
	v_mfma_f32_16x16x32_bf16 v[86:89], v[184:187], v[148:151], v[86:89]
	global_load_lds_dwordx4 v[206:207], off
	v_mfma_f32_16x16x32_bf16 v[70:73], v[184:187], v[152:155], v[70:73]
	v_lshl_add_u64 v[206:207], v[206:207], 0, s[98:99]
	s_waitcnt lgkmcnt(4)
	v_mfma_f32_16x16x32_bf16 v[114:117], v[188:191], v[140:143], v[114:117]
	v_mfma_f32_16x16x32_bf16 v[98:101], v[188:191], v[144:147], v[98:101]
	v_mfma_f32_16x16x32_bf16 v[82:85], v[188:191], v[148:151], v[82:85]
	v_mfma_f32_16x16x32_bf16 v[66:69], v[188:191], v[152:155], v[66:69]
	s_waitcnt vmcnt(6) lgkmcnt(0)
	s_barrier
	s_add_i32 s13, s11, 0x6000
	s_cmp_eq_u32 s11, 0xc000
	s_cselect_b32 s11, 0, s13
	v_add_u32_e32 v192, s11, v160
	v_add_u32_e32 v193, s11, v0
	v_mfma_f32_16x16x32_bf16 v[62:65], v[176:179], v[156:159], v[62:65]
	ds_read_b128 v[140:143], v192
	v_mfma_f32_16x16x32_bf16 v[46:49], v[176:179], v[164:167], v[46:49]
	ds_read_b128 v[144:147], v192 offset:1024
	v_mfma_f32_16x16x32_bf16 v[30:33], v[176:179], v[168:171], v[30:33]
	ds_read_b128 v[148:151], v192 offset:2048
	v_mfma_f32_16x16x32_bf16 v[14:17], v[176:179], v[172:175], v[14:17]
	ds_read_b128 v[152:155], v192 offset:3072
	ds_read_b128 v[176:179], v193 offset:16384
	v_mfma_f32_16x16x32_bf16 v[58:61], v[180:183], v[156:159], v[58:61]
	v_mfma_f32_16x16x32_bf16 v[42:45], v[180:183], v[164:167], v[42:45]
	v_mfma_f32_16x16x32_bf16 v[26:29], v[180:183], v[168:171], v[26:29]
	v_mfma_f32_16x16x32_bf16 v[10:13], v[180:183], v[172:175], v[10:13]
	ds_read_b128 v[180:183], v193 offset:17408
	v_mfma_f32_16x16x32_bf16 v[54:57], v[184:187], v[156:159], v[54:57]
	v_mfma_f32_16x16x32_bf16 v[38:41], v[184:187], v[164:167], v[38:41]
	v_mfma_f32_16x16x32_bf16 v[22:25], v[184:187], v[168:171], v[22:25]
	v_mfma_f32_16x16x32_bf16 v[6:9], v[184:187], v[172:175], v[6:9]
	ds_read_b128 v[184:187], v193 offset:18432
	v_mfma_f32_16x16x32_bf16 v[50:53], v[188:191], v[156:159], v[50:53]
	v_mfma_f32_16x16x32_bf16 v[34:37], v[188:191], v[164:167], v[34:37]
	v_mfma_f32_16x16x32_bf16 v[18:21], v[188:191], v[168:171], v[18:21]
	v_mfma_f32_16x16x32_bf16 v[2:5], v[188:191], v[172:175], v[2:5]
	ds_read_b128 v[188:191], v193 offset:19456
	s_sub_i32 s100, s100, 1
	s_cmp_lg_u32 s100, 0
	s_cbranch_scc1 .Lpipe_mlp2
	v_add_u32_e32 v161, s11, v160
	ds_read_b128 v[156:159], v161 offset:4096
	ds_read_b128 v[164:167], v161 offset:5120
	ds_read_b128 v[168:171], v161 offset:6144
	ds_read_b128 v[172:175], v161 offset:7168
	s_add_i32 s12, s11, 0xffffa000
	s_cmp_eq_u32 s11, 0
	s_cselect_b32 s12, 0xc000, s12
	s_add_i32 s13, s12, s0
	s_add_i32 s12, s12, s1
	s_mov_b32 m0, s13
	s_waitcnt lgkmcnt(7)
	v_mfma_f32_16x16x32_bf16 v[126:129], v[176:179], v[140:143], v[126:129]
	global_load_lds_dwordx4 v[196:197], off
	v_mfma_f32_16x16x32_bf16 v[110:113], v[176:179], v[144:147], v[110:113]
	v_lshl_add_u64 v[196:197], v[196:197], 0, s[98:99]
	s_add_i32 m0, s13, 0x400
	v_mfma_f32_16x16x32_bf16 v[94:97], v[176:179], v[148:151], v[94:97]
	global_load_lds_dwordx4 v[198:199], off
	v_mfma_f32_16x16x32_bf16 v[78:81], v[176:179], v[152:155], v[78:81]
	v_lshl_add_u64 v[198:199], v[198:199], 0, s[98:99]
	s_add_i32 m0, s13, 0x800
	s_waitcnt lgkmcnt(6)
	v_mfma_f32_16x16x32_bf16 v[122:125], v[180:183], v[140:143], v[122:125]
	global_load_lds_dwordx4 v[200:201], off
	v_mfma_f32_16x16x32_bf16 v[106:109], v[180:183], v[144:147], v[106:109]
	v_lshl_add_u64 v[200:201], v[200:201], 0, s[98:99]
	s_add_i32 m0, s13, 0xc00
	v_mfma_f32_16x16x32_bf16 v[90:93], v[180:183], v[148:151], v[90:93]
	global_load_lds_dwordx4 v[202:203], off
	v_mfma_f32_16x16x32_bf16 v[74:77], v[180:183], v[152:155], v[74:77]
	v_lshl_add_u64 v[202:203], v[202:203], 0, s[98:99]
	s_mov_b32 m0, s12
	s_waitcnt lgkmcnt(5)
; template <int MI, int NI>
; DI void gemm256(f32x4 (&acc)[MI][NI], const u16* __restrict__ A, int lda, const u16* __restrict__ Bt, int ldb, int K, int m0, int n0, char* smem) {
;     ...
;     const char* sb = smem + st * STAGE + foff;
;     bf16x8 af[MI], bfr[NI];
; #pragma unroll
;     for (int mi = 0; mi < MI; ++mi) af[mi] = *(const bf16x8*)(sb + (wr * MI + mi) * 1024);
; #pragma unroll
;     for (int ni = 0; ni < NI; ++ni) bfr[ni] = *(const bf16x8*)(sb + ABYTES + (wc * NI + ni) * 1024);
;     __builtin_amdgcn_sched_barrier(0x0);
;     if (kt + 2 < nk) { const int s2 = st >= 1 ? st - 1 : 2; G256_ISSUE(s2, (kt + 2) * 32); }
;     __builtin_amdgcn_s_setprio(0);
; #pragma unroll
;     for (int mi = 0; mi < MI; ++mi)
; #pragma unroll
;       for (int ni = 0; ni < NI; ++ni)
;         acc[mi][ni] = __builtin_amdgcn_mfma_f32_16x16x32_bf16(bfr[ni], af[mi], acc[mi][ni], 0, 0, 0);
	v_mfma_f32_16x16x32_bf16 v[118:121], v[184:187], v[140:143], v[118:121]
	global_load_lds_dwordx4 v[204:205], off
	v_mfma_f32_16x16x32_bf16 v[102:105], v[184:187], v[144:147], v[102:105]
	v_lshl_add_u64 v[204:205], v[204:205], 0, s[98:99]
	s_add_i32 m0, s12, 0x400
	v_mfma_f32_16x16x32_bf16 v[86:89], v[184:187], v[148:151], v[86:89]
	global_load_lds_dwordx4 v[206:207], off
	v_mfma_f32_16x16x32_bf16 v[70:73], v[184:187], v[152:155], v[70:73]
	v_lshl_add_u64 v[206:207], v[206:207], 0, s[98:99]
	s_waitcnt lgkmcnt(4)
	v_mfma_f32_16x16x32_bf16 v[114:117], v[188:191], v[140:143], v[114:117]
	v_mfma_f32_16x16x32_bf16 v[98:101], v[188:191], v[144:147], v[98:101]
	v_mfma_f32_16x16x32_bf16 v[82:85], v[188:191], v[148:151], v[82:85]
	v_mfma_f32_16x16x32_bf16 v[66:69], v[188:191], v[152:155], v[66:69]
	s_waitcnt lgkmcnt(0)
	v_mfma_f32_16x16x32_bf16 v[62:65], v[176:179], v[156:159], v[62:65]
	v_mfma_f32_16x16x32_bf16 v[46:49], v[176:179], v[164:167], v[46:49]
	v_mfma_f32_16x16x32_bf16 v[30:33], v[176:179], v[168:171], v[30:33]
	v_mfma_f32_16x16x32_bf16 v[14:17], v[176:179], v[172:175], v[14:17]
	v_mfma_f32_16x16x32_bf16 v[58:61], v[180:183], v[156:159], v[58:61]
	v_mfma_f32_16x16x32_bf16 v[42:45], v[180:183], v[164:167], v[42:45]
	v_mfma_f32_16x16x32_bf16 v[26:29], v[180:183], v[168:171], v[26:29]
	v_mfma_f32_16x16x32_bf16 v[10:13], v[180:183], v[172:175], v[10:13]
	v_mfma_f32_16x16x32_bf16 v[54:57], v[184:187], v[156:159], v[54:57]
	v_mfma_f32_16x16x32_bf16 v[38:41], v[184:187], v[164:167], v[38:41]
	v_mfma_f32_16x16x32_bf16 v[22:25], v[184:187], v[168:171], v[22:25]
	v_mfma_f32_16x16x32_bf16 v[6:9], v[184:187], v[172:175], v[6:9]
	v_mfma_f32_16x16x32_bf16 v[50:53], v[188:191], v[156:159], v[50:53]
	v_mfma_f32_16x16x32_bf16 v[34:37], v[188:191], v[164:167], v[34:37]
	v_mfma_f32_16x16x32_bf16 v[18:21], v[188:191], v[168:171], v[18:21]
	v_mfma_f32_16x16x32_bf16 v[2:5], v[188:191], v[172:175], v[2:5]
	s_mov_b32 s10, 0
	s_waitcnt vmcnt(6) lgkmcnt(0)
	s_barrier
	s_nop 0
	s_mul_i32 s0, s10, 0x6000
	v_or_b32_e32 v0, s0, v138
	v_add_u32_e32 v136, v0, v139
	ds_read_b128 v[130:133], v136
	ds_read_b128 v[140:143], v136 offset:1024
	ds_read_b128 v[144:147], v136 offset:2048
	ds_read_b128 v[148:151], v136 offset:3072
	ds_read_b128 v[152:155], v136 offset:4096
	ds_read_b128 v[156:159], v136 offset:5120
	ds_read_b128 v[164:167], v136 offset:6144
	ds_read_b128 v[168:171], v136 offset:7168
	v_add_u32_e32 v0, v0, v135
	ds_read_b128 v[172:175], v0 offset:16384
	ds_read_b128 v[176:179], v0 offset:17408
	ds_read_b128 v[180:183], v0 offset:18432
	ds_read_b128 v[184:187], v0 offset:19456
	v_bfe_u32 v0, v134, 6, 1
	s_nop 0
	s_waitcnt vmcnt(0) lgkmcnt(0)
	s_waitcnt lgkmcnt(3)
	v_mfma_f32_16x16x32_bf16 v[126:129], v[172:175], v[130:133], v[126:129]
	v_ashrrev_i32_e32 v160, 7, v134
	v_and_b32_e32 v161, 15, v134
	v_bfe_u32 v134, v134, 4, 2
	s_waitcnt lgkmcnt(2)
	v_mfma_f32_16x16x32_bf16 v[122:125], v[176:179], v[130:133], v[122:125]
	s_barrier
	s_waitcnt lgkmcnt(1)
	v_mfma_f32_16x16x32_bf16 v[118:121], v[180:183], v[130:133], v[118:121]
	s_waitcnt lgkmcnt(0)
	v_mfma_f32_16x16x32_bf16 v[114:117], v[184:187], v[130:133], v[114:117]
	v_mfma_f32_16x16x32_bf16 v[110:113], v[172:175], v[140:143], v[110:113]
	v_mfma_f32_16x16x32_bf16 v[106:109], v[176:179], v[140:143], v[106:109]
	v_mfma_f32_16x16x32_bf16 v[102:105], v[180:183], v[140:143], v[102:105]
	v_mfma_f32_16x16x32_bf16 v[98:101], v[184:187], v[140:143], v[98:101]
	v_mfma_f32_16x16x32_bf16 v[94:97], v[172:175], v[144:147], v[94:97]
	v_mfma_f32_16x16x32_bf16 v[90:93], v[176:179], v[144:147], v[90:93]
	v_mfma_f32_16x16x32_bf16 v[86:89], v[180:183], v[144:147], v[86:89]
	v_mfma_f32_16x16x32_bf16 v[82:85], v[184:187], v[144:147], v[82:85]
	v_mfma_f32_16x16x32_bf16 v[78:81], v[172:175], v[148:151], v[78:81]
	v_mfma_f32_16x16x32_bf16 v[130:133], v[176:179], v[148:151], v[74:77]
	v_mfma_f32_16x16x32_bf16 v[70:73], v[180:183], v[148:151], v[70:73]
	v_mfma_f32_16x16x32_bf16 v[66:69], v[184:187], v[148:151], v[66:69]
	v_mfma_f32_16x16x32_bf16 v[62:65], v[172:175], v[152:155], v[62:65]
	v_mfma_f32_16x16x32_bf16 v[58:61], v[176:179], v[152:155], v[58:61]
	v_mfma_f32_16x16x32_bf16 v[54:57], v[180:183], v[152:155], v[54:57]
	v_mfma_f32_16x16x32_bf16 v[50:53], v[184:187], v[152:155], v[50:53]
	v_mfma_f32_16x16x32_bf16 v[46:49], v[172:175], v[156:159], v[46:49]
	v_mfma_f32_16x16x32_bf16 v[42:45], v[176:179], v[156:159], v[42:45]
	v_mfma_f32_16x16x32_bf16 v[38:41], v[180:183], v[156:159], v[38:41]
	v_mfma_f32_16x16x32_bf16 v[34:37], v[184:187], v[156:159], v[34:37]
	v_mfma_f32_16x16x32_bf16 v[30:33], v[172:175], v[164:167], v[30:33]
	v_mfma_f32_16x16x32_bf16 v[26:29], v[176:179], v[164:167], v[26:29]
	v_mfma_f32_16x16x32_bf16 v[22:25], v[180:183], v[164:167], v[22:25]
	v_mfma_f32_16x16x32_bf16 v[18:21], v[184:187], v[164:167], v[18:21]
	v_mfma_f32_16x16x32_bf16 v[14:17], v[172:175], v[168:171], v[14:17]
	v_mfma_f32_16x16x32_bf16 v[10:13], v[176:179], v[168:171], v[10:13]
	v_mfma_f32_16x16x32_bf16 v[6:9], v[180:183], v[168:171], v[6:9]
	v_mfma_f32_16x16x32_bf16 v[140:143], v[184:187], v[168:171], v[2:5]
	s_nop 0
	s_addk_i32 s0, 0x6000
	s_cmp_lg_u32 s10, 2
	s_cselect_b32 s0, s0, 0
	v_or_b32_e32 v168, s0, v138
	v_add_u32_e32 v164, v168, v139
	ds_read_b128 v[2:5], v164
	ds_read_b128 v[74:77], v164 offset:1024
	ds_read_b128 v[136:139], v164 offset:2048
	ds_read_b128 v[144:147], v164 offset:3072
	ds_read_b128 v[148:151], v164 offset:4096
	ds_read_b128 v[152:155], v164 offset:5120
	ds_read_b128 v[156:159], v164 offset:6144
	ds_read_b128 v[164:167], v164 offset:7168
	v_add_u32_e32 v135, v168, v135
	ds_read_b128 v[168:171], v135 offset:16384
	ds_read_b128 v[172:175], v135 offset:17408
	ds_read_b128 v[176:179], v135 offset:18432
	ds_read_b128 v[180:183], v135 offset:19456
	s_nop 0
	s_waitcnt lgkmcnt(3)
	v_mfma_f32_16x16x32_bf16 v[126:129], v[168:171], v[2:5], v[126:129]
	s_waitcnt lgkmcnt(0)
	s_barrier
; template <int MI, int NI>
; DI void gemm256(f32x4 (&acc)[MI][NI], const u16* __restrict__ A, int lda, const u16* __restrict__ Bt, int ldb, int K, int m0, int n0, char* smem) {
;     ...
;     for (int mi = 0; mi < MI; ++mi)
; #pragma unroll
;       for (int ni = 0; ni < NI; ++ni)
;         acc[mi][ni] = __builtin_amdgcn_mfma_f32_16x16x32_bf16(bfr[ni], af[mi], acc[mi][ni], 0, 0, 0);
; template <int MI, int NI>
; DI void resid_tile(const u16* A, int K, const u16* Bt, const float* gate, const float* xl_in, const float* xc_in, float* xl_out, float* xc_out,
;                    int m0, int n0, char* smem) {
;     ...
; #pragma unroll
;   for (int mi = 0; mi < MI; ++mi) {
;     const int m = m0 + wr * 16 * MI + mi * 16 + lr;
;     const int b9 = m < NTL ? m >> 12 : 8;
;     const float* xi = xrow(xl_in, xc_in, m);
;     float* xo = m < NTL ? xl_out + (size_t)m * D : xc_out + (size_t)(m - NTL) * D;
; #pragma unroll
;     for (int ni = 0; ni < NI; ++ni) {
;       const int n = n0 + wc * 16 * NI + ni * 16 + lq * 4;
;       const float4 g = *(const float4*)(gate + (size_t)b9 * 6144 + n);
;       const float4 xv = *(const float4*)(xi + n);
;       float4 ov;
;       ov.x = xv.x + g.x * acc[mi][ni][0]; ov.y = xv.y + g.y * acc[mi][ni][1]; ov.z = xv.z + g.z * acc[mi][ni][2]; ov.w = xv.w + g.w * acc[mi][ni][3];
;       *(float4*)(xo + n) = ov;
;     }
	s_waitcnt lgkmcnt(2)
	v_mfma_f32_16x16x32_bf16 v[122:125], v[172:175], v[2:5], v[122:125]
	s_waitcnt lgkmcnt(1)
	v_mfma_f32_16x16x32_bf16 v[184:187], v[176:179], v[2:5], v[118:121]
	v_lshlrev_b32_e32 v0, 6, v0
	s_waitcnt lgkmcnt(0)
	v_mfma_f32_16x16x32_bf16 v[188:191], v[180:183], v[2:5], v[114:117]
	v_lshlrev_b32_e32 v2, 7, v160
	v_mov_b32_e32 v118, s95
	v_mov_b32_e32 v119, s49
	v_add3_u32 v116, v161, s8, v2
	v_lshlrev_b32_e32 v2, 2, v134
	v_add3_u32 v2, v2, s9, v0
	v_min_i32_e32 v0, 0x8000, v116
	v_mfma_f32_16x16x32_bf16 v[110:113], v[168:171], v[74:77], v[110:113]
	v_ashrrev_i32_e32 v117, 31, v116
	v_cmp_gt_i32_e32 vcc, s58, v116
	v_mov_b32_e32 v120, s94
	v_mfma_f32_16x16x32_bf16 v[106:109], v[172:175], v[74:77], v[106:109]
	v_cndmask_b32_e32 v5, 0, v117, vcc
	v_mov_b32_e32 v121, s48
	v_cndmask_b32_e32 v115, v118, v119, vcc
	v_mfma_f32_16x16x32_bf16 v[102:105], v[176:179], v[74:77], v[102:105]
	v_cndmask_b32_e32 v114, v120, v121, vcc
	v_ashrrev_i32_e32 v3, 31, v2
	v_mfma_f32_16x16x32_bf16 v[98:101], v[180:183], v[74:77], v[98:101]
	v_mfma_f32_16x16x32_bf16 v[74:77], v[168:171], v[144:147], v[78:81]
	v_mfma_f32_16x16x32_bf16 v[78:81], v[172:175], v[144:147], v[130:133]
	s_nop 2
	v_ashrrev_i32_e32 v130, 12, v0
	v_add_u32_e32 v0, 0xffff8000, v116
	v_cndmask_b32_e32 v4, v0, v116, vcc
	v_lshlrev_b64 v[4:5], 12, v[4:5]
	v_lshl_add_u64 v[4:5], v[114:115], 0, v[4:5]
	v_mul_hi_i32_i24_e32 v115, 0x6000, v130
	v_mul_i32_i24_e32 v114, 0x6000, v130
	v_lshl_add_u64 v[130:131], s[82:83], 0, v[114:115]
	v_lshlrev_b64 v[114:115], 2, v[2:3]
	v_mfma_f32_16x16x32_bf16 v[94:97], v[168:171], v[136:139], v[94:97]
	v_lshl_add_u64 v[134:135], v[130:131], 0, v[114:115]
	v_mfma_f32_16x16x32_bf16 v[90:93], v[172:175], v[136:139], v[90:93]
	v_mfma_f32_16x16x32_bf16 v[86:89], v[176:179], v[136:139], v[86:89]
	v_mfma_f32_16x16x32_bf16 v[82:85], v[180:183], v[136:139], v[82:85]
	v_lshl_add_u64 v[136:137], v[4:5], 0, v[114:115]
	flat_load_dwordx4 v[2:5], v[134:135]
	flat_load_dwordx4 v[130:133], v[136:137]
	v_mfma_f32_16x16x32_bf16 v[70:73], v[176:179], v[144:147], v[70:73]
	v_lshlrev_b64 v[138:139], 12, v[116:117]
	v_lshl_add_u64 v[138:139], s[48:49], 0, v[138:139]
	s_waitcnt vmcnt(0) lgkmcnt(0)
	v_pk_fma_f32 v[2:3], v[126:127], v[2:3], v[130:131]
	v_mfma_f32_16x16x32_bf16 v[66:69], v[180:183], v[144:147], v[66:69]
	v_lshlrev_b64 v[144:145], 12, v[0:1]
	v_lshl_add_u64 v[144:145], s[94:95], 0, v[144:145]
	v_cndmask_b32_e32 v139, v145, v139, vcc
	v_cndmask_b32_e32 v138, v144, v138, vcc
	v_lshl_add_u64 v[138:139], v[138:139], 0, v[114:115]
	v_pk_fma_f32 v[4:5], v[128:129], v[4:5], v[132:133]
	flat_store_dwordx4 v[138:139], v[2:5]
	flat_load_dwordx4 v[126:129], v[134:135] offset:64
	flat_load_dwordx4 v[130:133], v[136:137] offset:64
	v_mfma_f32_16x16x32_bf16 v[2:5], v[172:175], v[164:167], v[10:13]
	v_mfma_f32_16x16x32_bf16 v[62:65], v[168:171], v[148:151], v[62:65]
	s_waitcnt vmcnt(0) lgkmcnt(0)
	s_nop 0
	v_pk_fma_f32 v[10:11], v[122:123], v[126:127], v[130:131]
	v_pk_fma_f32 v[12:13], v[124:125], v[128:129], v[132:133]
	flat_store_dwordx4 v[138:139], v[10:13] offset:64
	flat_load_dwordx4 v[10:13], v[134:135] offset:128
	s_nop 0
	flat_load_dwordx4 v[122:125], v[136:137] offset:128
	v_mfma_f32_16x16x32_bf16 v[58:61], v[172:175], v[148:151], v[58:61]
	s_waitcnt vmcnt(0) lgkmcnt(0)
	v_pk_fma_f32 v[10:11], v[184:185], v[10:11], v[122:123]
	v_pk_fma_f32 v[12:13], v[186:187], v[12:13], v[124:125]
	flat_store_dwordx4 v[138:139], v[10:13] offset:128
	flat_load_dwordx4 v[122:125], v[134:135] offset:192
	flat_load_dwordx4 v[126:129], v[136:137] offset:192
	v_mfma_f32_16x16x32_bf16 v[54:57], v[176:179], v[148:151], v[54:57]
	s_waitcnt vmcnt(0) lgkmcnt(0)
	v_pk_fma_f32 v[122:123], v[188:189], v[122:123], v[126:127]
	v_pk_fma_f32 v[124:125], v[190:191], v[124:125], v[128:129]
	v_mfma_f32_16x16x32_bf16 v[50:53], v[180:183], v[148:151], v[50:53]
	flat_store_dwordx4 v[138:139], v[122:125] offset:192
	v_mfma_f32_16x16x32_bf16 v[46:49], v[168:171], v[152:155], v[46:49]
	v_mfma_f32_16x16x32_bf16 v[42:45], v[172:175], v[152:155], v[42:45]
	v_mfma_f32_16x16x32_bf16 v[38:41], v[176:179], v[152:155], v[38:41]
	v_mfma_f32_16x16x32_bf16 v[34:37], v[180:183], v[152:155], v[34:37]
	v_mfma_f32_16x16x32_bf16 v[30:33], v[168:171], v[156:159], v[30:33]
	v_mfma_f32_16x16x32_bf16 v[26:29], v[172:175], v[156:159], v[26:29]
	v_mfma_f32_16x16x32_bf16 v[22:25], v[176:179], v[156:159], v[22:25]
	v_mfma_f32_16x16x32_bf16 v[18:21], v[180:183], v[156:159], v[18:21]
	v_mfma_f32_16x16x32_bf16 v[14:17], v[168:171], v[164:167], v[14:17]
	v_mfma_f32_16x16x32_bf16 v[6:9], v[176:179], v[164:167], v[6:9]
	v_mfma_f32_16x16x32_bf16 v[10:13], v[180:183], v[164:167], v[140:143]
	v_add_u32_e32 v122, 16, v116
	v_min_i32_e32 v0, 0x8000, v122
	v_cmp_gt_i32_e32 vcc, s58, v122
	v_ashrrev_i32_e32 v117, 12, v0
	v_add_u32_e32 v0, 0xffff8010, v116
	v_ashrrev_i32_e32 v123, 31, v122
	v_cndmask_b32_e32 v125, 0, v123, vcc
	v_cndmask_b32_e32 v124, v0, v122, vcc
	v_cndmask_b32_e32 v127, v118, v119, vcc
	v_cndmask_b32_e32 v126, v120, v121, vcc
	v_lshlrev_b64 v[124:125], 12, v[124:125]
	v_lshl_add_u64 v[124:125], v[126:127], 0, v[124:125]
	v_lshlrev_b64 v[122:123], 12, v[122:123]
	v_lshlrev_b64 v[126:127], 12, v[0:1]
	v_lshl_add_u64 v[122:123], s[48:49], 0, v[122:123]
	v_lshl_add_u64 v[126:127], s[94:95], 0, v[126:127]
	v_cndmask_b32_e32 v123, v127, v123, vcc
	v_cndmask_b32_e32 v122, v126, v122, vcc
	v_mul_hi_i32_i24_e32 v127, 0x6000, v117
	v_mul_i32_i24_e32 v126, 0x6000, v117
	v_lshl_add_u64 v[126:127], s[82:83], 0, v[126:127]
	v_lshl_add_u64 v[130:131], v[126:127], 0, v[114:115]
	v_lshl_add_u64 v[132:133], v[124:125], 0, v[114:115]
	v_lshl_add_u64 v[134:135], v[122:123], 0, v[114:115]
	global_load_dwordx4 v[156:159], v[130:131], off
	global_load_dwordx4 v[164:167], v[130:131], off offset:64
	global_load_dwordx4 v[168:171], v[130:131], off offset:128
	global_load_dwordx4 v[172:175], v[130:131], off offset:192
	global_load_dwordx4 v[140:143], v[132:133], off
	global_load_dwordx4 v[144:147], v[132:133], off offset:64
	global_load_dwordx4 v[148:151], v[132:133], off offset:128
	global_load_dwordx4 v[152:155], v[132:133], off offset:192
	v_mov_b32_e32 v216, 0x10000
	v_mov_b32_e32 v217, 0
	v_lshl_add_u64 v[212:213], v[132:133], 0, v[216:217]
	v_lshl_add_u64 v[214:215], v[134:135], 0, v[216:217]
	global_load_dwordx4 v[176:179], v[212:213], off
	global_load_dwordx4 v[180:183], v[212:213], off offset:64
	global_load_dwordx4 v[184:187], v[212:213], off offset:128
	global_load_dwordx4 v[188:191], v[212:213], off offset:192
	v_lshl_add_u64 v[212:213], v[212:213], 0, v[216:217]
	s_waitcnt vmcnt(4)
; template <int MI, int NI>
; DI void resid_tile(const u16* A, int K, const u16* Bt, const float* gate, const float* xl_in, const float* xc_in, float* xl_out, float* xc_out,
;                    int m0, int n0, char* smem) {
;     ...
; #pragma unroll
;   for (int mi = 0; mi < MI; ++mi) {
;     const int m = m0 + wr * 16 * MI + mi * 16 + lr;
;     const int b9 = m < NTL ? m >> 12 : 8;
;     const float* xi = xrow(xl_in, xc_in, m);
;     float* xo = m < NTL ? xl_out + (size_t)m * D : xc_out + (size_t)(m - NTL) * D;
; #pragma unroll
;     for (int ni = 0; ni < NI; ++ni) {
;       const int n = n0 + wc * 16 * NI + ni * 16 + lq * 4;
;       const float4 g = *(const float4*)(gate + (size_t)b9 * 6144 + n);
;       const float4 xv = *(const float4*)(xi + n);
;       float4 ov;
;       ov.x = xv.x + g.x * acc[mi][ni][0]; ov.y = xv.y + g.y * acc[mi][ni][1]; ov.z = xv.z + g.z * acc[mi][ni][2]; ov.w = xv.w + g.w * acc[mi][ni][3];
;       *(float4*)(xo + n) = ov;
;     }
;     __builtin_amdgcn_sched_barrier(0);
	v_pk_fma_f32 v[110:111], v[110:111], v[156:157], v[140:141]
	v_pk_fma_f32 v[112:113], v[112:113], v[158:159], v[142:143]
	v_pk_fma_f32 v[106:107], v[106:107], v[164:165], v[144:145]
	v_pk_fma_f32 v[108:109], v[108:109], v[166:167], v[146:147]
	v_pk_fma_f32 v[102:103], v[102:103], v[168:169], v[148:149]
	v_pk_fma_f32 v[104:105], v[104:105], v[170:171], v[150:151]
	v_pk_fma_f32 v[98:99], v[98:99], v[172:173], v[152:153]
	v_pk_fma_f32 v[100:101], v[100:101], v[174:175], v[154:155]
	global_store_dwordx4 v[134:135], v[110:113], off
	global_store_dwordx4 v[134:135], v[106:109], off offset:64
	global_store_dwordx4 v[134:135], v[102:105], off offset:128
	global_store_dwordx4 v[134:135], v[98:101], off offset:192
	global_load_dwordx4 v[140:143], v[212:213], off
	global_load_dwordx4 v[144:147], v[212:213], off offset:64
	global_load_dwordx4 v[148:151], v[212:213], off offset:128
	global_load_dwordx4 v[152:155], v[212:213], off offset:192
	v_lshl_add_u64 v[212:213], v[212:213], 0, v[216:217]
	s_waitcnt vmcnt(8)
	v_pk_fma_f32 v[94:95], v[94:95], v[156:157], v[176:177]
	v_pk_fma_f32 v[96:97], v[96:97], v[158:159], v[178:179]
	v_pk_fma_f32 v[90:91], v[90:91], v[164:165], v[180:181]
	v_pk_fma_f32 v[92:93], v[92:93], v[166:167], v[182:183]
	v_pk_fma_f32 v[86:87], v[86:87], v[168:169], v[184:185]
	v_pk_fma_f32 v[88:89], v[88:89], v[170:171], v[186:187]
	v_pk_fma_f32 v[82:83], v[82:83], v[172:173], v[188:189]
	v_pk_fma_f32 v[84:85], v[84:85], v[174:175], v[190:191]
	global_store_dwordx4 v[214:215], v[94:97], off
	global_store_dwordx4 v[214:215], v[90:93], off offset:64
	global_store_dwordx4 v[214:215], v[86:89], off offset:128
	global_store_dwordx4 v[214:215], v[82:85], off offset:192
	v_lshl_add_u64 v[214:215], v[214:215], 0, v[216:217]
	global_load_dwordx4 v[176:179], v[212:213], off
	global_load_dwordx4 v[180:183], v[212:213], off offset:64
	global_load_dwordx4 v[184:187], v[212:213], off offset:128
	global_load_dwordx4 v[188:191], v[212:213], off offset:192
	v_lshl_add_u64 v[212:213], v[212:213], 0, v[216:217]
	s_waitcnt vmcnt(8)
	v_pk_fma_f32 v[74:75], v[74:75], v[156:157], v[140:141]
	v_pk_fma_f32 v[76:77], v[76:77], v[158:159], v[142:143]
	v_pk_fma_f32 v[78:79], v[78:79], v[164:165], v[144:145]
	v_pk_fma_f32 v[80:81], v[80:81], v[166:167], v[146:147]
	v_pk_fma_f32 v[70:71], v[70:71], v[168:169], v[148:149]
	v_pk_fma_f32 v[72:73], v[72:73], v[170:171], v[150:151]
	v_pk_fma_f32 v[66:67], v[66:67], v[172:173], v[152:153]
	v_pk_fma_f32 v[68:69], v[68:69], v[174:175], v[154:155]
	global_store_dwordx4 v[214:215], v[74:77], off
	global_store_dwordx4 v[214:215], v[78:81], off offset:64
	global_store_dwordx4 v[214:215], v[70:73], off offset:128
	global_store_dwordx4 v[214:215], v[66:69], off offset:192
	v_lshl_add_u64 v[214:215], v[214:215], 0, v[216:217]
	global_load_dwordx4 v[140:143], v[212:213], off
	global_load_dwordx4 v[144:147], v[212:213], off offset:64
	global_load_dwordx4 v[148:151], v[212:213], off offset:128
	global_load_dwordx4 v[152:155], v[212:213], off offset:192
	v_lshl_add_u64 v[212:213], v[212:213], 0, v[216:217]
	s_waitcnt vmcnt(8)
	v_pk_fma_f32 v[62:63], v[62:63], v[156:157], v[176:177]
	v_pk_fma_f32 v[64:65], v[64:65], v[158:159], v[178:179]
	v_pk_fma_f32 v[58:59], v[58:59], v[164:165], v[180:181]
	v_pk_fma_f32 v[60:61], v[60:61], v[166:167], v[182:183]
	v_pk_fma_f32 v[54:55], v[54:55], v[168:169], v[184:185]
	v_pk_fma_f32 v[56:57], v[56:57], v[170:171], v[186:187]
	v_pk_fma_f32 v[50:51], v[50:51], v[172:173], v[188:189]
	v_pk_fma_f32 v[52:53], v[52:53], v[174:175], v[190:191]
	global_store_dwordx4 v[214:215], v[62:65], off
	global_store_dwordx4 v[214:215], v[58:61], off offset:64
	global_store_dwordx4 v[214:215], v[54:57], off offset:128
	global_store_dwordx4 v[214:215], v[50:53], off offset:192
	v_lshl_add_u64 v[214:215], v[214:215], 0, v[216:217]
	global_load_dwordx4 v[176:179], v[212:213], off
	global_load_dwordx4 v[180:183], v[212:213], off offset:64
	global_load_dwordx4 v[184:187], v[212:213], off offset:128
	global_load_dwordx4 v[188:191], v[212:213], off offset:192
	v_lshl_add_u64 v[212:213], v[212:213], 0, v[216:217]
	s_waitcnt vmcnt(8)
	v_pk_fma_f32 v[46:47], v[46:47], v[156:157], v[140:141]
	v_pk_fma_f32 v[48:49], v[48:49], v[158:159], v[142:143]
	v_pk_fma_f32 v[42:43], v[42:43], v[164:165], v[144:145]
	v_pk_fma_f32 v[44:45], v[44:45], v[166:167], v[146:147]
	v_pk_fma_f32 v[38:39], v[38:39], v[168:169], v[148:149]
	v_pk_fma_f32 v[40:41], v[40:41], v[170:171], v[150:151]
	v_pk_fma_f32 v[34:35], v[34:35], v[172:173], v[152:153]
	v_pk_fma_f32 v[36:37], v[36:37], v[174:175], v[154:155]
	global_store_dwordx4 v[214:215], v[46:49], off
	global_store_dwordx4 v[214:215], v[42:45], off offset:64
	global_store_dwordx4 v[214:215], v[38:41], off offset:128
	global_store_dwordx4 v[214:215], v[34:37], off offset:192
	v_lshl_add_u64 v[214:215], v[214:215], 0, v[216:217]
	global_load_dwordx4 v[140:143], v[212:213], off
	global_load_dwordx4 v[144:147], v[212:213], off offset:64
	global_load_dwordx4 v[148:151], v[212:213], off offset:128
	global_load_dwordx4 v[152:155], v[212:213], off offset:192
	s_waitcnt vmcnt(8)
	v_pk_fma_f32 v[30:31], v[30:31], v[156:157], v[176:177]
	v_pk_fma_f32 v[32:33], v[32:33], v[158:159], v[178:179]
	v_pk_fma_f32 v[26:27], v[26:27], v[164:165], v[180:181]
	v_pk_fma_f32 v[28:29], v[28:29], v[166:167], v[182:183]
	v_pk_fma_f32 v[22:23], v[22:23], v[168:169], v[184:185]
	v_pk_fma_f32 v[24:25], v[24:25], v[170:171], v[186:187]
	v_pk_fma_f32 v[18:19], v[18:19], v[172:173], v[188:189]
	v_pk_fma_f32 v[20:21], v[20:21], v[174:175], v[190:191]
	global_store_dwordx4 v[214:215], v[30:33], off
	global_store_dwordx4 v[214:215], v[26:29], off offset:64
	global_store_dwordx4 v[214:215], v[22:25], off offset:128
	global_store_dwordx4 v[214:215], v[18:21], off offset:192
	v_lshl_add_u64 v[214:215], v[214:215], 0, v[216:217]
	s_waitcnt vmcnt(4)
	v_pk_fma_f32 v[14:15], v[14:15], v[156:157], v[140:141]
	v_pk_fma_f32 v[16:17], v[16:17], v[158:159], v[142:143]
	v_pk_fma_f32 v[2:3], v[2:3], v[164:165], v[144:145]
	v_pk_fma_f32 v[4:5], v[4:5], v[166:167], v[146:147]
	v_pk_fma_f32 v[6:7], v[6:7], v[168:169], v[148:149]
	v_pk_fma_f32 v[8:9], v[8:9], v[170:171], v[150:151]
	v_pk_fma_f32 v[10:11], v[10:11], v[172:173], v[152:153]
	v_pk_fma_f32 v[12:13], v[12:13], v[174:175], v[154:155]
	global_store_dwordx4 v[214:215], v[14:17], off
	global_store_dwordx4 v[214:215], v[2:5], off offset:64
	global_store_dwordx4 v[214:215], v[6:9], off offset:128
	global_store_dwordx4 v[214:215], v[10:13], off offset:192
	s_add_i32 s7, s7, 1
	s_mul_i32 s0, s7, s39
	s_add_i32 s0, s0, s5
	s_cmpk_gt_i32 s0, 0x7f
	s_cbranch_scc0 .LBB0_961

; template <int MI, int NI>
; DI void gemm256(f32x4 (&acc)[MI][NI], const u16* __restrict__ A, int lda, const u16* __restrict__ Bt, int ldb, int K, int m0, int n0, char* smem) {
;     ...
;   for (int kt = 0; kt < nk; ++kt) {
;     if (kt + 1 < nk) asm volatile("s_waitcnt vmcnt(%0) lgkmcnt(0)" :: "n"(LPS) : "memory");
;     else asm volatile("s_waitcnt vmcnt(0) lgkmcnt(0)" ::: "memory");
;     __builtin_amdgcn_s_barrier();
;     __builtin_amdgcn_s_setprio(1);
;     const char* sb = smem + st * STAGE + foff;
;     bf16x8 af[MI], bfr[NI];
; #pragma unroll
;     for (int mi = 0; mi < MI; ++mi) af[mi] = *(const bf16x8*)(sb + (wr * MI + mi) * 1024);
; #pragma unroll
;     for (int ni = 0; ni < NI; ++ni) bfr[ni] = *(const bf16x8*)(sb + ABYTES + (wc * NI + ni) * 1024);
;     __builtin_amdgcn_sched_barrier(0x0);
;     if (kt + 2 < nk) { const int s2 = st >= 1 ? st - 1 : 2; G256_ISSUE(s2, (kt + 2) * 32); }
;     __builtin_amdgcn_s_setprio(0);
; #pragma unroll
;     for (int mi = 0; mi < MI; ++mi)
; #pragma unroll
;       for (int ni = 0; ni < NI; ++ni)
;         acc[mi][ni] = __builtin_amdgcn_mfma_f32_16x16x32_bf16(bfr[ni], af[mi], acc[mi][ni], 0, 0, 0);
;     st = st == 2 ? 0 : st + 1;
;   }
.LBB0_967:
	s_waitcnt vmcnt(2) lgkmcnt(0)
	s_barrier
	s_nop 0
	s_lshl_b32 s10, s9, 13
	v_or_b32_e32 v0, s10, v24
	v_add_u32_e32 v28, v0, v26
	v_add_u32_e32 v32, v0, v25
	v_add_u32_e32 v0, v0, v23
	ds_read_b128 v[28:31], v28
	ds_read_b128 v[32:35], v32
	ds_read_b128 v[36:39], v0 offset:4096
	ds_read_b128 v[40:43], v0 offset:5120
	s_addk_i32 s10, 0xe000
	s_cmp_gt_i32 s9, 0
	s_cselect_b32 s10, s10, 0x4000
	v_add_u32_e32 v0, s10, v27
	v_add_u32_e32 v52, 0x1000, v0
	v_lshl_add_u64 v[48:49], v[18:19], 0, s[0:1]
	v_lshl_add_u64 v[48:49], v[48:49], 0, s[0:1]
	v_readfirstlane_b32 s10, v0
	v_lshl_add_u64 v[44:45], v[20:21], 0, s[0:1]
	v_lshl_add_u64 v[44:45], v[44:45], 0, s[0:1]
	s_mov_b64 s[98:99], 0x47e1100
	v_lshl_add_u64 v[50:51], v[48:49], 0, s[98:99]
	s_mov_b32 m0, s10
	v_readfirstlane_b32 s10, v52
	s_mov_b64 s[98:99], 0x2061100
	v_lshl_add_u64 v[46:47], v[44:45], 0, s[98:99]
	global_load_lds_dwordx4 v[50:51], off
	s_mov_b32 m0, s10
	s_nop 0
	global_load_lds_dwordx4 v[46:47], off
	s_nop 0
	s_waitcnt lgkmcnt(0)
	v_mfma_f32_16x16x32_bf16 v[14:17], v[36:39], v[28:31], v[14:17]
	s_add_i32 s10, s9, 1
	s_waitcnt vmcnt(2) lgkmcnt(0)
	s_cmp_lg_u32 s9, 2
	v_mfma_f32_16x16x32_bf16 v[10:13], v[40:43], v[28:31], v[10:13]
	s_cselect_b32 s9, s10, 0
	s_barrier
	v_mfma_f32_16x16x32_bf16 v[2:5], v[36:39], v[32:35], v[2:5]
	v_mfma_f32_16x16x32_bf16 v[6:9], v[40:43], v[32:35], v[6:9]
	s_nop 0
	s_lshl_b32 s10, s9, 13
	v_or_b32_e32 v0, s10, v24
	v_add_u32_e32 v28, v0, v26
	v_add_u32_e32 v32, v0, v25
	v_add_u32_e32 v0, v0, v23
	ds_read_b128 v[28:31], v28
	ds_read_b128 v[32:35], v32
	ds_read_b128 v[36:39], v0 offset:4096
	ds_read_b128 v[40:43], v0 offset:5120
	s_addk_i32 s10, 0xe000
	s_cmp_gt_i32 s9, 0
	s_cselect_b32 s10, s10, 0x4000
	v_add_u32_e32 v0, s10, v27
	s_mov_b64 s[10:11], 0x20610c0
	v_add_u32_e32 v52, 0x1000, v0
	s_mov_b64 s[98:99], 0x2061180
	v_lshl_add_u64 v[46:47], v[44:45], 0, s[98:99]
	v_readfirstlane_b32 s10, v0
	s_mov_b64 s[98:99], 0x47e1180
	v_lshl_add_u64 v[50:51], v[48:49], 0, s[98:99]
	s_mov_b32 m0, s10
	v_readfirstlane_b32 s10, v52
	global_load_lds_dwordx4 v[50:51], off
	s_mov_b32 m0, s10
	s_nop 0
	global_load_lds_dwordx4 v[46:47], off
	s_nop 0
	s_waitcnt lgkmcnt(0)
	v_mfma_f32_16x16x32_bf16 v[14:17], v[36:39], v[28:31], v[14:17]
	s_add_i32 s10, s9, 1
	s_waitcnt vmcnt(2) lgkmcnt(0)
	s_cmp_lg_u32 s9, 2
	v_mfma_f32_16x16x32_bf16 v[10:13], v[40:43], v[28:31], v[10:13]
	s_cselect_b32 s9, s10, 0
	s_barrier
	v_mfma_f32_16x16x32_bf16 v[2:5], v[36:39], v[32:35], v[2:5]
	v_mfma_f32_16x16x32_bf16 v[6:9], v[40:43], v[32:35], v[6:9]
	s_nop 0
	s_lshl_b32 s10, s9, 13
	v_or_b32_e32 v0, s10, v24
	v_add_u32_e32 v28, v0, v26
	v_add_u32_e32 v32, v0, v25
	v_add_u32_e32 v0, v0, v23
	ds_read_b128 v[28:31], v28
	ds_read_b128 v[32:35], v32
	ds_read_b128 v[36:39], v0 offset:4096
	ds_read_b128 v[40:43], v0 offset:5120
	s_addk_i32 s10, 0xe000
	s_cmp_gt_i32 s9, 0
	s_cselect_b32 s10, s10, 0x4000
	v_add_u32_e32 v0, s10, v27
	s_mov_b64 s[10:11], 0x2061100
	v_add_u32_e32 v50, 0x1000, v0
	s_mov_b64 s[98:99], 0x2061200
	v_lshl_add_u64 v[44:45], v[44:45], 0, s[98:99]
	v_readfirstlane_b32 s10, v0
	s_mov_b64 s[98:99], 0x47e1200
	v_lshl_add_u64 v[46:47], v[48:49], 0, s[98:99]
	s_mov_b32 m0, s10
	v_readfirstlane_b32 s10, v50
	global_load_lds_dwordx4 v[46:47], off
	s_mov_b32 m0, s10
	s_nop 0
	global_load_lds_dwordx4 v[44:45], off
	s_nop 0
	s_add_i32 s10, s9, 1
	s_waitcnt lgkmcnt(0)
	v_mfma_f32_16x16x32_bf16 v[14:17], v[36:39], v[28:31], v[14:17]
	s_cmp_lg_u32 s9, 2
	s_cselect_b32 s9, s10, 0
	s_add_u32 s0, s0, 0xc0
	v_mfma_f32_16x16x32_bf16 v[10:13], v[40:43], v[28:31], v[10:13]
	s_addc_u32 s1, s1, 0
	s_cmpk_eq_i32 s0, 0x1f80
	v_mfma_f32_16x16x32_bf16 v[2:5], v[36:39], v[32:35], v[2:5]
	v_mfma_f32_16x16x32_bf16 v[6:9], v[40:43], v[32:35], v[6:9]
	s_cbranch_scc0 .LBB0_967
	s_waitcnt vmcnt(2) lgkmcnt(0)
	s_barrier
	s_nop 0
	s_lshl_b32 s0, s9, 13
	v_or_b32_e32 v0, s0, v24
	v_add_u32_e32 v18, v0, v26
	v_add_u32_e32 v27, v0, v25
	v_add_u32_e32 v0, v0, v23
	ds_read_b128 v[18:21], v18
	ds_read_b128 v[28:31], v27
	ds_read_b128 v[32:35], v0 offset:4096
	ds_read_b128 v[36:39], v0 offset:5120
	v_bfe_u32 v0, v22, 6, 1
	s_nop 0
	s_waitcnt vmcnt(0) lgkmcnt(0)
	s_waitcnt lgkmcnt(1)
	v_mfma_f32_16x16x32_bf16 v[14:17], v[32:35], v[18:21], v[14:17]
	v_ashrrev_i32_e32 v40, 7, v22
	v_and_b32_e32 v41, 15, v22
	v_bfe_u32 v22, v22, 4, 2
	s_waitcnt lgkmcnt(0)
	v_mfma_f32_16x16x32_bf16 v[10:13], v[36:39], v[18:21], v[10:13]
	s_barrier
; template <int MI, int NI>
; DI void gemm256(f32x4 (&acc)[MI][NI], const u16* __restrict__ A, int lda, const u16* __restrict__ Bt, int ldb, int K, int m0, int n0, char* smem) {
;     ...
; #pragma unroll
;     for (int mi = 0; mi < MI; ++mi)
; #pragma unroll
;       for (int ni = 0; ni < NI; ++ni)
;         acc[mi][ni] = __builtin_amdgcn_mfma_f32_16x16x32_bf16(bfr[ni], af[mi], acc[mi][ni], 0, 0, 0);
;     st = st == 2 ? 0 : st + 1;
;   }
;   asm volatile("s_waitcnt lgkmcnt(0)" ::: "memory");
;   __builtin_amdgcn_s_barrier();
; template <int MI, int NI>
; DI void resid_tile(const u16* A, int K, const u16* Bt, const float* gate, const float* xl_in, const float* xc_in, float* xl_out, float* xc_out,
;                    int m0, int n0, char* smem) {
;     ...
; #pragma unroll
;   for (int mi = 0; mi < MI; ++mi) {
;     const int m = m0 + wr * 16 * MI + mi * 16 + lr;
;     const int b9 = m < NTL ? m >> 12 : 8;
;     const float* xi = xrow(xl_in, xc_in, m);
;     float* xo = m < NTL ? xl_out + (size_t)m * D : xc_out + (size_t)(m - NTL) * D;
; #pragma unroll
;     for (int ni = 0; ni < NI; ++ni) {
;       const int n = n0 + wc * 16 * NI + ni * 16 + lq * 4;
;       const float4 g = *(const float4*)(gate + (size_t)b9 * 6144 + n);
;       const float4 xv = *(const float4*)(xi + n);
;       float4 ov;
;       ov.x = xv.x + g.x * acc[mi][ni][0]; ov.y = xv.y + g.y * acc[mi][ni][1]; ov.z = xv.z + g.z * acc[mi][ni][2]; ov.w = xv.w + g.w * acc[mi][ni][3];
;       *(float4*)(xo + n) = ov;
;     }
	v_mfma_f32_16x16x32_bf16 v[2:5], v[32:35], v[28:31], v[2:5]
	v_mfma_f32_16x16x32_bf16 v[18:21], v[36:39], v[28:31], v[6:9]
	s_nop 0
	s_addk_i32 s0, 0x2000
	s_cmp_lg_u32 s9, 2
	s_cselect_b32 s0, s0, 0
	v_or_b32_e32 v28, s0, v24
	v_add_u32_e32 v6, v28, v26
	v_add_u32_e32 v24, v28, v25
	v_add_u32_e32 v23, v28, v23
	ds_read_b128 v[6:9], v6
	ds_read_b128 v[24:27], v24
	ds_read_b128 v[28:31], v23 offset:4096
	ds_read_b128 v[32:35], v23 offset:5120
	s_nop 0
	s_waitcnt lgkmcnt(1)
	v_mfma_f32_16x16x32_bf16 v[14:17], v[28:31], v[6:9], v[14:17]
	s_waitcnt lgkmcnt(0)
	s_barrier
	s_waitcnt lgkmcnt(0)
	v_mfma_f32_16x16x32_bf16 v[10:13], v[32:35], v[6:9], v[10:13]
	v_mfma_f32_16x16x32_bf16 v[6:9], v[28:31], v[24:27], v[2:5]
	v_lshlrev_b32_e32 v0, 5, v0
	v_mov_b32_e32 v36, s95
	v_mov_b32_e32 v37, s49
	v_mfma_f32_16x16x32_bf16 v[2:5], v[32:35], v[24:27], v[18:21]
	v_mov_b32_e32 v38, s94
	v_mov_b32_e32 v39, s48
	s_nop 0
	v_lshlrev_b32_e32 v18, 5, v40
	v_add3_u32 v26, v41, s8, v18
	v_lshlrev_b32_e32 v18, 2, v22
	v_add3_u32 v18, v18, s7, v0
	v_min_i32_e32 v0, 0x8000, v26
	v_cmp_gt_i32_e32 vcc, s58, v26
	v_ashrrev_i32_e32 v28, 12, v0
	v_add_u32_e32 v0, 0xffff8000, v26
	v_ashrrev_i32_e32 v27, 31, v26
	v_cndmask_b32_e32 v21, 0, v27, vcc
	v_cndmask_b32_e32 v20, v0, v26, vcc
	v_cndmask_b32_e32 v23, v36, v37, vcc
	v_cndmask_b32_e32 v22, v38, v39, vcc
	v_lshlrev_b64 v[20:21], 12, v[20:21]
	v_lshl_add_u64 v[20:21], v[22:23], 0, v[20:21]
	v_lshlrev_b64 v[22:23], 12, v[26:27]
	v_lshlrev_b64 v[24:25], 12, v[0:1]
	v_lshl_add_u64 v[22:23], s[48:49], 0, v[22:23]
	v_lshl_add_u64 v[24:25], s[94:95], 0, v[24:25]
	v_ashrrev_i32_e32 v19, 31, v18
	v_cndmask_b32_e32 v23, v25, v23, vcc
	v_cndmask_b32_e32 v22, v24, v22, vcc
	v_mul_hi_i32_i24_e32 v25, 0x6000, v28
	v_mul_i32_i24_e32 v24, 0x6000, v28
	v_lshl_add_u64 v[24:25], s[82:83], 0, v[24:25]
	v_lshlrev_b64 v[28:29], 2, v[18:19]
	v_lshl_add_u64 v[30:31], v[24:25], 0, v[28:29]
	v_lshl_add_u64 v[32:33], v[20:21], 0, v[28:29]
	v_lshl_add_u64 v[34:35], v[22:23], 0, v[28:29]
	flat_load_dwordx4 v[18:21], v[30:31]
	flat_load_dwordx4 v[22:25], v[32:33]
	s_waitcnt vmcnt(0) lgkmcnt(0)
	v_pk_fma_f32 v[14:15], v[14:15], v[18:19], v[22:23]
	v_pk_fma_f32 v[16:17], v[16:17], v[20:21], v[24:25]
	flat_store_dwordx4 v[34:35], v[14:17]
	flat_load_dwordx4 v[14:17], v[30:31] offset:64
	s_nop 0
	flat_load_dwordx4 v[18:21], v[32:33] offset:64
	s_waitcnt vmcnt(0) lgkmcnt(0)
	v_pk_fma_f32 v[10:11], v[10:11], v[14:15], v[18:19]
	v_pk_fma_f32 v[12:13], v[12:13], v[16:17], v[20:21]
	flat_store_dwordx4 v[34:35], v[10:13] offset:64
	s_nop 1
	v_add_u32_e32 v10, 16, v26
	v_min_i32_e32 v0, 0x8000, v10
	v_cmp_gt_i32_e32 vcc, s58, v10
	v_ashrrev_i32_e32 v16, 12, v0
	v_add_u32_e32 v0, 0xffff8010, v26
	v_ashrrev_i32_e32 v11, 31, v10
	v_cndmask_b32_e32 v13, 0, v11, vcc
	v_cndmask_b32_e32 v12, v0, v10, vcc
	v_cndmask_b32_e32 v15, v36, v37, vcc
	v_cndmask_b32_e32 v14, v38, v39, vcc
	v_lshlrev_b64 v[12:13], 12, v[12:13]
	v_lshl_add_u64 v[12:13], v[14:15], 0, v[12:13]
	v_lshlrev_b64 v[10:11], 12, v[10:11]
	v_lshlrev_b64 v[14:15], 12, v[0:1]
	v_lshl_add_u64 v[10:11], s[48:49], 0, v[10:11]
	v_lshl_add_u64 v[14:15], s[94:95], 0, v[14:15]
	v_cndmask_b32_e32 v11, v15, v11, vcc
	v_cndmask_b32_e32 v10, v14, v10, vcc
	v_mul_hi_i32_i24_e32 v15, 0x6000, v16
	v_mul_i32_i24_e32 v14, 0x6000, v16
	v_lshl_add_u64 v[14:15], s[82:83], 0, v[14:15]
	v_lshl_add_u64 v[18:19], v[14:15], 0, v[28:29]
	v_lshl_add_u64 v[20:21], v[12:13], 0, v[28:29]
	v_lshl_add_u64 v[22:23], v[10:11], 0, v[28:29]
	flat_load_dwordx4 v[10:13], v[18:19]
	flat_load_dwordx4 v[14:17], v[20:21]
	s_waitcnt vmcnt(0) lgkmcnt(0)
	v_pk_fma_f32 v[6:7], v[6:7], v[10:11], v[14:15]
	v_pk_fma_f32 v[8:9], v[8:9], v[12:13], v[16:17]
	flat_store_dwordx4 v[22:23], v[6:9]
	flat_load_dwordx4 v[6:9], v[18:19] offset:64
	s_nop 0
	flat_load_dwordx4 v[10:13], v[20:21] offset:64
	s_waitcnt vmcnt(0) lgkmcnt(0)
	v_pk_fma_f32 v[2:3], v[2:3], v[6:7], v[10:11]
	v_pk_fma_f32 v[4:5], v[4:5], v[8:9], v[12:13]
	flat_store_dwordx4 v[22:23], v[2:5] offset:64
	s_add_i32 s4, s4, s79
	s_add_i32 s5, s5, s40
	s_add_i32 s6, s6, s41
	s_cmpk_gt_i32 s4, 0x1ff
	s_cbranch_scc0 .LBB0_966
